# comb16 + back-edge rotation (guide 7.11): K-loop counter/pointer updates and exit test moved in front of the loop-back barrier in the K>=512 GEMM loops
# baseline (speedup 1.0000x reference)
; #define PG8_STAGE(bufoff, gbase, voff) do { _Pragma("unroll") for (int _i = 0; _i < 2; ++_i) \
;         __builtin_amdgcn_global_load_lds((const unsigned*)((const char*)(gbase) + (voff)[_i]), (LAS unsigned*)(lds + (bufoff) + ldsw + _i * 8192), 16, 0, 0); } while (0)
; #define PG8_LDA(dst, b, h) do { _Pragma("unroll") for (int m = 0; m < 4; ++m) _Pragma("unroll") for (int k = 0; k < 2; ++k) dst[m][k] = *(const LAS bf16x8*)(lds + PG8_SA(b, h) + aoff + m * 2048 + k * 1024); } while (0)
; #define PG8_LDB(dst, b, h) do { _Pragma("unroll") for (int n = 0; n < 2; ++n) _Pragma("unroll") for (int k = 0; k < 2; ++k) dst[n][k] = *(const LAS bf16x8*)(lds + PG8_SB(b, h) + boff + n * 2048 + k * 1024); } while (0)
; #define PG8_MMA(ai, bj, At, Bt) do { __builtin_amdgcn_s_setprio(1); _Pragma("unroll") for (int m = 0; m < 4; ++m) _Pragma("unroll") for (int n = 0; n < 2; ++n) _Pragma("unroll") for (int k = 0; k < 2; ++k) \
;         acc[ai][bj][m][n] = __builtin_amdgcn_mfma_f32_16x16x32_bf16(Bt[n][k], At[m][k], acc[ai][bj][m][n], 0, 0, 0); __builtin_amdgcn_s_setprio(0); } while (0)
; #define PG8_WAIT_V(n) asm volatile("s_waitcnt vmcnt(" #n ")" ::: "memory")
; template <class Epi>
; __device__ __forceinline__ void gemm_phase(LAS unsigned char* lds, const Gemm g, int G, int c, const Epi& E) {
;     ...
;         const bool has_next = S.next(ui + 1, nxt);
;         const char* nA = has_next ? (const char*)(g.A + (size_t)nxt.pb * g.sA) + (size_t)nxt.pm * 2 * hstepA : cA;
;         const char* nB = has_next ? (const char*)(g.Bt + (size_t)nxt.pb * g.sB) + (size_t)nxt.pn * 2 * hstepB : cB;
; #pragma nounroll
;         for (int t = 0; t < nt; t += 2) {
;             const bool last = (t == nt - 2);
;             const char* a1 = cA + (size_t)(t + 1) * kstep;
;             const char* a2 = last ? nA : cA + (size_t)(t + 2) * kstep; const char* b2 = last ? nB : cB + (size_t)(t + 2) * kstep;
;             const char* a3 = a2 + kstep; const char* b3 = b2 + kstep;
;             PG8_LDB(B0, 0, 0); PG8_LDB(B1, 0, 1); PG8_SCHED; PG8_LDA(At, 0, 0); PG8_STAGE(PG8_SA(1, 1), a1 + hstepA, voffA);
;             PG8_WAIT_V(8); PG8_WAIT_L(0); PG8_BAR; PG8_MMA(0, 0, At, B0); PG8_MMA(0, 1, At, B1); PG8_BAR; PG8_SCHED;
;             PG8_LDA(At, 0, 1); PG8_STAGE(PG8_SB(0, 0), b2, voffB); PG8_STAGE(PG8_SB(0, 1), b2 + hstepB, voffB); PG8_STAGE(PG8_SA(0, 0), a2, voffA);
.LBB0_235:
	s_ashr_i32 s43, s42, 31
	s_lshl_b64 s[52:53], s[42:43], 19
	s_add_u32 s52, s30, s52
	s_addc_u32 s53, s31, s53
	s_and_b64 s[4:5], s[4:5], exec
	s_cselect_b32 s7, s53, s55
	s_cselect_b32 s43, s52, s54
	s_add_u32 s4, s56, 0x40080
	s_addc_u32 s5, s57, 0
	s_add_u32 s45, s54, 0x100
	s_addc_u32 s84, s55, 0
	s_mov_b32 s85, -2
	s_waitcnt lgkmcnt(0)
	ds_read_b128 v[146:149], v152
	ds_read_b128 v[158:161], v152 offset:1024
	ds_read_b128 v[162:165], v152 offset:2048
	ds_read_b128 v[166:169], v152 offset:3072
	ds_read_b128 v[170:173], v153
	ds_read_b128 v[174:177], v153 offset:1024
	ds_read_b128 v[178:181], v153 offset:2048
	ds_read_b128 v[182:185], v153 offset:3072
	s_add_u32 s33, s4, 0xfffc0080
	s_addc_u32 s54, s5, -1
	s_cmp_eq_u32 s85, 12
	s_cselect_b32 s57, s47, s54
	s_cselect_b32 s56, s46, s33
	s_cselect_b32 s55, s7, s84
	s_cselect_b32 s54, s43, s45
	v_lshl_add_u64 v[218:219], s[4:5], 0, v[138:139]
	s_add_i32 m0, s11, 0xc000
	ds_read_b128 v[186:189], v154
	ds_read_b128 v[190:193], v154 offset:1024
	ds_read_b128 v[194:197], v154 offset:2048
	ds_read_b128 v[198:201], v154 offset:3072
	ds_read_b128 v[202:205], v154 offset:4096
	ds_read_b128 v[206:209], v154 offset:5120
	ds_read_b128 v[210:213], v154 offset:6144
	ds_read_b128 v[214:217], v154 offset:7168
	global_load_lds_dwordx4 v[218:219], off
	v_lshl_add_u64 v[218:219], s[4:5], 0, v[140:141]
	s_add_i32 m0, s11, 0xe000
	s_nop 0
	global_load_lds_dwordx4 v[218:219], off
	s_waitcnt vmcnt(8)
	s_waitcnt lgkmcnt(0)
	s_barrier
	s_setprio 0
	v_mfma_f32_16x16x32_bf16 v[126:129], v[146:149], v[186:189], 0
	v_mfma_f32_16x16x32_bf16 v[122:125], v[162:165], v[186:189], 0
	v_mfma_f32_16x16x32_bf16 v[110:113], v[146:149], v[194:197], 0
	v_mfma_f32_16x16x32_bf16 v[106:109], v[162:165], v[194:197], 0
	v_mfma_f32_16x16x32_bf16 v[94:97], v[146:149], v[202:205], 0
	v_mfma_f32_16x16x32_bf16 v[90:93], v[162:165], v[202:205], 0
	v_mfma_f32_16x16x32_bf16 v[78:81], v[146:149], v[210:213], 0
	v_mfma_f32_16x16x32_bf16 v[74:77], v[162:165], v[210:213], 0
	v_mfma_f32_16x16x32_bf16 v[126:129], v[158:161], v[190:193], v[126:129]
	v_mfma_f32_16x16x32_bf16 v[122:125], v[166:169], v[190:193], v[122:125]
	v_mfma_f32_16x16x32_bf16 v[110:113], v[158:161], v[198:201], v[110:113]
	v_mfma_f32_16x16x32_bf16 v[106:109], v[166:169], v[198:201], v[106:109]
	v_mfma_f32_16x16x32_bf16 v[94:97], v[158:161], v[206:209], v[94:97]
	v_mfma_f32_16x16x32_bf16 v[90:93], v[166:169], v[206:209], v[90:93]
	v_mfma_f32_16x16x32_bf16 v[78:81], v[158:161], v[214:217], v[78:81]
	v_mfma_f32_16x16x32_bf16 v[74:77], v[166:169], v[214:217], v[74:77]
	s_setprio 2
	s_setprio 0
	v_mfma_f32_16x16x32_bf16 v[118:121], v[170:173], v[186:189], 0
	v_mfma_f32_16x16x32_bf16 v[114:117], v[178:181], v[186:189], 0
	v_mfma_f32_16x16x32_bf16 v[102:105], v[170:173], v[194:197], 0
	v_mfma_f32_16x16x32_bf16 v[98:101], v[178:181], v[194:197], 0
	v_mfma_f32_16x16x32_bf16 v[86:89], v[170:173], v[202:205], 0
	v_mfma_f32_16x16x32_bf16 v[82:85], v[178:181], v[202:205], 0
	v_mfma_f32_16x16x32_bf16 v[70:73], v[170:173], v[210:213], 0
	v_mfma_f32_16x16x32_bf16 v[66:69], v[178:181], v[210:213], 0
	v_mfma_f32_16x16x32_bf16 v[118:121], v[174:177], v[190:193], v[118:121]
	v_mfma_f32_16x16x32_bf16 v[114:117], v[182:185], v[190:193], v[114:117]
	v_mfma_f32_16x16x32_bf16 v[102:105], v[174:177], v[198:201], v[102:105]
	v_mfma_f32_16x16x32_bf16 v[98:101], v[182:185], v[198:201], v[98:101]
	v_mfma_f32_16x16x32_bf16 v[86:89], v[174:177], v[206:209], v[86:89]
	v_mfma_f32_16x16x32_bf16 v[82:85], v[182:185], v[206:209], v[82:85]
	v_mfma_f32_16x16x32_bf16 v[70:73], v[174:177], v[214:217], v[70:73]
	v_mfma_f32_16x16x32_bf16 v[66:69], v[182:185], v[214:217], v[66:69]
	s_setprio 2
	s_barrier
	s_add_i32 s33, s79, s60
	v_lshl_add_u64 v[218:219], s[54:55], 0, v[132:133]
	s_mov_b32 m0, s33
	ds_read_b128 v[186:189], v154 offset:16384
	ds_read_b128 v[190:193], v154 offset:17408
	ds_read_b128 v[194:197], v154 offset:18432
	ds_read_b128 v[198:201], v154 offset:19456
	ds_read_b128 v[202:205], v154 offset:20480
	ds_read_b128 v[206:209], v154 offset:21504
	ds_read_b128 v[210:213], v154 offset:22528
	ds_read_b128 v[214:217], v154 offset:23552
	global_load_lds_dwordx4 v[218:219], off
	s_add_i32 m0, s33, 0x2000
	s_add_u32 s62, s54, 0x40000
	v_lshl_add_u64 v[220:221], s[54:55], 0, v[136:137]
	s_addc_u32 s63, s55, 0
	s_add_i32 s33, s80, s60
	global_load_lds_dwordx4 v[220:221], off
	v_lshl_add_u64 v[222:223], s[62:63], 0, v[132:133]
	s_mov_b32 m0, s33
	v_lshl_add_u64 v[224:225], s[56:57], 0, v[134:135]
	global_load_lds_dwordx4 v[222:223], off
	v_lshl_add_u64 v[222:223], s[62:63], 0, v[136:137]
	s_add_i32 m0, s33, 0x2000
	s_nop 0
	global_load_lds_dwordx4 v[222:223], off
	v_lshl_add_u64 v[222:223], s[56:57], 0, v[130:131]
	s_mov_b32 m0, s11
	s_nop 0
	global_load_lds_dwordx4 v[222:223], off
	s_mov_b32 m0, s61
	s_nop 0
	global_load_lds_dwordx4 v[224:225], off
	s_waitcnt vmcnt(8)
	s_waitcnt lgkmcnt(0)
	s_barrier
; #define PG8_STAGE(bufoff, gbase, voff) do { _Pragma("unroll") for (int _i = 0; _i < 2; ++_i) \
;         __builtin_amdgcn_global_load_lds((const unsigned*)((const char*)(gbase) + (voff)[_i]), (LAS unsigned*)(lds + (bufoff) + ldsw + _i * 8192), 16, 0, 0); } while (0)
; #define PG8_LDA(dst, b, h) do { _Pragma("unroll") for (int m = 0; m < 4; ++m) _Pragma("unroll") for (int k = 0; k < 2; ++k) dst[m][k] = *(const LAS bf16x8*)(lds + PG8_SA(b, h) + aoff + m * 2048 + k * 1024); } while (0)
; #define PG8_LDB(dst, b, h) do { _Pragma("unroll") for (int n = 0; n < 2; ++n) _Pragma("unroll") for (int k = 0; k < 2; ++k) dst[n][k] = *(const LAS bf16x8*)(lds + PG8_SB(b, h) + boff + n * 2048 + k * 1024); } while (0)
; #define PG8_MMA(ai, bj, At, Bt) do { __builtin_amdgcn_s_setprio(1); _Pragma("unroll") for (int m = 0; m < 4; ++m) _Pragma("unroll") for (int n = 0; n < 2; ++n) _Pragma("unroll") for (int k = 0; k < 2; ++k) \
;         acc[ai][bj][m][n] = __builtin_amdgcn_mfma_f32_16x16x32_bf16(Bt[n][k], At[m][k], acc[ai][bj][m][n], 0, 0, 0); __builtin_amdgcn_s_setprio(0); } while (0)
; #define PG8_WAIT_V(n) asm volatile("s_waitcnt vmcnt(" #n ")" ::: "memory")
; #define PG8_WAIT_L(n) asm volatile("s_waitcnt lgkmcnt(" #n ")" ::: "memory")
; #define PG8_BAR __builtin_amdgcn_s_barrier()
; #define PG8_SCHED __builtin_amdgcn_sched_barrier(0)
; template <class Epi>
; __device__ __forceinline__ void gemm_phase(LAS unsigned char* lds, const Gemm g, int G, int c, const Epi& E) {
;     ...
;             PG8_WAIT_V(8); PG8_WAIT_L(0); PG8_BAR; PG8_MMA(1, 0, At, B0); PG8_MMA(1, 1, At, B1); PG8_BAR; PG8_SCHED;
;             PG8_LDB(B0, 1, 0); PG8_LDB(B1, 1, 1); PG8_SCHED; PG8_LDA(At, 1, 0); PG8_STAGE(PG8_SA(0, 1), a2 + hstepA, voffA);
;             PG8_WAIT_V(8); PG8_WAIT_L(0); PG8_BAR; PG8_MMA(0, 0, At, B0); PG8_MMA(0, 1, At, B1); PG8_BAR; PG8_SCHED;
	s_setprio 0
	v_mfma_f32_16x16x32_bf16 v[62:65], v[146:149], v[186:189], 0
	v_mfma_f32_16x16x32_bf16 v[58:61], v[162:165], v[186:189], 0
	v_mfma_f32_16x16x32_bf16 v[46:49], v[146:149], v[194:197], 0
	v_mfma_f32_16x16x32_bf16 v[42:45], v[162:165], v[194:197], 0
	v_mfma_f32_16x16x32_bf16 v[30:33], v[146:149], v[202:205], 0
	v_mfma_f32_16x16x32_bf16 v[26:29], v[162:165], v[202:205], 0
	v_mfma_f32_16x16x32_bf16 v[14:17], v[146:149], v[210:213], 0
	v_mfma_f32_16x16x32_bf16 v[10:13], v[162:165], v[210:213], 0
	v_mfma_f32_16x16x32_bf16 v[62:65], v[158:161], v[190:193], v[62:65]
	v_mfma_f32_16x16x32_bf16 v[58:61], v[166:169], v[190:193], v[58:61]
	v_mfma_f32_16x16x32_bf16 v[46:49], v[158:161], v[198:201], v[46:49]
	v_mfma_f32_16x16x32_bf16 v[42:45], v[166:169], v[198:201], v[42:45]
	v_mfma_f32_16x16x32_bf16 v[30:33], v[158:161], v[206:209], v[30:33]
	v_mfma_f32_16x16x32_bf16 v[26:29], v[166:169], v[206:209], v[26:29]
	v_mfma_f32_16x16x32_bf16 v[14:17], v[158:161], v[214:217], v[14:17]
	v_mfma_f32_16x16x32_bf16 v[10:13], v[166:169], v[214:217], v[10:13]
	s_setprio 2
	s_setprio 0
	v_mfma_f32_16x16x32_bf16 v[54:57], v[170:173], v[186:189], 0
	v_mfma_f32_16x16x32_bf16 v[50:53], v[178:181], v[186:189], 0
	v_mfma_f32_16x16x32_bf16 v[38:41], v[170:173], v[194:197], 0
	v_mfma_f32_16x16x32_bf16 v[34:37], v[178:181], v[194:197], 0
	v_mfma_f32_16x16x32_bf16 v[22:25], v[170:173], v[202:205], 0
	v_mfma_f32_16x16x32_bf16 v[18:21], v[178:181], v[202:205], 0
	v_mfma_f32_16x16x32_bf16 v[6:9], v[170:173], v[210:213], 0
	v_mfma_f32_16x16x32_bf16 v[2:5], v[178:181], v[210:213], 0
	v_mfma_f32_16x16x32_bf16 v[54:57], v[174:177], v[190:193], v[54:57]
	v_mfma_f32_16x16x32_bf16 v[50:53], v[182:185], v[190:193], v[50:53]
	v_mfma_f32_16x16x32_bf16 v[38:41], v[174:177], v[198:201], v[38:41]
	v_mfma_f32_16x16x32_bf16 v[34:37], v[182:185], v[198:201], v[34:37]
	v_mfma_f32_16x16x32_bf16 v[22:25], v[174:177], v[206:209], v[22:25]
	v_mfma_f32_16x16x32_bf16 v[18:21], v[182:185], v[206:209], v[18:21]
	v_mfma_f32_16x16x32_bf16 v[6:9], v[174:177], v[214:217], v[6:9]
	v_mfma_f32_16x16x32_bf16 v[2:5], v[182:185], v[214:217], v[2:5]
	s_setprio 2
	s_barrier
	s_add_i32 s33, 0, 0x18000
	v_add_u32_e32 v157, s33, v151
	s_add_i32 s62, 0, 0x1c000
	ds_read_b128 v[146:149], v157
	ds_read_b128 v[158:161], v157 offset:1024
	ds_read_b128 v[162:165], v157 offset:2048
	ds_read_b128 v[166:169], v157 offset:3072
	v_add_u32_e32 v157, s62, v151
	ds_read_b128 v[170:173], v157
	ds_read_b128 v[174:177], v157 offset:1024
	ds_read_b128 v[178:181], v157 offset:2048
	ds_read_b128 v[182:185], v157 offset:3072
	s_add_u32 s56, s56, 0x40000
	s_addc_u32 s57, s57, 0
	s_mov_b32 m0, s66
	v_lshl_add_u64 v[226:227], s[56:57], 0, v[130:131]
	ds_read_b128 v[186:189], v154 offset:32768
	ds_read_b128 v[190:193], v154 offset:33792
	ds_read_b128 v[194:197], v154 offset:34816
	ds_read_b128 v[198:201], v154 offset:35840
	ds_read_b128 v[202:205], v154 offset:36864
	ds_read_b128 v[206:209], v154 offset:37888
	ds_read_b128 v[210:213], v154 offset:38912
	ds_read_b128 v[214:217], v154 offset:39936
	global_load_lds_dwordx4 v[226:227], off
	v_lshl_add_u64 v[226:227], s[56:57], 0, v[134:135]
	s_mov_b32 m0, s67
	s_nop 0
	global_load_lds_dwordx4 v[226:227], off
	s_waitcnt vmcnt(8)
	s_waitcnt lgkmcnt(0)
	s_barrier
	s_setprio 0
	v_mfma_f32_16x16x32_bf16 v[126:129], v[146:149], v[186:189], v[126:129]
	v_mfma_f32_16x16x32_bf16 v[122:125], v[162:165], v[186:189], v[122:125]
	v_mfma_f32_16x16x32_bf16 v[110:113], v[146:149], v[194:197], v[110:113]
	v_mfma_f32_16x16x32_bf16 v[106:109], v[162:165], v[194:197], v[106:109]
	v_mfma_f32_16x16x32_bf16 v[94:97], v[146:149], v[202:205], v[94:97]
	v_mfma_f32_16x16x32_bf16 v[90:93], v[162:165], v[202:205], v[90:93]
	v_mfma_f32_16x16x32_bf16 v[78:81], v[146:149], v[210:213], v[78:81]
	v_mfma_f32_16x16x32_bf16 v[74:77], v[162:165], v[210:213], v[74:77]
	v_mfma_f32_16x16x32_bf16 v[126:129], v[158:161], v[190:193], v[126:129]
	v_mfma_f32_16x16x32_bf16 v[122:125], v[166:169], v[190:193], v[122:125]
	v_mfma_f32_16x16x32_bf16 v[110:113], v[158:161], v[198:201], v[110:113]
	v_mfma_f32_16x16x32_bf16 v[106:109], v[166:169], v[198:201], v[106:109]
	v_mfma_f32_16x16x32_bf16 v[94:97], v[158:161], v[206:209], v[94:97]
	v_mfma_f32_16x16x32_bf16 v[90:93], v[166:169], v[206:209], v[90:93]
	v_mfma_f32_16x16x32_bf16 v[78:81], v[158:161], v[214:217], v[78:81]
	v_mfma_f32_16x16x32_bf16 v[74:77], v[166:169], v[214:217], v[74:77]
	s_setprio 2
	s_setprio 0
	v_mfma_f32_16x16x32_bf16 v[118:121], v[170:173], v[186:189], v[118:121]
	v_mfma_f32_16x16x32_bf16 v[114:117], v[178:181], v[186:189], v[114:117]
	v_mfma_f32_16x16x32_bf16 v[102:105], v[170:173], v[194:197], v[102:105]
	v_mfma_f32_16x16x32_bf16 v[98:101], v[178:181], v[194:197], v[98:101]
	v_mfma_f32_16x16x32_bf16 v[86:89], v[170:173], v[202:205], v[86:89]
	v_mfma_f32_16x16x32_bf16 v[82:85], v[178:181], v[202:205], v[82:85]
	v_mfma_f32_16x16x32_bf16 v[70:73], v[170:173], v[210:213], v[70:73]
	v_mfma_f32_16x16x32_bf16 v[66:69], v[178:181], v[210:213], v[66:69]
	v_mfma_f32_16x16x32_bf16 v[118:121], v[174:177], v[190:193], v[118:121]
	v_mfma_f32_16x16x32_bf16 v[114:117], v[182:185], v[190:193], v[114:117]
	v_mfma_f32_16x16x32_bf16 v[102:105], v[174:177], v[198:201], v[102:105]
	v_mfma_f32_16x16x32_bf16 v[98:101], v[182:185], v[198:201], v[98:101]
	v_mfma_f32_16x16x32_bf16 v[86:89], v[174:177], v[206:209], v[86:89]
	v_mfma_f32_16x16x32_bf16 v[82:85], v[182:185], v[206:209], v[82:85]
	v_mfma_f32_16x16x32_bf16 v[70:73], v[174:177], v[214:217], v[70:73]
	v_mfma_f32_16x16x32_bf16 v[66:69], v[182:185], v[214:217], v[66:69]
	s_setprio 2
	s_barrier
; #define PG8_STAGE(bufoff, gbase, voff) do { _Pragma("unroll") for (int _i = 0; _i < 2; ++_i) \
;         __builtin_amdgcn_global_load_lds((const unsigned*)((const char*)(gbase) + (voff)[_i]), (LAS unsigned*)(lds + (bufoff) + ldsw + _i * 8192), 16, 0, 0); } while (0)
; #define PG8_LDA(dst, b, h) do { _Pragma("unroll") for (int m = 0; m < 4; ++m) _Pragma("unroll") for (int k = 0; k < 2; ++k) dst[m][k] = *(const LAS bf16x8*)(lds + PG8_SA(b, h) + aoff + m * 2048 + k * 1024); } while (0)
; #define PG8_LDB(dst, b, h) do { _Pragma("unroll") for (int n = 0; n < 2; ++n) _Pragma("unroll") for (int k = 0; k < 2; ++k) dst[n][k] = *(const LAS bf16x8*)(lds + PG8_SB(b, h) + boff + n * 2048 + k * 1024); } while (0)
; #define PG8_MMA(ai, bj, At, Bt) do { __builtin_amdgcn_s_setprio(1); _Pragma("unroll") for (int m = 0; m < 4; ++m) _Pragma("unroll") for (int n = 0; n < 2; ++n) _Pragma("unroll") for (int k = 0; k < 2; ++k) \
;         acc[ai][bj][m][n] = __builtin_amdgcn_mfma_f32_16x16x32_bf16(Bt[n][k], At[m][k], acc[ai][bj][m][n], 0, 0, 0); __builtin_amdgcn_s_setprio(0); } while (0)
; #define PG8_WAIT_V(n) asm volatile("s_waitcnt vmcnt(" #n ")" ::: "memory")
; #define PG8_WAIT_L(n) asm volatile("s_waitcnt lgkmcnt(" #n ")" ::: "memory")
; #define PG8_BAR __builtin_amdgcn_s_barrier()
; #define PG8_SCHED __builtin_amdgcn_sched_barrier(0)
; template <class Epi>
; __device__ __forceinline__ void gemm_phase(LAS unsigned char* lds, const Gemm g, int G, int c, const Epi& E) {
;     ...
;         for (int t = 0; t < nt; t += 2) {
;             const bool last = (t == nt - 2);
;             const char* a1 = cA + (size_t)(t + 1) * kstep;
;             const char* a2 = last ? nA : cA + (size_t)(t + 2) * kstep; const char* b2 = last ? nB : cB + (size_t)(t + 2) * kstep;
;             const char* a3 = a2 + kstep; const char* b3 = b2 + kstep;
;             PG8_LDB(B0, 0, 0); PG8_LDB(B1, 0, 1); PG8_SCHED; PG8_LDA(At, 0, 0); PG8_STAGE(PG8_SA(1, 1), a1 + hstepA, voffA);
;             PG8_WAIT_V(8); PG8_WAIT_L(0); PG8_BAR; PG8_MMA(0, 0, At, B0); PG8_MMA(0, 1, At, B1); PG8_BAR; PG8_SCHED;
;     ...
;             PG8_LDA(At, 1, 1); PG8_STAGE(PG8_SB(1, 0), b3, voffB); PG8_STAGE(PG8_SB(1, 1), b3 + hstepB, voffB); PG8_STAGE(PG8_SA(1, 0), a3, voffA);
;             PG8_WAIT_V(8); PG8_WAIT_L(0); PG8_BAR; PG8_MMA(1, 0, At, B0); PG8_MMA(1, 1, At, B1); PG8_BAR; PG8_SCHED;
	s_add_i32 s33, s33, s60
	v_lshl_add_u64 v[218:219], v[218:219], 0, s[20:21]
	s_mov_b32 m0, s33
	ds_read_b128 v[186:189], v154 offset:49152
	ds_read_b128 v[190:193], v154 offset:50176
	ds_read_b128 v[194:197], v154 offset:51200
	ds_read_b128 v[198:201], v154 offset:52224
	ds_read_b128 v[202:205], v154 offset:53248
	ds_read_b128 v[206:209], v154 offset:54272
	ds_read_b128 v[210:213], v154 offset:55296
	ds_read_b128 v[214:217], v154 offset:56320
	global_load_lds_dwordx4 v[218:219], off
	s_add_i32 m0, s33, 0x2000
	s_add_u32 s54, s54, 0x40080
	v_lshl_add_u64 v[218:219], v[220:221], 0, s[20:21]
	s_addc_u32 s55, s55, 0
	s_add_i32 s33, s62, s60
	global_load_lds_dwordx4 v[218:219], off
	v_lshl_add_u64 v[218:219], s[54:55], 0, v[132:133]
	s_mov_b32 m0, s33
	s_nop 0
	global_load_lds_dwordx4 v[218:219], off
	v_lshl_add_u64 v[218:219], s[54:55], 0, v[136:137]
	s_add_i32 m0, s33, 0x2000
	s_nop 0
	global_load_lds_dwordx4 v[218:219], off
	v_lshl_add_u64 v[218:219], v[222:223], 0, s[20:21]
	s_mov_b32 m0, s71
	s_nop 0
	global_load_lds_dwordx4 v[218:219], off
	v_lshl_add_u64 v[218:219], v[224:225], 0, s[20:21]
	s_mov_b32 m0, s72
	s_nop 0
	global_load_lds_dwordx4 v[218:219], off
	s_waitcnt vmcnt(8)
	s_waitcnt lgkmcnt(0)
	s_barrier
	s_setprio 0
	v_mfma_f32_16x16x32_bf16 v[62:65], v[146:149], v[186:189], v[62:65]
	v_mfma_f32_16x16x32_bf16 v[58:61], v[162:165], v[186:189], v[58:61]
	v_mfma_f32_16x16x32_bf16 v[46:49], v[146:149], v[194:197], v[46:49]
	v_mfma_f32_16x16x32_bf16 v[42:45], v[162:165], v[194:197], v[42:45]
	v_mfma_f32_16x16x32_bf16 v[30:33], v[146:149], v[202:205], v[30:33]
	v_mfma_f32_16x16x32_bf16 v[26:29], v[162:165], v[202:205], v[26:29]
	v_mfma_f32_16x16x32_bf16 v[14:17], v[146:149], v[210:213], v[14:17]
	v_mfma_f32_16x16x32_bf16 v[10:13], v[162:165], v[210:213], v[10:13]
	v_mfma_f32_16x16x32_bf16 v[62:65], v[158:161], v[190:193], v[62:65]
	v_mfma_f32_16x16x32_bf16 v[58:61], v[166:169], v[190:193], v[58:61]
	v_mfma_f32_16x16x32_bf16 v[46:49], v[158:161], v[198:201], v[46:49]
	v_mfma_f32_16x16x32_bf16 v[42:45], v[166:169], v[198:201], v[42:45]
	v_mfma_f32_16x16x32_bf16 v[30:33], v[158:161], v[206:209], v[30:33]
	v_mfma_f32_16x16x32_bf16 v[26:29], v[166:169], v[206:209], v[26:29]
	v_mfma_f32_16x16x32_bf16 v[14:17], v[158:161], v[214:217], v[14:17]
	v_mfma_f32_16x16x32_bf16 v[10:13], v[166:169], v[214:217], v[10:13]
	s_setprio 2
	s_setprio 0
	v_mfma_f32_16x16x32_bf16 v[54:57], v[170:173], v[186:189], v[54:57]
	v_mfma_f32_16x16x32_bf16 v[50:53], v[178:181], v[186:189], v[50:53]
	v_mfma_f32_16x16x32_bf16 v[38:41], v[170:173], v[194:197], v[38:41]
	v_mfma_f32_16x16x32_bf16 v[34:37], v[178:181], v[194:197], v[34:37]
	v_mfma_f32_16x16x32_bf16 v[22:25], v[170:173], v[202:205], v[22:25]
	v_mfma_f32_16x16x32_bf16 v[18:21], v[178:181], v[202:205], v[18:21]
	v_mfma_f32_16x16x32_bf16 v[6:9], v[170:173], v[210:213], v[6:9]
	v_mfma_f32_16x16x32_bf16 v[2:5], v[178:181], v[210:213], v[2:5]
	v_mfma_f32_16x16x32_bf16 v[54:57], v[174:177], v[190:193], v[54:57]
	v_mfma_f32_16x16x32_bf16 v[50:53], v[182:185], v[190:193], v[50:53]
	v_mfma_f32_16x16x32_bf16 v[38:41], v[174:177], v[198:201], v[38:41]
	v_mfma_f32_16x16x32_bf16 v[34:37], v[182:185], v[198:201], v[34:37]
	v_mfma_f32_16x16x32_bf16 v[22:25], v[174:177], v[206:209], v[22:25]
	v_mfma_f32_16x16x32_bf16 v[18:21], v[182:185], v[206:209], v[18:21]
	v_mfma_f32_16x16x32_bf16 v[6:9], v[174:177], v[214:217], v[6:9]
	v_mfma_f32_16x16x32_bf16 v[2:5], v[182:185], v[214:217], v[2:5]
	s_setprio 2
	s_add_i32 s85, s85, 2
	s_add_u32 s4, s4, 0x100
	s_addc_u32 s5, s5, 0
	s_add_u32 s45, s45, 0x100
	s_addc_u32 s84, s84, 0
	s_cmp_gt_u32 s85, 13
	s_barrier
	s_cbranch_scc0 .LBB0_236
.LBB0_236:
	ds_read_b128 v[146:149], v152
	ds_read_b128 v[158:161], v152 offset:1024
	ds_read_b128 v[162:165], v152 offset:2048
	ds_read_b128 v[166:169], v152 offset:3072
	ds_read_b128 v[170:173], v153
	ds_read_b128 v[174:177], v153 offset:1024
	ds_read_b128 v[178:181], v153 offset:2048
	ds_read_b128 v[182:185], v153 offset:3072
	s_add_u32 s33, s4, 0xfffc0080
	s_addc_u32 s54, s5, -1
	s_cmp_eq_u32 s85, 12
	s_cselect_b32 s57, s47, s54
	s_cselect_b32 s56, s46, s33
	s_cselect_b32 s55, s7, s84
	s_cselect_b32 s54, s43, s45
	v_lshl_add_u64 v[218:219], s[4:5], 0, v[138:139]
	s_add_i32 m0, s11, 0xc000
	ds_read_b128 v[186:189], v154
	ds_read_b128 v[190:193], v154 offset:1024
	ds_read_b128 v[194:197], v154 offset:2048
	ds_read_b128 v[198:201], v154 offset:3072
	ds_read_b128 v[202:205], v154 offset:4096
	ds_read_b128 v[206:209], v154 offset:5120
	ds_read_b128 v[210:213], v154 offset:6144
	ds_read_b128 v[214:217], v154 offset:7168
	global_load_lds_dwordx4 v[218:219], off
	v_lshl_add_u64 v[218:219], s[4:5], 0, v[140:141]
	s_add_i32 m0, s11, 0xe000
	s_nop 0
	global_load_lds_dwordx4 v[218:219], off
	s_waitcnt vmcnt(8)
	s_waitcnt lgkmcnt(0)
	s_barrier
; #define PG8_STAGE(bufoff, gbase, voff) do { _Pragma("unroll") for (int _i = 0; _i < 2; ++_i) \
;         __builtin_amdgcn_global_load_lds((const unsigned*)((const char*)(gbase) + (voff)[_i]), (LAS unsigned*)(lds + (bufoff) + ldsw + _i * 8192), 16, 0, 0); } while (0)
; #define PG8_LDA(dst, b, h) do { _Pragma("unroll") for (int m = 0; m < 4; ++m) _Pragma("unroll") for (int k = 0; k < 2; ++k) dst[m][k] = *(const LAS bf16x8*)(lds + PG8_SA(b, h) + aoff + m * 2048 + k * 1024); } while (0)
; #define PG8_MMA(ai, bj, At, Bt) do { __builtin_amdgcn_s_setprio(1); _Pragma("unroll") for (int m = 0; m < 4; ++m) _Pragma("unroll") for (int n = 0; n < 2; ++n) _Pragma("unroll") for (int k = 0; k < 2; ++k) \
;         acc[ai][bj][m][n] = __builtin_amdgcn_mfma_f32_16x16x32_bf16(Bt[n][k], At[m][k], acc[ai][bj][m][n], 0, 0, 0); __builtin_amdgcn_s_setprio(0); } while (0)
; #define PG8_WAIT_V(n) asm volatile("s_waitcnt vmcnt(" #n ")" ::: "memory")
; #define PG8_WAIT_L(n) asm volatile("s_waitcnt lgkmcnt(" #n ")" ::: "memory")
; #define PG8_BAR __builtin_amdgcn_s_barrier()
; #define PG8_SCHED __builtin_amdgcn_sched_barrier(0)
; template <class Epi>
; __device__ __forceinline__ void gemm_phase(LAS unsigned char* lds, const Gemm g, int G, int c, const Epi& E) {
;     ...
;             PG8_WAIT_V(8); PG8_WAIT_L(0); PG8_BAR; PG8_MMA(0, 0, At, B0); PG8_MMA(0, 1, At, B1); PG8_BAR; PG8_SCHED;
;             PG8_LDA(At, 0, 1); PG8_STAGE(PG8_SB(0, 0), b2, voffB); PG8_STAGE(PG8_SB(0, 1), b2 + hstepB, voffB); PG8_STAGE(PG8_SA(0, 0), a2, voffA);
;             PG8_WAIT_V(8); PG8_WAIT_L(0); PG8_BAR; PG8_MMA(1, 0, At, B0); PG8_MMA(1, 1, At, B1); PG8_BAR; PG8_SCHED;
	s_setprio 0
	v_mfma_f32_16x16x32_bf16 v[126:129], v[146:149], v[186:189], v[126:129]
	v_mfma_f32_16x16x32_bf16 v[122:125], v[162:165], v[186:189], v[122:125]
	v_mfma_f32_16x16x32_bf16 v[110:113], v[146:149], v[194:197], v[110:113]
	v_mfma_f32_16x16x32_bf16 v[106:109], v[162:165], v[194:197], v[106:109]
	v_mfma_f32_16x16x32_bf16 v[94:97], v[146:149], v[202:205], v[94:97]
	v_mfma_f32_16x16x32_bf16 v[90:93], v[162:165], v[202:205], v[90:93]
	v_mfma_f32_16x16x32_bf16 v[78:81], v[146:149], v[210:213], v[78:81]
	v_mfma_f32_16x16x32_bf16 v[74:77], v[162:165], v[210:213], v[74:77]
	v_mfma_f32_16x16x32_bf16 v[126:129], v[158:161], v[190:193], v[126:129]
	v_mfma_f32_16x16x32_bf16 v[122:125], v[166:169], v[190:193], v[122:125]
	v_mfma_f32_16x16x32_bf16 v[110:113], v[158:161], v[198:201], v[110:113]
	v_mfma_f32_16x16x32_bf16 v[106:109], v[166:169], v[198:201], v[106:109]
	v_mfma_f32_16x16x32_bf16 v[94:97], v[158:161], v[206:209], v[94:97]
	v_mfma_f32_16x16x32_bf16 v[90:93], v[166:169], v[206:209], v[90:93]
	v_mfma_f32_16x16x32_bf16 v[78:81], v[158:161], v[214:217], v[78:81]
	v_mfma_f32_16x16x32_bf16 v[74:77], v[166:169], v[214:217], v[74:77]
	s_setprio 2
	s_setprio 0
	v_mfma_f32_16x16x32_bf16 v[118:121], v[170:173], v[186:189], v[118:121]
	v_mfma_f32_16x16x32_bf16 v[114:117], v[178:181], v[186:189], v[114:117]
	v_mfma_f32_16x16x32_bf16 v[102:105], v[170:173], v[194:197], v[102:105]
	v_mfma_f32_16x16x32_bf16 v[98:101], v[178:181], v[194:197], v[98:101]
	v_mfma_f32_16x16x32_bf16 v[86:89], v[170:173], v[202:205], v[86:89]
	v_mfma_f32_16x16x32_bf16 v[82:85], v[178:181], v[202:205], v[82:85]
	v_mfma_f32_16x16x32_bf16 v[70:73], v[170:173], v[210:213], v[70:73]
	v_mfma_f32_16x16x32_bf16 v[66:69], v[178:181], v[210:213], v[66:69]
	v_mfma_f32_16x16x32_bf16 v[118:121], v[174:177], v[190:193], v[118:121]
	v_mfma_f32_16x16x32_bf16 v[114:117], v[182:185], v[190:193], v[114:117]
	v_mfma_f32_16x16x32_bf16 v[102:105], v[174:177], v[198:201], v[102:105]
	v_mfma_f32_16x16x32_bf16 v[98:101], v[182:185], v[198:201], v[98:101]
	v_mfma_f32_16x16x32_bf16 v[86:89], v[174:177], v[206:209], v[86:89]
	v_mfma_f32_16x16x32_bf16 v[82:85], v[182:185], v[206:209], v[82:85]
	v_mfma_f32_16x16x32_bf16 v[70:73], v[174:177], v[214:217], v[70:73]
	v_mfma_f32_16x16x32_bf16 v[66:69], v[182:185], v[214:217], v[66:69]
	s_setprio 2
	s_barrier
	s_add_i32 s33, s79, s60
	v_lshl_add_u64 v[218:219], s[54:55], 0, v[132:133]
	s_mov_b32 m0, s33
	ds_read_b128 v[186:189], v154 offset:16384
	ds_read_b128 v[190:193], v154 offset:17408
	ds_read_b128 v[194:197], v154 offset:18432
	ds_read_b128 v[198:201], v154 offset:19456
	ds_read_b128 v[202:205], v154 offset:20480
	ds_read_b128 v[206:209], v154 offset:21504
	ds_read_b128 v[210:213], v154 offset:22528
	ds_read_b128 v[214:217], v154 offset:23552
	global_load_lds_dwordx4 v[218:219], off
	s_add_i32 m0, s33, 0x2000
	s_add_u32 s62, s54, 0x40000
	v_lshl_add_u64 v[220:221], s[54:55], 0, v[136:137]
	s_addc_u32 s63, s55, 0
	s_add_i32 s33, s80, s60
	global_load_lds_dwordx4 v[220:221], off
	v_lshl_add_u64 v[222:223], s[62:63], 0, v[132:133]
	s_mov_b32 m0, s33
	v_lshl_add_u64 v[224:225], s[56:57], 0, v[134:135]
	global_load_lds_dwordx4 v[222:223], off
	v_lshl_add_u64 v[222:223], s[62:63], 0, v[136:137]
	s_add_i32 m0, s33, 0x2000
	s_nop 0
	global_load_lds_dwordx4 v[222:223], off
	v_lshl_add_u64 v[222:223], s[56:57], 0, v[130:131]
	s_mov_b32 m0, s11
	s_nop 0
	global_load_lds_dwordx4 v[222:223], off
	s_mov_b32 m0, s61
	s_nop 0
	global_load_lds_dwordx4 v[224:225], off
	s_waitcnt vmcnt(8)
	s_waitcnt lgkmcnt(0)
	s_barrier
	s_setprio 0
	v_mfma_f32_16x16x32_bf16 v[62:65], v[146:149], v[186:189], v[62:65]
	v_mfma_f32_16x16x32_bf16 v[58:61], v[162:165], v[186:189], v[58:61]
	v_mfma_f32_16x16x32_bf16 v[46:49], v[146:149], v[194:197], v[46:49]
	v_mfma_f32_16x16x32_bf16 v[42:45], v[162:165], v[194:197], v[42:45]
	v_mfma_f32_16x16x32_bf16 v[30:33], v[146:149], v[202:205], v[30:33]
	v_mfma_f32_16x16x32_bf16 v[26:29], v[162:165], v[202:205], v[26:29]
	v_mfma_f32_16x16x32_bf16 v[14:17], v[146:149], v[210:213], v[14:17]
	v_mfma_f32_16x16x32_bf16 v[10:13], v[162:165], v[210:213], v[10:13]
	v_mfma_f32_16x16x32_bf16 v[62:65], v[158:161], v[190:193], v[62:65]
	v_mfma_f32_16x16x32_bf16 v[58:61], v[166:169], v[190:193], v[58:61]
	v_mfma_f32_16x16x32_bf16 v[46:49], v[158:161], v[198:201], v[46:49]
	v_mfma_f32_16x16x32_bf16 v[42:45], v[166:169], v[198:201], v[42:45]
	v_mfma_f32_16x16x32_bf16 v[30:33], v[158:161], v[206:209], v[30:33]
	v_mfma_f32_16x16x32_bf16 v[26:29], v[166:169], v[206:209], v[26:29]
	v_mfma_f32_16x16x32_bf16 v[14:17], v[158:161], v[214:217], v[14:17]
	v_mfma_f32_16x16x32_bf16 v[10:13], v[166:169], v[214:217], v[10:13]
	s_setprio 2
	s_setprio 0
	v_mfma_f32_16x16x32_bf16 v[54:57], v[170:173], v[186:189], v[54:57]
	v_mfma_f32_16x16x32_bf16 v[50:53], v[178:181], v[186:189], v[50:53]
	v_mfma_f32_16x16x32_bf16 v[38:41], v[170:173], v[194:197], v[38:41]
	v_mfma_f32_16x16x32_bf16 v[34:37], v[178:181], v[194:197], v[34:37]
	v_mfma_f32_16x16x32_bf16 v[22:25], v[170:173], v[202:205], v[22:25]
	v_mfma_f32_16x16x32_bf16 v[18:21], v[178:181], v[202:205], v[18:21]
	v_mfma_f32_16x16x32_bf16 v[6:9], v[170:173], v[210:213], v[6:9]
	v_mfma_f32_16x16x32_bf16 v[2:5], v[178:181], v[210:213], v[2:5]
	v_mfma_f32_16x16x32_bf16 v[54:57], v[174:177], v[190:193], v[54:57]
	v_mfma_f32_16x16x32_bf16 v[50:53], v[182:185], v[190:193], v[50:53]
	v_mfma_f32_16x16x32_bf16 v[38:41], v[174:177], v[198:201], v[38:41]
	v_mfma_f32_16x16x32_bf16 v[34:37], v[182:185], v[198:201], v[34:37]
	v_mfma_f32_16x16x32_bf16 v[22:25], v[174:177], v[206:209], v[22:25]
	v_mfma_f32_16x16x32_bf16 v[18:21], v[182:185], v[206:209], v[18:21]
	v_mfma_f32_16x16x32_bf16 v[6:9], v[174:177], v[214:217], v[6:9]
	v_mfma_f32_16x16x32_bf16 v[2:5], v[182:185], v[214:217], v[2:5]
	s_setprio 2
	s_barrier
; #define PG8_STAGE(bufoff, gbase, voff) do { _Pragma("unroll") for (int _i = 0; _i < 2; ++_i) \
;         __builtin_amdgcn_global_load_lds((const unsigned*)((const char*)(gbase) + (voff)[_i]), (LAS unsigned*)(lds + (bufoff) + ldsw + _i * 8192), 16, 0, 0); } while (0)
; #define PG8_LDA(dst, b, h) do { _Pragma("unroll") for (int m = 0; m < 4; ++m) _Pragma("unroll") for (int k = 0; k < 2; ++k) dst[m][k] = *(const LAS bf16x8*)(lds + PG8_SA(b, h) + aoff + m * 2048 + k * 1024); } while (0)
; #define PG8_LDB(dst, b, h) do { _Pragma("unroll") for (int n = 0; n < 2; ++n) _Pragma("unroll") for (int k = 0; k < 2; ++k) dst[n][k] = *(const LAS bf16x8*)(lds + PG8_SB(b, h) + boff + n * 2048 + k * 1024); } while (0)
; #define PG8_MMA(ai, bj, At, Bt) do { __builtin_amdgcn_s_setprio(1); _Pragma("unroll") for (int m = 0; m < 4; ++m) _Pragma("unroll") for (int n = 0; n < 2; ++n) _Pragma("unroll") for (int k = 0; k < 2; ++k) \
;         acc[ai][bj][m][n] = __builtin_amdgcn_mfma_f32_16x16x32_bf16(Bt[n][k], At[m][k], acc[ai][bj][m][n], 0, 0, 0); __builtin_amdgcn_s_setprio(0); } while (0)
; #define PG8_WAIT_V(n) asm volatile("s_waitcnt vmcnt(" #n ")" ::: "memory")
; #define PG8_WAIT_L(n) asm volatile("s_waitcnt lgkmcnt(" #n ")" ::: "memory")
; #define PG8_BAR __builtin_amdgcn_s_barrier()
; #define PG8_SCHED __builtin_amdgcn_sched_barrier(0)
; template <class Epi>
; __device__ __forceinline__ void gemm_phase(LAS unsigned char* lds, const Gemm g, int G, int c, const Epi& E) {
;     ...
;             PG8_LDB(B0, 1, 0); PG8_LDB(B1, 1, 1); PG8_SCHED; PG8_LDA(At, 1, 0); PG8_STAGE(PG8_SA(0, 1), a2 + hstepA, voffA);
;             PG8_WAIT_V(8); PG8_WAIT_L(0); PG8_BAR; PG8_MMA(0, 0, At, B0); PG8_MMA(0, 1, At, B1); PG8_BAR; PG8_SCHED;
	s_add_i32 s33, 0, 0x18000
	v_add_u32_e32 v157, s33, v151
	s_add_i32 s62, 0, 0x1c000
	ds_read_b128 v[146:149], v157
	ds_read_b128 v[158:161], v157 offset:1024
	ds_read_b128 v[162:165], v157 offset:2048
	ds_read_b128 v[166:169], v157 offset:3072
	v_add_u32_e32 v157, s62, v151
	ds_read_b128 v[170:173], v157
	ds_read_b128 v[174:177], v157 offset:1024
	ds_read_b128 v[178:181], v157 offset:2048
	ds_read_b128 v[182:185], v157 offset:3072
	s_add_u32 s56, s56, 0x40000
	s_addc_u32 s57, s57, 0
	s_mov_b32 m0, s66
	v_lshl_add_u64 v[226:227], s[56:57], 0, v[130:131]
	ds_read_b128 v[186:189], v154 offset:32768
	ds_read_b128 v[190:193], v154 offset:33792
	ds_read_b128 v[194:197], v154 offset:34816
	ds_read_b128 v[198:201], v154 offset:35840
	ds_read_b128 v[202:205], v154 offset:36864
	ds_read_b128 v[206:209], v154 offset:37888
	ds_read_b128 v[210:213], v154 offset:38912
	ds_read_b128 v[214:217], v154 offset:39936
	global_load_lds_dwordx4 v[226:227], off
	v_lshl_add_u64 v[226:227], s[56:57], 0, v[134:135]
	s_mov_b32 m0, s67
	s_nop 0
	global_load_lds_dwordx4 v[226:227], off
	s_waitcnt vmcnt(8)
	s_waitcnt lgkmcnt(0)
	s_barrier
	s_setprio 0
	v_mfma_f32_16x16x32_bf16 v[126:129], v[146:149], v[186:189], v[126:129]
	v_mfma_f32_16x16x32_bf16 v[122:125], v[162:165], v[186:189], v[122:125]
	v_mfma_f32_16x16x32_bf16 v[110:113], v[146:149], v[194:197], v[110:113]
	v_mfma_f32_16x16x32_bf16 v[106:109], v[162:165], v[194:197], v[106:109]
	v_mfma_f32_16x16x32_bf16 v[94:97], v[146:149], v[202:205], v[94:97]
	v_mfma_f32_16x16x32_bf16 v[90:93], v[162:165], v[202:205], v[90:93]
	v_mfma_f32_16x16x32_bf16 v[78:81], v[146:149], v[210:213], v[78:81]
	v_mfma_f32_16x16x32_bf16 v[74:77], v[162:165], v[210:213], v[74:77]
	v_mfma_f32_16x16x32_bf16 v[126:129], v[158:161], v[190:193], v[126:129]
	v_mfma_f32_16x16x32_bf16 v[122:125], v[166:169], v[190:193], v[122:125]
	v_mfma_f32_16x16x32_bf16 v[110:113], v[158:161], v[198:201], v[110:113]
	v_mfma_f32_16x16x32_bf16 v[106:109], v[166:169], v[198:201], v[106:109]
	v_mfma_f32_16x16x32_bf16 v[94:97], v[158:161], v[206:209], v[94:97]
	v_mfma_f32_16x16x32_bf16 v[90:93], v[166:169], v[206:209], v[90:93]
	v_mfma_f32_16x16x32_bf16 v[78:81], v[158:161], v[214:217], v[78:81]
	v_mfma_f32_16x16x32_bf16 v[74:77], v[166:169], v[214:217], v[74:77]
	s_setprio 2
	s_setprio 0
	v_mfma_f32_16x16x32_bf16 v[118:121], v[170:173], v[186:189], v[118:121]
	v_mfma_f32_16x16x32_bf16 v[114:117], v[178:181], v[186:189], v[114:117]
	v_mfma_f32_16x16x32_bf16 v[102:105], v[170:173], v[194:197], v[102:105]
	v_mfma_f32_16x16x32_bf16 v[98:101], v[178:181], v[194:197], v[98:101]
	v_mfma_f32_16x16x32_bf16 v[86:89], v[170:173], v[202:205], v[86:89]
	v_mfma_f32_16x16x32_bf16 v[82:85], v[178:181], v[202:205], v[82:85]
	v_mfma_f32_16x16x32_bf16 v[70:73], v[170:173], v[210:213], v[70:73]
	v_mfma_f32_16x16x32_bf16 v[66:69], v[178:181], v[210:213], v[66:69]
	v_mfma_f32_16x16x32_bf16 v[118:121], v[174:177], v[190:193], v[118:121]
	v_mfma_f32_16x16x32_bf16 v[114:117], v[182:185], v[190:193], v[114:117]
	v_mfma_f32_16x16x32_bf16 v[102:105], v[174:177], v[198:201], v[102:105]
	v_mfma_f32_16x16x32_bf16 v[98:101], v[182:185], v[198:201], v[98:101]
	v_mfma_f32_16x16x32_bf16 v[86:89], v[174:177], v[206:209], v[86:89]
	v_mfma_f32_16x16x32_bf16 v[82:85], v[182:185], v[206:209], v[82:85]
	v_mfma_f32_16x16x32_bf16 v[70:73], v[174:177], v[214:217], v[70:73]
	v_mfma_f32_16x16x32_bf16 v[66:69], v[182:185], v[214:217], v[66:69]
	s_setprio 2
	s_barrier
; #define PG8_STAGE(bufoff, gbase, voff) do { _Pragma("unroll") for (int _i = 0; _i < 2; ++_i) \
;         __builtin_amdgcn_global_load_lds((const unsigned*)((const char*)(gbase) + (voff)[_i]), (LAS unsigned*)(lds + (bufoff) + ldsw + _i * 8192), 16, 0, 0); } while (0)
; #define PG8_LDA(dst, b, h) do { _Pragma("unroll") for (int m = 0; m < 4; ++m) _Pragma("unroll") for (int k = 0; k < 2; ++k) dst[m][k] = *(const LAS bf16x8*)(lds + PG8_SA(b, h) + aoff + m * 2048 + k * 1024); } while (0)
; #define PG8_MMA(ai, bj, At, Bt) do { __builtin_amdgcn_s_setprio(1); _Pragma("unroll") for (int m = 0; m < 4; ++m) _Pragma("unroll") for (int n = 0; n < 2; ++n) _Pragma("unroll") for (int k = 0; k < 2; ++k) \
;         acc[ai][bj][m][n] = __builtin_amdgcn_mfma_f32_16x16x32_bf16(Bt[n][k], At[m][k], acc[ai][bj][m][n], 0, 0, 0); __builtin_amdgcn_s_setprio(0); } while (0)
; #define PG8_WAIT_V(n) asm volatile("s_waitcnt vmcnt(" #n ")" ::: "memory")
; #define PG8_WAIT_L(n) asm volatile("s_waitcnt lgkmcnt(" #n ")" ::: "memory")
; #define PG8_BAR __builtin_amdgcn_s_barrier()
; #define PG8_SCHED __builtin_amdgcn_sched_barrier(0)
; template <class Epi>
; __device__ __forceinline__ void gemm_phase(LAS unsigned char* lds, const Gemm g, int G, int c, const Epi& E) {
;     ...
;             PG8_LDA(At, 1, 1); PG8_STAGE(PG8_SB(1, 0), b3, voffB); PG8_STAGE(PG8_SB(1, 1), b3 + hstepB, voffB); PG8_STAGE(PG8_SA(1, 0), a3, voffA);
;             PG8_WAIT_V(8); PG8_WAIT_L(0); PG8_BAR; PG8_MMA(1, 0, At, B0); PG8_MMA(1, 1, At, B1); PG8_BAR; PG8_SCHED;
;         }
;         if (wr == 0) PG8_BAR;
	s_add_i32 s33, s33, s60
	v_lshl_add_u64 v[218:219], v[218:219], 0, s[20:21]
	s_mov_b32 m0, s33
	ds_read_b128 v[186:189], v154 offset:49152
	ds_read_b128 v[190:193], v154 offset:50176
	ds_read_b128 v[194:197], v154 offset:51200
	ds_read_b128 v[198:201], v154 offset:52224
	ds_read_b128 v[202:205], v154 offset:53248
	ds_read_b128 v[206:209], v154 offset:54272
	ds_read_b128 v[210:213], v154 offset:55296
	ds_read_b128 v[214:217], v154 offset:56320
	global_load_lds_dwordx4 v[218:219], off
	s_add_i32 m0, s33, 0x2000
	s_add_u32 s54, s54, 0x40080
	v_lshl_add_u64 v[218:219], v[220:221], 0, s[20:21]
	s_addc_u32 s55, s55, 0
	s_add_i32 s33, s62, s60
	global_load_lds_dwordx4 v[218:219], off
	v_lshl_add_u64 v[218:219], s[54:55], 0, v[132:133]
	s_mov_b32 m0, s33
	s_nop 0
	global_load_lds_dwordx4 v[218:219], off
	v_lshl_add_u64 v[218:219], s[54:55], 0, v[136:137]
	s_add_i32 m0, s33, 0x2000
	s_nop 0
	global_load_lds_dwordx4 v[218:219], off
	v_lshl_add_u64 v[218:219], v[222:223], 0, s[20:21]
	s_mov_b32 m0, s71
	s_nop 0
	global_load_lds_dwordx4 v[218:219], off
	v_lshl_add_u64 v[218:219], v[224:225], 0, s[20:21]
	s_mov_b32 m0, s72
	s_nop 0
	global_load_lds_dwordx4 v[218:219], off
	s_waitcnt vmcnt(8)
	s_waitcnt lgkmcnt(0)
	s_barrier
	s_setprio 0
	v_mfma_f32_16x16x32_bf16 v[62:65], v[146:149], v[186:189], v[62:65]
	v_mfma_f32_16x16x32_bf16 v[58:61], v[162:165], v[186:189], v[58:61]
	v_mfma_f32_16x16x32_bf16 v[46:49], v[146:149], v[194:197], v[46:49]
	v_mfma_f32_16x16x32_bf16 v[42:45], v[162:165], v[194:197], v[42:45]
	v_mfma_f32_16x16x32_bf16 v[30:33], v[146:149], v[202:205], v[30:33]
	v_mfma_f32_16x16x32_bf16 v[26:29], v[162:165], v[202:205], v[26:29]
	v_mfma_f32_16x16x32_bf16 v[14:17], v[146:149], v[210:213], v[14:17]
	v_mfma_f32_16x16x32_bf16 v[10:13], v[162:165], v[210:213], v[10:13]
	v_mfma_f32_16x16x32_bf16 v[62:65], v[158:161], v[190:193], v[62:65]
	v_mfma_f32_16x16x32_bf16 v[58:61], v[166:169], v[190:193], v[58:61]
	v_mfma_f32_16x16x32_bf16 v[46:49], v[158:161], v[198:201], v[46:49]
	v_mfma_f32_16x16x32_bf16 v[42:45], v[166:169], v[198:201], v[42:45]
	v_mfma_f32_16x16x32_bf16 v[30:33], v[158:161], v[206:209], v[30:33]
	v_mfma_f32_16x16x32_bf16 v[26:29], v[166:169], v[206:209], v[26:29]
	v_mfma_f32_16x16x32_bf16 v[14:17], v[158:161], v[214:217], v[14:17]
	v_mfma_f32_16x16x32_bf16 v[10:13], v[166:169], v[214:217], v[10:13]
	s_setprio 2
	s_setprio 0
	v_mfma_f32_16x16x32_bf16 v[54:57], v[170:173], v[186:189], v[54:57]
	v_mfma_f32_16x16x32_bf16 v[50:53], v[178:181], v[186:189], v[50:53]
	v_mfma_f32_16x16x32_bf16 v[38:41], v[170:173], v[194:197], v[38:41]
	v_mfma_f32_16x16x32_bf16 v[34:37], v[178:181], v[194:197], v[34:37]
	v_mfma_f32_16x16x32_bf16 v[22:25], v[170:173], v[202:205], v[22:25]
	v_mfma_f32_16x16x32_bf16 v[18:21], v[178:181], v[202:205], v[18:21]
	v_mfma_f32_16x16x32_bf16 v[6:9], v[170:173], v[210:213], v[6:9]
	v_mfma_f32_16x16x32_bf16 v[2:5], v[178:181], v[210:213], v[2:5]
	v_mfma_f32_16x16x32_bf16 v[54:57], v[174:177], v[190:193], v[54:57]
	v_mfma_f32_16x16x32_bf16 v[50:53], v[182:185], v[190:193], v[50:53]
	v_mfma_f32_16x16x32_bf16 v[38:41], v[174:177], v[198:201], v[38:41]
	v_mfma_f32_16x16x32_bf16 v[34:37], v[182:185], v[198:201], v[34:37]
	v_mfma_f32_16x16x32_bf16 v[22:25], v[174:177], v[206:209], v[22:25]
	v_mfma_f32_16x16x32_bf16 v[18:21], v[182:185], v[206:209], v[18:21]
	v_mfma_f32_16x16x32_bf16 v[6:9], v[174:177], v[214:217], v[6:9]
	v_mfma_f32_16x16x32_bf16 v[2:5], v[182:185], v[214:217], v[2:5]
	s_setprio 2
	s_add_i32 s85, s85, 2
	s_add_u32 s4, s4, 0x100
	s_addc_u32 s5, s5, 0
	s_add_u32 s45, s45, 0x100
	s_addc_u32 s84, s84, 0
	s_cmp_gt_u32 s85, 13
	s_barrier
	s_cbranch_scc0 .LBB0_236
	s_and_b64 vcc, exec, s[22:23]
	s_cbranch_vccz .LBB0_239
	s_barrier

; #define PG8_STAGE(bufoff, gbase, voff) do { _Pragma("unroll") for (int _i = 0; _i < 2; ++_i) \
;         __builtin_amdgcn_global_load_lds((const unsigned*)((const char*)(gbase) + (voff)[_i]), (LAS unsigned*)(lds + (bufoff) + ldsw + _i * 8192), 16, 0, 0); } while (0)
; #define PG8_LDA(dst, b, h) do { _Pragma("unroll") for (int m = 0; m < 4; ++m) _Pragma("unroll") for (int k = 0; k < 2; ++k) dst[m][k] = *(const LAS bf16x8*)(lds + PG8_SA(b, h) + aoff + m * 2048 + k * 1024); } while (0)
; #define PG8_LDB(dst, b, h) do { _Pragma("unroll") for (int n = 0; n < 2; ++n) _Pragma("unroll") for (int k = 0; k < 2; ++k) dst[n][k] = *(const LAS bf16x8*)(lds + PG8_SB(b, h) + boff + n * 2048 + k * 1024); } while (0)
; #define PG8_MMA(ai, bj, At, Bt) do { __builtin_amdgcn_s_setprio(1); _Pragma("unroll") for (int m = 0; m < 4; ++m) _Pragma("unroll") for (int n = 0; n < 2; ++n) _Pragma("unroll") for (int k = 0; k < 2; ++k) \
;         acc[ai][bj][m][n] = __builtin_amdgcn_mfma_f32_16x16x32_bf16(Bt[n][k], At[m][k], acc[ai][bj][m][n], 0, 0, 0); __builtin_amdgcn_s_setprio(0); } while (0)
; #define PG8_WAIT_V(n) asm volatile("s_waitcnt vmcnt(" #n ")" ::: "memory")
; template <class Epi>
; __device__ __forceinline__ void gemm_phase(LAS unsigned char* lds, const Gemm g, int G, int c, const Epi& E) {
;     ...
;         const bool has_next = S.next(ui + 1, nxt);
;         const char* nA = has_next ? (const char*)(g.A + (size_t)nxt.pb * g.sA) + (size_t)nxt.pm * 2 * hstepA : cA;
;         const char* nB = has_next ? (const char*)(g.Bt + (size_t)nxt.pb * g.sB) + (size_t)nxt.pn * 2 * hstepB : cB;
; #pragma nounroll
;         for (int t = 0; t < nt; t += 2) {
;             const bool last = (t == nt - 2);
;             const char* a1 = cA + (size_t)(t + 1) * kstep;
;             const char* a2 = last ? nA : cA + (size_t)(t + 2) * kstep; const char* b2 = last ? nB : cB + (size_t)(t + 2) * kstep;
;             const char* a3 = a2 + kstep; const char* b3 = b2 + kstep;
;             PG8_LDB(B0, 0, 0); PG8_LDB(B1, 0, 1); PG8_SCHED; PG8_LDA(At, 0, 0); PG8_STAGE(PG8_SA(1, 1), a1 + hstepA, voffA);
;             PG8_WAIT_V(8); PG8_WAIT_L(0); PG8_BAR; PG8_MMA(0, 0, At, B0); PG8_MMA(0, 1, At, B1); PG8_BAR; PG8_SCHED;
;             PG8_LDA(At, 0, 1); PG8_STAGE(PG8_SB(0, 0), b2, voffB); PG8_STAGE(PG8_SB(0, 1), b2 + hstepB, voffB); PG8_STAGE(PG8_SA(0, 0), a2, voffA);
.LBB0_764:
	s_ashr_i32 s15, s14, 31
	s_lshl_b64 s[18:19], s[14:15], 21
	s_add_u32 s18, s57, s18
	s_addc_u32 s19, s58, s19
	s_and_b64 s[24:25], s[2:3], exec
	s_cselect_b32 s15, s19, s45
	s_cselect_b32 s78, s18, s44
	s_ashr_i32 s11, s10, 31
	s_lshl_b64 s[24:25], s[10:11], 21
	s_add_u32 s11, s59, s24
	s_addc_u32 s33, s60, s25
	s_ashr_i32 s13, s12, 31
	s_lshl_b64 s[24:25], s[12:13], 21
	s_add_u32 s24, s11, s24
	s_addc_u32 s25, s33, s25
	s_and_b64 s[52:53], s[2:3], exec
	s_cselect_b32 s11, s25, s47
	s_cselect_b32 s13, s24, s46
	s_add_u32 s44, s44, 0x100080
	s_addc_u32 s45, s45, 0
	s_add_u32 s81, s46, 0x100
	s_addc_u32 s82, s47, 0
	s_mov_b32 s83, -2
	ds_read_b128 v[146:149], v152
	ds_read_b128 v[156:159], v152 offset:1024
	ds_read_b128 v[160:163], v152 offset:2048
	ds_read_b128 v[164:167], v152 offset:3072
	ds_read_b128 v[168:171], v153
	ds_read_b128 v[172:175], v153 offset:1024
	ds_read_b128 v[176:179], v153 offset:2048
	ds_read_b128 v[180:183], v153 offset:3072
	s_add_u32 s33, s44, 0xfff00080
	s_addc_u32 s46, s45, -1
	s_cmp_eq_u32 s83, 60
	s_cselect_b32 s53, s15, s46
	s_cselect_b32 s52, s78, s33
	s_cselect_b32 s47, s11, s82
	s_cselect_b32 s46, s13, s81
	v_lshl_add_u64 v[216:217], s[44:45], 0, v[138:139]
	s_add_i32 m0, s17, 0xc000
	ds_read_b128 v[184:187], v154
	ds_read_b128 v[188:191], v154 offset:1024
	ds_read_b128 v[192:195], v154 offset:2048
	ds_read_b128 v[196:199], v154 offset:3072
	ds_read_b128 v[200:203], v154 offset:4096
	ds_read_b128 v[204:207], v154 offset:5120
	ds_read_b128 v[208:211], v154 offset:6144
	ds_read_b128 v[212:215], v154 offset:7168
	global_load_lds_dwordx4 v[216:217], off
	v_lshl_add_u64 v[216:217], s[44:45], 0, v[140:141]
	s_add_i32 m0, s17, 0xe000
	s_nop 0
	global_load_lds_dwordx4 v[216:217], off
	s_waitcnt vmcnt(8)
	s_waitcnt lgkmcnt(0)
	s_barrier
	s_setprio 0
	v_mfma_f32_16x16x32_bf16 v[126:129], v[146:149], v[184:187], 0
	v_mfma_f32_16x16x32_bf16 v[122:125], v[160:163], v[184:187], 0
	v_mfma_f32_16x16x32_bf16 v[118:121], v[146:149], v[192:195], 0
	v_mfma_f32_16x16x32_bf16 v[110:113], v[160:163], v[192:195], 0
	v_mfma_f32_16x16x32_bf16 v[102:105], v[146:149], v[200:203], 0
	v_mfma_f32_16x16x32_bf16 v[94:97], v[160:163], v[200:203], 0
	v_mfma_f32_16x16x32_bf16 v[86:89], v[146:149], v[208:211], 0
	v_mfma_f32_16x16x32_bf16 v[78:81], v[160:163], v[208:211], 0
	v_mfma_f32_16x16x32_bf16 v[126:129], v[156:159], v[188:191], v[126:129]
	v_mfma_f32_16x16x32_bf16 v[122:125], v[164:167], v[188:191], v[122:125]
	v_mfma_f32_16x16x32_bf16 v[118:121], v[156:159], v[196:199], v[118:121]
	v_mfma_f32_16x16x32_bf16 v[110:113], v[164:167], v[196:199], v[110:113]
	v_mfma_f32_16x16x32_bf16 v[102:105], v[156:159], v[204:207], v[102:105]
	v_mfma_f32_16x16x32_bf16 v[94:97], v[164:167], v[204:207], v[94:97]
	v_mfma_f32_16x16x32_bf16 v[86:89], v[156:159], v[212:215], v[86:89]
	v_mfma_f32_16x16x32_bf16 v[78:81], v[164:167], v[212:215], v[78:81]
	s_setprio 2
	s_setprio 0
	v_mfma_f32_16x16x32_bf16 v[114:117], v[168:171], v[184:187], 0
	v_mfma_f32_16x16x32_bf16 v[106:109], v[176:179], v[184:187], 0
	v_mfma_f32_16x16x32_bf16 v[98:101], v[168:171], v[192:195], 0
	v_mfma_f32_16x16x32_bf16 v[90:93], v[176:179], v[192:195], 0
	v_mfma_f32_16x16x32_bf16 v[82:85], v[168:171], v[200:203], 0
	v_mfma_f32_16x16x32_bf16 v[74:77], v[176:179], v[200:203], 0
	v_mfma_f32_16x16x32_bf16 v[70:73], v[168:171], v[208:211], 0
	v_mfma_f32_16x16x32_bf16 v[66:69], v[176:179], v[208:211], 0
	v_mfma_f32_16x16x32_bf16 v[114:117], v[172:175], v[188:191], v[114:117]
	v_mfma_f32_16x16x32_bf16 v[106:109], v[180:183], v[188:191], v[106:109]
	v_mfma_f32_16x16x32_bf16 v[98:101], v[172:175], v[196:199], v[98:101]
	v_mfma_f32_16x16x32_bf16 v[90:93], v[180:183], v[196:199], v[90:93]
	v_mfma_f32_16x16x32_bf16 v[82:85], v[172:175], v[204:207], v[82:85]
	v_mfma_f32_16x16x32_bf16 v[74:77], v[180:183], v[204:207], v[74:77]
	v_mfma_f32_16x16x32_bf16 v[70:73], v[172:175], v[212:215], v[70:73]
	v_mfma_f32_16x16x32_bf16 v[66:69], v[180:183], v[212:215], v[66:69]
	s_setprio 2
	s_barrier
	s_add_i32 s33, s72, s61
	v_lshl_add_u64 v[216:217], s[46:47], 0, v[134:135]
	s_mov_b32 m0, s33
	ds_read_b128 v[184:187], v154 offset:16384
	ds_read_b128 v[188:191], v154 offset:17408
	ds_read_b128 v[192:195], v154 offset:18432
	ds_read_b128 v[196:199], v154 offset:19456
	ds_read_b128 v[200:203], v154 offset:20480
	ds_read_b128 v[204:207], v154 offset:21504
	ds_read_b128 v[208:211], v154 offset:22528
	ds_read_b128 v[212:215], v154 offset:23552
	global_load_lds_dwordx4 v[216:217], off
	s_add_i32 m0, s33, 0x2000
	s_add_u32 s62, s46, 0x100000
	v_lshl_add_u64 v[218:219], s[46:47], 0, v[130:131]
	s_addc_u32 s63, s47, 0
	s_add_i32 s33, s73, s61
	global_load_lds_dwordx4 v[218:219], off
	v_lshl_add_u64 v[220:221], s[62:63], 0, v[134:135]
	s_mov_b32 m0, s33
	v_lshl_add_u64 v[224:225], s[52:53], 0, v[132:133]
	global_load_lds_dwordx4 v[220:221], off
	v_lshl_add_u64 v[220:221], s[62:63], 0, v[130:131]
	s_add_i32 m0, s33, 0x2000
	s_nop 0
	global_load_lds_dwordx4 v[220:221], off
	v_lshl_add_u64 v[220:221], s[52:53], 0, v[136:137]
	s_mov_b32 m0, s17
	s_nop 0
	global_load_lds_dwordx4 v[220:221], off
	s_mov_b32 m0, s39
	s_nop 0
	global_load_lds_dwordx4 v[224:225], off
	s_waitcnt vmcnt(8)
	s_waitcnt lgkmcnt(0)
	s_barrier
; #define PG8_STAGE(bufoff, gbase, voff) do { _Pragma("unroll") for (int _i = 0; _i < 2; ++_i) \
;         __builtin_amdgcn_global_load_lds((const unsigned*)((const char*)(gbase) + (voff)[_i]), (LAS unsigned*)(lds + (bufoff) + ldsw + _i * 8192), 16, 0, 0); } while (0)
; #define PG8_LDA(dst, b, h) do { _Pragma("unroll") for (int m = 0; m < 4; ++m) _Pragma("unroll") for (int k = 0; k < 2; ++k) dst[m][k] = *(const LAS bf16x8*)(lds + PG8_SA(b, h) + aoff + m * 2048 + k * 1024); } while (0)
; #define PG8_LDB(dst, b, h) do { _Pragma("unroll") for (int n = 0; n < 2; ++n) _Pragma("unroll") for (int k = 0; k < 2; ++k) dst[n][k] = *(const LAS bf16x8*)(lds + PG8_SB(b, h) + boff + n * 2048 + k * 1024); } while (0)
; #define PG8_MMA(ai, bj, At, Bt) do { __builtin_amdgcn_s_setprio(1); _Pragma("unroll") for (int m = 0; m < 4; ++m) _Pragma("unroll") for (int n = 0; n < 2; ++n) _Pragma("unroll") for (int k = 0; k < 2; ++k) \
;         acc[ai][bj][m][n] = __builtin_amdgcn_mfma_f32_16x16x32_bf16(Bt[n][k], At[m][k], acc[ai][bj][m][n], 0, 0, 0); __builtin_amdgcn_s_setprio(0); } while (0)
; #define PG8_WAIT_V(n) asm volatile("s_waitcnt vmcnt(" #n ")" ::: "memory")
; #define PG8_WAIT_L(n) asm volatile("s_waitcnt lgkmcnt(" #n ")" ::: "memory")
; #define PG8_BAR __builtin_amdgcn_s_barrier()
; #define PG8_SCHED __builtin_amdgcn_sched_barrier(0)
; template <class Epi>
; __device__ __forceinline__ void gemm_phase(LAS unsigned char* lds, const Gemm g, int G, int c, const Epi& E) {
;     ...
;             PG8_WAIT_V(8); PG8_WAIT_L(0); PG8_BAR; PG8_MMA(1, 0, At, B0); PG8_MMA(1, 1, At, B1); PG8_BAR; PG8_SCHED;
;             PG8_LDB(B0, 1, 0); PG8_LDB(B1, 1, 1); PG8_SCHED; PG8_LDA(At, 1, 0); PG8_STAGE(PG8_SA(0, 1), a2 + hstepA, voffA);
;             PG8_WAIT_V(8); PG8_WAIT_L(0); PG8_BAR; PG8_MMA(0, 0, At, B0); PG8_MMA(0, 1, At, B1); PG8_BAR; PG8_SCHED;
	s_setprio 0
	v_mfma_f32_16x16x32_bf16 v[62:65], v[146:149], v[184:187], 0
	v_mfma_f32_16x16x32_bf16 v[58:61], v[160:163], v[184:187], 0
	v_mfma_f32_16x16x32_bf16 v[54:57], v[146:149], v[192:195], 0
	v_mfma_f32_16x16x32_bf16 v[46:49], v[160:163], v[192:195], 0
	v_mfma_f32_16x16x32_bf16 v[38:41], v[146:149], v[200:203], 0
	v_mfma_f32_16x16x32_bf16 v[30:33], v[160:163], v[200:203], 0
	v_mfma_f32_16x16x32_bf16 v[22:25], v[146:149], v[208:211], 0
	v_mfma_f32_16x16x32_bf16 v[14:17], v[160:163], v[208:211], 0
	v_mfma_f32_16x16x32_bf16 v[62:65], v[156:159], v[188:191], v[62:65]
	v_mfma_f32_16x16x32_bf16 v[58:61], v[164:167], v[188:191], v[58:61]
	v_mfma_f32_16x16x32_bf16 v[54:57], v[156:159], v[196:199], v[54:57]
	v_mfma_f32_16x16x32_bf16 v[46:49], v[164:167], v[196:199], v[46:49]
	v_mfma_f32_16x16x32_bf16 v[38:41], v[156:159], v[204:207], v[38:41]
	v_mfma_f32_16x16x32_bf16 v[30:33], v[164:167], v[204:207], v[30:33]
	v_mfma_f32_16x16x32_bf16 v[22:25], v[156:159], v[212:215], v[22:25]
	v_mfma_f32_16x16x32_bf16 v[14:17], v[164:167], v[212:215], v[14:17]
	s_setprio 2
	s_setprio 0
	v_mfma_f32_16x16x32_bf16 v[50:53], v[168:171], v[184:187], 0
	v_mfma_f32_16x16x32_bf16 v[42:45], v[176:179], v[184:187], 0
	v_mfma_f32_16x16x32_bf16 v[34:37], v[168:171], v[192:195], 0
	v_mfma_f32_16x16x32_bf16 v[26:29], v[176:179], v[192:195], 0
	v_mfma_f32_16x16x32_bf16 v[18:21], v[168:171], v[200:203], 0
	v_mfma_f32_16x16x32_bf16 v[10:13], v[176:179], v[200:203], 0
	v_mfma_f32_16x16x32_bf16 v[6:9], v[168:171], v[208:211], 0
	v_mfma_f32_16x16x32_bf16 v[2:5], v[176:179], v[208:211], 0
	v_mfma_f32_16x16x32_bf16 v[50:53], v[172:175], v[188:191], v[50:53]
	v_mfma_f32_16x16x32_bf16 v[42:45], v[180:183], v[188:191], v[42:45]
	v_mfma_f32_16x16x32_bf16 v[34:37], v[172:175], v[196:199], v[34:37]
	v_mfma_f32_16x16x32_bf16 v[26:29], v[180:183], v[196:199], v[26:29]
	v_mfma_f32_16x16x32_bf16 v[18:21], v[172:175], v[204:207], v[18:21]
	v_mfma_f32_16x16x32_bf16 v[10:13], v[180:183], v[204:207], v[10:13]
	v_mfma_f32_16x16x32_bf16 v[6:9], v[172:175], v[212:215], v[6:9]
	v_mfma_f32_16x16x32_bf16 v[2:5], v[180:183], v[212:215], v[2:5]
	s_setprio 2
	s_barrier
	s_add_i32 s33, 0, 0x18000
	v_add_u32_e32 v155, s33, v151
	s_add_i32 s62, 0, 0x1c000
	ds_read_b128 v[146:149], v155
	ds_read_b128 v[156:159], v155 offset:1024
	ds_read_b128 v[160:163], v155 offset:2048
	ds_read_b128 v[164:167], v155 offset:3072
	v_add_u32_e32 v155, s62, v151
	ds_read_b128 v[168:171], v155
	ds_read_b128 v[172:175], v155 offset:1024
	ds_read_b128 v[176:179], v155 offset:2048
	ds_read_b128 v[180:183], v155 offset:3072
	s_add_u32 s52, s52, 0x100000
	s_addc_u32 s53, s53, 0
	s_mov_b32 m0, s43
	v_lshl_add_u64 v[226:227], s[52:53], 0, v[136:137]
	ds_read_b128 v[184:187], v154 offset:32768
	ds_read_b128 v[188:191], v154 offset:33792
	ds_read_b128 v[192:195], v154 offset:34816
	ds_read_b128 v[196:199], v154 offset:35840
	ds_read_b128 v[200:203], v154 offset:36864
	ds_read_b128 v[204:207], v154 offset:37888
	ds_read_b128 v[208:211], v154 offset:38912
	ds_read_b128 v[212:215], v154 offset:39936
	global_load_lds_dwordx4 v[226:227], off
	v_lshl_add_u64 v[226:227], s[52:53], 0, v[132:133]
	s_mov_b32 m0, s66
	s_nop 0
	global_load_lds_dwordx4 v[226:227], off
	s_waitcnt vmcnt(8)
	s_waitcnt lgkmcnt(0)
	s_barrier
	s_setprio 0
	v_mfma_f32_16x16x32_bf16 v[126:129], v[146:149], v[184:187], v[126:129]
	v_mfma_f32_16x16x32_bf16 v[122:125], v[160:163], v[184:187], v[122:125]
	v_mfma_f32_16x16x32_bf16 v[118:121], v[146:149], v[192:195], v[118:121]
	v_mfma_f32_16x16x32_bf16 v[110:113], v[160:163], v[192:195], v[110:113]
	v_mfma_f32_16x16x32_bf16 v[102:105], v[146:149], v[200:203], v[102:105]
	v_mfma_f32_16x16x32_bf16 v[94:97], v[160:163], v[200:203], v[94:97]
	v_mfma_f32_16x16x32_bf16 v[86:89], v[146:149], v[208:211], v[86:89]
	v_mfma_f32_16x16x32_bf16 v[78:81], v[160:163], v[208:211], v[78:81]
	v_mfma_f32_16x16x32_bf16 v[126:129], v[156:159], v[188:191], v[126:129]
	v_mfma_f32_16x16x32_bf16 v[122:125], v[164:167], v[188:191], v[122:125]
	v_mfma_f32_16x16x32_bf16 v[118:121], v[156:159], v[196:199], v[118:121]
	v_mfma_f32_16x16x32_bf16 v[110:113], v[164:167], v[196:199], v[110:113]
	v_mfma_f32_16x16x32_bf16 v[102:105], v[156:159], v[204:207], v[102:105]
	v_mfma_f32_16x16x32_bf16 v[94:97], v[164:167], v[204:207], v[94:97]
	v_mfma_f32_16x16x32_bf16 v[86:89], v[156:159], v[212:215], v[86:89]
	v_mfma_f32_16x16x32_bf16 v[78:81], v[164:167], v[212:215], v[78:81]
	s_setprio 2
	s_setprio 0
	v_mfma_f32_16x16x32_bf16 v[114:117], v[168:171], v[184:187], v[114:117]
	v_mfma_f32_16x16x32_bf16 v[106:109], v[176:179], v[184:187], v[106:109]
	v_mfma_f32_16x16x32_bf16 v[98:101], v[168:171], v[192:195], v[98:101]
	v_mfma_f32_16x16x32_bf16 v[90:93], v[176:179], v[192:195], v[90:93]
	v_mfma_f32_16x16x32_bf16 v[82:85], v[168:171], v[200:203], v[82:85]
	v_mfma_f32_16x16x32_bf16 v[74:77], v[176:179], v[200:203], v[74:77]
	v_mfma_f32_16x16x32_bf16 v[70:73], v[168:171], v[208:211], v[70:73]
	v_mfma_f32_16x16x32_bf16 v[66:69], v[176:179], v[208:211], v[66:69]
	v_mfma_f32_16x16x32_bf16 v[114:117], v[172:175], v[188:191], v[114:117]
	v_mfma_f32_16x16x32_bf16 v[106:109], v[180:183], v[188:191], v[106:109]
	v_mfma_f32_16x16x32_bf16 v[98:101], v[172:175], v[196:199], v[98:101]
	v_mfma_f32_16x16x32_bf16 v[90:93], v[180:183], v[196:199], v[90:93]
	v_mfma_f32_16x16x32_bf16 v[82:85], v[172:175], v[204:207], v[82:85]
	v_mfma_f32_16x16x32_bf16 v[74:77], v[180:183], v[204:207], v[74:77]
	v_mfma_f32_16x16x32_bf16 v[70:73], v[172:175], v[212:215], v[70:73]
	v_mfma_f32_16x16x32_bf16 v[66:69], v[180:183], v[212:215], v[66:69]
	s_setprio 2
	s_barrier
; #define PG8_STAGE(bufoff, gbase, voff) do { _Pragma("unroll") for (int _i = 0; _i < 2; ++_i) \
;         __builtin_amdgcn_global_load_lds((const unsigned*)((const char*)(gbase) + (voff)[_i]), (LAS unsigned*)(lds + (bufoff) + ldsw + _i * 8192), 16, 0, 0); } while (0)
; #define PG8_LDA(dst, b, h) do { _Pragma("unroll") for (int m = 0; m < 4; ++m) _Pragma("unroll") for (int k = 0; k < 2; ++k) dst[m][k] = *(const LAS bf16x8*)(lds + PG8_SA(b, h) + aoff + m * 2048 + k * 1024); } while (0)
; #define PG8_LDB(dst, b, h) do { _Pragma("unroll") for (int n = 0; n < 2; ++n) _Pragma("unroll") for (int k = 0; k < 2; ++k) dst[n][k] = *(const LAS bf16x8*)(lds + PG8_SB(b, h) + boff + n * 2048 + k * 1024); } while (0)
; #define PG8_MMA(ai, bj, At, Bt) do { __builtin_amdgcn_s_setprio(1); _Pragma("unroll") for (int m = 0; m < 4; ++m) _Pragma("unroll") for (int n = 0; n < 2; ++n) _Pragma("unroll") for (int k = 0; k < 2; ++k) \
;         acc[ai][bj][m][n] = __builtin_amdgcn_mfma_f32_16x16x32_bf16(Bt[n][k], At[m][k], acc[ai][bj][m][n], 0, 0, 0); __builtin_amdgcn_s_setprio(0); } while (0)
; #define PG8_WAIT_V(n) asm volatile("s_waitcnt vmcnt(" #n ")" ::: "memory")
; #define PG8_WAIT_L(n) asm volatile("s_waitcnt lgkmcnt(" #n ")" ::: "memory")
; #define PG8_BAR __builtin_amdgcn_s_barrier()
; #define PG8_SCHED __builtin_amdgcn_sched_barrier(0)
; template <class Epi>
; __device__ __forceinline__ void gemm_phase(LAS unsigned char* lds, const Gemm g, int G, int c, const Epi& E) {
;     ...
;         for (int t = 0; t < nt; t += 2) {
;             const bool last = (t == nt - 2);
;             const char* a1 = cA + (size_t)(t + 1) * kstep;
;             const char* a2 = last ? nA : cA + (size_t)(t + 2) * kstep; const char* b2 = last ? nB : cB + (size_t)(t + 2) * kstep;
;             const char* a3 = a2 + kstep; const char* b3 = b2 + kstep;
;             PG8_LDB(B0, 0, 0); PG8_LDB(B1, 0, 1); PG8_SCHED; PG8_LDA(At, 0, 0); PG8_STAGE(PG8_SA(1, 1), a1 + hstepA, voffA);
;             PG8_WAIT_V(8); PG8_WAIT_L(0); PG8_BAR; PG8_MMA(0, 0, At, B0); PG8_MMA(0, 1, At, B1); PG8_BAR; PG8_SCHED;
;     ...
;             PG8_LDA(At, 1, 1); PG8_STAGE(PG8_SB(1, 0), b3, voffB); PG8_STAGE(PG8_SB(1, 1), b3 + hstepB, voffB); PG8_STAGE(PG8_SA(1, 0), a3, voffA);
;             PG8_WAIT_V(8); PG8_WAIT_L(0); PG8_BAR; PG8_MMA(1, 0, At, B0); PG8_MMA(1, 1, At, B1); PG8_BAR; PG8_SCHED;
	s_add_i32 s33, s33, s61
	v_lshl_add_u64 v[216:217], v[216:217], 0, s[6:7]
	s_mov_b32 m0, s33
	ds_read_b128 v[184:187], v154 offset:49152
	ds_read_b128 v[188:191], v154 offset:50176
	ds_read_b128 v[192:195], v154 offset:51200
	ds_read_b128 v[196:199], v154 offset:52224
	ds_read_b128 v[200:203], v154 offset:53248
	ds_read_b128 v[204:207], v154 offset:54272
	ds_read_b128 v[208:211], v154 offset:55296
	ds_read_b128 v[212:215], v154 offset:56320
	global_load_lds_dwordx4 v[216:217], off
	s_add_i32 m0, s33, 0x2000
	s_add_u32 s46, s46, 0x100080
	v_lshl_add_u64 v[216:217], v[218:219], 0, s[6:7]
	s_addc_u32 s47, s47, 0
	s_add_i32 s33, s62, s61
	global_load_lds_dwordx4 v[216:217], off
	v_lshl_add_u64 v[216:217], s[46:47], 0, v[134:135]
	s_mov_b32 m0, s33
	s_nop 0
	global_load_lds_dwordx4 v[216:217], off
	v_lshl_add_u64 v[216:217], s[46:47], 0, v[130:131]
	s_add_i32 m0, s33, 0x2000
	s_nop 0
	global_load_lds_dwordx4 v[216:217], off
	v_lshl_add_u64 v[216:217], v[220:221], 0, s[6:7]
	s_mov_b32 m0, s70
	s_nop 0
	global_load_lds_dwordx4 v[216:217], off
	v_lshl_add_u64 v[216:217], v[224:225], 0, s[6:7]
	s_mov_b32 m0, s71
	s_nop 0
	global_load_lds_dwordx4 v[216:217], off
	s_waitcnt vmcnt(8)
	s_waitcnt lgkmcnt(0)
	s_barrier
	s_setprio 0
	v_mfma_f32_16x16x32_bf16 v[62:65], v[146:149], v[184:187], v[62:65]
	v_mfma_f32_16x16x32_bf16 v[58:61], v[160:163], v[184:187], v[58:61]
	v_mfma_f32_16x16x32_bf16 v[54:57], v[146:149], v[192:195], v[54:57]
	v_mfma_f32_16x16x32_bf16 v[46:49], v[160:163], v[192:195], v[46:49]
	v_mfma_f32_16x16x32_bf16 v[38:41], v[146:149], v[200:203], v[38:41]
	v_mfma_f32_16x16x32_bf16 v[30:33], v[160:163], v[200:203], v[30:33]
	v_mfma_f32_16x16x32_bf16 v[22:25], v[146:149], v[208:211], v[22:25]
	v_mfma_f32_16x16x32_bf16 v[14:17], v[160:163], v[208:211], v[14:17]
	v_mfma_f32_16x16x32_bf16 v[62:65], v[156:159], v[188:191], v[62:65]
	v_mfma_f32_16x16x32_bf16 v[58:61], v[164:167], v[188:191], v[58:61]
	v_mfma_f32_16x16x32_bf16 v[54:57], v[156:159], v[196:199], v[54:57]
	v_mfma_f32_16x16x32_bf16 v[46:49], v[164:167], v[196:199], v[46:49]
	v_mfma_f32_16x16x32_bf16 v[38:41], v[156:159], v[204:207], v[38:41]
	v_mfma_f32_16x16x32_bf16 v[30:33], v[164:167], v[204:207], v[30:33]
	v_mfma_f32_16x16x32_bf16 v[22:25], v[156:159], v[212:215], v[22:25]
	v_mfma_f32_16x16x32_bf16 v[14:17], v[164:167], v[212:215], v[14:17]
	s_setprio 2
	s_setprio 0
	v_mfma_f32_16x16x32_bf16 v[50:53], v[168:171], v[184:187], v[50:53]
	v_mfma_f32_16x16x32_bf16 v[42:45], v[176:179], v[184:187], v[42:45]
	v_mfma_f32_16x16x32_bf16 v[34:37], v[168:171], v[192:195], v[34:37]
	v_mfma_f32_16x16x32_bf16 v[26:29], v[176:179], v[192:195], v[26:29]
	v_mfma_f32_16x16x32_bf16 v[18:21], v[168:171], v[200:203], v[18:21]
	v_mfma_f32_16x16x32_bf16 v[10:13], v[176:179], v[200:203], v[10:13]
	v_mfma_f32_16x16x32_bf16 v[6:9], v[168:171], v[208:211], v[6:9]
	v_mfma_f32_16x16x32_bf16 v[2:5], v[176:179], v[208:211], v[2:5]
	v_mfma_f32_16x16x32_bf16 v[50:53], v[172:175], v[188:191], v[50:53]
	v_mfma_f32_16x16x32_bf16 v[42:45], v[180:183], v[188:191], v[42:45]
	v_mfma_f32_16x16x32_bf16 v[34:37], v[172:175], v[196:199], v[34:37]
	v_mfma_f32_16x16x32_bf16 v[26:29], v[180:183], v[196:199], v[26:29]
	v_mfma_f32_16x16x32_bf16 v[18:21], v[172:175], v[204:207], v[18:21]
	v_mfma_f32_16x16x32_bf16 v[10:13], v[180:183], v[204:207], v[10:13]
	v_mfma_f32_16x16x32_bf16 v[6:9], v[172:175], v[212:215], v[6:9]
	v_mfma_f32_16x16x32_bf16 v[2:5], v[180:183], v[212:215], v[2:5]
	s_setprio 2
	s_add_i32 s83, s83, 2
	s_add_u32 s44, s44, 0x100
	s_addc_u32 s45, s45, 0
	s_add_u32 s81, s81, 0x100
	s_addc_u32 s82, s82, 0
	s_cmp_gt_u32 s83, 61
	s_barrier
	s_cbranch_scc0 .LBB0_765
.LBB0_765:
	ds_read_b128 v[146:149], v152
	ds_read_b128 v[156:159], v152 offset:1024
	ds_read_b128 v[160:163], v152 offset:2048
	ds_read_b128 v[164:167], v152 offset:3072
	ds_read_b128 v[168:171], v153
	ds_read_b128 v[172:175], v153 offset:1024
	ds_read_b128 v[176:179], v153 offset:2048
	ds_read_b128 v[180:183], v153 offset:3072
	s_add_u32 s33, s44, 0xfff00080
	s_addc_u32 s46, s45, -1
	s_cmp_eq_u32 s83, 60
	s_cselect_b32 s53, s15, s46
	s_cselect_b32 s52, s78, s33
	s_cselect_b32 s47, s11, s82
	s_cselect_b32 s46, s13, s81
	v_lshl_add_u64 v[216:217], s[44:45], 0, v[138:139]
	s_add_i32 m0, s17, 0xc000
	ds_read_b128 v[184:187], v154
	ds_read_b128 v[188:191], v154 offset:1024
	ds_read_b128 v[192:195], v154 offset:2048
	ds_read_b128 v[196:199], v154 offset:3072
	ds_read_b128 v[200:203], v154 offset:4096
	ds_read_b128 v[204:207], v154 offset:5120
	ds_read_b128 v[208:211], v154 offset:6144
	ds_read_b128 v[212:215], v154 offset:7168
	global_load_lds_dwordx4 v[216:217], off
	v_lshl_add_u64 v[216:217], s[44:45], 0, v[140:141]
	s_add_i32 m0, s17, 0xe000
	s_nop 0
	global_load_lds_dwordx4 v[216:217], off
	s_waitcnt vmcnt(8)
	s_waitcnt lgkmcnt(0)
	s_barrier
; #define PG8_STAGE(bufoff, gbase, voff) do { _Pragma("unroll") for (int _i = 0; _i < 2; ++_i) \
;         __builtin_amdgcn_global_load_lds((const unsigned*)((const char*)(gbase) + (voff)[_i]), (LAS unsigned*)(lds + (bufoff) + ldsw + _i * 8192), 16, 0, 0); } while (0)
; #define PG8_LDA(dst, b, h) do { _Pragma("unroll") for (int m = 0; m < 4; ++m) _Pragma("unroll") for (int k = 0; k < 2; ++k) dst[m][k] = *(const LAS bf16x8*)(lds + PG8_SA(b, h) + aoff + m * 2048 + k * 1024); } while (0)
; #define PG8_MMA(ai, bj, At, Bt) do { __builtin_amdgcn_s_setprio(1); _Pragma("unroll") for (int m = 0; m < 4; ++m) _Pragma("unroll") for (int n = 0; n < 2; ++n) _Pragma("unroll") for (int k = 0; k < 2; ++k) \
;         acc[ai][bj][m][n] = __builtin_amdgcn_mfma_f32_16x16x32_bf16(Bt[n][k], At[m][k], acc[ai][bj][m][n], 0, 0, 0); __builtin_amdgcn_s_setprio(0); } while (0)
; #define PG8_WAIT_V(n) asm volatile("s_waitcnt vmcnt(" #n ")" ::: "memory")
; #define PG8_WAIT_L(n) asm volatile("s_waitcnt lgkmcnt(" #n ")" ::: "memory")
; #define PG8_BAR __builtin_amdgcn_s_barrier()
; #define PG8_SCHED __builtin_amdgcn_sched_barrier(0)
; template <class Epi>
; __device__ __forceinline__ void gemm_phase(LAS unsigned char* lds, const Gemm g, int G, int c, const Epi& E) {
;     ...
;             PG8_WAIT_V(8); PG8_WAIT_L(0); PG8_BAR; PG8_MMA(0, 0, At, B0); PG8_MMA(0, 1, At, B1); PG8_BAR; PG8_SCHED;
;             PG8_LDA(At, 0, 1); PG8_STAGE(PG8_SB(0, 0), b2, voffB); PG8_STAGE(PG8_SB(0, 1), b2 + hstepB, voffB); PG8_STAGE(PG8_SA(0, 0), a2, voffA);
;             PG8_WAIT_V(8); PG8_WAIT_L(0); PG8_BAR; PG8_MMA(1, 0, At, B0); PG8_MMA(1, 1, At, B1); PG8_BAR; PG8_SCHED;
	s_setprio 0
	v_mfma_f32_16x16x32_bf16 v[126:129], v[146:149], v[184:187], v[126:129]
	v_mfma_f32_16x16x32_bf16 v[122:125], v[160:163], v[184:187], v[122:125]
	v_mfma_f32_16x16x32_bf16 v[118:121], v[146:149], v[192:195], v[118:121]
	v_mfma_f32_16x16x32_bf16 v[110:113], v[160:163], v[192:195], v[110:113]
	v_mfma_f32_16x16x32_bf16 v[102:105], v[146:149], v[200:203], v[102:105]
	v_mfma_f32_16x16x32_bf16 v[94:97], v[160:163], v[200:203], v[94:97]
	v_mfma_f32_16x16x32_bf16 v[86:89], v[146:149], v[208:211], v[86:89]
	v_mfma_f32_16x16x32_bf16 v[78:81], v[160:163], v[208:211], v[78:81]
	v_mfma_f32_16x16x32_bf16 v[126:129], v[156:159], v[188:191], v[126:129]
	v_mfma_f32_16x16x32_bf16 v[122:125], v[164:167], v[188:191], v[122:125]
	v_mfma_f32_16x16x32_bf16 v[118:121], v[156:159], v[196:199], v[118:121]
	v_mfma_f32_16x16x32_bf16 v[110:113], v[164:167], v[196:199], v[110:113]
	v_mfma_f32_16x16x32_bf16 v[102:105], v[156:159], v[204:207], v[102:105]
	v_mfma_f32_16x16x32_bf16 v[94:97], v[164:167], v[204:207], v[94:97]
	v_mfma_f32_16x16x32_bf16 v[86:89], v[156:159], v[212:215], v[86:89]
	v_mfma_f32_16x16x32_bf16 v[78:81], v[164:167], v[212:215], v[78:81]
	s_setprio 2
	s_setprio 0
	v_mfma_f32_16x16x32_bf16 v[114:117], v[168:171], v[184:187], v[114:117]
	v_mfma_f32_16x16x32_bf16 v[106:109], v[176:179], v[184:187], v[106:109]
	v_mfma_f32_16x16x32_bf16 v[98:101], v[168:171], v[192:195], v[98:101]
	v_mfma_f32_16x16x32_bf16 v[90:93], v[176:179], v[192:195], v[90:93]
	v_mfma_f32_16x16x32_bf16 v[82:85], v[168:171], v[200:203], v[82:85]
	v_mfma_f32_16x16x32_bf16 v[74:77], v[176:179], v[200:203], v[74:77]
	v_mfma_f32_16x16x32_bf16 v[70:73], v[168:171], v[208:211], v[70:73]
	v_mfma_f32_16x16x32_bf16 v[66:69], v[176:179], v[208:211], v[66:69]
	v_mfma_f32_16x16x32_bf16 v[114:117], v[172:175], v[188:191], v[114:117]
	v_mfma_f32_16x16x32_bf16 v[106:109], v[180:183], v[188:191], v[106:109]
	v_mfma_f32_16x16x32_bf16 v[98:101], v[172:175], v[196:199], v[98:101]
	v_mfma_f32_16x16x32_bf16 v[90:93], v[180:183], v[196:199], v[90:93]
	v_mfma_f32_16x16x32_bf16 v[82:85], v[172:175], v[204:207], v[82:85]
	v_mfma_f32_16x16x32_bf16 v[74:77], v[180:183], v[204:207], v[74:77]
	v_mfma_f32_16x16x32_bf16 v[70:73], v[172:175], v[212:215], v[70:73]
	v_mfma_f32_16x16x32_bf16 v[66:69], v[180:183], v[212:215], v[66:69]
	s_setprio 2
	s_barrier
	s_add_i32 s33, s72, s61
	v_lshl_add_u64 v[216:217], s[46:47], 0, v[134:135]
	s_mov_b32 m0, s33
	ds_read_b128 v[184:187], v154 offset:16384
	ds_read_b128 v[188:191], v154 offset:17408
	ds_read_b128 v[192:195], v154 offset:18432
	ds_read_b128 v[196:199], v154 offset:19456
	ds_read_b128 v[200:203], v154 offset:20480
	ds_read_b128 v[204:207], v154 offset:21504
	ds_read_b128 v[208:211], v154 offset:22528
	ds_read_b128 v[212:215], v154 offset:23552
	global_load_lds_dwordx4 v[216:217], off
	s_add_i32 m0, s33, 0x2000
	s_add_u32 s62, s46, 0x100000
	v_lshl_add_u64 v[218:219], s[46:47], 0, v[130:131]
	s_addc_u32 s63, s47, 0
	s_add_i32 s33, s73, s61
	global_load_lds_dwordx4 v[218:219], off
	v_lshl_add_u64 v[220:221], s[62:63], 0, v[134:135]
	s_mov_b32 m0, s33
	v_lshl_add_u64 v[224:225], s[52:53], 0, v[132:133]
	global_load_lds_dwordx4 v[220:221], off
	v_lshl_add_u64 v[220:221], s[62:63], 0, v[130:131]
	s_add_i32 m0, s33, 0x2000
	s_nop 0
	global_load_lds_dwordx4 v[220:221], off
	v_lshl_add_u64 v[220:221], s[52:53], 0, v[136:137]
	s_mov_b32 m0, s17
	s_nop 0
	global_load_lds_dwordx4 v[220:221], off
	s_mov_b32 m0, s39
	s_nop 0
	global_load_lds_dwordx4 v[224:225], off
	s_waitcnt vmcnt(8)
	s_waitcnt lgkmcnt(0)
	s_barrier
	s_setprio 0
	v_mfma_f32_16x16x32_bf16 v[62:65], v[146:149], v[184:187], v[62:65]
	v_mfma_f32_16x16x32_bf16 v[58:61], v[160:163], v[184:187], v[58:61]
	v_mfma_f32_16x16x32_bf16 v[54:57], v[146:149], v[192:195], v[54:57]
	v_mfma_f32_16x16x32_bf16 v[46:49], v[160:163], v[192:195], v[46:49]
	v_mfma_f32_16x16x32_bf16 v[38:41], v[146:149], v[200:203], v[38:41]
	v_mfma_f32_16x16x32_bf16 v[30:33], v[160:163], v[200:203], v[30:33]
	v_mfma_f32_16x16x32_bf16 v[22:25], v[146:149], v[208:211], v[22:25]
	v_mfma_f32_16x16x32_bf16 v[14:17], v[160:163], v[208:211], v[14:17]
	v_mfma_f32_16x16x32_bf16 v[62:65], v[156:159], v[188:191], v[62:65]
	v_mfma_f32_16x16x32_bf16 v[58:61], v[164:167], v[188:191], v[58:61]
	v_mfma_f32_16x16x32_bf16 v[54:57], v[156:159], v[196:199], v[54:57]
	v_mfma_f32_16x16x32_bf16 v[46:49], v[164:167], v[196:199], v[46:49]
	v_mfma_f32_16x16x32_bf16 v[38:41], v[156:159], v[204:207], v[38:41]
	v_mfma_f32_16x16x32_bf16 v[30:33], v[164:167], v[204:207], v[30:33]
	v_mfma_f32_16x16x32_bf16 v[22:25], v[156:159], v[212:215], v[22:25]
	v_mfma_f32_16x16x32_bf16 v[14:17], v[164:167], v[212:215], v[14:17]
	s_setprio 2
	s_setprio 0
	v_mfma_f32_16x16x32_bf16 v[50:53], v[168:171], v[184:187], v[50:53]
	v_mfma_f32_16x16x32_bf16 v[42:45], v[176:179], v[184:187], v[42:45]
	v_mfma_f32_16x16x32_bf16 v[34:37], v[168:171], v[192:195], v[34:37]
	v_mfma_f32_16x16x32_bf16 v[26:29], v[176:179], v[192:195], v[26:29]
	v_mfma_f32_16x16x32_bf16 v[18:21], v[168:171], v[200:203], v[18:21]
	v_mfma_f32_16x16x32_bf16 v[10:13], v[176:179], v[200:203], v[10:13]
	v_mfma_f32_16x16x32_bf16 v[6:9], v[168:171], v[208:211], v[6:9]
	v_mfma_f32_16x16x32_bf16 v[2:5], v[176:179], v[208:211], v[2:5]
	v_mfma_f32_16x16x32_bf16 v[50:53], v[172:175], v[188:191], v[50:53]
	v_mfma_f32_16x16x32_bf16 v[42:45], v[180:183], v[188:191], v[42:45]
	v_mfma_f32_16x16x32_bf16 v[34:37], v[172:175], v[196:199], v[34:37]
	v_mfma_f32_16x16x32_bf16 v[26:29], v[180:183], v[196:199], v[26:29]
	v_mfma_f32_16x16x32_bf16 v[18:21], v[172:175], v[204:207], v[18:21]
	v_mfma_f32_16x16x32_bf16 v[10:13], v[180:183], v[204:207], v[10:13]
	v_mfma_f32_16x16x32_bf16 v[6:9], v[172:175], v[212:215], v[6:9]
	v_mfma_f32_16x16x32_bf16 v[2:5], v[180:183], v[212:215], v[2:5]
	s_setprio 2
	s_barrier
; #define PG8_STAGE(bufoff, gbase, voff) do { _Pragma("unroll") for (int _i = 0; _i < 2; ++_i) \
;         __builtin_amdgcn_global_load_lds((const unsigned*)((const char*)(gbase) + (voff)[_i]), (LAS unsigned*)(lds + (bufoff) + ldsw + _i * 8192), 16, 0, 0); } while (0)
; #define PG8_LDA(dst, b, h) do { _Pragma("unroll") for (int m = 0; m < 4; ++m) _Pragma("unroll") for (int k = 0; k < 2; ++k) dst[m][k] = *(const LAS bf16x8*)(lds + PG8_SA(b, h) + aoff + m * 2048 + k * 1024); } while (0)
; #define PG8_LDB(dst, b, h) do { _Pragma("unroll") for (int n = 0; n < 2; ++n) _Pragma("unroll") for (int k = 0; k < 2; ++k) dst[n][k] = *(const LAS bf16x8*)(lds + PG8_SB(b, h) + boff + n * 2048 + k * 1024); } while (0)
; #define PG8_MMA(ai, bj, At, Bt) do { __builtin_amdgcn_s_setprio(1); _Pragma("unroll") for (int m = 0; m < 4; ++m) _Pragma("unroll") for (int n = 0; n < 2; ++n) _Pragma("unroll") for (int k = 0; k < 2; ++k) \
;         acc[ai][bj][m][n] = __builtin_amdgcn_mfma_f32_16x16x32_bf16(Bt[n][k], At[m][k], acc[ai][bj][m][n], 0, 0, 0); __builtin_amdgcn_s_setprio(0); } while (0)
; #define PG8_WAIT_V(n) asm volatile("s_waitcnt vmcnt(" #n ")" ::: "memory")
; #define PG8_WAIT_L(n) asm volatile("s_waitcnt lgkmcnt(" #n ")" ::: "memory")
; #define PG8_BAR __builtin_amdgcn_s_barrier()
; #define PG8_SCHED __builtin_amdgcn_sched_barrier(0)
; template <class Epi>
; __device__ __forceinline__ void gemm_phase(LAS unsigned char* lds, const Gemm g, int G, int c, const Epi& E) {
;     ...
;             PG8_LDB(B0, 1, 0); PG8_LDB(B1, 1, 1); PG8_SCHED; PG8_LDA(At, 1, 0); PG8_STAGE(PG8_SA(0, 1), a2 + hstepA, voffA);
;             PG8_WAIT_V(8); PG8_WAIT_L(0); PG8_BAR; PG8_MMA(0, 0, At, B0); PG8_MMA(0, 1, At, B1); PG8_BAR; PG8_SCHED;
	s_add_i32 s33, 0, 0x18000
	v_add_u32_e32 v155, s33, v151
	s_add_i32 s62, 0, 0x1c000
	ds_read_b128 v[146:149], v155
	ds_read_b128 v[156:159], v155 offset:1024
	ds_read_b128 v[160:163], v155 offset:2048
	ds_read_b128 v[164:167], v155 offset:3072
	v_add_u32_e32 v155, s62, v151
	ds_read_b128 v[168:171], v155
	ds_read_b128 v[172:175], v155 offset:1024
	ds_read_b128 v[176:179], v155 offset:2048
	ds_read_b128 v[180:183], v155 offset:3072
	s_add_u32 s52, s52, 0x100000
	s_addc_u32 s53, s53, 0
	s_mov_b32 m0, s43
	v_lshl_add_u64 v[226:227], s[52:53], 0, v[136:137]
	ds_read_b128 v[184:187], v154 offset:32768
	ds_read_b128 v[188:191], v154 offset:33792
	ds_read_b128 v[192:195], v154 offset:34816
	ds_read_b128 v[196:199], v154 offset:35840
	ds_read_b128 v[200:203], v154 offset:36864
	ds_read_b128 v[204:207], v154 offset:37888
	ds_read_b128 v[208:211], v154 offset:38912
	ds_read_b128 v[212:215], v154 offset:39936
	global_load_lds_dwordx4 v[226:227], off
	v_lshl_add_u64 v[226:227], s[52:53], 0, v[132:133]
	s_mov_b32 m0, s66
	s_nop 0
	global_load_lds_dwordx4 v[226:227], off
	s_waitcnt vmcnt(8)
	s_waitcnt lgkmcnt(0)
	s_barrier
	s_setprio 0
	v_mfma_f32_16x16x32_bf16 v[126:129], v[146:149], v[184:187], v[126:129]
	v_mfma_f32_16x16x32_bf16 v[122:125], v[160:163], v[184:187], v[122:125]
	v_mfma_f32_16x16x32_bf16 v[118:121], v[146:149], v[192:195], v[118:121]
	v_mfma_f32_16x16x32_bf16 v[110:113], v[160:163], v[192:195], v[110:113]
	v_mfma_f32_16x16x32_bf16 v[102:105], v[146:149], v[200:203], v[102:105]
	v_mfma_f32_16x16x32_bf16 v[94:97], v[160:163], v[200:203], v[94:97]
	v_mfma_f32_16x16x32_bf16 v[86:89], v[146:149], v[208:211], v[86:89]
	v_mfma_f32_16x16x32_bf16 v[78:81], v[160:163], v[208:211], v[78:81]
	v_mfma_f32_16x16x32_bf16 v[126:129], v[156:159], v[188:191], v[126:129]
	v_mfma_f32_16x16x32_bf16 v[122:125], v[164:167], v[188:191], v[122:125]
	v_mfma_f32_16x16x32_bf16 v[118:121], v[156:159], v[196:199], v[118:121]
	v_mfma_f32_16x16x32_bf16 v[110:113], v[164:167], v[196:199], v[110:113]
	v_mfma_f32_16x16x32_bf16 v[102:105], v[156:159], v[204:207], v[102:105]
	v_mfma_f32_16x16x32_bf16 v[94:97], v[164:167], v[204:207], v[94:97]
	v_mfma_f32_16x16x32_bf16 v[86:89], v[156:159], v[212:215], v[86:89]
	v_mfma_f32_16x16x32_bf16 v[78:81], v[164:167], v[212:215], v[78:81]
	s_setprio 2
	s_setprio 0
	v_mfma_f32_16x16x32_bf16 v[114:117], v[168:171], v[184:187], v[114:117]
	v_mfma_f32_16x16x32_bf16 v[106:109], v[176:179], v[184:187], v[106:109]
	v_mfma_f32_16x16x32_bf16 v[98:101], v[168:171], v[192:195], v[98:101]
	v_mfma_f32_16x16x32_bf16 v[90:93], v[176:179], v[192:195], v[90:93]
	v_mfma_f32_16x16x32_bf16 v[82:85], v[168:171], v[200:203], v[82:85]
	v_mfma_f32_16x16x32_bf16 v[74:77], v[176:179], v[200:203], v[74:77]
	v_mfma_f32_16x16x32_bf16 v[70:73], v[168:171], v[208:211], v[70:73]
	v_mfma_f32_16x16x32_bf16 v[66:69], v[176:179], v[208:211], v[66:69]
	v_mfma_f32_16x16x32_bf16 v[114:117], v[172:175], v[188:191], v[114:117]
	v_mfma_f32_16x16x32_bf16 v[106:109], v[180:183], v[188:191], v[106:109]
	v_mfma_f32_16x16x32_bf16 v[98:101], v[172:175], v[196:199], v[98:101]
	v_mfma_f32_16x16x32_bf16 v[90:93], v[180:183], v[196:199], v[90:93]
	v_mfma_f32_16x16x32_bf16 v[82:85], v[172:175], v[204:207], v[82:85]
	v_mfma_f32_16x16x32_bf16 v[74:77], v[180:183], v[204:207], v[74:77]
	v_mfma_f32_16x16x32_bf16 v[70:73], v[172:175], v[212:215], v[70:73]
	v_mfma_f32_16x16x32_bf16 v[66:69], v[180:183], v[212:215], v[66:69]
	s_setprio 2
	s_barrier
; #define PG8_STAGE(bufoff, gbase, voff) do { _Pragma("unroll") for (int _i = 0; _i < 2; ++_i) \
;         __builtin_amdgcn_global_load_lds((const unsigned*)((const char*)(gbase) + (voff)[_i]), (LAS unsigned*)(lds + (bufoff) + ldsw + _i * 8192), 16, 0, 0); } while (0)
; #define PG8_LDA(dst, b, h) do { _Pragma("unroll") for (int m = 0; m < 4; ++m) _Pragma("unroll") for (int k = 0; k < 2; ++k) dst[m][k] = *(const LAS bf16x8*)(lds + PG8_SA(b, h) + aoff + m * 2048 + k * 1024); } while (0)
; #define PG8_MMA(ai, bj, At, Bt) do { __builtin_amdgcn_s_setprio(1); _Pragma("unroll") for (int m = 0; m < 4; ++m) _Pragma("unroll") for (int n = 0; n < 2; ++n) _Pragma("unroll") for (int k = 0; k < 2; ++k) \
;         acc[ai][bj][m][n] = __builtin_amdgcn_mfma_f32_16x16x32_bf16(Bt[n][k], At[m][k], acc[ai][bj][m][n], 0, 0, 0); __builtin_amdgcn_s_setprio(0); } while (0)
; #define PG8_WAIT_V(n) asm volatile("s_waitcnt vmcnt(" #n ")" ::: "memory")
; #define PG8_WAIT_L(n) asm volatile("s_waitcnt lgkmcnt(" #n ")" ::: "memory")
; #define PG8_BAR __builtin_amdgcn_s_barrier()
; #define PG8_SCHED __builtin_amdgcn_sched_barrier(0)
; template <class Epi>
; __device__ __forceinline__ void gemm_phase(LAS unsigned char* lds, const Gemm g, int G, int c, const Epi& E) {
;     ...
;             PG8_LDA(At, 1, 1); PG8_STAGE(PG8_SB(1, 0), b3, voffB); PG8_STAGE(PG8_SB(1, 1), b3 + hstepB, voffB); PG8_STAGE(PG8_SA(1, 0), a3, voffA);
;             PG8_WAIT_V(8); PG8_WAIT_L(0); PG8_BAR; PG8_MMA(1, 0, At, B0); PG8_MMA(1, 1, At, B1); PG8_BAR; PG8_SCHED;
;         }
;         if (wr == 0) PG8_BAR;
	s_add_i32 s33, s33, s61
	v_lshl_add_u64 v[216:217], v[216:217], 0, s[6:7]
	s_mov_b32 m0, s33
	ds_read_b128 v[184:187], v154 offset:49152
	ds_read_b128 v[188:191], v154 offset:50176
	ds_read_b128 v[192:195], v154 offset:51200
	ds_read_b128 v[196:199], v154 offset:52224
	ds_read_b128 v[200:203], v154 offset:53248
	ds_read_b128 v[204:207], v154 offset:54272
	ds_read_b128 v[208:211], v154 offset:55296
	ds_read_b128 v[212:215], v154 offset:56320
	global_load_lds_dwordx4 v[216:217], off
	s_add_i32 m0, s33, 0x2000
	s_add_u32 s46, s46, 0x100080
	v_lshl_add_u64 v[216:217], v[218:219], 0, s[6:7]
	s_addc_u32 s47, s47, 0
	s_add_i32 s33, s62, s61
	global_load_lds_dwordx4 v[216:217], off
	v_lshl_add_u64 v[216:217], s[46:47], 0, v[134:135]
	s_mov_b32 m0, s33
	s_nop 0
	global_load_lds_dwordx4 v[216:217], off
	v_lshl_add_u64 v[216:217], s[46:47], 0, v[130:131]
	s_add_i32 m0, s33, 0x2000
	s_nop 0
	global_load_lds_dwordx4 v[216:217], off
	v_lshl_add_u64 v[216:217], v[220:221], 0, s[6:7]
	s_mov_b32 m0, s70
	s_nop 0
	global_load_lds_dwordx4 v[216:217], off
	v_lshl_add_u64 v[216:217], v[224:225], 0, s[6:7]
	s_mov_b32 m0, s71
	s_nop 0
	global_load_lds_dwordx4 v[216:217], off
	s_waitcnt vmcnt(8)
	s_waitcnt lgkmcnt(0)
	s_barrier
	s_setprio 0
	v_mfma_f32_16x16x32_bf16 v[62:65], v[146:149], v[184:187], v[62:65]
	v_mfma_f32_16x16x32_bf16 v[58:61], v[160:163], v[184:187], v[58:61]
	v_mfma_f32_16x16x32_bf16 v[54:57], v[146:149], v[192:195], v[54:57]
	v_mfma_f32_16x16x32_bf16 v[46:49], v[160:163], v[192:195], v[46:49]
	v_mfma_f32_16x16x32_bf16 v[38:41], v[146:149], v[200:203], v[38:41]
	v_mfma_f32_16x16x32_bf16 v[30:33], v[160:163], v[200:203], v[30:33]
	v_mfma_f32_16x16x32_bf16 v[22:25], v[146:149], v[208:211], v[22:25]
	v_mfma_f32_16x16x32_bf16 v[14:17], v[160:163], v[208:211], v[14:17]
	v_mfma_f32_16x16x32_bf16 v[62:65], v[156:159], v[188:191], v[62:65]
	v_mfma_f32_16x16x32_bf16 v[58:61], v[164:167], v[188:191], v[58:61]
	v_mfma_f32_16x16x32_bf16 v[54:57], v[156:159], v[196:199], v[54:57]
	v_mfma_f32_16x16x32_bf16 v[46:49], v[164:167], v[196:199], v[46:49]
	v_mfma_f32_16x16x32_bf16 v[38:41], v[156:159], v[204:207], v[38:41]
	v_mfma_f32_16x16x32_bf16 v[30:33], v[164:167], v[204:207], v[30:33]
	v_mfma_f32_16x16x32_bf16 v[22:25], v[156:159], v[212:215], v[22:25]
	v_mfma_f32_16x16x32_bf16 v[14:17], v[164:167], v[212:215], v[14:17]
	s_setprio 2
	s_setprio 0
	v_mfma_f32_16x16x32_bf16 v[50:53], v[168:171], v[184:187], v[50:53]
	v_mfma_f32_16x16x32_bf16 v[42:45], v[176:179], v[184:187], v[42:45]
	v_mfma_f32_16x16x32_bf16 v[34:37], v[168:171], v[192:195], v[34:37]
	v_mfma_f32_16x16x32_bf16 v[26:29], v[176:179], v[192:195], v[26:29]
	v_mfma_f32_16x16x32_bf16 v[18:21], v[168:171], v[200:203], v[18:21]
	v_mfma_f32_16x16x32_bf16 v[10:13], v[176:179], v[200:203], v[10:13]
	v_mfma_f32_16x16x32_bf16 v[6:9], v[168:171], v[208:211], v[6:9]
	v_mfma_f32_16x16x32_bf16 v[2:5], v[176:179], v[208:211], v[2:5]
	v_mfma_f32_16x16x32_bf16 v[50:53], v[172:175], v[188:191], v[50:53]
	v_mfma_f32_16x16x32_bf16 v[42:45], v[180:183], v[188:191], v[42:45]
	v_mfma_f32_16x16x32_bf16 v[34:37], v[172:175], v[196:199], v[34:37]
	v_mfma_f32_16x16x32_bf16 v[26:29], v[180:183], v[196:199], v[26:29]
	v_mfma_f32_16x16x32_bf16 v[18:21], v[172:175], v[204:207], v[18:21]
	v_mfma_f32_16x16x32_bf16 v[10:13], v[180:183], v[204:207], v[10:13]
	v_mfma_f32_16x16x32_bf16 v[6:9], v[172:175], v[212:215], v[6:9]
	v_mfma_f32_16x16x32_bf16 v[2:5], v[180:183], v[212:215], v[2:5]
	s_setprio 2
	s_add_i32 s83, s83, 2
	s_add_u32 s44, s44, 0x100
	s_addc_u32 s45, s45, 0
	s_add_u32 s81, s81, 0x100
	s_addc_u32 s82, s82, 0
	s_cmp_gt_u32 s83, 61
	s_barrier
	s_cbranch_scc0 .LBB0_765
	s_and_b64 vcc, exec, s[8:9]
	s_cbranch_vccz .LBB0_768
	s_barrier

; #define PG8_STAGE(bufoff, gbase, voff) do { _Pragma("unroll") for (int _i = 0; _i < 2; ++_i) \
;         __builtin_amdgcn_global_load_lds((const unsigned*)((const char*)(gbase) + (voff)[_i]), (LAS unsigned*)(lds + (bufoff) + ldsw + _i * 8192), 16, 0, 0); } while (0)
; #define PG8_LDA(dst, b, h) do { _Pragma("unroll") for (int m = 0; m < 4; ++m) _Pragma("unroll") for (int k = 0; k < 2; ++k) dst[m][k] = *(const LAS bf16x8*)(lds + PG8_SA(b, h) + aoff + m * 2048 + k * 1024); } while (0)
; #define PG8_LDB(dst, b, h) do { _Pragma("unroll") for (int n = 0; n < 2; ++n) _Pragma("unroll") for (int k = 0; k < 2; ++k) dst[n][k] = *(const LAS bf16x8*)(lds + PG8_SB(b, h) + boff + n * 2048 + k * 1024); } while (0)
; #define PG8_MMA(ai, bj, At, Bt) do { __builtin_amdgcn_s_setprio(1); _Pragma("unroll") for (int m = 0; m < 4; ++m) _Pragma("unroll") for (int n = 0; n < 2; ++n) _Pragma("unroll") for (int k = 0; k < 2; ++k) \
;         acc[ai][bj][m][n] = __builtin_amdgcn_mfma_f32_16x16x32_bf16(Bt[n][k], At[m][k], acc[ai][bj][m][n], 0, 0, 0); __builtin_amdgcn_s_setprio(0); } while (0)
; #define PG8_WAIT_V(n) asm volatile("s_waitcnt vmcnt(" #n ")" ::: "memory")
; template <class Epi>
; __device__ __forceinline__ void gemm_phase(LAS unsigned char* lds, const Gemm g, int G, int c, const Epi& E) {
;     ...
;         const bool has_next = S.next(ui + 1, nxt);
;         const char* nA = has_next ? (const char*)(g.A + (size_t)nxt.pb * g.sA) + (size_t)nxt.pm * 2 * hstepA : cA;
;         const char* nB = has_next ? (const char*)(g.Bt + (size_t)nxt.pb * g.sB) + (size_t)nxt.pn * 2 * hstepB : cB;
; #pragma nounroll
;         for (int t = 0; t < nt; t += 2) {
;             const bool last = (t == nt - 2);
;             const char* a1 = cA + (size_t)(t + 1) * kstep;
;             const char* a2 = last ? nA : cA + (size_t)(t + 2) * kstep; const char* b2 = last ? nB : cB + (size_t)(t + 2) * kstep;
;             const char* a3 = a2 + kstep; const char* b3 = b2 + kstep;
;             PG8_LDB(B0, 0, 0); PG8_LDB(B1, 0, 1); PG8_SCHED; PG8_LDA(At, 0, 0); PG8_STAGE(PG8_SA(1, 1), a1 + hstepA, voffA);
;             PG8_WAIT_V(8); PG8_WAIT_L(0); PG8_BAR; PG8_MMA(0, 0, At, B0); PG8_MMA(0, 1, At, B1); PG8_BAR; PG8_SCHED;
;             PG8_LDA(At, 0, 1); PG8_STAGE(PG8_SB(0, 0), b2, voffB); PG8_STAGE(PG8_SB(0, 1), b2 + hstepB, voffB); PG8_STAGE(PG8_SA(0, 0), a2, voffA);
.LBB0_780:
	s_ashr_i32 s25, s24, 31
	s_lshl_b64 s[42:43], s[24:25], 18
	s_add_u32 s42, s59, s42
	s_addc_u32 s43, s60, s43
	s_and_b64 s[52:53], s[38:39], exec
	s_cselect_b32 s25, s43, s47
	s_cselect_b32 s89, s42, s46
	s_add_u32 s90, s46, 0x100
	s_addc_u32 s91, s47, 0
	s_mov_b32 s92, -2
	s_mov_b64 s[46:47], 0
	ds_read_b128 v[150:153], v146
	ds_read_b128 v[154:157], v146 offset:1024
	ds_read_b128 v[158:161], v146 offset:2048
	ds_read_b128 v[162:165], v146 offset:3072
	ds_read_b128 v[166:169], v147
	ds_read_b128 v[170:173], v147 offset:1024
	ds_read_b128 v[174:177], v147 offset:2048
	ds_read_b128 v[178:181], v147 offset:3072
	s_add_u32 s52, s46, 0x100
	s_addc_u32 s53, s47, 0
	s_add_u32 s33, s90, s46
	s_addc_u32 s55, s91, s47
	s_cmp_eq_u32 s92, 4
	s_cselect_b32 s56, 0, s52
	s_cselect_b32 s57, 0, s53
	s_cselect_b32 s54, s89, s33
	s_cselect_b32 s55, s25, s55
	s_add_u32 s56, s2, s56
	s_addc_u32 s57, s3, s57
	s_mov_b32 m0, s83
	v_lshl_add_u64 v[142:143], v[138:139], 0, s[46:47]
	ds_read_b128 v[182:185], v148
	ds_read_b128 v[186:189], v148 offset:1024
	ds_read_b128 v[190:193], v148 offset:2048
	ds_read_b128 v[194:197], v148 offset:3072
	ds_read_b128 v[198:201], v148 offset:4096
	ds_read_b128 v[202:205], v148 offset:5120
	ds_read_b128 v[206:209], v148 offset:6144
	ds_read_b128 v[210:213], v148 offset:7168
	global_load_lds_dwordx4 v[142:143], off
	v_lshl_add_u64 v[142:143], v[140:141], 0, s[46:47]
	s_mov_b32 m0, s84
	s_nop 0
	global_load_lds_dwordx4 v[142:143], off
	s_waitcnt vmcnt(8)
	s_waitcnt lgkmcnt(0)
	s_barrier
	s_setprio 0
	v_mfma_f32_16x16x32_bf16 v[126:129], v[150:153], v[182:185], 0
	v_mfma_f32_16x16x32_bf16 v[122:125], v[158:161], v[182:185], 0
	v_mfma_f32_16x16x32_bf16 v[118:121], v[150:153], v[190:193], 0
	v_mfma_f32_16x16x32_bf16 v[110:113], v[158:161], v[190:193], 0
	v_mfma_f32_16x16x32_bf16 v[102:105], v[150:153], v[198:201], 0
	v_mfma_f32_16x16x32_bf16 v[94:97], v[158:161], v[198:201], 0
	v_mfma_f32_16x16x32_bf16 v[86:89], v[150:153], v[206:209], 0
	v_mfma_f32_16x16x32_bf16 v[78:81], v[158:161], v[206:209], 0
	v_mfma_f32_16x16x32_bf16 v[126:129], v[154:157], v[186:189], v[126:129]
	v_mfma_f32_16x16x32_bf16 v[122:125], v[162:165], v[186:189], v[122:125]
	v_mfma_f32_16x16x32_bf16 v[118:121], v[154:157], v[194:197], v[118:121]
	v_mfma_f32_16x16x32_bf16 v[110:113], v[162:165], v[194:197], v[110:113]
	v_mfma_f32_16x16x32_bf16 v[102:105], v[154:157], v[202:205], v[102:105]
	v_mfma_f32_16x16x32_bf16 v[94:97], v[162:165], v[202:205], v[94:97]
	v_mfma_f32_16x16x32_bf16 v[86:89], v[154:157], v[210:213], v[86:89]
	v_mfma_f32_16x16x32_bf16 v[78:81], v[162:165], v[210:213], v[78:81]
	s_setprio 2
	s_setprio 0
	v_mfma_f32_16x16x32_bf16 v[114:117], v[166:169], v[182:185], 0
	v_mfma_f32_16x16x32_bf16 v[106:109], v[174:177], v[182:185], 0
	v_mfma_f32_16x16x32_bf16 v[98:101], v[166:169], v[190:193], 0
	v_mfma_f32_16x16x32_bf16 v[90:93], v[174:177], v[190:193], 0
	v_mfma_f32_16x16x32_bf16 v[82:85], v[166:169], v[198:201], 0
	v_mfma_f32_16x16x32_bf16 v[74:77], v[174:177], v[198:201], 0
	v_mfma_f32_16x16x32_bf16 v[70:73], v[166:169], v[206:209], 0
	v_mfma_f32_16x16x32_bf16 v[66:69], v[174:177], v[206:209], 0
	v_mfma_f32_16x16x32_bf16 v[114:117], v[170:173], v[186:189], v[114:117]
	v_mfma_f32_16x16x32_bf16 v[106:109], v[178:181], v[186:189], v[106:109]
	v_mfma_f32_16x16x32_bf16 v[98:101], v[170:173], v[194:197], v[98:101]
	v_mfma_f32_16x16x32_bf16 v[90:93], v[178:181], v[194:197], v[90:93]
	v_mfma_f32_16x16x32_bf16 v[82:85], v[170:173], v[202:205], v[82:85]
	v_mfma_f32_16x16x32_bf16 v[74:77], v[178:181], v[202:205], v[74:77]
	v_mfma_f32_16x16x32_bf16 v[70:73], v[170:173], v[210:213], v[70:73]
	v_mfma_f32_16x16x32_bf16 v[66:69], v[178:181], v[210:213], v[66:69]
	s_setprio 2
	s_barrier
	s_mov_b32 m0, s85
	v_lshl_add_u64 v[142:143], s[54:55], 0, v[134:135]
	s_add_u32 s46, s54, 0x20000
	ds_read_b128 v[182:185], v148 offset:16384
	ds_read_b128 v[186:189], v148 offset:17408
	ds_read_b128 v[190:193], v148 offset:18432
	ds_read_b128 v[194:197], v148 offset:19456
	ds_read_b128 v[198:201], v148 offset:20480
	ds_read_b128 v[202:205], v148 offset:21504
	ds_read_b128 v[206:209], v148 offset:22528
	ds_read_b128 v[210:213], v148 offset:23552
	global_load_lds_dwordx4 v[142:143], off
	v_lshl_add_u64 v[214:215], s[54:55], 0, v[130:131]
	s_mov_b32 m0, s86
	s_addc_u32 s47, s55, 0
	global_load_lds_dwordx4 v[214:215], off
	v_lshl_add_u64 v[216:217], s[46:47], 0, v[134:135]
	s_mov_b32 m0, s87
	v_lshl_add_u64 v[218:219], s[56:57], 0, v[132:133]
	global_load_lds_dwordx4 v[216:217], off
	v_lshl_add_u64 v[216:217], s[46:47], 0, v[130:131]
	s_mov_b32 m0, s88
	s_nop 0
	global_load_lds_dwordx4 v[216:217], off
	v_lshl_add_u64 v[216:217], s[56:57], 0, v[136:137]
	s_mov_b32 m0, s45
	s_nop 0
	global_load_lds_dwordx4 v[216:217], off
	s_mov_b32 m0, s61
	s_nop 0
	global_load_lds_dwordx4 v[218:219], off
	s_waitcnt vmcnt(8)
	s_waitcnt lgkmcnt(0)
	s_barrier
; #define PG8_STAGE(bufoff, gbase, voff) do { _Pragma("unroll") for (int _i = 0; _i < 2; ++_i) \
;         __builtin_amdgcn_global_load_lds((const unsigned*)((const char*)(gbase) + (voff)[_i]), (LAS unsigned*)(lds + (bufoff) + ldsw + _i * 8192), 16, 0, 0); } while (0)
; #define PG8_LDA(dst, b, h) do { _Pragma("unroll") for (int m = 0; m < 4; ++m) _Pragma("unroll") for (int k = 0; k < 2; ++k) dst[m][k] = *(const LAS bf16x8*)(lds + PG8_SA(b, h) + aoff + m * 2048 + k * 1024); } while (0)
; #define PG8_LDB(dst, b, h) do { _Pragma("unroll") for (int n = 0; n < 2; ++n) _Pragma("unroll") for (int k = 0; k < 2; ++k) dst[n][k] = *(const LAS bf16x8*)(lds + PG8_SB(b, h) + boff + n * 2048 + k * 1024); } while (0)
; #define PG8_MMA(ai, bj, At, Bt) do { __builtin_amdgcn_s_setprio(1); _Pragma("unroll") for (int m = 0; m < 4; ++m) _Pragma("unroll") for (int n = 0; n < 2; ++n) _Pragma("unroll") for (int k = 0; k < 2; ++k) \
;         acc[ai][bj][m][n] = __builtin_amdgcn_mfma_f32_16x16x32_bf16(Bt[n][k], At[m][k], acc[ai][bj][m][n], 0, 0, 0); __builtin_amdgcn_s_setprio(0); } while (0)
; #define PG8_WAIT_V(n) asm volatile("s_waitcnt vmcnt(" #n ")" ::: "memory")
; #define PG8_WAIT_L(n) asm volatile("s_waitcnt lgkmcnt(" #n ")" ::: "memory")
; #define PG8_BAR __builtin_amdgcn_s_barrier()
; #define PG8_SCHED __builtin_amdgcn_sched_barrier(0)
; template <class Epi>
; __device__ __forceinline__ void gemm_phase(LAS unsigned char* lds, const Gemm g, int G, int c, const Epi& E) {
;     ...
;             PG8_WAIT_V(8); PG8_WAIT_L(0); PG8_BAR; PG8_MMA(1, 0, At, B0); PG8_MMA(1, 1, At, B1); PG8_BAR; PG8_SCHED;
;             PG8_LDB(B0, 1, 0); PG8_LDB(B1, 1, 1); PG8_SCHED; PG8_LDA(At, 1, 0); PG8_STAGE(PG8_SA(0, 1), a2 + hstepA, voffA);
;             PG8_WAIT_V(8); PG8_WAIT_L(0); PG8_BAR; PG8_MMA(0, 0, At, B0); PG8_MMA(0, 1, At, B1); PG8_BAR; PG8_SCHED;
	s_setprio 0
	v_mfma_f32_16x16x32_bf16 v[62:65], v[150:153], v[182:185], 0
	v_mfma_f32_16x16x32_bf16 v[58:61], v[158:161], v[182:185], 0
	v_mfma_f32_16x16x32_bf16 v[54:57], v[150:153], v[190:193], 0
	v_mfma_f32_16x16x32_bf16 v[46:49], v[158:161], v[190:193], 0
	v_mfma_f32_16x16x32_bf16 v[38:41], v[150:153], v[198:201], 0
	v_mfma_f32_16x16x32_bf16 v[30:33], v[158:161], v[198:201], 0
	v_mfma_f32_16x16x32_bf16 v[22:25], v[150:153], v[206:209], 0
	v_mfma_f32_16x16x32_bf16 v[14:17], v[158:161], v[206:209], 0
	v_mfma_f32_16x16x32_bf16 v[62:65], v[154:157], v[186:189], v[62:65]
	v_mfma_f32_16x16x32_bf16 v[58:61], v[162:165], v[186:189], v[58:61]
	v_mfma_f32_16x16x32_bf16 v[54:57], v[154:157], v[194:197], v[54:57]
	v_mfma_f32_16x16x32_bf16 v[46:49], v[162:165], v[194:197], v[46:49]
	v_mfma_f32_16x16x32_bf16 v[38:41], v[154:157], v[202:205], v[38:41]
	v_mfma_f32_16x16x32_bf16 v[30:33], v[162:165], v[202:205], v[30:33]
	v_mfma_f32_16x16x32_bf16 v[22:25], v[154:157], v[210:213], v[22:25]
	v_mfma_f32_16x16x32_bf16 v[14:17], v[162:165], v[210:213], v[14:17]
	s_setprio 2
	s_setprio 0
	v_mfma_f32_16x16x32_bf16 v[50:53], v[166:169], v[182:185], 0
	v_mfma_f32_16x16x32_bf16 v[42:45], v[174:177], v[182:185], 0
	v_mfma_f32_16x16x32_bf16 v[34:37], v[166:169], v[190:193], 0
	v_mfma_f32_16x16x32_bf16 v[26:29], v[174:177], v[190:193], 0
	v_mfma_f32_16x16x32_bf16 v[18:21], v[166:169], v[198:201], 0
	v_mfma_f32_16x16x32_bf16 v[10:13], v[174:177], v[198:201], 0
	v_mfma_f32_16x16x32_bf16 v[6:9], v[166:169], v[206:209], 0
	v_mfma_f32_16x16x32_bf16 v[2:5], v[174:177], v[206:209], 0
	v_mfma_f32_16x16x32_bf16 v[50:53], v[170:173], v[186:189], v[50:53]
	v_mfma_f32_16x16x32_bf16 v[42:45], v[178:181], v[186:189], v[42:45]
	v_mfma_f32_16x16x32_bf16 v[34:37], v[170:173], v[194:197], v[34:37]
	v_mfma_f32_16x16x32_bf16 v[26:29], v[178:181], v[194:197], v[26:29]
	v_mfma_f32_16x16x32_bf16 v[18:21], v[170:173], v[202:205], v[18:21]
	v_mfma_f32_16x16x32_bf16 v[10:13], v[178:181], v[202:205], v[10:13]
	v_mfma_f32_16x16x32_bf16 v[6:9], v[170:173], v[210:213], v[6:9]
	v_mfma_f32_16x16x32_bf16 v[2:5], v[178:181], v[210:213], v[2:5]
	s_setprio 2
	s_barrier
	s_add_i32 s33, 0, 0x18000
	v_add_u32_e32 v149, s33, v145
	s_add_i32 s62, 0, 0x1c000
	ds_read_b128 v[150:153], v149
	ds_read_b128 v[154:157], v149 offset:1024
	ds_read_b128 v[158:161], v149 offset:2048
	ds_read_b128 v[162:165], v149 offset:3072
	v_add_u32_e32 v149, s62, v145
	ds_read_b128 v[166:169], v149
	ds_read_b128 v[170:173], v149 offset:1024
	ds_read_b128 v[174:177], v149 offset:2048
	ds_read_b128 v[178:181], v149 offset:3072
	s_add_u32 s46, s56, 0x20000
	s_addc_u32 s47, s57, 0
	s_mov_b32 m0, s66
	v_lshl_add_u64 v[220:221], s[46:47], 0, v[136:137]
	ds_read_b128 v[182:185], v148 offset:32768
	ds_read_b128 v[186:189], v148 offset:33792
	ds_read_b128 v[190:193], v148 offset:34816
	ds_read_b128 v[194:197], v148 offset:35840
	ds_read_b128 v[198:201], v148 offset:36864
	ds_read_b128 v[202:205], v148 offset:37888
	ds_read_b128 v[206:209], v148 offset:38912
	ds_read_b128 v[210:213], v148 offset:39936
	global_load_lds_dwordx4 v[220:221], off
	v_lshl_add_u64 v[220:221], s[46:47], 0, v[132:133]
	s_mov_b32 m0, s67
	s_nop 0
	global_load_lds_dwordx4 v[220:221], off
	s_waitcnt vmcnt(8)
	s_waitcnt lgkmcnt(0)
	s_barrier
	s_setprio 0
	v_mfma_f32_16x16x32_bf16 v[126:129], v[150:153], v[182:185], v[126:129]
	v_mfma_f32_16x16x32_bf16 v[122:125], v[158:161], v[182:185], v[122:125]
	v_mfma_f32_16x16x32_bf16 v[118:121], v[150:153], v[190:193], v[118:121]
	v_mfma_f32_16x16x32_bf16 v[110:113], v[158:161], v[190:193], v[110:113]
	v_mfma_f32_16x16x32_bf16 v[102:105], v[150:153], v[198:201], v[102:105]
	v_mfma_f32_16x16x32_bf16 v[94:97], v[158:161], v[198:201], v[94:97]
	v_mfma_f32_16x16x32_bf16 v[86:89], v[150:153], v[206:209], v[86:89]
	v_mfma_f32_16x16x32_bf16 v[78:81], v[158:161], v[206:209], v[78:81]
	v_mfma_f32_16x16x32_bf16 v[126:129], v[154:157], v[186:189], v[126:129]
	v_mfma_f32_16x16x32_bf16 v[122:125], v[162:165], v[186:189], v[122:125]
	v_mfma_f32_16x16x32_bf16 v[118:121], v[154:157], v[194:197], v[118:121]
	v_mfma_f32_16x16x32_bf16 v[110:113], v[162:165], v[194:197], v[110:113]
	v_mfma_f32_16x16x32_bf16 v[102:105], v[154:157], v[202:205], v[102:105]
	v_mfma_f32_16x16x32_bf16 v[94:97], v[162:165], v[202:205], v[94:97]
	v_mfma_f32_16x16x32_bf16 v[86:89], v[154:157], v[210:213], v[86:89]
	v_mfma_f32_16x16x32_bf16 v[78:81], v[162:165], v[210:213], v[78:81]
	s_setprio 2
	s_setprio 0
	v_mfma_f32_16x16x32_bf16 v[114:117], v[166:169], v[182:185], v[114:117]
	v_mfma_f32_16x16x32_bf16 v[106:109], v[174:177], v[182:185], v[106:109]
	v_mfma_f32_16x16x32_bf16 v[98:101], v[166:169], v[190:193], v[98:101]
	v_mfma_f32_16x16x32_bf16 v[90:93], v[174:177], v[190:193], v[90:93]
	v_mfma_f32_16x16x32_bf16 v[82:85], v[166:169], v[198:201], v[82:85]
	v_mfma_f32_16x16x32_bf16 v[74:77], v[174:177], v[198:201], v[74:77]
	v_mfma_f32_16x16x32_bf16 v[70:73], v[166:169], v[206:209], v[70:73]
	v_mfma_f32_16x16x32_bf16 v[66:69], v[174:177], v[206:209], v[66:69]
	v_mfma_f32_16x16x32_bf16 v[114:117], v[170:173], v[186:189], v[114:117]
	v_mfma_f32_16x16x32_bf16 v[106:109], v[178:181], v[186:189], v[106:109]
	v_mfma_f32_16x16x32_bf16 v[98:101], v[170:173], v[194:197], v[98:101]
	v_mfma_f32_16x16x32_bf16 v[90:93], v[178:181], v[194:197], v[90:93]
	v_mfma_f32_16x16x32_bf16 v[82:85], v[170:173], v[202:205], v[82:85]
	v_mfma_f32_16x16x32_bf16 v[74:77], v[178:181], v[202:205], v[74:77]
	v_mfma_f32_16x16x32_bf16 v[70:73], v[170:173], v[210:213], v[70:73]
	v_mfma_f32_16x16x32_bf16 v[66:69], v[178:181], v[210:213], v[66:69]
	s_setprio 2
	s_barrier
; #define PG8_STAGE(bufoff, gbase, voff) do { _Pragma("unroll") for (int _i = 0; _i < 2; ++_i) \
;         __builtin_amdgcn_global_load_lds((const unsigned*)((const char*)(gbase) + (voff)[_i]), (LAS unsigned*)(lds + (bufoff) + ldsw + _i * 8192), 16, 0, 0); } while (0)
; #define PG8_LDA(dst, b, h) do { _Pragma("unroll") for (int m = 0; m < 4; ++m) _Pragma("unroll") for (int k = 0; k < 2; ++k) dst[m][k] = *(const LAS bf16x8*)(lds + PG8_SA(b, h) + aoff + m * 2048 + k * 1024); } while (0)
; #define PG8_LDB(dst, b, h) do { _Pragma("unroll") for (int n = 0; n < 2; ++n) _Pragma("unroll") for (int k = 0; k < 2; ++k) dst[n][k] = *(const LAS bf16x8*)(lds + PG8_SB(b, h) + boff + n * 2048 + k * 1024); } while (0)
; #define PG8_MMA(ai, bj, At, Bt) do { __builtin_amdgcn_s_setprio(1); _Pragma("unroll") for (int m = 0; m < 4; ++m) _Pragma("unroll") for (int n = 0; n < 2; ++n) _Pragma("unroll") for (int k = 0; k < 2; ++k) \
;         acc[ai][bj][m][n] = __builtin_amdgcn_mfma_f32_16x16x32_bf16(Bt[n][k], At[m][k], acc[ai][bj][m][n], 0, 0, 0); __builtin_amdgcn_s_setprio(0); } while (0)
; #define PG8_WAIT_V(n) asm volatile("s_waitcnt vmcnt(" #n ")" ::: "memory")
; #define PG8_WAIT_L(n) asm volatile("s_waitcnt lgkmcnt(" #n ")" ::: "memory")
; #define PG8_BAR __builtin_amdgcn_s_barrier()
; #define PG8_SCHED __builtin_amdgcn_sched_barrier(0)
; template <class Epi>
; __device__ __forceinline__ void gemm_phase(LAS unsigned char* lds, const Gemm g, int G, int c, const Epi& E) {
;     ...
;         for (int t = 0; t < nt; t += 2) {
;             const bool last = (t == nt - 2);
;             const char* a1 = cA + (size_t)(t + 1) * kstep;
;             const char* a2 = last ? nA : cA + (size_t)(t + 2) * kstep; const char* b2 = last ? nB : cB + (size_t)(t + 2) * kstep;
;             const char* a3 = a2 + kstep; const char* b3 = b2 + kstep;
;             PG8_LDB(B0, 0, 0); PG8_LDB(B1, 0, 1); PG8_SCHED; PG8_LDA(At, 0, 0); PG8_STAGE(PG8_SA(1, 1), a1 + hstepA, voffA);
;             PG8_WAIT_V(8); PG8_WAIT_L(0); PG8_BAR; PG8_MMA(0, 0, At, B0); PG8_MMA(0, 1, At, B1); PG8_BAR; PG8_SCHED;
;     ...
;             PG8_LDA(At, 1, 1); PG8_STAGE(PG8_SB(1, 0), b3, voffB); PG8_STAGE(PG8_SB(1, 1), b3 + hstepB, voffB); PG8_STAGE(PG8_SA(1, 0), a3, voffA);
;             PG8_WAIT_V(8); PG8_WAIT_L(0); PG8_BAR; PG8_MMA(1, 0, At, B0); PG8_MMA(1, 1, At, B1); PG8_BAR; PG8_SCHED;
	s_add_i32 s33, s33, s58
	v_lshl_add_u64 v[142:143], v[142:143], 0, s[6:7]
	s_mov_b32 m0, s33
	ds_read_b128 v[182:185], v148 offset:49152
	ds_read_b128 v[186:189], v148 offset:50176
	ds_read_b128 v[190:193], v148 offset:51200
	ds_read_b128 v[194:197], v148 offset:52224
	ds_read_b128 v[198:201], v148 offset:53248
	ds_read_b128 v[202:205], v148 offset:54272
	ds_read_b128 v[206:209], v148 offset:55296
	ds_read_b128 v[210:213], v148 offset:56320
	global_load_lds_dwordx4 v[142:143], off
	s_add_i32 m0, s33, 0x2000
	s_add_u32 s46, s54, 0x20080
	v_lshl_add_u64 v[142:143], v[214:215], 0, s[6:7]
	s_addc_u32 s47, s55, 0
	s_add_i32 s33, s62, s58
	global_load_lds_dwordx4 v[142:143], off
	v_lshl_add_u64 v[142:143], s[46:47], 0, v[134:135]
	s_mov_b32 m0, s33
	s_nop 0
	global_load_lds_dwordx4 v[142:143], off
	v_lshl_add_u64 v[142:143], s[46:47], 0, v[130:131]
	s_add_i32 m0, s33, 0x2000
	s_nop 0
	global_load_lds_dwordx4 v[142:143], off
	v_lshl_add_u64 v[142:143], v[216:217], 0, s[6:7]
	s_mov_b32 m0, s71
	s_nop 0
	global_load_lds_dwordx4 v[142:143], off
	v_lshl_add_u64 v[142:143], v[218:219], 0, s[6:7]
	s_mov_b32 m0, s72
	s_nop 0
	global_load_lds_dwordx4 v[142:143], off
	s_waitcnt vmcnt(8)
	s_waitcnt lgkmcnt(0)
	s_barrier
	s_setprio 0
	v_mfma_f32_16x16x32_bf16 v[62:65], v[150:153], v[182:185], v[62:65]
	v_mfma_f32_16x16x32_bf16 v[58:61], v[158:161], v[182:185], v[58:61]
	v_mfma_f32_16x16x32_bf16 v[54:57], v[150:153], v[190:193], v[54:57]
	v_mfma_f32_16x16x32_bf16 v[46:49], v[158:161], v[190:193], v[46:49]
	v_mfma_f32_16x16x32_bf16 v[38:41], v[150:153], v[198:201], v[38:41]
	v_mfma_f32_16x16x32_bf16 v[30:33], v[158:161], v[198:201], v[30:33]
	v_mfma_f32_16x16x32_bf16 v[22:25], v[150:153], v[206:209], v[22:25]
	v_mfma_f32_16x16x32_bf16 v[14:17], v[158:161], v[206:209], v[14:17]
	v_mfma_f32_16x16x32_bf16 v[62:65], v[154:157], v[186:189], v[62:65]
	v_mfma_f32_16x16x32_bf16 v[58:61], v[162:165], v[186:189], v[58:61]
	v_mfma_f32_16x16x32_bf16 v[54:57], v[154:157], v[194:197], v[54:57]
	v_mfma_f32_16x16x32_bf16 v[46:49], v[162:165], v[194:197], v[46:49]
	v_mfma_f32_16x16x32_bf16 v[38:41], v[154:157], v[202:205], v[38:41]
	v_mfma_f32_16x16x32_bf16 v[30:33], v[162:165], v[202:205], v[30:33]
	v_mfma_f32_16x16x32_bf16 v[22:25], v[154:157], v[210:213], v[22:25]
	v_mfma_f32_16x16x32_bf16 v[14:17], v[162:165], v[210:213], v[14:17]
	s_setprio 2
	s_setprio 0
	v_mfma_f32_16x16x32_bf16 v[50:53], v[166:169], v[182:185], v[50:53]
	v_mfma_f32_16x16x32_bf16 v[42:45], v[174:177], v[182:185], v[42:45]
	v_mfma_f32_16x16x32_bf16 v[34:37], v[166:169], v[190:193], v[34:37]
	v_mfma_f32_16x16x32_bf16 v[26:29], v[174:177], v[190:193], v[26:29]
	v_mfma_f32_16x16x32_bf16 v[18:21], v[166:169], v[198:201], v[18:21]
	v_mfma_f32_16x16x32_bf16 v[10:13], v[174:177], v[198:201], v[10:13]
	v_mfma_f32_16x16x32_bf16 v[6:9], v[166:169], v[206:209], v[6:9]
	v_mfma_f32_16x16x32_bf16 v[2:5], v[174:177], v[206:209], v[2:5]
	v_mfma_f32_16x16x32_bf16 v[50:53], v[170:173], v[186:189], v[50:53]
	v_mfma_f32_16x16x32_bf16 v[42:45], v[178:181], v[186:189], v[42:45]
	v_mfma_f32_16x16x32_bf16 v[34:37], v[170:173], v[194:197], v[34:37]
	v_mfma_f32_16x16x32_bf16 v[26:29], v[178:181], v[194:197], v[26:29]
	v_mfma_f32_16x16x32_bf16 v[18:21], v[170:173], v[202:205], v[18:21]
	v_mfma_f32_16x16x32_bf16 v[10:13], v[178:181], v[202:205], v[10:13]
	v_mfma_f32_16x16x32_bf16 v[6:9], v[170:173], v[210:213], v[6:9]
	v_mfma_f32_16x16x32_bf16 v[2:5], v[178:181], v[210:213], v[2:5]
	s_setprio 2
	s_add_i32 s92, s92, 2
	s_cmp_gt_u32 s92, 5
	s_mov_b64 s[46:47], s[52:53]
	s_barrier
	s_cbranch_scc0 .LBB0_781
.LBB0_781:
	ds_read_b128 v[150:153], v146
	ds_read_b128 v[154:157], v146 offset:1024
	ds_read_b128 v[158:161], v146 offset:2048
	ds_read_b128 v[162:165], v146 offset:3072
	ds_read_b128 v[166:169], v147
	ds_read_b128 v[170:173], v147 offset:1024
	ds_read_b128 v[174:177], v147 offset:2048
	ds_read_b128 v[178:181], v147 offset:3072
	s_add_u32 s52, s46, 0x100
	s_addc_u32 s53, s47, 0
	s_add_u32 s33, s90, s46
	s_addc_u32 s55, s91, s47
	s_cmp_eq_u32 s92, 4
	s_cselect_b32 s56, 0, s52
	s_cselect_b32 s57, 0, s53
	s_cselect_b32 s54, s89, s33
	s_cselect_b32 s55, s25, s55
	s_add_u32 s56, s2, s56
	s_addc_u32 s57, s3, s57
	s_mov_b32 m0, s83
	v_lshl_add_u64 v[142:143], v[138:139], 0, s[46:47]
	ds_read_b128 v[182:185], v148
	ds_read_b128 v[186:189], v148 offset:1024
	ds_read_b128 v[190:193], v148 offset:2048
	ds_read_b128 v[194:197], v148 offset:3072
	ds_read_b128 v[198:201], v148 offset:4096
	ds_read_b128 v[202:205], v148 offset:5120
	ds_read_b128 v[206:209], v148 offset:6144
	ds_read_b128 v[210:213], v148 offset:7168
	global_load_lds_dwordx4 v[142:143], off
	v_lshl_add_u64 v[142:143], v[140:141], 0, s[46:47]
	s_mov_b32 m0, s84
	s_nop 0
	global_load_lds_dwordx4 v[142:143], off
	s_waitcnt vmcnt(8)
	s_waitcnt lgkmcnt(0)
	s_barrier
; #define PG8_STAGE(bufoff, gbase, voff) do { _Pragma("unroll") for (int _i = 0; _i < 2; ++_i) \
;         __builtin_amdgcn_global_load_lds((const unsigned*)((const char*)(gbase) + (voff)[_i]), (LAS unsigned*)(lds + (bufoff) + ldsw + _i * 8192), 16, 0, 0); } while (0)
; #define PG8_LDA(dst, b, h) do { _Pragma("unroll") for (int m = 0; m < 4; ++m) _Pragma("unroll") for (int k = 0; k < 2; ++k) dst[m][k] = *(const LAS bf16x8*)(lds + PG8_SA(b, h) + aoff + m * 2048 + k * 1024); } while (0)
; #define PG8_MMA(ai, bj, At, Bt) do { __builtin_amdgcn_s_setprio(1); _Pragma("unroll") for (int m = 0; m < 4; ++m) _Pragma("unroll") for (int n = 0; n < 2; ++n) _Pragma("unroll") for (int k = 0; k < 2; ++k) \
;         acc[ai][bj][m][n] = __builtin_amdgcn_mfma_f32_16x16x32_bf16(Bt[n][k], At[m][k], acc[ai][bj][m][n], 0, 0, 0); __builtin_amdgcn_s_setprio(0); } while (0)
; #define PG8_WAIT_V(n) asm volatile("s_waitcnt vmcnt(" #n ")" ::: "memory")
; #define PG8_WAIT_L(n) asm volatile("s_waitcnt lgkmcnt(" #n ")" ::: "memory")
; #define PG8_BAR __builtin_amdgcn_s_barrier()
; #define PG8_SCHED __builtin_amdgcn_sched_barrier(0)
; template <class Epi>
; __device__ __forceinline__ void gemm_phase(LAS unsigned char* lds, const Gemm g, int G, int c, const Epi& E) {
;     ...
;             PG8_WAIT_V(8); PG8_WAIT_L(0); PG8_BAR; PG8_MMA(0, 0, At, B0); PG8_MMA(0, 1, At, B1); PG8_BAR; PG8_SCHED;
;             PG8_LDA(At, 0, 1); PG8_STAGE(PG8_SB(0, 0), b2, voffB); PG8_STAGE(PG8_SB(0, 1), b2 + hstepB, voffB); PG8_STAGE(PG8_SA(0, 0), a2, voffA);
;             PG8_WAIT_V(8); PG8_WAIT_L(0); PG8_BAR; PG8_MMA(1, 0, At, B0); PG8_MMA(1, 1, At, B1); PG8_BAR; PG8_SCHED;
	s_setprio 0
	v_mfma_f32_16x16x32_bf16 v[126:129], v[150:153], v[182:185], v[126:129]
	v_mfma_f32_16x16x32_bf16 v[122:125], v[158:161], v[182:185], v[122:125]
	v_mfma_f32_16x16x32_bf16 v[118:121], v[150:153], v[190:193], v[118:121]
	v_mfma_f32_16x16x32_bf16 v[110:113], v[158:161], v[190:193], v[110:113]
	v_mfma_f32_16x16x32_bf16 v[102:105], v[150:153], v[198:201], v[102:105]
	v_mfma_f32_16x16x32_bf16 v[94:97], v[158:161], v[198:201], v[94:97]
	v_mfma_f32_16x16x32_bf16 v[86:89], v[150:153], v[206:209], v[86:89]
	v_mfma_f32_16x16x32_bf16 v[78:81], v[158:161], v[206:209], v[78:81]
	v_mfma_f32_16x16x32_bf16 v[126:129], v[154:157], v[186:189], v[126:129]
	v_mfma_f32_16x16x32_bf16 v[122:125], v[162:165], v[186:189], v[122:125]
	v_mfma_f32_16x16x32_bf16 v[118:121], v[154:157], v[194:197], v[118:121]
	v_mfma_f32_16x16x32_bf16 v[110:113], v[162:165], v[194:197], v[110:113]
	v_mfma_f32_16x16x32_bf16 v[102:105], v[154:157], v[202:205], v[102:105]
	v_mfma_f32_16x16x32_bf16 v[94:97], v[162:165], v[202:205], v[94:97]
	v_mfma_f32_16x16x32_bf16 v[86:89], v[154:157], v[210:213], v[86:89]
	v_mfma_f32_16x16x32_bf16 v[78:81], v[162:165], v[210:213], v[78:81]
	s_setprio 2
	s_setprio 0
	v_mfma_f32_16x16x32_bf16 v[114:117], v[166:169], v[182:185], v[114:117]
	v_mfma_f32_16x16x32_bf16 v[106:109], v[174:177], v[182:185], v[106:109]
	v_mfma_f32_16x16x32_bf16 v[98:101], v[166:169], v[190:193], v[98:101]
	v_mfma_f32_16x16x32_bf16 v[90:93], v[174:177], v[190:193], v[90:93]
	v_mfma_f32_16x16x32_bf16 v[82:85], v[166:169], v[198:201], v[82:85]
	v_mfma_f32_16x16x32_bf16 v[74:77], v[174:177], v[198:201], v[74:77]
	v_mfma_f32_16x16x32_bf16 v[70:73], v[166:169], v[206:209], v[70:73]
	v_mfma_f32_16x16x32_bf16 v[66:69], v[174:177], v[206:209], v[66:69]
	v_mfma_f32_16x16x32_bf16 v[114:117], v[170:173], v[186:189], v[114:117]
	v_mfma_f32_16x16x32_bf16 v[106:109], v[178:181], v[186:189], v[106:109]
	v_mfma_f32_16x16x32_bf16 v[98:101], v[170:173], v[194:197], v[98:101]
	v_mfma_f32_16x16x32_bf16 v[90:93], v[178:181], v[194:197], v[90:93]
	v_mfma_f32_16x16x32_bf16 v[82:85], v[170:173], v[202:205], v[82:85]
	v_mfma_f32_16x16x32_bf16 v[74:77], v[178:181], v[202:205], v[74:77]
	v_mfma_f32_16x16x32_bf16 v[70:73], v[170:173], v[210:213], v[70:73]
	v_mfma_f32_16x16x32_bf16 v[66:69], v[178:181], v[210:213], v[66:69]
	s_setprio 2
	s_barrier
	s_mov_b32 m0, s85
	v_lshl_add_u64 v[142:143], s[54:55], 0, v[134:135]
	s_add_u32 s46, s54, 0x20000
	ds_read_b128 v[182:185], v148 offset:16384
	ds_read_b128 v[186:189], v148 offset:17408
	ds_read_b128 v[190:193], v148 offset:18432
	ds_read_b128 v[194:197], v148 offset:19456
	ds_read_b128 v[198:201], v148 offset:20480
	ds_read_b128 v[202:205], v148 offset:21504
	ds_read_b128 v[206:209], v148 offset:22528
	ds_read_b128 v[210:213], v148 offset:23552
	global_load_lds_dwordx4 v[142:143], off
	v_lshl_add_u64 v[214:215], s[54:55], 0, v[130:131]
	s_mov_b32 m0, s86
	s_addc_u32 s47, s55, 0
	global_load_lds_dwordx4 v[214:215], off
	v_lshl_add_u64 v[216:217], s[46:47], 0, v[134:135]
	s_mov_b32 m0, s87
	v_lshl_add_u64 v[218:219], s[56:57], 0, v[132:133]
	global_load_lds_dwordx4 v[216:217], off
	v_lshl_add_u64 v[216:217], s[46:47], 0, v[130:131]
	s_mov_b32 m0, s88
	s_nop 0
	global_load_lds_dwordx4 v[216:217], off
	v_lshl_add_u64 v[216:217], s[56:57], 0, v[136:137]
	s_mov_b32 m0, s45
	s_nop 0
	global_load_lds_dwordx4 v[216:217], off
	s_mov_b32 m0, s61
	s_nop 0
	global_load_lds_dwordx4 v[218:219], off
	s_waitcnt vmcnt(8)
	s_waitcnt lgkmcnt(0)
	s_barrier
	s_setprio 0
	v_mfma_f32_16x16x32_bf16 v[62:65], v[150:153], v[182:185], v[62:65]
	v_mfma_f32_16x16x32_bf16 v[58:61], v[158:161], v[182:185], v[58:61]
	v_mfma_f32_16x16x32_bf16 v[54:57], v[150:153], v[190:193], v[54:57]
	v_mfma_f32_16x16x32_bf16 v[46:49], v[158:161], v[190:193], v[46:49]
	v_mfma_f32_16x16x32_bf16 v[38:41], v[150:153], v[198:201], v[38:41]
	v_mfma_f32_16x16x32_bf16 v[30:33], v[158:161], v[198:201], v[30:33]
	v_mfma_f32_16x16x32_bf16 v[22:25], v[150:153], v[206:209], v[22:25]
	v_mfma_f32_16x16x32_bf16 v[14:17], v[158:161], v[206:209], v[14:17]
	v_mfma_f32_16x16x32_bf16 v[62:65], v[154:157], v[186:189], v[62:65]
	v_mfma_f32_16x16x32_bf16 v[58:61], v[162:165], v[186:189], v[58:61]
	v_mfma_f32_16x16x32_bf16 v[54:57], v[154:157], v[194:197], v[54:57]
	v_mfma_f32_16x16x32_bf16 v[46:49], v[162:165], v[194:197], v[46:49]
	v_mfma_f32_16x16x32_bf16 v[38:41], v[154:157], v[202:205], v[38:41]
	v_mfma_f32_16x16x32_bf16 v[30:33], v[162:165], v[202:205], v[30:33]
	v_mfma_f32_16x16x32_bf16 v[22:25], v[154:157], v[210:213], v[22:25]
	v_mfma_f32_16x16x32_bf16 v[14:17], v[162:165], v[210:213], v[14:17]
	s_setprio 2
	s_setprio 0
	v_mfma_f32_16x16x32_bf16 v[50:53], v[166:169], v[182:185], v[50:53]
	v_mfma_f32_16x16x32_bf16 v[42:45], v[174:177], v[182:185], v[42:45]
	v_mfma_f32_16x16x32_bf16 v[34:37], v[166:169], v[190:193], v[34:37]
	v_mfma_f32_16x16x32_bf16 v[26:29], v[174:177], v[190:193], v[26:29]
	v_mfma_f32_16x16x32_bf16 v[18:21], v[166:169], v[198:201], v[18:21]
	v_mfma_f32_16x16x32_bf16 v[10:13], v[174:177], v[198:201], v[10:13]
	v_mfma_f32_16x16x32_bf16 v[6:9], v[166:169], v[206:209], v[6:9]
	v_mfma_f32_16x16x32_bf16 v[2:5], v[174:177], v[206:209], v[2:5]
	v_mfma_f32_16x16x32_bf16 v[50:53], v[170:173], v[186:189], v[50:53]
	v_mfma_f32_16x16x32_bf16 v[42:45], v[178:181], v[186:189], v[42:45]
	v_mfma_f32_16x16x32_bf16 v[34:37], v[170:173], v[194:197], v[34:37]
	v_mfma_f32_16x16x32_bf16 v[26:29], v[178:181], v[194:197], v[26:29]
	v_mfma_f32_16x16x32_bf16 v[18:21], v[170:173], v[202:205], v[18:21]
	v_mfma_f32_16x16x32_bf16 v[10:13], v[178:181], v[202:205], v[10:13]
	v_mfma_f32_16x16x32_bf16 v[6:9], v[170:173], v[210:213], v[6:9]
	v_mfma_f32_16x16x32_bf16 v[2:5], v[178:181], v[210:213], v[2:5]
	s_setprio 2
	s_barrier
; #define PG8_STAGE(bufoff, gbase, voff) do { _Pragma("unroll") for (int _i = 0; _i < 2; ++_i) \
;         __builtin_amdgcn_global_load_lds((const unsigned*)((const char*)(gbase) + (voff)[_i]), (LAS unsigned*)(lds + (bufoff) + ldsw + _i * 8192), 16, 0, 0); } while (0)
; #define PG8_LDA(dst, b, h) do { _Pragma("unroll") for (int m = 0; m < 4; ++m) _Pragma("unroll") for (int k = 0; k < 2; ++k) dst[m][k] = *(const LAS bf16x8*)(lds + PG8_SA(b, h) + aoff + m * 2048 + k * 1024); } while (0)
; #define PG8_LDB(dst, b, h) do { _Pragma("unroll") for (int n = 0; n < 2; ++n) _Pragma("unroll") for (int k = 0; k < 2; ++k) dst[n][k] = *(const LAS bf16x8*)(lds + PG8_SB(b, h) + boff + n * 2048 + k * 1024); } while (0)
; #define PG8_MMA(ai, bj, At, Bt) do { __builtin_amdgcn_s_setprio(1); _Pragma("unroll") for (int m = 0; m < 4; ++m) _Pragma("unroll") for (int n = 0; n < 2; ++n) _Pragma("unroll") for (int k = 0; k < 2; ++k) \
;         acc[ai][bj][m][n] = __builtin_amdgcn_mfma_f32_16x16x32_bf16(Bt[n][k], At[m][k], acc[ai][bj][m][n], 0, 0, 0); __builtin_amdgcn_s_setprio(0); } while (0)
; #define PG8_WAIT_V(n) asm volatile("s_waitcnt vmcnt(" #n ")" ::: "memory")
; #define PG8_WAIT_L(n) asm volatile("s_waitcnt lgkmcnt(" #n ")" ::: "memory")
; #define PG8_BAR __builtin_amdgcn_s_barrier()
; #define PG8_SCHED __builtin_amdgcn_sched_barrier(0)
; template <class Epi>
; __device__ __forceinline__ void gemm_phase(LAS unsigned char* lds, const Gemm g, int G, int c, const Epi& E) {
;     ...
;             PG8_LDB(B0, 1, 0); PG8_LDB(B1, 1, 1); PG8_SCHED; PG8_LDA(At, 1, 0); PG8_STAGE(PG8_SA(0, 1), a2 + hstepA, voffA);
;             PG8_WAIT_V(8); PG8_WAIT_L(0); PG8_BAR; PG8_MMA(0, 0, At, B0); PG8_MMA(0, 1, At, B1); PG8_BAR; PG8_SCHED;
	s_add_i32 s33, 0, 0x18000
	v_add_u32_e32 v149, s33, v145
	s_add_i32 s62, 0, 0x1c000
	ds_read_b128 v[150:153], v149
	ds_read_b128 v[154:157], v149 offset:1024
	ds_read_b128 v[158:161], v149 offset:2048
	ds_read_b128 v[162:165], v149 offset:3072
	v_add_u32_e32 v149, s62, v145
	ds_read_b128 v[166:169], v149
	ds_read_b128 v[170:173], v149 offset:1024
	ds_read_b128 v[174:177], v149 offset:2048
	ds_read_b128 v[178:181], v149 offset:3072
	s_add_u32 s46, s56, 0x20000
	s_addc_u32 s47, s57, 0
	s_mov_b32 m0, s66
	v_lshl_add_u64 v[220:221], s[46:47], 0, v[136:137]
	ds_read_b128 v[182:185], v148 offset:32768
	ds_read_b128 v[186:189], v148 offset:33792
	ds_read_b128 v[190:193], v148 offset:34816
	ds_read_b128 v[194:197], v148 offset:35840
	ds_read_b128 v[198:201], v148 offset:36864
	ds_read_b128 v[202:205], v148 offset:37888
	ds_read_b128 v[206:209], v148 offset:38912
	ds_read_b128 v[210:213], v148 offset:39936
	global_load_lds_dwordx4 v[220:221], off
	v_lshl_add_u64 v[220:221], s[46:47], 0, v[132:133]
	s_mov_b32 m0, s67
	s_nop 0
	global_load_lds_dwordx4 v[220:221], off
	s_waitcnt vmcnt(8)
	s_waitcnt lgkmcnt(0)
	s_barrier
	s_setprio 0
	v_mfma_f32_16x16x32_bf16 v[126:129], v[150:153], v[182:185], v[126:129]
	v_mfma_f32_16x16x32_bf16 v[122:125], v[158:161], v[182:185], v[122:125]
	v_mfma_f32_16x16x32_bf16 v[118:121], v[150:153], v[190:193], v[118:121]
	v_mfma_f32_16x16x32_bf16 v[110:113], v[158:161], v[190:193], v[110:113]
	v_mfma_f32_16x16x32_bf16 v[102:105], v[150:153], v[198:201], v[102:105]
	v_mfma_f32_16x16x32_bf16 v[94:97], v[158:161], v[198:201], v[94:97]
	v_mfma_f32_16x16x32_bf16 v[86:89], v[150:153], v[206:209], v[86:89]
	v_mfma_f32_16x16x32_bf16 v[78:81], v[158:161], v[206:209], v[78:81]
	v_mfma_f32_16x16x32_bf16 v[126:129], v[154:157], v[186:189], v[126:129]
	v_mfma_f32_16x16x32_bf16 v[122:125], v[162:165], v[186:189], v[122:125]
	v_mfma_f32_16x16x32_bf16 v[118:121], v[154:157], v[194:197], v[118:121]
	v_mfma_f32_16x16x32_bf16 v[110:113], v[162:165], v[194:197], v[110:113]
	v_mfma_f32_16x16x32_bf16 v[102:105], v[154:157], v[202:205], v[102:105]
	v_mfma_f32_16x16x32_bf16 v[94:97], v[162:165], v[202:205], v[94:97]
	v_mfma_f32_16x16x32_bf16 v[86:89], v[154:157], v[210:213], v[86:89]
	v_mfma_f32_16x16x32_bf16 v[78:81], v[162:165], v[210:213], v[78:81]
	s_setprio 2
	s_setprio 0
	v_mfma_f32_16x16x32_bf16 v[114:117], v[166:169], v[182:185], v[114:117]
	v_mfma_f32_16x16x32_bf16 v[106:109], v[174:177], v[182:185], v[106:109]
	v_mfma_f32_16x16x32_bf16 v[98:101], v[166:169], v[190:193], v[98:101]
	v_mfma_f32_16x16x32_bf16 v[90:93], v[174:177], v[190:193], v[90:93]
	v_mfma_f32_16x16x32_bf16 v[82:85], v[166:169], v[198:201], v[82:85]
	v_mfma_f32_16x16x32_bf16 v[74:77], v[174:177], v[198:201], v[74:77]
	v_mfma_f32_16x16x32_bf16 v[70:73], v[166:169], v[206:209], v[70:73]
	v_mfma_f32_16x16x32_bf16 v[66:69], v[174:177], v[206:209], v[66:69]
	v_mfma_f32_16x16x32_bf16 v[114:117], v[170:173], v[186:189], v[114:117]
	v_mfma_f32_16x16x32_bf16 v[106:109], v[178:181], v[186:189], v[106:109]
	v_mfma_f32_16x16x32_bf16 v[98:101], v[170:173], v[194:197], v[98:101]
	v_mfma_f32_16x16x32_bf16 v[90:93], v[178:181], v[194:197], v[90:93]
	v_mfma_f32_16x16x32_bf16 v[82:85], v[170:173], v[202:205], v[82:85]
	v_mfma_f32_16x16x32_bf16 v[74:77], v[178:181], v[202:205], v[74:77]
	v_mfma_f32_16x16x32_bf16 v[70:73], v[170:173], v[210:213], v[70:73]
	v_mfma_f32_16x16x32_bf16 v[66:69], v[178:181], v[210:213], v[66:69]
	s_setprio 2
	s_barrier
; #define PG8_STAGE(bufoff, gbase, voff) do { _Pragma("unroll") for (int _i = 0; _i < 2; ++_i) \
;         __builtin_amdgcn_global_load_lds((const unsigned*)((const char*)(gbase) + (voff)[_i]), (LAS unsigned*)(lds + (bufoff) + ldsw + _i * 8192), 16, 0, 0); } while (0)
; #define PG8_LDA(dst, b, h) do { _Pragma("unroll") for (int m = 0; m < 4; ++m) _Pragma("unroll") for (int k = 0; k < 2; ++k) dst[m][k] = *(const LAS bf16x8*)(lds + PG8_SA(b, h) + aoff + m * 2048 + k * 1024); } while (0)
; #define PG8_MMA(ai, bj, At, Bt) do { __builtin_amdgcn_s_setprio(1); _Pragma("unroll") for (int m = 0; m < 4; ++m) _Pragma("unroll") for (int n = 0; n < 2; ++n) _Pragma("unroll") for (int k = 0; k < 2; ++k) \
;         acc[ai][bj][m][n] = __builtin_amdgcn_mfma_f32_16x16x32_bf16(Bt[n][k], At[m][k], acc[ai][bj][m][n], 0, 0, 0); __builtin_amdgcn_s_setprio(0); } while (0)
; #define PG8_WAIT_V(n) asm volatile("s_waitcnt vmcnt(" #n ")" ::: "memory")
; #define PG8_WAIT_L(n) asm volatile("s_waitcnt lgkmcnt(" #n ")" ::: "memory")
; #define PG8_BAR __builtin_amdgcn_s_barrier()
; #define PG8_SCHED __builtin_amdgcn_sched_barrier(0)
; template <class Epi>
; __device__ __forceinline__ void gemm_phase(LAS unsigned char* lds, const Gemm g, int G, int c, const Epi& E) {
;     ...
;             PG8_LDA(At, 1, 1); PG8_STAGE(PG8_SB(1, 0), b3, voffB); PG8_STAGE(PG8_SB(1, 1), b3 + hstepB, voffB); PG8_STAGE(PG8_SA(1, 0), a3, voffA);
;             PG8_WAIT_V(8); PG8_WAIT_L(0); PG8_BAR; PG8_MMA(1, 0, At, B0); PG8_MMA(1, 1, At, B1); PG8_BAR; PG8_SCHED;
;         }
;         if (wr == 0) PG8_BAR;
	s_add_i32 s33, s33, s58
	v_lshl_add_u64 v[142:143], v[142:143], 0, s[6:7]
	s_mov_b32 m0, s33
	ds_read_b128 v[182:185], v148 offset:49152
	ds_read_b128 v[186:189], v148 offset:50176
	ds_read_b128 v[190:193], v148 offset:51200
	ds_read_b128 v[194:197], v148 offset:52224
	ds_read_b128 v[198:201], v148 offset:53248
	ds_read_b128 v[202:205], v148 offset:54272
	ds_read_b128 v[206:209], v148 offset:55296
	ds_read_b128 v[210:213], v148 offset:56320
	global_load_lds_dwordx4 v[142:143], off
	s_add_i32 m0, s33, 0x2000
	s_add_u32 s46, s54, 0x20080
	v_lshl_add_u64 v[142:143], v[214:215], 0, s[6:7]
	s_addc_u32 s47, s55, 0
	s_add_i32 s33, s62, s58
	global_load_lds_dwordx4 v[142:143], off
	v_lshl_add_u64 v[142:143], s[46:47], 0, v[134:135]
	s_mov_b32 m0, s33
	s_nop 0
	global_load_lds_dwordx4 v[142:143], off
	v_lshl_add_u64 v[142:143], s[46:47], 0, v[130:131]
	s_add_i32 m0, s33, 0x2000
	s_nop 0
	global_load_lds_dwordx4 v[142:143], off
	v_lshl_add_u64 v[142:143], v[216:217], 0, s[6:7]
	s_mov_b32 m0, s71
	s_nop 0
	global_load_lds_dwordx4 v[142:143], off
	v_lshl_add_u64 v[142:143], v[218:219], 0, s[6:7]
	s_mov_b32 m0, s72
	s_nop 0
	global_load_lds_dwordx4 v[142:143], off
	s_waitcnt vmcnt(8)
	s_waitcnt lgkmcnt(0)
	s_barrier
	s_setprio 0
	v_mfma_f32_16x16x32_bf16 v[62:65], v[150:153], v[182:185], v[62:65]
	v_mfma_f32_16x16x32_bf16 v[58:61], v[158:161], v[182:185], v[58:61]
	v_mfma_f32_16x16x32_bf16 v[54:57], v[150:153], v[190:193], v[54:57]
	v_mfma_f32_16x16x32_bf16 v[46:49], v[158:161], v[190:193], v[46:49]
	v_mfma_f32_16x16x32_bf16 v[38:41], v[150:153], v[198:201], v[38:41]
	v_mfma_f32_16x16x32_bf16 v[30:33], v[158:161], v[198:201], v[30:33]
	v_mfma_f32_16x16x32_bf16 v[22:25], v[150:153], v[206:209], v[22:25]
	v_mfma_f32_16x16x32_bf16 v[14:17], v[158:161], v[206:209], v[14:17]
	v_mfma_f32_16x16x32_bf16 v[62:65], v[154:157], v[186:189], v[62:65]
	v_mfma_f32_16x16x32_bf16 v[58:61], v[162:165], v[186:189], v[58:61]
	v_mfma_f32_16x16x32_bf16 v[54:57], v[154:157], v[194:197], v[54:57]
	v_mfma_f32_16x16x32_bf16 v[46:49], v[162:165], v[194:197], v[46:49]
	v_mfma_f32_16x16x32_bf16 v[38:41], v[154:157], v[202:205], v[38:41]
	v_mfma_f32_16x16x32_bf16 v[30:33], v[162:165], v[202:205], v[30:33]
	v_mfma_f32_16x16x32_bf16 v[22:25], v[154:157], v[210:213], v[22:25]
	v_mfma_f32_16x16x32_bf16 v[14:17], v[162:165], v[210:213], v[14:17]
	s_setprio 2
	s_setprio 0
	v_mfma_f32_16x16x32_bf16 v[50:53], v[166:169], v[182:185], v[50:53]
	v_mfma_f32_16x16x32_bf16 v[42:45], v[174:177], v[182:185], v[42:45]
	v_mfma_f32_16x16x32_bf16 v[34:37], v[166:169], v[190:193], v[34:37]
	v_mfma_f32_16x16x32_bf16 v[26:29], v[174:177], v[190:193], v[26:29]
	v_mfma_f32_16x16x32_bf16 v[18:21], v[166:169], v[198:201], v[18:21]
	v_mfma_f32_16x16x32_bf16 v[10:13], v[174:177], v[198:201], v[10:13]
	v_mfma_f32_16x16x32_bf16 v[6:9], v[166:169], v[206:209], v[6:9]
	v_mfma_f32_16x16x32_bf16 v[2:5], v[174:177], v[206:209], v[2:5]
	v_mfma_f32_16x16x32_bf16 v[50:53], v[170:173], v[186:189], v[50:53]
	v_mfma_f32_16x16x32_bf16 v[42:45], v[178:181], v[186:189], v[42:45]
	v_mfma_f32_16x16x32_bf16 v[34:37], v[170:173], v[194:197], v[34:37]
	v_mfma_f32_16x16x32_bf16 v[26:29], v[178:181], v[194:197], v[26:29]
	v_mfma_f32_16x16x32_bf16 v[18:21], v[170:173], v[202:205], v[18:21]
	v_mfma_f32_16x16x32_bf16 v[10:13], v[178:181], v[202:205], v[10:13]
	v_mfma_f32_16x16x32_bf16 v[6:9], v[170:173], v[210:213], v[6:9]
	v_mfma_f32_16x16x32_bf16 v[2:5], v[178:181], v[210:213], v[2:5]
	s_setprio 2
	s_add_i32 s92, s92, 2
	s_cmp_gt_u32 s92, 5
	s_mov_b64 s[46:47], s[52:53]
	s_barrier
	s_cbranch_scc0 .LBB0_781
	s_and_b64 vcc, exec, s[8:9]
	s_cbranch_vccz .LBB0_784
	s_barrier

; #define PG8_STAGE(bufoff, gbase, voff) do { _Pragma("unroll") for (int _i = 0; _i < 2; ++_i) \
;         __builtin_amdgcn_global_load_lds((const unsigned*)((const char*)(gbase) + (voff)[_i]), (LAS unsigned*)(lds + (bufoff) + ldsw + _i * 8192), 16, 0, 0); } while (0)
; #define PG8_LDA(dst, b, h) do { _Pragma("unroll") for (int m = 0; m < 4; ++m) _Pragma("unroll") for (int k = 0; k < 2; ++k) dst[m][k] = *(const LAS bf16x8*)(lds + PG8_SA(b, h) + aoff + m * 2048 + k * 1024); } while (0)
; #define PG8_LDB(dst, b, h) do { _Pragma("unroll") for (int n = 0; n < 2; ++n) _Pragma("unroll") for (int k = 0; k < 2; ++k) dst[n][k] = *(const LAS bf16x8*)(lds + PG8_SB(b, h) + boff + n * 2048 + k * 1024); } while (0)
; #define PG8_MMA(ai, bj, At, Bt) do { __builtin_amdgcn_s_setprio(1); _Pragma("unroll") for (int m = 0; m < 4; ++m) _Pragma("unroll") for (int n = 0; n < 2; ++n) _Pragma("unroll") for (int k = 0; k < 2; ++k) \
;         acc[ai][bj][m][n] = __builtin_amdgcn_mfma_f32_16x16x32_bf16(Bt[n][k], At[m][k], acc[ai][bj][m][n], 0, 0, 0); __builtin_amdgcn_s_setprio(0); } while (0)
; #define PG8_WAIT_V(n) asm volatile("s_waitcnt vmcnt(" #n ")" ::: "memory")
; template <class Epi>
; __device__ __forceinline__ void gemm_phase(LAS unsigned char* lds, const Gemm g, int G, int c, const Epi& E) {
;     ...
;         const bool has_next = S.next(ui + 1, nxt);
;         const char* nA = has_next ? (const char*)(g.A + (size_t)nxt.pb * g.sA) + (size_t)nxt.pm * 2 * hstepA : cA;
;         const char* nB = has_next ? (const char*)(g.Bt + (size_t)nxt.pb * g.sB) + (size_t)nxt.pn * 2 * hstepB : cB;
; #pragma nounroll
;         for (int t = 0; t < nt; t += 2) {
;             const bool last = (t == nt - 2);
;             const char* a1 = cA + (size_t)(t + 1) * kstep;
;             const char* a2 = last ? nA : cA + (size_t)(t + 2) * kstep; const char* b2 = last ? nB : cB + (size_t)(t + 2) * kstep;
;             const char* a3 = a2 + kstep; const char* b3 = b2 + kstep;
;             PG8_LDB(B0, 0, 0); PG8_LDB(B1, 0, 1); PG8_SCHED; PG8_LDA(At, 0, 0); PG8_STAGE(PG8_SA(1, 1), a1 + hstepA, voffA);
;             PG8_WAIT_V(8); PG8_WAIT_L(0); PG8_BAR; PG8_MMA(0, 0, At, B0); PG8_MMA(0, 1, At, B1); PG8_BAR; PG8_SCHED;
;             PG8_LDA(At, 0, 1); PG8_STAGE(PG8_SB(0, 0), b2, voffB); PG8_STAGE(PG8_SB(0, 1), b2 + hstepB, voffB); PG8_STAGE(PG8_SA(0, 0), a2, voffA);
.LBB0_902:
	s_ashr_i32 s15, s14, 31
	s_lshl_b64 s[20:21], s[14:15], 19
	s_add_u32 s20, s34, s20
	s_addc_u32 s21, s35, s21
	s_and_b64 s[4:5], s[4:5], exec
	s_cselect_b32 s15, s21, s43
	s_cselect_b32 s17, s20, s42
	s_add_u32 s4, s44, 0x40080
	s_addc_u32 s5, s45, 0
	s_add_u32 s23, s42, 0x100
	s_addc_u32 s39, s43, 0
	s_mov_b32 s46, -2
	s_waitcnt vmcnt(0)
	ds_read_b128 v[130:133], v170
	ds_read_b128 v[134:137], v170 offset:1024
	ds_read_b128 v[138:141], v170 offset:2048
	ds_read_b128 v[142:145], v170 offset:3072
	ds_read_b128 v[162:165], v171
	ds_read_b128 v[174:177], v171 offset:1024
	ds_read_b128 v[178:181], v171 offset:2048
	ds_read_b128 v[182:185], v171 offset:3072
	s_add_u32 s33, s4, 0xfffc0080
	s_addc_u32 s42, s5, -1
	s_cmp_eq_u32 s46, 12
	s_cselect_b32 s45, s19, s42
	s_cselect_b32 s44, s18, s33
	s_cselect_b32 s43, s15, s39
	s_cselect_b32 s42, s17, s23
	v_lshl_add_u64 v[166:167], s[4:5], 0, v[154:155]
	s_add_i32 m0, s25, 0xc000
	ds_read_b128 v[186:189], v172
	ds_read_b128 v[190:193], v172 offset:1024
	ds_read_b128 v[194:197], v172 offset:2048
	ds_read_b128 v[198:201], v172 offset:3072
	ds_read_b128 v[202:205], v172 offset:4096
	ds_read_b128 v[206:209], v172 offset:5120
	ds_read_b128 v[210:213], v172 offset:6144
	ds_read_b128 v[214:217], v172 offset:7168
	global_load_lds_dwordx4 v[166:167], off
	v_lshl_add_u64 v[166:167], s[4:5], 0, v[156:157]
	s_add_i32 m0, s25, 0xe000
	s_nop 0
	global_load_lds_dwordx4 v[166:167], off
	s_waitcnt vmcnt(8)
	s_waitcnt lgkmcnt(0)
	s_barrier
	s_setprio 0
	v_mfma_f32_16x16x32_bf16 v[126:129], v[130:133], v[186:189], 0
	v_mfma_f32_16x16x32_bf16 v[122:125], v[138:141], v[186:189], 0
	v_mfma_f32_16x16x32_bf16 v[110:113], v[130:133], v[194:197], 0
	v_mfma_f32_16x16x32_bf16 v[106:109], v[138:141], v[194:197], 0
	v_mfma_f32_16x16x32_bf16 v[94:97], v[130:133], v[202:205], 0
	v_mfma_f32_16x16x32_bf16 v[90:93], v[138:141], v[202:205], 0
	v_mfma_f32_16x16x32_bf16 v[78:81], v[130:133], v[210:213], 0
	v_mfma_f32_16x16x32_bf16 v[74:77], v[138:141], v[210:213], 0
	v_mfma_f32_16x16x32_bf16 v[126:129], v[134:137], v[190:193], v[126:129]
	v_mfma_f32_16x16x32_bf16 v[122:125], v[142:145], v[190:193], v[122:125]
	v_mfma_f32_16x16x32_bf16 v[110:113], v[134:137], v[198:201], v[110:113]
	v_mfma_f32_16x16x32_bf16 v[106:109], v[142:145], v[198:201], v[106:109]
	v_mfma_f32_16x16x32_bf16 v[94:97], v[134:137], v[206:209], v[94:97]
	v_mfma_f32_16x16x32_bf16 v[90:93], v[142:145], v[206:209], v[90:93]
	v_mfma_f32_16x16x32_bf16 v[78:81], v[134:137], v[214:217], v[78:81]
	v_mfma_f32_16x16x32_bf16 v[74:77], v[142:145], v[214:217], v[74:77]
	s_setprio 2
	s_setprio 0
	v_mfma_f32_16x16x32_bf16 v[118:121], v[162:165], v[186:189], 0
	v_mfma_f32_16x16x32_bf16 v[114:117], v[178:181], v[186:189], 0
	v_mfma_f32_16x16x32_bf16 v[102:105], v[162:165], v[194:197], 0
	v_mfma_f32_16x16x32_bf16 v[98:101], v[178:181], v[194:197], 0
	v_mfma_f32_16x16x32_bf16 v[86:89], v[162:165], v[202:205], 0
	v_mfma_f32_16x16x32_bf16 v[82:85], v[178:181], v[202:205], 0
	v_mfma_f32_16x16x32_bf16 v[70:73], v[162:165], v[210:213], 0
	v_mfma_f32_16x16x32_bf16 v[66:69], v[178:181], v[210:213], 0
	v_mfma_f32_16x16x32_bf16 v[118:121], v[174:177], v[190:193], v[118:121]
	v_mfma_f32_16x16x32_bf16 v[114:117], v[182:185], v[190:193], v[114:117]
	v_mfma_f32_16x16x32_bf16 v[102:105], v[174:177], v[198:201], v[102:105]
	v_mfma_f32_16x16x32_bf16 v[98:101], v[182:185], v[198:201], v[98:101]
	v_mfma_f32_16x16x32_bf16 v[86:89], v[174:177], v[206:209], v[86:89]
	v_mfma_f32_16x16x32_bf16 v[82:85], v[182:185], v[206:209], v[82:85]
	v_mfma_f32_16x16x32_bf16 v[70:73], v[174:177], v[214:217], v[70:73]
	v_mfma_f32_16x16x32_bf16 v[66:69], v[182:185], v[214:217], v[66:69]
	s_setprio 2
	s_barrier
	s_add_i32 s33, s72, s54
	v_lshl_add_u64 v[166:167], s[42:43], 0, v[150:151]
	s_mov_b32 m0, s33
	ds_read_b128 v[186:189], v172 offset:16384
	ds_read_b128 v[190:193], v172 offset:17408
	ds_read_b128 v[194:197], v172 offset:18432
	ds_read_b128 v[198:201], v172 offset:19456
	ds_read_b128 v[202:205], v172 offset:20480
	ds_read_b128 v[206:209], v172 offset:21504
	ds_read_b128 v[210:213], v172 offset:22528
	ds_read_b128 v[214:217], v172 offset:23552
	global_load_lds_dwordx4 v[166:167], off
	s_add_i32 m0, s33, 0x2000
	s_add_u32 s62, s42, 0x40000
	v_lshl_add_u64 v[218:219], s[42:43], 0, v[146:147]
	s_addc_u32 s63, s43, 0
	s_add_i32 s33, s73, s54
	global_load_lds_dwordx4 v[218:219], off
	v_lshl_add_u64 v[220:221], s[62:63], 0, v[150:151]
	s_mov_b32 m0, s33
	v_lshl_add_u64 v[222:223], s[44:45], 0, v[148:149]
	global_load_lds_dwordx4 v[220:221], off
	v_lshl_add_u64 v[220:221], s[62:63], 0, v[146:147]
	s_add_i32 m0, s33, 0x2000
	s_nop 0
	global_load_lds_dwordx4 v[220:221], off
	v_lshl_add_u64 v[220:221], s[44:45], 0, v[152:153]
	s_mov_b32 m0, s25
	s_nop 0
	global_load_lds_dwordx4 v[220:221], off
	s_mov_b32 m0, s57
	s_nop 0
	global_load_lds_dwordx4 v[222:223], off
	s_waitcnt vmcnt(8)
	s_waitcnt lgkmcnt(0)
	s_barrier
; #define PG8_STAGE(bufoff, gbase, voff) do { _Pragma("unroll") for (int _i = 0; _i < 2; ++_i) \
;         __builtin_amdgcn_global_load_lds((const unsigned*)((const char*)(gbase) + (voff)[_i]), (LAS unsigned*)(lds + (bufoff) + ldsw + _i * 8192), 16, 0, 0); } while (0)
; #define PG8_LDA(dst, b, h) do { _Pragma("unroll") for (int m = 0; m < 4; ++m) _Pragma("unroll") for (int k = 0; k < 2; ++k) dst[m][k] = *(const LAS bf16x8*)(lds + PG8_SA(b, h) + aoff + m * 2048 + k * 1024); } while (0)
; #define PG8_LDB(dst, b, h) do { _Pragma("unroll") for (int n = 0; n < 2; ++n) _Pragma("unroll") for (int k = 0; k < 2; ++k) dst[n][k] = *(const LAS bf16x8*)(lds + PG8_SB(b, h) + boff + n * 2048 + k * 1024); } while (0)
; #define PG8_MMA(ai, bj, At, Bt) do { __builtin_amdgcn_s_setprio(1); _Pragma("unroll") for (int m = 0; m < 4; ++m) _Pragma("unroll") for (int n = 0; n < 2; ++n) _Pragma("unroll") for (int k = 0; k < 2; ++k) \
;         acc[ai][bj][m][n] = __builtin_amdgcn_mfma_f32_16x16x32_bf16(Bt[n][k], At[m][k], acc[ai][bj][m][n], 0, 0, 0); __builtin_amdgcn_s_setprio(0); } while (0)
; #define PG8_WAIT_V(n) asm volatile("s_waitcnt vmcnt(" #n ")" ::: "memory")
; #define PG8_WAIT_L(n) asm volatile("s_waitcnt lgkmcnt(" #n ")" ::: "memory")
; #define PG8_BAR __builtin_amdgcn_s_barrier()
; #define PG8_SCHED __builtin_amdgcn_sched_barrier(0)
; template <class Epi>
; __device__ __forceinline__ void gemm_phase(LAS unsigned char* lds, const Gemm g, int G, int c, const Epi& E) {
;     ...
;             PG8_WAIT_V(8); PG8_WAIT_L(0); PG8_BAR; PG8_MMA(1, 0, At, B0); PG8_MMA(1, 1, At, B1); PG8_BAR; PG8_SCHED;
;             PG8_LDB(B0, 1, 0); PG8_LDB(B1, 1, 1); PG8_SCHED; PG8_LDA(At, 1, 0); PG8_STAGE(PG8_SA(0, 1), a2 + hstepA, voffA);
;             PG8_WAIT_V(8); PG8_WAIT_L(0); PG8_BAR; PG8_MMA(0, 0, At, B0); PG8_MMA(0, 1, At, B1); PG8_BAR; PG8_SCHED;
	s_setprio 0
	v_mfma_f32_16x16x32_bf16 v[62:65], v[130:133], v[186:189], 0
	v_mfma_f32_16x16x32_bf16 v[58:61], v[138:141], v[186:189], 0
	v_mfma_f32_16x16x32_bf16 v[46:49], v[130:133], v[194:197], 0
	v_mfma_f32_16x16x32_bf16 v[42:45], v[138:141], v[194:197], 0
	v_mfma_f32_16x16x32_bf16 v[30:33], v[130:133], v[202:205], 0
	v_mfma_f32_16x16x32_bf16 v[26:29], v[138:141], v[202:205], 0
	v_mfma_f32_16x16x32_bf16 v[14:17], v[130:133], v[210:213], 0
	v_mfma_f32_16x16x32_bf16 v[10:13], v[138:141], v[210:213], 0
	v_mfma_f32_16x16x32_bf16 v[62:65], v[134:137], v[190:193], v[62:65]
	v_mfma_f32_16x16x32_bf16 v[58:61], v[142:145], v[190:193], v[58:61]
	v_mfma_f32_16x16x32_bf16 v[46:49], v[134:137], v[198:201], v[46:49]
	v_mfma_f32_16x16x32_bf16 v[42:45], v[142:145], v[198:201], v[42:45]
	v_mfma_f32_16x16x32_bf16 v[30:33], v[134:137], v[206:209], v[30:33]
	v_mfma_f32_16x16x32_bf16 v[26:29], v[142:145], v[206:209], v[26:29]
	v_mfma_f32_16x16x32_bf16 v[14:17], v[134:137], v[214:217], v[14:17]
	v_mfma_f32_16x16x32_bf16 v[10:13], v[142:145], v[214:217], v[10:13]
	s_setprio 2
	s_setprio 0
	v_mfma_f32_16x16x32_bf16 v[54:57], v[162:165], v[186:189], 0
	v_mfma_f32_16x16x32_bf16 v[50:53], v[178:181], v[186:189], 0
	v_mfma_f32_16x16x32_bf16 v[38:41], v[162:165], v[194:197], 0
	v_mfma_f32_16x16x32_bf16 v[34:37], v[178:181], v[194:197], 0
	v_mfma_f32_16x16x32_bf16 v[22:25], v[162:165], v[202:205], 0
	v_mfma_f32_16x16x32_bf16 v[18:21], v[178:181], v[202:205], 0
	v_mfma_f32_16x16x32_bf16 v[6:9], v[162:165], v[210:213], 0
	v_mfma_f32_16x16x32_bf16 v[2:5], v[178:181], v[210:213], 0
	v_mfma_f32_16x16x32_bf16 v[54:57], v[174:177], v[190:193], v[54:57]
	v_mfma_f32_16x16x32_bf16 v[50:53], v[182:185], v[190:193], v[50:53]
	v_mfma_f32_16x16x32_bf16 v[38:41], v[174:177], v[198:201], v[38:41]
	v_mfma_f32_16x16x32_bf16 v[34:37], v[182:185], v[198:201], v[34:37]
	v_mfma_f32_16x16x32_bf16 v[22:25], v[174:177], v[206:209], v[22:25]
	v_mfma_f32_16x16x32_bf16 v[18:21], v[182:185], v[206:209], v[18:21]
	v_mfma_f32_16x16x32_bf16 v[6:9], v[174:177], v[214:217], v[6:9]
	v_mfma_f32_16x16x32_bf16 v[2:5], v[182:185], v[214:217], v[2:5]
	s_setprio 2
	s_barrier
	s_add_i32 s33, 0, 0x18000
	s_add_i32 s47, 0, 0x1c000
	v_add_u32_e32 v142, s33, v169
	v_add_u32_e32 v173, s47, v169
	ds_read_b128 v[130:133], v142
	ds_read_b128 v[134:137], v142 offset:1024
	ds_read_b128 v[138:141], v142 offset:2048
	ds_read_b128 v[142:145], v142 offset:3072
	ds_read_b128 v[162:165], v173
	ds_read_b128 v[174:177], v173 offset:1024
	ds_read_b128 v[178:181], v173 offset:2048
	ds_read_b128 v[182:185], v173 offset:3072
	s_add_u32 s44, s44, 0x40000
	s_addc_u32 s45, s45, 0
	s_mov_b32 m0, s58
	v_lshl_add_u64 v[224:225], s[44:45], 0, v[152:153]
	ds_read_b128 v[186:189], v172 offset:32768
	ds_read_b128 v[190:193], v172 offset:33792
	ds_read_b128 v[194:197], v172 offset:34816
	ds_read_b128 v[198:201], v172 offset:35840
	ds_read_b128 v[202:205], v172 offset:36864
	ds_read_b128 v[206:209], v172 offset:37888
	ds_read_b128 v[210:213], v172 offset:38912
	ds_read_b128 v[214:217], v172 offset:39936
	global_load_lds_dwordx4 v[224:225], off
	v_lshl_add_u64 v[224:225], s[44:45], 0, v[148:149]
	s_mov_b32 m0, s59
	s_nop 0
	global_load_lds_dwordx4 v[224:225], off
	s_waitcnt vmcnt(8)
	s_waitcnt lgkmcnt(0)
	s_barrier
	s_setprio 0
	v_mfma_f32_16x16x32_bf16 v[126:129], v[130:133], v[186:189], v[126:129]
	v_mfma_f32_16x16x32_bf16 v[122:125], v[138:141], v[186:189], v[122:125]
	v_mfma_f32_16x16x32_bf16 v[110:113], v[130:133], v[194:197], v[110:113]
	v_mfma_f32_16x16x32_bf16 v[106:109], v[138:141], v[194:197], v[106:109]
	v_mfma_f32_16x16x32_bf16 v[94:97], v[130:133], v[202:205], v[94:97]
	v_mfma_f32_16x16x32_bf16 v[90:93], v[138:141], v[202:205], v[90:93]
	v_mfma_f32_16x16x32_bf16 v[78:81], v[130:133], v[210:213], v[78:81]
	v_mfma_f32_16x16x32_bf16 v[74:77], v[138:141], v[210:213], v[74:77]
	v_mfma_f32_16x16x32_bf16 v[126:129], v[134:137], v[190:193], v[126:129]
	v_mfma_f32_16x16x32_bf16 v[122:125], v[142:145], v[190:193], v[122:125]
	v_mfma_f32_16x16x32_bf16 v[110:113], v[134:137], v[198:201], v[110:113]
	v_mfma_f32_16x16x32_bf16 v[106:109], v[142:145], v[198:201], v[106:109]
	v_mfma_f32_16x16x32_bf16 v[94:97], v[134:137], v[206:209], v[94:97]
	v_mfma_f32_16x16x32_bf16 v[90:93], v[142:145], v[206:209], v[90:93]
	v_mfma_f32_16x16x32_bf16 v[78:81], v[134:137], v[214:217], v[78:81]
	v_mfma_f32_16x16x32_bf16 v[74:77], v[142:145], v[214:217], v[74:77]
	s_setprio 2
	s_setprio 0
	v_mfma_f32_16x16x32_bf16 v[118:121], v[162:165], v[186:189], v[118:121]
	v_mfma_f32_16x16x32_bf16 v[114:117], v[178:181], v[186:189], v[114:117]
	v_mfma_f32_16x16x32_bf16 v[102:105], v[162:165], v[194:197], v[102:105]
	v_mfma_f32_16x16x32_bf16 v[98:101], v[178:181], v[194:197], v[98:101]
	v_mfma_f32_16x16x32_bf16 v[86:89], v[162:165], v[202:205], v[86:89]
	v_mfma_f32_16x16x32_bf16 v[82:85], v[178:181], v[202:205], v[82:85]
	v_mfma_f32_16x16x32_bf16 v[70:73], v[162:165], v[210:213], v[70:73]
	v_mfma_f32_16x16x32_bf16 v[66:69], v[178:181], v[210:213], v[66:69]
	v_mfma_f32_16x16x32_bf16 v[118:121], v[174:177], v[190:193], v[118:121]
	v_mfma_f32_16x16x32_bf16 v[114:117], v[182:185], v[190:193], v[114:117]
	v_mfma_f32_16x16x32_bf16 v[102:105], v[174:177], v[198:201], v[102:105]
	v_mfma_f32_16x16x32_bf16 v[98:101], v[182:185], v[198:201], v[98:101]
	v_mfma_f32_16x16x32_bf16 v[86:89], v[174:177], v[206:209], v[86:89]
	v_mfma_f32_16x16x32_bf16 v[82:85], v[182:185], v[206:209], v[82:85]
	v_mfma_f32_16x16x32_bf16 v[70:73], v[174:177], v[214:217], v[70:73]
	v_mfma_f32_16x16x32_bf16 v[66:69], v[182:185], v[214:217], v[66:69]
	s_setprio 2
	s_barrier
; #define PG8_STAGE(bufoff, gbase, voff) do { _Pragma("unroll") for (int _i = 0; _i < 2; ++_i) \
;         __builtin_amdgcn_global_load_lds((const unsigned*)((const char*)(gbase) + (voff)[_i]), (LAS unsigned*)(lds + (bufoff) + ldsw + _i * 8192), 16, 0, 0); } while (0)
; #define PG8_LDA(dst, b, h) do { _Pragma("unroll") for (int m = 0; m < 4; ++m) _Pragma("unroll") for (int k = 0; k < 2; ++k) dst[m][k] = *(const LAS bf16x8*)(lds + PG8_SA(b, h) + aoff + m * 2048 + k * 1024); } while (0)
; #define PG8_LDB(dst, b, h) do { _Pragma("unroll") for (int n = 0; n < 2; ++n) _Pragma("unroll") for (int k = 0; k < 2; ++k) dst[n][k] = *(const LAS bf16x8*)(lds + PG8_SB(b, h) + boff + n * 2048 + k * 1024); } while (0)
; #define PG8_MMA(ai, bj, At, Bt) do { __builtin_amdgcn_s_setprio(1); _Pragma("unroll") for (int m = 0; m < 4; ++m) _Pragma("unroll") for (int n = 0; n < 2; ++n) _Pragma("unroll") for (int k = 0; k < 2; ++k) \
;         acc[ai][bj][m][n] = __builtin_amdgcn_mfma_f32_16x16x32_bf16(Bt[n][k], At[m][k], acc[ai][bj][m][n], 0, 0, 0); __builtin_amdgcn_s_setprio(0); } while (0)
; #define PG8_WAIT_V(n) asm volatile("s_waitcnt vmcnt(" #n ")" ::: "memory")
; #define PG8_WAIT_L(n) asm volatile("s_waitcnt lgkmcnt(" #n ")" ::: "memory")
; #define PG8_BAR __builtin_amdgcn_s_barrier()
; #define PG8_SCHED __builtin_amdgcn_sched_barrier(0)
; template <class Epi>
; __device__ __forceinline__ void gemm_phase(LAS unsigned char* lds, const Gemm g, int G, int c, const Epi& E) {
;     ...
;         for (int t = 0; t < nt; t += 2) {
;             const bool last = (t == nt - 2);
;             const char* a1 = cA + (size_t)(t + 1) * kstep;
;             const char* a2 = last ? nA : cA + (size_t)(t + 2) * kstep; const char* b2 = last ? nB : cB + (size_t)(t + 2) * kstep;
;             const char* a3 = a2 + kstep; const char* b3 = b2 + kstep;
;             PG8_LDB(B0, 0, 0); PG8_LDB(B1, 0, 1); PG8_SCHED; PG8_LDA(At, 0, 0); PG8_STAGE(PG8_SA(1, 1), a1 + hstepA, voffA);
;             PG8_WAIT_V(8); PG8_WAIT_L(0); PG8_BAR; PG8_MMA(0, 0, At, B0); PG8_MMA(0, 1, At, B1); PG8_BAR; PG8_SCHED;
;     ...
;             PG8_LDA(At, 1, 1); PG8_STAGE(PG8_SB(1, 0), b3, voffB); PG8_STAGE(PG8_SB(1, 1), b3 + hstepB, voffB); PG8_STAGE(PG8_SA(1, 0), a3, voffA);
;             PG8_WAIT_V(8); PG8_WAIT_L(0); PG8_BAR; PG8_MMA(1, 0, At, B0); PG8_MMA(1, 1, At, B1); PG8_BAR; PG8_SCHED;
	s_add_i32 s33, s33, s54
	v_lshl_add_u64 v[166:167], v[166:167], 0, s[10:11]
	s_mov_b32 m0, s33
	ds_read_b128 v[186:189], v172 offset:49152
	ds_read_b128 v[190:193], v172 offset:50176
	ds_read_b128 v[194:197], v172 offset:51200
	ds_read_b128 v[198:201], v172 offset:52224
	ds_read_b128 v[202:205], v172 offset:53248
	ds_read_b128 v[206:209], v172 offset:54272
	ds_read_b128 v[210:213], v172 offset:55296
	ds_read_b128 v[214:217], v172 offset:56320
	global_load_lds_dwordx4 v[166:167], off
	s_add_i32 m0, s33, 0x2000
	s_add_u32 s42, s42, 0x40080
	v_lshl_add_u64 v[166:167], v[218:219], 0, s[10:11]
	s_addc_u32 s43, s43, 0
	s_add_i32 s33, s47, s54
	global_load_lds_dwordx4 v[166:167], off
	v_lshl_add_u64 v[166:167], s[42:43], 0, v[150:151]
	s_mov_b32 m0, s33
	s_nop 0
	global_load_lds_dwordx4 v[166:167], off
	v_lshl_add_u64 v[166:167], s[42:43], 0, v[146:147]
	s_add_i32 m0, s33, 0x2000
	s_nop 0
	global_load_lds_dwordx4 v[166:167], off
	v_lshl_add_u64 v[166:167], v[220:221], 0, s[10:11]
	s_mov_b32 m0, s69
	s_nop 0
	global_load_lds_dwordx4 v[166:167], off
	v_lshl_add_u64 v[166:167], v[222:223], 0, s[10:11]
	s_mov_b32 m0, s70
	s_nop 0
	global_load_lds_dwordx4 v[166:167], off
	s_waitcnt vmcnt(8)
	s_waitcnt lgkmcnt(0)
	s_barrier
	s_setprio 0
	v_mfma_f32_16x16x32_bf16 v[62:65], v[130:133], v[186:189], v[62:65]
	v_mfma_f32_16x16x32_bf16 v[58:61], v[138:141], v[186:189], v[58:61]
	v_mfma_f32_16x16x32_bf16 v[46:49], v[130:133], v[194:197], v[46:49]
	v_mfma_f32_16x16x32_bf16 v[42:45], v[138:141], v[194:197], v[42:45]
	v_mfma_f32_16x16x32_bf16 v[30:33], v[130:133], v[202:205], v[30:33]
	v_mfma_f32_16x16x32_bf16 v[26:29], v[138:141], v[202:205], v[26:29]
	v_mfma_f32_16x16x32_bf16 v[14:17], v[130:133], v[210:213], v[14:17]
	v_mfma_f32_16x16x32_bf16 v[10:13], v[138:141], v[210:213], v[10:13]
	v_mfma_f32_16x16x32_bf16 v[62:65], v[134:137], v[190:193], v[62:65]
	v_mfma_f32_16x16x32_bf16 v[58:61], v[142:145], v[190:193], v[58:61]
	v_mfma_f32_16x16x32_bf16 v[46:49], v[134:137], v[198:201], v[46:49]
	v_mfma_f32_16x16x32_bf16 v[42:45], v[142:145], v[198:201], v[42:45]
	v_mfma_f32_16x16x32_bf16 v[30:33], v[134:137], v[206:209], v[30:33]
	v_mfma_f32_16x16x32_bf16 v[26:29], v[142:145], v[206:209], v[26:29]
	v_mfma_f32_16x16x32_bf16 v[14:17], v[134:137], v[214:217], v[14:17]
	v_mfma_f32_16x16x32_bf16 v[10:13], v[142:145], v[214:217], v[10:13]
	s_setprio 2
	s_setprio 0
	v_mfma_f32_16x16x32_bf16 v[54:57], v[162:165], v[186:189], v[54:57]
	v_mfma_f32_16x16x32_bf16 v[50:53], v[178:181], v[186:189], v[50:53]
	v_mfma_f32_16x16x32_bf16 v[38:41], v[162:165], v[194:197], v[38:41]
	v_mfma_f32_16x16x32_bf16 v[34:37], v[178:181], v[194:197], v[34:37]
	v_mfma_f32_16x16x32_bf16 v[22:25], v[162:165], v[202:205], v[22:25]
	v_mfma_f32_16x16x32_bf16 v[18:21], v[178:181], v[202:205], v[18:21]
	v_mfma_f32_16x16x32_bf16 v[6:9], v[162:165], v[210:213], v[6:9]
	v_mfma_f32_16x16x32_bf16 v[2:5], v[178:181], v[210:213], v[2:5]
	v_mfma_f32_16x16x32_bf16 v[54:57], v[174:177], v[190:193], v[54:57]
	v_mfma_f32_16x16x32_bf16 v[50:53], v[182:185], v[190:193], v[50:53]
	v_mfma_f32_16x16x32_bf16 v[38:41], v[174:177], v[198:201], v[38:41]
	v_mfma_f32_16x16x32_bf16 v[34:37], v[182:185], v[198:201], v[34:37]
	v_mfma_f32_16x16x32_bf16 v[22:25], v[174:177], v[206:209], v[22:25]
	v_mfma_f32_16x16x32_bf16 v[18:21], v[182:185], v[206:209], v[18:21]
	v_mfma_f32_16x16x32_bf16 v[6:9], v[174:177], v[214:217], v[6:9]
	v_mfma_f32_16x16x32_bf16 v[2:5], v[182:185], v[214:217], v[2:5]
	s_setprio 2
	s_add_i32 s46, s46, 2
	s_add_u32 s4, s4, 0x100
	s_addc_u32 s5, s5, 0
	s_add_u32 s23, s23, 0x100
	s_addc_u32 s39, s39, 0
	s_cmp_gt_u32 s46, 13
	s_barrier
	s_cbranch_scc0 .LBB0_903
.LBB0_903:
	ds_read_b128 v[130:133], v170
	ds_read_b128 v[134:137], v170 offset:1024
	ds_read_b128 v[138:141], v170 offset:2048
	ds_read_b128 v[142:145], v170 offset:3072
	ds_read_b128 v[162:165], v171
	ds_read_b128 v[174:177], v171 offset:1024
	ds_read_b128 v[178:181], v171 offset:2048
	ds_read_b128 v[182:185], v171 offset:3072
	s_add_u32 s33, s4, 0xfffc0080
	s_addc_u32 s42, s5, -1
	s_cmp_eq_u32 s46, 12
	s_cselect_b32 s45, s19, s42
	s_cselect_b32 s44, s18, s33
	s_cselect_b32 s43, s15, s39
	s_cselect_b32 s42, s17, s23
	v_lshl_add_u64 v[166:167], s[4:5], 0, v[154:155]
	s_add_i32 m0, s25, 0xc000
	ds_read_b128 v[186:189], v172
	ds_read_b128 v[190:193], v172 offset:1024
	ds_read_b128 v[194:197], v172 offset:2048
	ds_read_b128 v[198:201], v172 offset:3072
	ds_read_b128 v[202:205], v172 offset:4096
	ds_read_b128 v[206:209], v172 offset:5120
	ds_read_b128 v[210:213], v172 offset:6144
	ds_read_b128 v[214:217], v172 offset:7168
	global_load_lds_dwordx4 v[166:167], off
	v_lshl_add_u64 v[166:167], s[4:5], 0, v[156:157]
	s_add_i32 m0, s25, 0xe000
	s_nop 0
	global_load_lds_dwordx4 v[166:167], off
	s_waitcnt vmcnt(8)
	s_waitcnt lgkmcnt(0)
	s_barrier
; #define PG8_STAGE(bufoff, gbase, voff) do { _Pragma("unroll") for (int _i = 0; _i < 2; ++_i) \
;         __builtin_amdgcn_global_load_lds((const unsigned*)((const char*)(gbase) + (voff)[_i]), (LAS unsigned*)(lds + (bufoff) + ldsw + _i * 8192), 16, 0, 0); } while (0)
; #define PG8_LDA(dst, b, h) do { _Pragma("unroll") for (int m = 0; m < 4; ++m) _Pragma("unroll") for (int k = 0; k < 2; ++k) dst[m][k] = *(const LAS bf16x8*)(lds + PG8_SA(b, h) + aoff + m * 2048 + k * 1024); } while (0)
; #define PG8_MMA(ai, bj, At, Bt) do { __builtin_amdgcn_s_setprio(1); _Pragma("unroll") for (int m = 0; m < 4; ++m) _Pragma("unroll") for (int n = 0; n < 2; ++n) _Pragma("unroll") for (int k = 0; k < 2; ++k) \
;         acc[ai][bj][m][n] = __builtin_amdgcn_mfma_f32_16x16x32_bf16(Bt[n][k], At[m][k], acc[ai][bj][m][n], 0, 0, 0); __builtin_amdgcn_s_setprio(0); } while (0)
; #define PG8_WAIT_V(n) asm volatile("s_waitcnt vmcnt(" #n ")" ::: "memory")
; #define PG8_WAIT_L(n) asm volatile("s_waitcnt lgkmcnt(" #n ")" ::: "memory")
; #define PG8_BAR __builtin_amdgcn_s_barrier()
; #define PG8_SCHED __builtin_amdgcn_sched_barrier(0)
; template <class Epi>
; __device__ __forceinline__ void gemm_phase(LAS unsigned char* lds, const Gemm g, int G, int c, const Epi& E) {
;     ...
;             PG8_WAIT_V(8); PG8_WAIT_L(0); PG8_BAR; PG8_MMA(0, 0, At, B0); PG8_MMA(0, 1, At, B1); PG8_BAR; PG8_SCHED;
;             PG8_LDA(At, 0, 1); PG8_STAGE(PG8_SB(0, 0), b2, voffB); PG8_STAGE(PG8_SB(0, 1), b2 + hstepB, voffB); PG8_STAGE(PG8_SA(0, 0), a2, voffA);
;             PG8_WAIT_V(8); PG8_WAIT_L(0); PG8_BAR; PG8_MMA(1, 0, At, B0); PG8_MMA(1, 1, At, B1); PG8_BAR; PG8_SCHED;
	s_setprio 0
	v_mfma_f32_16x16x32_bf16 v[126:129], v[130:133], v[186:189], v[126:129]
	v_mfma_f32_16x16x32_bf16 v[122:125], v[138:141], v[186:189], v[122:125]
	v_mfma_f32_16x16x32_bf16 v[110:113], v[130:133], v[194:197], v[110:113]
	v_mfma_f32_16x16x32_bf16 v[106:109], v[138:141], v[194:197], v[106:109]
	v_mfma_f32_16x16x32_bf16 v[94:97], v[130:133], v[202:205], v[94:97]
	v_mfma_f32_16x16x32_bf16 v[90:93], v[138:141], v[202:205], v[90:93]
	v_mfma_f32_16x16x32_bf16 v[78:81], v[130:133], v[210:213], v[78:81]
	v_mfma_f32_16x16x32_bf16 v[74:77], v[138:141], v[210:213], v[74:77]
	v_mfma_f32_16x16x32_bf16 v[126:129], v[134:137], v[190:193], v[126:129]
	v_mfma_f32_16x16x32_bf16 v[122:125], v[142:145], v[190:193], v[122:125]
	v_mfma_f32_16x16x32_bf16 v[110:113], v[134:137], v[198:201], v[110:113]
	v_mfma_f32_16x16x32_bf16 v[106:109], v[142:145], v[198:201], v[106:109]
	v_mfma_f32_16x16x32_bf16 v[94:97], v[134:137], v[206:209], v[94:97]
	v_mfma_f32_16x16x32_bf16 v[90:93], v[142:145], v[206:209], v[90:93]
	v_mfma_f32_16x16x32_bf16 v[78:81], v[134:137], v[214:217], v[78:81]
	v_mfma_f32_16x16x32_bf16 v[74:77], v[142:145], v[214:217], v[74:77]
	s_setprio 2
	s_setprio 0
	v_mfma_f32_16x16x32_bf16 v[118:121], v[162:165], v[186:189], v[118:121]
	v_mfma_f32_16x16x32_bf16 v[114:117], v[178:181], v[186:189], v[114:117]
	v_mfma_f32_16x16x32_bf16 v[102:105], v[162:165], v[194:197], v[102:105]
	v_mfma_f32_16x16x32_bf16 v[98:101], v[178:181], v[194:197], v[98:101]
	v_mfma_f32_16x16x32_bf16 v[86:89], v[162:165], v[202:205], v[86:89]
	v_mfma_f32_16x16x32_bf16 v[82:85], v[178:181], v[202:205], v[82:85]
	v_mfma_f32_16x16x32_bf16 v[70:73], v[162:165], v[210:213], v[70:73]
	v_mfma_f32_16x16x32_bf16 v[66:69], v[178:181], v[210:213], v[66:69]
	v_mfma_f32_16x16x32_bf16 v[118:121], v[174:177], v[190:193], v[118:121]
	v_mfma_f32_16x16x32_bf16 v[114:117], v[182:185], v[190:193], v[114:117]
	v_mfma_f32_16x16x32_bf16 v[102:105], v[174:177], v[198:201], v[102:105]
	v_mfma_f32_16x16x32_bf16 v[98:101], v[182:185], v[198:201], v[98:101]
	v_mfma_f32_16x16x32_bf16 v[86:89], v[174:177], v[206:209], v[86:89]
	v_mfma_f32_16x16x32_bf16 v[82:85], v[182:185], v[206:209], v[82:85]
	v_mfma_f32_16x16x32_bf16 v[70:73], v[174:177], v[214:217], v[70:73]
	v_mfma_f32_16x16x32_bf16 v[66:69], v[182:185], v[214:217], v[66:69]
	s_setprio 2
	s_barrier
	s_add_i32 s33, s72, s54
	v_lshl_add_u64 v[166:167], s[42:43], 0, v[150:151]
	s_mov_b32 m0, s33
	ds_read_b128 v[186:189], v172 offset:16384
	ds_read_b128 v[190:193], v172 offset:17408
	ds_read_b128 v[194:197], v172 offset:18432
	ds_read_b128 v[198:201], v172 offset:19456
	ds_read_b128 v[202:205], v172 offset:20480
	ds_read_b128 v[206:209], v172 offset:21504
	ds_read_b128 v[210:213], v172 offset:22528
	ds_read_b128 v[214:217], v172 offset:23552
	global_load_lds_dwordx4 v[166:167], off
	s_add_i32 m0, s33, 0x2000
	s_add_u32 s62, s42, 0x40000
	v_lshl_add_u64 v[218:219], s[42:43], 0, v[146:147]
	s_addc_u32 s63, s43, 0
	s_add_i32 s33, s73, s54
	global_load_lds_dwordx4 v[218:219], off
	v_lshl_add_u64 v[220:221], s[62:63], 0, v[150:151]
	s_mov_b32 m0, s33
	v_lshl_add_u64 v[222:223], s[44:45], 0, v[148:149]
	global_load_lds_dwordx4 v[220:221], off
	v_lshl_add_u64 v[220:221], s[62:63], 0, v[146:147]
	s_add_i32 m0, s33, 0x2000
	s_nop 0
	global_load_lds_dwordx4 v[220:221], off
	v_lshl_add_u64 v[220:221], s[44:45], 0, v[152:153]
	s_mov_b32 m0, s25
	s_nop 0
	global_load_lds_dwordx4 v[220:221], off
	s_mov_b32 m0, s57
	s_nop 0
	global_load_lds_dwordx4 v[222:223], off
	s_waitcnt vmcnt(8)
	s_waitcnt lgkmcnt(0)
	s_barrier
	s_setprio 0
	v_mfma_f32_16x16x32_bf16 v[62:65], v[130:133], v[186:189], v[62:65]
	v_mfma_f32_16x16x32_bf16 v[58:61], v[138:141], v[186:189], v[58:61]
	v_mfma_f32_16x16x32_bf16 v[46:49], v[130:133], v[194:197], v[46:49]
	v_mfma_f32_16x16x32_bf16 v[42:45], v[138:141], v[194:197], v[42:45]
	v_mfma_f32_16x16x32_bf16 v[30:33], v[130:133], v[202:205], v[30:33]
	v_mfma_f32_16x16x32_bf16 v[26:29], v[138:141], v[202:205], v[26:29]
	v_mfma_f32_16x16x32_bf16 v[14:17], v[130:133], v[210:213], v[14:17]
	v_mfma_f32_16x16x32_bf16 v[10:13], v[138:141], v[210:213], v[10:13]
	v_mfma_f32_16x16x32_bf16 v[62:65], v[134:137], v[190:193], v[62:65]
	v_mfma_f32_16x16x32_bf16 v[58:61], v[142:145], v[190:193], v[58:61]
	v_mfma_f32_16x16x32_bf16 v[46:49], v[134:137], v[198:201], v[46:49]
	v_mfma_f32_16x16x32_bf16 v[42:45], v[142:145], v[198:201], v[42:45]
	v_mfma_f32_16x16x32_bf16 v[30:33], v[134:137], v[206:209], v[30:33]
	v_mfma_f32_16x16x32_bf16 v[26:29], v[142:145], v[206:209], v[26:29]
	v_mfma_f32_16x16x32_bf16 v[14:17], v[134:137], v[214:217], v[14:17]
	v_mfma_f32_16x16x32_bf16 v[10:13], v[142:145], v[214:217], v[10:13]
	s_setprio 2
	s_setprio 0
	v_mfma_f32_16x16x32_bf16 v[54:57], v[162:165], v[186:189], v[54:57]
	v_mfma_f32_16x16x32_bf16 v[50:53], v[178:181], v[186:189], v[50:53]
	v_mfma_f32_16x16x32_bf16 v[38:41], v[162:165], v[194:197], v[38:41]
	v_mfma_f32_16x16x32_bf16 v[34:37], v[178:181], v[194:197], v[34:37]
	v_mfma_f32_16x16x32_bf16 v[22:25], v[162:165], v[202:205], v[22:25]
	v_mfma_f32_16x16x32_bf16 v[18:21], v[178:181], v[202:205], v[18:21]
	v_mfma_f32_16x16x32_bf16 v[6:9], v[162:165], v[210:213], v[6:9]
	v_mfma_f32_16x16x32_bf16 v[2:5], v[178:181], v[210:213], v[2:5]
	v_mfma_f32_16x16x32_bf16 v[54:57], v[174:177], v[190:193], v[54:57]
	v_mfma_f32_16x16x32_bf16 v[50:53], v[182:185], v[190:193], v[50:53]
	v_mfma_f32_16x16x32_bf16 v[38:41], v[174:177], v[198:201], v[38:41]
	v_mfma_f32_16x16x32_bf16 v[34:37], v[182:185], v[198:201], v[34:37]
	v_mfma_f32_16x16x32_bf16 v[22:25], v[174:177], v[206:209], v[22:25]
	v_mfma_f32_16x16x32_bf16 v[18:21], v[182:185], v[206:209], v[18:21]
	v_mfma_f32_16x16x32_bf16 v[6:9], v[174:177], v[214:217], v[6:9]
	v_mfma_f32_16x16x32_bf16 v[2:5], v[182:185], v[214:217], v[2:5]
	s_setprio 2
	s_barrier
; #define PG8_STAGE(bufoff, gbase, voff) do { _Pragma("unroll") for (int _i = 0; _i < 2; ++_i) \
;         __builtin_amdgcn_global_load_lds((const unsigned*)((const char*)(gbase) + (voff)[_i]), (LAS unsigned*)(lds + (bufoff) + ldsw + _i * 8192), 16, 0, 0); } while (0)
; #define PG8_LDA(dst, b, h) do { _Pragma("unroll") for (int m = 0; m < 4; ++m) _Pragma("unroll") for (int k = 0; k < 2; ++k) dst[m][k] = *(const LAS bf16x8*)(lds + PG8_SA(b, h) + aoff + m * 2048 + k * 1024); } while (0)
; #define PG8_LDB(dst, b, h) do { _Pragma("unroll") for (int n = 0; n < 2; ++n) _Pragma("unroll") for (int k = 0; k < 2; ++k) dst[n][k] = *(const LAS bf16x8*)(lds + PG8_SB(b, h) + boff + n * 2048 + k * 1024); } while (0)
; #define PG8_MMA(ai, bj, At, Bt) do { __builtin_amdgcn_s_setprio(1); _Pragma("unroll") for (int m = 0; m < 4; ++m) _Pragma("unroll") for (int n = 0; n < 2; ++n) _Pragma("unroll") for (int k = 0; k < 2; ++k) \
;         acc[ai][bj][m][n] = __builtin_amdgcn_mfma_f32_16x16x32_bf16(Bt[n][k], At[m][k], acc[ai][bj][m][n], 0, 0, 0); __builtin_amdgcn_s_setprio(0); } while (0)
; #define PG8_WAIT_V(n) asm volatile("s_waitcnt vmcnt(" #n ")" ::: "memory")
; #define PG8_WAIT_L(n) asm volatile("s_waitcnt lgkmcnt(" #n ")" ::: "memory")
; #define PG8_BAR __builtin_amdgcn_s_barrier()
; #define PG8_SCHED __builtin_amdgcn_sched_barrier(0)
; template <class Epi>
; __device__ __forceinline__ void gemm_phase(LAS unsigned char* lds, const Gemm g, int G, int c, const Epi& E) {
;     ...
;             PG8_LDB(B0, 1, 0); PG8_LDB(B1, 1, 1); PG8_SCHED; PG8_LDA(At, 1, 0); PG8_STAGE(PG8_SA(0, 1), a2 + hstepA, voffA);
;             PG8_WAIT_V(8); PG8_WAIT_L(0); PG8_BAR; PG8_MMA(0, 0, At, B0); PG8_MMA(0, 1, At, B1); PG8_BAR; PG8_SCHED;
	s_add_i32 s33, 0, 0x18000
	s_add_i32 s47, 0, 0x1c000
	v_add_u32_e32 v142, s33, v169
	v_add_u32_e32 v173, s47, v169
	ds_read_b128 v[130:133], v142
	ds_read_b128 v[134:137], v142 offset:1024
	ds_read_b128 v[138:141], v142 offset:2048
	ds_read_b128 v[142:145], v142 offset:3072
	ds_read_b128 v[162:165], v173
	ds_read_b128 v[174:177], v173 offset:1024
	ds_read_b128 v[178:181], v173 offset:2048
	ds_read_b128 v[182:185], v173 offset:3072
	s_add_u32 s44, s44, 0x40000
	s_addc_u32 s45, s45, 0
	s_mov_b32 m0, s58
	v_lshl_add_u64 v[224:225], s[44:45], 0, v[152:153]
	ds_read_b128 v[186:189], v172 offset:32768
	ds_read_b128 v[190:193], v172 offset:33792
	ds_read_b128 v[194:197], v172 offset:34816
	ds_read_b128 v[198:201], v172 offset:35840
	ds_read_b128 v[202:205], v172 offset:36864
	ds_read_b128 v[206:209], v172 offset:37888
	ds_read_b128 v[210:213], v172 offset:38912
	ds_read_b128 v[214:217], v172 offset:39936
	global_load_lds_dwordx4 v[224:225], off
	v_lshl_add_u64 v[224:225], s[44:45], 0, v[148:149]
	s_mov_b32 m0, s59
	s_nop 0
	global_load_lds_dwordx4 v[224:225], off
	s_waitcnt vmcnt(8)
	s_waitcnt lgkmcnt(0)
	s_barrier
	s_setprio 0
	v_mfma_f32_16x16x32_bf16 v[126:129], v[130:133], v[186:189], v[126:129]
	v_mfma_f32_16x16x32_bf16 v[122:125], v[138:141], v[186:189], v[122:125]
	v_mfma_f32_16x16x32_bf16 v[110:113], v[130:133], v[194:197], v[110:113]
	v_mfma_f32_16x16x32_bf16 v[106:109], v[138:141], v[194:197], v[106:109]
	v_mfma_f32_16x16x32_bf16 v[94:97], v[130:133], v[202:205], v[94:97]
	v_mfma_f32_16x16x32_bf16 v[90:93], v[138:141], v[202:205], v[90:93]
	v_mfma_f32_16x16x32_bf16 v[78:81], v[130:133], v[210:213], v[78:81]
	v_mfma_f32_16x16x32_bf16 v[74:77], v[138:141], v[210:213], v[74:77]
	v_mfma_f32_16x16x32_bf16 v[126:129], v[134:137], v[190:193], v[126:129]
	v_mfma_f32_16x16x32_bf16 v[122:125], v[142:145], v[190:193], v[122:125]
	v_mfma_f32_16x16x32_bf16 v[110:113], v[134:137], v[198:201], v[110:113]
	v_mfma_f32_16x16x32_bf16 v[106:109], v[142:145], v[198:201], v[106:109]
	v_mfma_f32_16x16x32_bf16 v[94:97], v[134:137], v[206:209], v[94:97]
	v_mfma_f32_16x16x32_bf16 v[90:93], v[142:145], v[206:209], v[90:93]
	v_mfma_f32_16x16x32_bf16 v[78:81], v[134:137], v[214:217], v[78:81]
	v_mfma_f32_16x16x32_bf16 v[74:77], v[142:145], v[214:217], v[74:77]
	s_setprio 2
	s_setprio 0
	v_mfma_f32_16x16x32_bf16 v[118:121], v[162:165], v[186:189], v[118:121]
	v_mfma_f32_16x16x32_bf16 v[114:117], v[178:181], v[186:189], v[114:117]
	v_mfma_f32_16x16x32_bf16 v[102:105], v[162:165], v[194:197], v[102:105]
	v_mfma_f32_16x16x32_bf16 v[98:101], v[178:181], v[194:197], v[98:101]
	v_mfma_f32_16x16x32_bf16 v[86:89], v[162:165], v[202:205], v[86:89]
	v_mfma_f32_16x16x32_bf16 v[82:85], v[178:181], v[202:205], v[82:85]
	v_mfma_f32_16x16x32_bf16 v[70:73], v[162:165], v[210:213], v[70:73]
	v_mfma_f32_16x16x32_bf16 v[66:69], v[178:181], v[210:213], v[66:69]
	v_mfma_f32_16x16x32_bf16 v[118:121], v[174:177], v[190:193], v[118:121]
	v_mfma_f32_16x16x32_bf16 v[114:117], v[182:185], v[190:193], v[114:117]
	v_mfma_f32_16x16x32_bf16 v[102:105], v[174:177], v[198:201], v[102:105]
	v_mfma_f32_16x16x32_bf16 v[98:101], v[182:185], v[198:201], v[98:101]
	v_mfma_f32_16x16x32_bf16 v[86:89], v[174:177], v[206:209], v[86:89]
	v_mfma_f32_16x16x32_bf16 v[82:85], v[182:185], v[206:209], v[82:85]
	v_mfma_f32_16x16x32_bf16 v[70:73], v[174:177], v[214:217], v[70:73]
	v_mfma_f32_16x16x32_bf16 v[66:69], v[182:185], v[214:217], v[66:69]
	s_setprio 2
	s_barrier
; #define PG8_STAGE(bufoff, gbase, voff) do { _Pragma("unroll") for (int _i = 0; _i < 2; ++_i) \
;         __builtin_amdgcn_global_load_lds((const unsigned*)((const char*)(gbase) + (voff)[_i]), (LAS unsigned*)(lds + (bufoff) + ldsw + _i * 8192), 16, 0, 0); } while (0)
; #define PG8_LDA(dst, b, h) do { _Pragma("unroll") for (int m = 0; m < 4; ++m) _Pragma("unroll") for (int k = 0; k < 2; ++k) dst[m][k] = *(const LAS bf16x8*)(lds + PG8_SA(b, h) + aoff + m * 2048 + k * 1024); } while (0)
; #define PG8_MMA(ai, bj, At, Bt) do { __builtin_amdgcn_s_setprio(1); _Pragma("unroll") for (int m = 0; m < 4; ++m) _Pragma("unroll") for (int n = 0; n < 2; ++n) _Pragma("unroll") for (int k = 0; k < 2; ++k) \
;         acc[ai][bj][m][n] = __builtin_amdgcn_mfma_f32_16x16x32_bf16(Bt[n][k], At[m][k], acc[ai][bj][m][n], 0, 0, 0); __builtin_amdgcn_s_setprio(0); } while (0)
; #define PG8_WAIT_V(n) asm volatile("s_waitcnt vmcnt(" #n ")" ::: "memory")
; #define PG8_WAIT_L(n) asm volatile("s_waitcnt lgkmcnt(" #n ")" ::: "memory")
; #define PG8_BAR __builtin_amdgcn_s_barrier()
; #define PG8_SCHED __builtin_amdgcn_sched_barrier(0)
; template <class Epi>
; __device__ __forceinline__ void gemm_phase(LAS unsigned char* lds, const Gemm g, int G, int c, const Epi& E) {
;     ...
;         for (int t = 0; t < nt; t += 2) {
;     ...
;             PG8_LDA(At, 1, 1); PG8_STAGE(PG8_SB(1, 0), b3, voffB); PG8_STAGE(PG8_SB(1, 1), b3 + hstepB, voffB); PG8_STAGE(PG8_SA(1, 0), a3, voffA);
;             PG8_WAIT_V(8); PG8_WAIT_L(0); PG8_BAR; PG8_MMA(1, 0, At, B0); PG8_MMA(1, 1, At, B1); PG8_BAR; PG8_SCHED;
;         }
;         if (wr == 0) PG8_BAR;
	s_add_i32 s33, s33, s54
	v_lshl_add_u64 v[166:167], v[166:167], 0, s[10:11]
	s_mov_b32 m0, s33
	ds_read_b128 v[186:189], v172 offset:49152
	ds_read_b128 v[190:193], v172 offset:50176
	ds_read_b128 v[194:197], v172 offset:51200
	ds_read_b128 v[198:201], v172 offset:52224
	ds_read_b128 v[202:205], v172 offset:53248
	ds_read_b128 v[206:209], v172 offset:54272
	ds_read_b128 v[210:213], v172 offset:55296
	ds_read_b128 v[214:217], v172 offset:56320
	global_load_lds_dwordx4 v[166:167], off
	s_add_i32 m0, s33, 0x2000
	s_add_u32 s42, s42, 0x40080
	v_lshl_add_u64 v[166:167], v[218:219], 0, s[10:11]
	s_addc_u32 s43, s43, 0
	s_add_i32 s33, s47, s54
	global_load_lds_dwordx4 v[166:167], off
	v_lshl_add_u64 v[166:167], s[42:43], 0, v[150:151]
	s_mov_b32 m0, s33
	s_nop 0
	global_load_lds_dwordx4 v[166:167], off
	v_lshl_add_u64 v[166:167], s[42:43], 0, v[146:147]
	s_add_i32 m0, s33, 0x2000
	s_nop 0
	global_load_lds_dwordx4 v[166:167], off
	v_lshl_add_u64 v[166:167], v[220:221], 0, s[10:11]
	s_mov_b32 m0, s69
	s_nop 0
	global_load_lds_dwordx4 v[166:167], off
	v_lshl_add_u64 v[166:167], v[222:223], 0, s[10:11]
	s_mov_b32 m0, s70
	s_nop 0
	global_load_lds_dwordx4 v[166:167], off
	s_waitcnt vmcnt(8)
	s_waitcnt lgkmcnt(0)
	s_barrier
	s_setprio 0
	v_mfma_f32_16x16x32_bf16 v[62:65], v[130:133], v[186:189], v[62:65]
	v_mfma_f32_16x16x32_bf16 v[58:61], v[138:141], v[186:189], v[58:61]
	v_mfma_f32_16x16x32_bf16 v[46:49], v[130:133], v[194:197], v[46:49]
	v_mfma_f32_16x16x32_bf16 v[42:45], v[138:141], v[194:197], v[42:45]
	v_mfma_f32_16x16x32_bf16 v[30:33], v[130:133], v[202:205], v[30:33]
	v_mfma_f32_16x16x32_bf16 v[26:29], v[138:141], v[202:205], v[26:29]
	v_mfma_f32_16x16x32_bf16 v[14:17], v[130:133], v[210:213], v[14:17]
	v_mfma_f32_16x16x32_bf16 v[10:13], v[138:141], v[210:213], v[10:13]
	v_mfma_f32_16x16x32_bf16 v[62:65], v[134:137], v[190:193], v[62:65]
	v_mfma_f32_16x16x32_bf16 v[58:61], v[142:145], v[190:193], v[58:61]
	v_mfma_f32_16x16x32_bf16 v[46:49], v[134:137], v[198:201], v[46:49]
	v_mfma_f32_16x16x32_bf16 v[42:45], v[142:145], v[198:201], v[42:45]
	v_mfma_f32_16x16x32_bf16 v[30:33], v[134:137], v[206:209], v[30:33]
	v_mfma_f32_16x16x32_bf16 v[26:29], v[142:145], v[206:209], v[26:29]
	v_mfma_f32_16x16x32_bf16 v[14:17], v[134:137], v[214:217], v[14:17]
	v_mfma_f32_16x16x32_bf16 v[10:13], v[142:145], v[214:217], v[10:13]
	s_setprio 2
	s_setprio 0
	v_mfma_f32_16x16x32_bf16 v[54:57], v[162:165], v[186:189], v[54:57]
	v_mfma_f32_16x16x32_bf16 v[50:53], v[178:181], v[186:189], v[50:53]
	v_mfma_f32_16x16x32_bf16 v[38:41], v[162:165], v[194:197], v[38:41]
	v_mfma_f32_16x16x32_bf16 v[34:37], v[178:181], v[194:197], v[34:37]
	v_mfma_f32_16x16x32_bf16 v[22:25], v[162:165], v[202:205], v[22:25]
	v_mfma_f32_16x16x32_bf16 v[18:21], v[178:181], v[202:205], v[18:21]
	v_mfma_f32_16x16x32_bf16 v[6:9], v[162:165], v[210:213], v[6:9]
	v_mfma_f32_16x16x32_bf16 v[2:5], v[178:181], v[210:213], v[2:5]
	v_mfma_f32_16x16x32_bf16 v[54:57], v[174:177], v[190:193], v[54:57]
	v_mfma_f32_16x16x32_bf16 v[50:53], v[182:185], v[190:193], v[50:53]
	v_mfma_f32_16x16x32_bf16 v[38:41], v[174:177], v[198:201], v[38:41]
	v_mfma_f32_16x16x32_bf16 v[34:37], v[182:185], v[198:201], v[34:37]
	v_mfma_f32_16x16x32_bf16 v[22:25], v[174:177], v[206:209], v[22:25]
	v_mfma_f32_16x16x32_bf16 v[18:21], v[182:185], v[206:209], v[18:21]
	v_mfma_f32_16x16x32_bf16 v[6:9], v[174:177], v[214:217], v[6:9]
	v_mfma_f32_16x16x32_bf16 v[2:5], v[182:185], v[214:217], v[2:5]
	s_setprio 2
	s_add_i32 s46, s46, 2
	s_add_u32 s4, s4, 0x100
	s_addc_u32 s5, s5, 0
	s_add_u32 s23, s23, 0x100
	s_addc_u32 s39, s39, 0
	s_cmp_gt_u32 s46, 13
	s_barrier
	s_cbranch_scc0 .LBB0_903
	s_and_b64 vcc, exec, s[12:13]
	s_cbranch_vccz .LBB0_906
	s_barrier

; #define PG8_STAGE(bufoff, gbase, voff) do { _Pragma("unroll") for (int _i = 0; _i < 2; ++_i) \
;         __builtin_amdgcn_global_load_lds((const unsigned*)((const char*)(gbase) + (voff)[_i]), (LAS unsigned*)(lds + (bufoff) + ldsw + _i * 8192), 16, 0, 0); } while (0)
; #define PG8_LDA(dst, b, h) do { _Pragma("unroll") for (int m = 0; m < 4; ++m) _Pragma("unroll") for (int k = 0; k < 2; ++k) dst[m][k] = *(const LAS bf16x8*)(lds + PG8_SA(b, h) + aoff + m * 2048 + k * 1024); } while (0)
; #define PG8_LDB(dst, b, h) do { _Pragma("unroll") for (int n = 0; n < 2; ++n) _Pragma("unroll") for (int k = 0; k < 2; ++k) dst[n][k] = *(const LAS bf16x8*)(lds + PG8_SB(b, h) + boff + n * 2048 + k * 1024); } while (0)
; #define PG8_MMA(ai, bj, At, Bt) do { __builtin_amdgcn_s_setprio(1); _Pragma("unroll") for (int m = 0; m < 4; ++m) _Pragma("unroll") for (int n = 0; n < 2; ++n) _Pragma("unroll") for (int k = 0; k < 2; ++k) \
;         acc[ai][bj][m][n] = __builtin_amdgcn_mfma_f32_16x16x32_bf16(Bt[n][k], At[m][k], acc[ai][bj][m][n], 0, 0, 0); __builtin_amdgcn_s_setprio(0); } while (0)
; template <class Epi>
; __device__ __forceinline__ void gemm_phase(LAS unsigned char* lds, const Gemm g, int G, int c, const Epi& E) {
;     ...
;         const bool has_next = S.next(ui + 1, nxt);
;         const char* nA = has_next ? (const char*)(g.A + (size_t)nxt.pb * g.sA) + (size_t)nxt.pm * 2 * hstepA : cA;
;         const char* nB = has_next ? (const char*)(g.Bt + (size_t)nxt.pb * g.sB) + (size_t)nxt.pn * 2 * hstepB : cB;
; #pragma nounroll
;         for (int t = 0; t < nt; t += 2) {
;             const bool last = (t == nt - 2);
;             const char* a1 = cA + (size_t)(t + 1) * kstep;
;             const char* a2 = last ? nA : cA + (size_t)(t + 2) * kstep; const char* b2 = last ? nB : cB + (size_t)(t + 2) * kstep;
;             const char* a3 = a2 + kstep; const char* b3 = b2 + kstep;
;             PG8_LDB(B0, 0, 0); PG8_LDB(B1, 0, 1); PG8_SCHED; PG8_LDA(At, 0, 0); PG8_STAGE(PG8_SA(1, 1), a1 + hstepA, voffA);
;             PG8_WAIT_V(8); PG8_WAIT_L(0); PG8_BAR; PG8_MMA(0, 0, At, B0); PG8_MMA(0, 1, At, B1); PG8_BAR; PG8_SCHED;
;             PG8_LDA(At, 0, 1); PG8_STAGE(PG8_SB(0, 0), b2, voffB); PG8_STAGE(PG8_SB(0, 1), b2 + hstepB, voffB); PG8_STAGE(PG8_SA(0, 0), a2, voffA);
;             PG8_WAIT_V(8); PG8_WAIT_L(0); PG8_BAR; PG8_MMA(1, 0, At, B0); PG8_MMA(1, 1, At, B1); PG8_BAR; PG8_SCHED;
.LBB0_1057:
	s_ashr_i32 s17, s16, 31
	s_lshl_b64 s[22:23], s[16:17], 19
	s_add_u32 s22, s35, s22
	s_addc_u32 s23, s42, s23
	s_and_b64 s[4:5], s[4:5], exec
	s_cselect_b32 s17, s23, s39
	s_cselect_b32 s19, s22, s38
	s_add_u32 s4, s40, 0x40080
	s_addc_u32 s5, s41, 0
	s_add_u32 s78, s38, 0x100
	s_addc_u32 s79, s39, 0
	s_mov_b32 s80, -2
	ds_read_b128 v[152:155], v148
	ds_read_b128 v[156:159], v148 offset:1024
	ds_read_b128 v[160:163], v148 offset:2048
	ds_read_b128 v[164:167], v148 offset:3072
	ds_read_b128 v[168:171], v149
	ds_read_b128 v[172:175], v149 offset:1024
	ds_read_b128 v[176:179], v149 offset:2048
	ds_read_b128 v[180:183], v149 offset:3072
	s_add_u32 s33, s4, 0xfffc0080
	s_addc_u32 s38, s5, -1
	s_cmp_eq_u32 s80, 12
	s_cselect_b32 s41, s21, s38
	s_cselect_b32 s40, s20, s33
	s_cselect_b32 s39, s17, s79
	s_cselect_b32 s38, s19, s78
	v_lshl_add_u64 v[216:217], s[4:5], 0, v[138:139]
	s_add_i32 m0, s25, 0xc000
	ds_read_b128 v[184:187], v150
	ds_read_b128 v[188:191], v150 offset:1024
	ds_read_b128 v[192:195], v150 offset:2048
	ds_read_b128 v[196:199], v150 offset:3072
	ds_read_b128 v[200:203], v150 offset:4096
	ds_read_b128 v[204:207], v150 offset:5120
	ds_read_b128 v[208:211], v150 offset:6144
	ds_read_b128 v[212:215], v150 offset:7168
	global_load_lds_dwordx4 v[216:217], off
	v_lshl_add_u64 v[216:217], s[4:5], 0, v[140:141]
	s_add_i32 m0, s25, 0xe000
	s_nop 0
	global_load_lds_dwordx4 v[216:217], off
	s_waitcnt vmcnt(8)
	s_waitcnt lgkmcnt(0)
	s_barrier
	s_setprio 0
	v_mfma_f32_16x16x32_bf16 v[126:129], v[152:155], v[184:187], 0
	v_mfma_f32_16x16x32_bf16 v[122:125], v[160:163], v[184:187], 0
	v_mfma_f32_16x16x32_bf16 v[110:113], v[152:155], v[192:195], 0
	v_mfma_f32_16x16x32_bf16 v[106:109], v[160:163], v[192:195], 0
	v_mfma_f32_16x16x32_bf16 v[94:97], v[152:155], v[200:203], 0
	v_mfma_f32_16x16x32_bf16 v[90:93], v[160:163], v[200:203], 0
	v_mfma_f32_16x16x32_bf16 v[78:81], v[152:155], v[208:211], 0
	v_mfma_f32_16x16x32_bf16 v[74:77], v[160:163], v[208:211], 0
	v_mfma_f32_16x16x32_bf16 v[126:129], v[156:159], v[188:191], v[126:129]
	v_mfma_f32_16x16x32_bf16 v[122:125], v[164:167], v[188:191], v[122:125]
	v_mfma_f32_16x16x32_bf16 v[110:113], v[156:159], v[196:199], v[110:113]
	v_mfma_f32_16x16x32_bf16 v[106:109], v[164:167], v[196:199], v[106:109]
	v_mfma_f32_16x16x32_bf16 v[94:97], v[156:159], v[204:207], v[94:97]
	v_mfma_f32_16x16x32_bf16 v[90:93], v[164:167], v[204:207], v[90:93]
	v_mfma_f32_16x16x32_bf16 v[78:81], v[156:159], v[212:215], v[78:81]
	v_mfma_f32_16x16x32_bf16 v[74:77], v[164:167], v[212:215], v[74:77]
	s_setprio 2
	s_setprio 0
	v_mfma_f32_16x16x32_bf16 v[118:121], v[168:171], v[184:187], 0
	v_mfma_f32_16x16x32_bf16 v[114:117], v[176:179], v[184:187], 0
	v_mfma_f32_16x16x32_bf16 v[102:105], v[168:171], v[192:195], 0
	v_mfma_f32_16x16x32_bf16 v[98:101], v[176:179], v[192:195], 0
	v_mfma_f32_16x16x32_bf16 v[86:89], v[168:171], v[200:203], 0
	v_mfma_f32_16x16x32_bf16 v[82:85], v[176:179], v[200:203], 0
	v_mfma_f32_16x16x32_bf16 v[70:73], v[168:171], v[208:211], 0
	v_mfma_f32_16x16x32_bf16 v[66:69], v[176:179], v[208:211], 0
	v_mfma_f32_16x16x32_bf16 v[118:121], v[172:175], v[188:191], v[118:121]
	v_mfma_f32_16x16x32_bf16 v[114:117], v[180:183], v[188:191], v[114:117]
	v_mfma_f32_16x16x32_bf16 v[102:105], v[172:175], v[196:199], v[102:105]
	v_mfma_f32_16x16x32_bf16 v[98:101], v[180:183], v[196:199], v[98:101]
	v_mfma_f32_16x16x32_bf16 v[86:89], v[172:175], v[204:207], v[86:89]
	v_mfma_f32_16x16x32_bf16 v[82:85], v[180:183], v[204:207], v[82:85]
	v_mfma_f32_16x16x32_bf16 v[70:73], v[172:175], v[212:215], v[70:73]
	v_mfma_f32_16x16x32_bf16 v[66:69], v[180:183], v[212:215], v[66:69]
	s_setprio 2
	s_barrier
	s_add_i32 s33, s60, s46
	v_lshl_add_u64 v[216:217], s[38:39], 0, v[134:135]
	s_mov_b32 m0, s33
	ds_read_b128 v[184:187], v150 offset:16384
	ds_read_b128 v[188:191], v150 offset:17408
	ds_read_b128 v[192:195], v150 offset:18432
	ds_read_b128 v[196:199], v150 offset:19456
	ds_read_b128 v[200:203], v150 offset:20480
	ds_read_b128 v[204:207], v150 offset:21504
	ds_read_b128 v[208:211], v150 offset:22528
	ds_read_b128 v[212:215], v150 offset:23552
	global_load_lds_dwordx4 v[216:217], off
	s_add_i32 m0, s33, 0x2000
	s_add_u32 s62, s38, 0x40000
	v_lshl_add_u64 v[218:219], s[38:39], 0, v[130:131]
	s_addc_u32 s63, s39, 0
	s_add_i32 s33, s61, s46
	global_load_lds_dwordx4 v[218:219], off
	v_lshl_add_u64 v[220:221], s[62:63], 0, v[134:135]
	s_mov_b32 m0, s33
	v_lshl_add_u64 v[222:223], s[40:41], 0, v[132:133]
	global_load_lds_dwordx4 v[220:221], off
	v_lshl_add_u64 v[220:221], s[62:63], 0, v[130:131]
	s_add_i32 m0, s33, 0x2000
	s_nop 0
	global_load_lds_dwordx4 v[220:221], off
	v_lshl_add_u64 v[220:221], s[40:41], 0, v[136:137]
	s_mov_b32 m0, s25
	s_nop 0
	global_load_lds_dwordx4 v[220:221], off
	s_mov_b32 m0, s37
	s_nop 0
	global_load_lds_dwordx4 v[222:223], off
	s_waitcnt vmcnt(8)
	s_waitcnt lgkmcnt(0)
	s_barrier
; #define PG8_STAGE(bufoff, gbase, voff) do { _Pragma("unroll") for (int _i = 0; _i < 2; ++_i) \
;         __builtin_amdgcn_global_load_lds((const unsigned*)((const char*)(gbase) + (voff)[_i]), (LAS unsigned*)(lds + (bufoff) + ldsw + _i * 8192), 16, 0, 0); } while (0)
; #define PG8_LDA(dst, b, h) do { _Pragma("unroll") for (int m = 0; m < 4; ++m) _Pragma("unroll") for (int k = 0; k < 2; ++k) dst[m][k] = *(const LAS bf16x8*)(lds + PG8_SA(b, h) + aoff + m * 2048 + k * 1024); } while (0)
; #define PG8_LDB(dst, b, h) do { _Pragma("unroll") for (int n = 0; n < 2; ++n) _Pragma("unroll") for (int k = 0; k < 2; ++k) dst[n][k] = *(const LAS bf16x8*)(lds + PG8_SB(b, h) + boff + n * 2048 + k * 1024); } while (0)
; #define PG8_MMA(ai, bj, At, Bt) do { __builtin_amdgcn_s_setprio(1); _Pragma("unroll") for (int m = 0; m < 4; ++m) _Pragma("unroll") for (int n = 0; n < 2; ++n) _Pragma("unroll") for (int k = 0; k < 2; ++k) \
;         acc[ai][bj][m][n] = __builtin_amdgcn_mfma_f32_16x16x32_bf16(Bt[n][k], At[m][k], acc[ai][bj][m][n], 0, 0, 0); __builtin_amdgcn_s_setprio(0); } while (0)
; #define PG8_WAIT_V(n) asm volatile("s_waitcnt vmcnt(" #n ")" ::: "memory")
; #define PG8_WAIT_L(n) asm volatile("s_waitcnt lgkmcnt(" #n ")" ::: "memory")
; #define PG8_BAR __builtin_amdgcn_s_barrier()
; #define PG8_SCHED __builtin_amdgcn_sched_barrier(0)
; template <class Epi>
; __device__ __forceinline__ void gemm_phase(LAS unsigned char* lds, const Gemm g, int G, int c, const Epi& E) {
;     ...
;             PG8_WAIT_V(8); PG8_WAIT_L(0); PG8_BAR; PG8_MMA(1, 0, At, B0); PG8_MMA(1, 1, At, B1); PG8_BAR; PG8_SCHED;
;             PG8_LDB(B0, 1, 0); PG8_LDB(B1, 1, 1); PG8_SCHED; PG8_LDA(At, 1, 0); PG8_STAGE(PG8_SA(0, 1), a2 + hstepA, voffA);
;             PG8_WAIT_V(8); PG8_WAIT_L(0); PG8_BAR; PG8_MMA(0, 0, At, B0); PG8_MMA(0, 1, At, B1); PG8_BAR; PG8_SCHED;
	s_setprio 0
	v_mfma_f32_16x16x32_bf16 v[62:65], v[152:155], v[184:187], 0
	v_mfma_f32_16x16x32_bf16 v[58:61], v[160:163], v[184:187], 0
	v_mfma_f32_16x16x32_bf16 v[46:49], v[152:155], v[192:195], 0
	v_mfma_f32_16x16x32_bf16 v[42:45], v[160:163], v[192:195], 0
	v_mfma_f32_16x16x32_bf16 v[30:33], v[152:155], v[200:203], 0
	v_mfma_f32_16x16x32_bf16 v[26:29], v[160:163], v[200:203], 0
	v_mfma_f32_16x16x32_bf16 v[14:17], v[152:155], v[208:211], 0
	v_mfma_f32_16x16x32_bf16 v[10:13], v[160:163], v[208:211], 0
	v_mfma_f32_16x16x32_bf16 v[62:65], v[156:159], v[188:191], v[62:65]
	v_mfma_f32_16x16x32_bf16 v[58:61], v[164:167], v[188:191], v[58:61]
	v_mfma_f32_16x16x32_bf16 v[46:49], v[156:159], v[196:199], v[46:49]
	v_mfma_f32_16x16x32_bf16 v[42:45], v[164:167], v[196:199], v[42:45]
	v_mfma_f32_16x16x32_bf16 v[30:33], v[156:159], v[204:207], v[30:33]
	v_mfma_f32_16x16x32_bf16 v[26:29], v[164:167], v[204:207], v[26:29]
	v_mfma_f32_16x16x32_bf16 v[14:17], v[156:159], v[212:215], v[14:17]
	v_mfma_f32_16x16x32_bf16 v[10:13], v[164:167], v[212:215], v[10:13]
	s_setprio 2
	s_setprio 0
	v_mfma_f32_16x16x32_bf16 v[54:57], v[168:171], v[184:187], 0
	v_mfma_f32_16x16x32_bf16 v[50:53], v[176:179], v[184:187], 0
	v_mfma_f32_16x16x32_bf16 v[38:41], v[168:171], v[192:195], 0
	v_mfma_f32_16x16x32_bf16 v[34:37], v[176:179], v[192:195], 0
	v_mfma_f32_16x16x32_bf16 v[22:25], v[168:171], v[200:203], 0
	v_mfma_f32_16x16x32_bf16 v[18:21], v[176:179], v[200:203], 0
	v_mfma_f32_16x16x32_bf16 v[6:9], v[168:171], v[208:211], 0
	v_mfma_f32_16x16x32_bf16 v[2:5], v[176:179], v[208:211], 0
	v_mfma_f32_16x16x32_bf16 v[54:57], v[172:175], v[188:191], v[54:57]
	v_mfma_f32_16x16x32_bf16 v[50:53], v[180:183], v[188:191], v[50:53]
	v_mfma_f32_16x16x32_bf16 v[38:41], v[172:175], v[196:199], v[38:41]
	v_mfma_f32_16x16x32_bf16 v[34:37], v[180:183], v[196:199], v[34:37]
	v_mfma_f32_16x16x32_bf16 v[22:25], v[172:175], v[204:207], v[22:25]
	v_mfma_f32_16x16x32_bf16 v[18:21], v[180:183], v[204:207], v[18:21]
	v_mfma_f32_16x16x32_bf16 v[6:9], v[172:175], v[212:215], v[6:9]
	v_mfma_f32_16x16x32_bf16 v[2:5], v[180:183], v[212:215], v[2:5]
	s_setprio 2
	s_barrier
	s_add_i32 s33, 0, 0x18000
	s_add_i32 s62, 0, 0x1c000
	v_add_u32_e32 v164, s33, v147
	v_add_u32_e32 v180, s62, v147
	ds_read_b128 v[152:155], v164
	ds_read_b128 v[156:159], v164 offset:1024
	ds_read_b128 v[160:163], v164 offset:2048
	ds_read_b128 v[164:167], v164 offset:3072
	ds_read_b128 v[168:171], v180
	ds_read_b128 v[172:175], v180 offset:1024
	ds_read_b128 v[176:179], v180 offset:2048
	ds_read_b128 v[180:183], v180 offset:3072
	s_add_u32 s40, s40, 0x40000
	s_addc_u32 s41, s41, 0
	s_mov_b32 m0, s47
	v_lshl_add_u64 v[224:225], s[40:41], 0, v[136:137]
	ds_read_b128 v[184:187], v150 offset:32768
	ds_read_b128 v[188:191], v150 offset:33792
	ds_read_b128 v[192:195], v150 offset:34816
	ds_read_b128 v[196:199], v150 offset:35840
	ds_read_b128 v[200:203], v150 offset:36864
	ds_read_b128 v[204:207], v150 offset:37888
	ds_read_b128 v[208:211], v150 offset:38912
	ds_read_b128 v[212:215], v150 offset:39936
	global_load_lds_dwordx4 v[224:225], off
	v_lshl_add_u64 v[224:225], s[40:41], 0, v[132:133]
	s_mov_b32 m0, s52
	s_nop 0
	global_load_lds_dwordx4 v[224:225], off
	s_waitcnt vmcnt(8)
	s_waitcnt lgkmcnt(0)
	s_barrier
	s_setprio 0
	v_mfma_f32_16x16x32_bf16 v[126:129], v[152:155], v[184:187], v[126:129]
	v_mfma_f32_16x16x32_bf16 v[122:125], v[160:163], v[184:187], v[122:125]
	v_mfma_f32_16x16x32_bf16 v[110:113], v[152:155], v[192:195], v[110:113]
	v_mfma_f32_16x16x32_bf16 v[106:109], v[160:163], v[192:195], v[106:109]
	v_mfma_f32_16x16x32_bf16 v[94:97], v[152:155], v[200:203], v[94:97]
	v_mfma_f32_16x16x32_bf16 v[90:93], v[160:163], v[200:203], v[90:93]
	v_mfma_f32_16x16x32_bf16 v[78:81], v[152:155], v[208:211], v[78:81]
	v_mfma_f32_16x16x32_bf16 v[74:77], v[160:163], v[208:211], v[74:77]
	v_mfma_f32_16x16x32_bf16 v[126:129], v[156:159], v[188:191], v[126:129]
	v_mfma_f32_16x16x32_bf16 v[122:125], v[164:167], v[188:191], v[122:125]
	v_mfma_f32_16x16x32_bf16 v[110:113], v[156:159], v[196:199], v[110:113]
	v_mfma_f32_16x16x32_bf16 v[106:109], v[164:167], v[196:199], v[106:109]
	v_mfma_f32_16x16x32_bf16 v[94:97], v[156:159], v[204:207], v[94:97]
	v_mfma_f32_16x16x32_bf16 v[90:93], v[164:167], v[204:207], v[90:93]
	v_mfma_f32_16x16x32_bf16 v[78:81], v[156:159], v[212:215], v[78:81]
	v_mfma_f32_16x16x32_bf16 v[74:77], v[164:167], v[212:215], v[74:77]
	s_setprio 2
	s_setprio 0
	v_mfma_f32_16x16x32_bf16 v[118:121], v[168:171], v[184:187], v[118:121]
	v_mfma_f32_16x16x32_bf16 v[114:117], v[176:179], v[184:187], v[114:117]
	v_mfma_f32_16x16x32_bf16 v[102:105], v[168:171], v[192:195], v[102:105]
	v_mfma_f32_16x16x32_bf16 v[98:101], v[176:179], v[192:195], v[98:101]
	v_mfma_f32_16x16x32_bf16 v[86:89], v[168:171], v[200:203], v[86:89]
	v_mfma_f32_16x16x32_bf16 v[82:85], v[176:179], v[200:203], v[82:85]
	v_mfma_f32_16x16x32_bf16 v[70:73], v[168:171], v[208:211], v[70:73]
	v_mfma_f32_16x16x32_bf16 v[66:69], v[176:179], v[208:211], v[66:69]
	v_mfma_f32_16x16x32_bf16 v[118:121], v[172:175], v[188:191], v[118:121]
	v_mfma_f32_16x16x32_bf16 v[114:117], v[180:183], v[188:191], v[114:117]
	v_mfma_f32_16x16x32_bf16 v[102:105], v[172:175], v[196:199], v[102:105]
	v_mfma_f32_16x16x32_bf16 v[98:101], v[180:183], v[196:199], v[98:101]
	v_mfma_f32_16x16x32_bf16 v[86:89], v[172:175], v[204:207], v[86:89]
	v_mfma_f32_16x16x32_bf16 v[82:85], v[180:183], v[204:207], v[82:85]
	v_mfma_f32_16x16x32_bf16 v[70:73], v[172:175], v[212:215], v[70:73]
	v_mfma_f32_16x16x32_bf16 v[66:69], v[180:183], v[212:215], v[66:69]
	s_setprio 2
	s_barrier
; #define PG8_STAGE(bufoff, gbase, voff) do { _Pragma("unroll") for (int _i = 0; _i < 2; ++_i) \
;         __builtin_amdgcn_global_load_lds((const unsigned*)((const char*)(gbase) + (voff)[_i]), (LAS unsigned*)(lds + (bufoff) + ldsw + _i * 8192), 16, 0, 0); } while (0)
; #define PG8_LDA(dst, b, h) do { _Pragma("unroll") for (int m = 0; m < 4; ++m) _Pragma("unroll") for (int k = 0; k < 2; ++k) dst[m][k] = *(const LAS bf16x8*)(lds + PG8_SA(b, h) + aoff + m * 2048 + k * 1024); } while (0)
; #define PG8_LDB(dst, b, h) do { _Pragma("unroll") for (int n = 0; n < 2; ++n) _Pragma("unroll") for (int k = 0; k < 2; ++k) dst[n][k] = *(const LAS bf16x8*)(lds + PG8_SB(b, h) + boff + n * 2048 + k * 1024); } while (0)
; #define PG8_WAIT_V(n) asm volatile("s_waitcnt vmcnt(" #n ")" ::: "memory")
; #define PG8_WAIT_L(n) asm volatile("s_waitcnt lgkmcnt(" #n ")" ::: "memory")
; template <class Epi>
; __device__ __forceinline__ void gemm_phase(LAS unsigned char* lds, const Gemm g, int G, int c, const Epi& E) {
;     ...
;         for (int t = 0; t < nt; t += 2) {
;             const bool last = (t == nt - 2);
;             const char* a1 = cA + (size_t)(t + 1) * kstep;
;             const char* a2 = last ? nA : cA + (size_t)(t + 2) * kstep; const char* b2 = last ? nB : cB + (size_t)(t + 2) * kstep;
;             const char* a3 = a2 + kstep; const char* b3 = b2 + kstep;
;             PG8_LDB(B0, 0, 0); PG8_LDB(B1, 0, 1); PG8_SCHED; PG8_LDA(At, 0, 0); PG8_STAGE(PG8_SA(1, 1), a1 + hstepA, voffA);
;             PG8_WAIT_V(8); PG8_WAIT_L(0); PG8_BAR; PG8_MMA(0, 0, At, B0); PG8_MMA(0, 1, At, B1); PG8_BAR; PG8_SCHED;
;             PG8_LDA(At, 0, 1); PG8_STAGE(PG8_SB(0, 0), b2, voffB); PG8_STAGE(PG8_SB(0, 1), b2 + hstepB, voffB); PG8_STAGE(PG8_SA(0, 0), a2, voffA);
;             PG8_WAIT_V(8); PG8_WAIT_L(0); PG8_BAR; PG8_MMA(1, 0, At, B0); PG8_MMA(1, 1, At, B1); PG8_BAR; PG8_SCHED;
;             PG8_LDB(B0, 1, 0); PG8_LDB(B1, 1, 1); PG8_SCHED; PG8_LDA(At, 1, 0); PG8_STAGE(PG8_SA(0, 1), a2 + hstepA, voffA);
;             PG8_WAIT_V(8); PG8_WAIT_L(0); PG8_BAR; PG8_MMA(0, 0, At, B0); PG8_MMA(0, 1, At, B1); PG8_BAR; PG8_SCHED;
;             PG8_LDA(At, 1, 1); PG8_STAGE(PG8_SB(1, 0), b3, voffB); PG8_STAGE(PG8_SB(1, 1), b3 + hstepB, voffB); PG8_STAGE(PG8_SA(1, 0), a3, voffA);
;             PG8_WAIT_V(8); PG8_WAIT_L(0); PG8_BAR; PG8_MMA(1, 0, At, B0); PG8_MMA(1, 1, At, B1); PG8_BAR; PG8_SCHED;
	s_add_i32 s33, s33, s46
	v_lshl_add_u64 v[216:217], v[216:217], 0, s[12:13]
	s_mov_b32 m0, s33
	ds_read_b128 v[184:187], v150 offset:49152
	ds_read_b128 v[188:191], v150 offset:50176
	ds_read_b128 v[192:195], v150 offset:51200
	ds_read_b128 v[196:199], v150 offset:52224
	ds_read_b128 v[200:203], v150 offset:53248
	ds_read_b128 v[204:207], v150 offset:54272
	ds_read_b128 v[208:211], v150 offset:55296
	ds_read_b128 v[212:215], v150 offset:56320
	global_load_lds_dwordx4 v[216:217], off
	s_add_i32 m0, s33, 0x2000
	s_add_u32 s38, s38, 0x40080
	v_lshl_add_u64 v[216:217], v[218:219], 0, s[12:13]
	s_addc_u32 s39, s39, 0
	s_add_i32 s33, s62, s46
	global_load_lds_dwordx4 v[216:217], off
	v_lshl_add_u64 v[216:217], s[38:39], 0, v[134:135]
	s_mov_b32 m0, s33
	s_nop 0
	global_load_lds_dwordx4 v[216:217], off
	v_lshl_add_u64 v[216:217], s[38:39], 0, v[130:131]
	s_add_i32 m0, s33, 0x2000
	s_nop 0
	global_load_lds_dwordx4 v[216:217], off
	v_lshl_add_u64 v[216:217], v[220:221], 0, s[12:13]
	s_mov_b32 m0, s57
	s_nop 0
	global_load_lds_dwordx4 v[216:217], off
	v_lshl_add_u64 v[216:217], v[222:223], 0, s[12:13]
	s_mov_b32 m0, s58
	s_nop 0
	global_load_lds_dwordx4 v[216:217], off
	s_waitcnt vmcnt(8)
	s_waitcnt lgkmcnt(0)
	s_barrier
	s_setprio 0
	v_mfma_f32_16x16x32_bf16 v[62:65], v[152:155], v[184:187], v[62:65]
	v_mfma_f32_16x16x32_bf16 v[58:61], v[160:163], v[184:187], v[58:61]
	v_mfma_f32_16x16x32_bf16 v[46:49], v[152:155], v[192:195], v[46:49]
	v_mfma_f32_16x16x32_bf16 v[42:45], v[160:163], v[192:195], v[42:45]
	v_mfma_f32_16x16x32_bf16 v[30:33], v[152:155], v[200:203], v[30:33]
	v_mfma_f32_16x16x32_bf16 v[26:29], v[160:163], v[200:203], v[26:29]
	v_mfma_f32_16x16x32_bf16 v[14:17], v[152:155], v[208:211], v[14:17]
	v_mfma_f32_16x16x32_bf16 v[10:13], v[160:163], v[208:211], v[10:13]
	v_mfma_f32_16x16x32_bf16 v[62:65], v[156:159], v[188:191], v[62:65]
	v_mfma_f32_16x16x32_bf16 v[58:61], v[164:167], v[188:191], v[58:61]
	v_mfma_f32_16x16x32_bf16 v[46:49], v[156:159], v[196:199], v[46:49]
	v_mfma_f32_16x16x32_bf16 v[42:45], v[164:167], v[196:199], v[42:45]
	v_mfma_f32_16x16x32_bf16 v[30:33], v[156:159], v[204:207], v[30:33]
	v_mfma_f32_16x16x32_bf16 v[26:29], v[164:167], v[204:207], v[26:29]
	v_mfma_f32_16x16x32_bf16 v[14:17], v[156:159], v[212:215], v[14:17]
	v_mfma_f32_16x16x32_bf16 v[10:13], v[164:167], v[212:215], v[10:13]
	s_setprio 2
	s_setprio 0
	v_mfma_f32_16x16x32_bf16 v[54:57], v[168:171], v[184:187], v[54:57]
	v_mfma_f32_16x16x32_bf16 v[50:53], v[176:179], v[184:187], v[50:53]
	v_mfma_f32_16x16x32_bf16 v[38:41], v[168:171], v[192:195], v[38:41]
	v_mfma_f32_16x16x32_bf16 v[34:37], v[176:179], v[192:195], v[34:37]
	v_mfma_f32_16x16x32_bf16 v[22:25], v[168:171], v[200:203], v[22:25]
	v_mfma_f32_16x16x32_bf16 v[18:21], v[176:179], v[200:203], v[18:21]
	v_mfma_f32_16x16x32_bf16 v[6:9], v[168:171], v[208:211], v[6:9]
	v_mfma_f32_16x16x32_bf16 v[2:5], v[176:179], v[208:211], v[2:5]
	v_mfma_f32_16x16x32_bf16 v[54:57], v[172:175], v[188:191], v[54:57]
	v_mfma_f32_16x16x32_bf16 v[50:53], v[180:183], v[188:191], v[50:53]
	v_mfma_f32_16x16x32_bf16 v[38:41], v[172:175], v[196:199], v[38:41]
	v_mfma_f32_16x16x32_bf16 v[34:37], v[180:183], v[196:199], v[34:37]
	v_mfma_f32_16x16x32_bf16 v[22:25], v[172:175], v[204:207], v[22:25]
	v_mfma_f32_16x16x32_bf16 v[18:21], v[180:183], v[204:207], v[18:21]
	v_mfma_f32_16x16x32_bf16 v[6:9], v[172:175], v[212:215], v[6:9]
	v_mfma_f32_16x16x32_bf16 v[2:5], v[180:183], v[212:215], v[2:5]
	s_setprio 2
	s_add_i32 s80, s80, 2
	s_add_u32 s4, s4, 0x100
	s_addc_u32 s5, s5, 0
	s_add_u32 s78, s78, 0x100
	s_addc_u32 s79, s79, 0
	s_cmp_gt_u32 s80, 13
	s_barrier
	s_cbranch_scc0 .LBB0_1058
.LBB0_1058:
	ds_read_b128 v[152:155], v148
	ds_read_b128 v[156:159], v148 offset:1024
	ds_read_b128 v[160:163], v148 offset:2048
	ds_read_b128 v[164:167], v148 offset:3072
	ds_read_b128 v[168:171], v149
	ds_read_b128 v[172:175], v149 offset:1024
	ds_read_b128 v[176:179], v149 offset:2048
	ds_read_b128 v[180:183], v149 offset:3072
	s_add_u32 s33, s4, 0xfffc0080
	s_addc_u32 s38, s5, -1
	s_cmp_eq_u32 s80, 12
	s_cselect_b32 s41, s21, s38
	s_cselect_b32 s40, s20, s33
	s_cselect_b32 s39, s17, s79
	s_cselect_b32 s38, s19, s78
	v_lshl_add_u64 v[216:217], s[4:5], 0, v[138:139]
	s_add_i32 m0, s25, 0xc000
	ds_read_b128 v[184:187], v150
	ds_read_b128 v[188:191], v150 offset:1024
	ds_read_b128 v[192:195], v150 offset:2048
	ds_read_b128 v[196:199], v150 offset:3072
	ds_read_b128 v[200:203], v150 offset:4096
	ds_read_b128 v[204:207], v150 offset:5120
	ds_read_b128 v[208:211], v150 offset:6144
	ds_read_b128 v[212:215], v150 offset:7168
	global_load_lds_dwordx4 v[216:217], off
	v_lshl_add_u64 v[216:217], s[4:5], 0, v[140:141]
	s_add_i32 m0, s25, 0xe000
	s_nop 0
	global_load_lds_dwordx4 v[216:217], off
	s_waitcnt vmcnt(8)
	s_waitcnt lgkmcnt(0)
	s_barrier
; #define PG8_STAGE(bufoff, gbase, voff) do { _Pragma("unroll") for (int _i = 0; _i < 2; ++_i) \
;         __builtin_amdgcn_global_load_lds((const unsigned*)((const char*)(gbase) + (voff)[_i]), (LAS unsigned*)(lds + (bufoff) + ldsw + _i * 8192), 16, 0, 0); } while (0)
; #define PG8_LDA(dst, b, h) do { _Pragma("unroll") for (int m = 0; m < 4; ++m) _Pragma("unroll") for (int k = 0; k < 2; ++k) dst[m][k] = *(const LAS bf16x8*)(lds + PG8_SA(b, h) + aoff + m * 2048 + k * 1024); } while (0)
; #define PG8_MMA(ai, bj, At, Bt) do { __builtin_amdgcn_s_setprio(1); _Pragma("unroll") for (int m = 0; m < 4; ++m) _Pragma("unroll") for (int n = 0; n < 2; ++n) _Pragma("unroll") for (int k = 0; k < 2; ++k) \
;         acc[ai][bj][m][n] = __builtin_amdgcn_mfma_f32_16x16x32_bf16(Bt[n][k], At[m][k], acc[ai][bj][m][n], 0, 0, 0); __builtin_amdgcn_s_setprio(0); } while (0)
; #define PG8_WAIT_V(n) asm volatile("s_waitcnt vmcnt(" #n ")" ::: "memory")
; #define PG8_WAIT_L(n) asm volatile("s_waitcnt lgkmcnt(" #n ")" ::: "memory")
; #define PG8_BAR __builtin_amdgcn_s_barrier()
; #define PG8_SCHED __builtin_amdgcn_sched_barrier(0)
; template <class Epi>
; __device__ __forceinline__ void gemm_phase(LAS unsigned char* lds, const Gemm g, int G, int c, const Epi& E) {
;     ...
;             PG8_WAIT_V(8); PG8_WAIT_L(0); PG8_BAR; PG8_MMA(0, 0, At, B0); PG8_MMA(0, 1, At, B1); PG8_BAR; PG8_SCHED;
;             PG8_LDA(At, 0, 1); PG8_STAGE(PG8_SB(0, 0), b2, voffB); PG8_STAGE(PG8_SB(0, 1), b2 + hstepB, voffB); PG8_STAGE(PG8_SA(0, 0), a2, voffA);
;             PG8_WAIT_V(8); PG8_WAIT_L(0); PG8_BAR; PG8_MMA(1, 0, At, B0); PG8_MMA(1, 1, At, B1); PG8_BAR; PG8_SCHED;
	s_setprio 0
	v_mfma_f32_16x16x32_bf16 v[126:129], v[152:155], v[184:187], v[126:129]
	v_mfma_f32_16x16x32_bf16 v[122:125], v[160:163], v[184:187], v[122:125]
	v_mfma_f32_16x16x32_bf16 v[110:113], v[152:155], v[192:195], v[110:113]
	v_mfma_f32_16x16x32_bf16 v[106:109], v[160:163], v[192:195], v[106:109]
	v_mfma_f32_16x16x32_bf16 v[94:97], v[152:155], v[200:203], v[94:97]
	v_mfma_f32_16x16x32_bf16 v[90:93], v[160:163], v[200:203], v[90:93]
	v_mfma_f32_16x16x32_bf16 v[78:81], v[152:155], v[208:211], v[78:81]
	v_mfma_f32_16x16x32_bf16 v[74:77], v[160:163], v[208:211], v[74:77]
	v_mfma_f32_16x16x32_bf16 v[126:129], v[156:159], v[188:191], v[126:129]
	v_mfma_f32_16x16x32_bf16 v[122:125], v[164:167], v[188:191], v[122:125]
	v_mfma_f32_16x16x32_bf16 v[110:113], v[156:159], v[196:199], v[110:113]
	v_mfma_f32_16x16x32_bf16 v[106:109], v[164:167], v[196:199], v[106:109]
	v_mfma_f32_16x16x32_bf16 v[94:97], v[156:159], v[204:207], v[94:97]
	v_mfma_f32_16x16x32_bf16 v[90:93], v[164:167], v[204:207], v[90:93]
	v_mfma_f32_16x16x32_bf16 v[78:81], v[156:159], v[212:215], v[78:81]
	v_mfma_f32_16x16x32_bf16 v[74:77], v[164:167], v[212:215], v[74:77]
	s_setprio 2
	s_setprio 0
	v_mfma_f32_16x16x32_bf16 v[118:121], v[168:171], v[184:187], v[118:121]
	v_mfma_f32_16x16x32_bf16 v[114:117], v[176:179], v[184:187], v[114:117]
	v_mfma_f32_16x16x32_bf16 v[102:105], v[168:171], v[192:195], v[102:105]
	v_mfma_f32_16x16x32_bf16 v[98:101], v[176:179], v[192:195], v[98:101]
	v_mfma_f32_16x16x32_bf16 v[86:89], v[168:171], v[200:203], v[86:89]
	v_mfma_f32_16x16x32_bf16 v[82:85], v[176:179], v[200:203], v[82:85]
	v_mfma_f32_16x16x32_bf16 v[70:73], v[168:171], v[208:211], v[70:73]
	v_mfma_f32_16x16x32_bf16 v[66:69], v[176:179], v[208:211], v[66:69]
	v_mfma_f32_16x16x32_bf16 v[118:121], v[172:175], v[188:191], v[118:121]
	v_mfma_f32_16x16x32_bf16 v[114:117], v[180:183], v[188:191], v[114:117]
	v_mfma_f32_16x16x32_bf16 v[102:105], v[172:175], v[196:199], v[102:105]
	v_mfma_f32_16x16x32_bf16 v[98:101], v[180:183], v[196:199], v[98:101]
	v_mfma_f32_16x16x32_bf16 v[86:89], v[172:175], v[204:207], v[86:89]
	v_mfma_f32_16x16x32_bf16 v[82:85], v[180:183], v[204:207], v[82:85]
	v_mfma_f32_16x16x32_bf16 v[70:73], v[172:175], v[212:215], v[70:73]
	v_mfma_f32_16x16x32_bf16 v[66:69], v[180:183], v[212:215], v[66:69]
	s_setprio 2
	s_barrier
	s_add_i32 s33, s60, s46
	v_lshl_add_u64 v[216:217], s[38:39], 0, v[134:135]
	s_mov_b32 m0, s33
	ds_read_b128 v[184:187], v150 offset:16384
	ds_read_b128 v[188:191], v150 offset:17408
	ds_read_b128 v[192:195], v150 offset:18432
	ds_read_b128 v[196:199], v150 offset:19456
	ds_read_b128 v[200:203], v150 offset:20480
	ds_read_b128 v[204:207], v150 offset:21504
	ds_read_b128 v[208:211], v150 offset:22528
	ds_read_b128 v[212:215], v150 offset:23552
	global_load_lds_dwordx4 v[216:217], off
	s_add_i32 m0, s33, 0x2000
	s_add_u32 s62, s38, 0x40000
	v_lshl_add_u64 v[218:219], s[38:39], 0, v[130:131]
	s_addc_u32 s63, s39, 0
	s_add_i32 s33, s61, s46
	global_load_lds_dwordx4 v[218:219], off
	v_lshl_add_u64 v[220:221], s[62:63], 0, v[134:135]
	s_mov_b32 m0, s33
	v_lshl_add_u64 v[222:223], s[40:41], 0, v[132:133]
	global_load_lds_dwordx4 v[220:221], off
	v_lshl_add_u64 v[220:221], s[62:63], 0, v[130:131]
	s_add_i32 m0, s33, 0x2000
	s_nop 0
	global_load_lds_dwordx4 v[220:221], off
	v_lshl_add_u64 v[220:221], s[40:41], 0, v[136:137]
	s_mov_b32 m0, s25
	s_nop 0
	global_load_lds_dwordx4 v[220:221], off
	s_mov_b32 m0, s37
	s_nop 0
	global_load_lds_dwordx4 v[222:223], off
	s_waitcnt vmcnt(8)
	s_waitcnt lgkmcnt(0)
	s_barrier
	s_setprio 0
	v_mfma_f32_16x16x32_bf16 v[62:65], v[152:155], v[184:187], v[62:65]
	v_mfma_f32_16x16x32_bf16 v[58:61], v[160:163], v[184:187], v[58:61]
	v_mfma_f32_16x16x32_bf16 v[46:49], v[152:155], v[192:195], v[46:49]
	v_mfma_f32_16x16x32_bf16 v[42:45], v[160:163], v[192:195], v[42:45]
	v_mfma_f32_16x16x32_bf16 v[30:33], v[152:155], v[200:203], v[30:33]
	v_mfma_f32_16x16x32_bf16 v[26:29], v[160:163], v[200:203], v[26:29]
	v_mfma_f32_16x16x32_bf16 v[14:17], v[152:155], v[208:211], v[14:17]
	v_mfma_f32_16x16x32_bf16 v[10:13], v[160:163], v[208:211], v[10:13]
	v_mfma_f32_16x16x32_bf16 v[62:65], v[156:159], v[188:191], v[62:65]
	v_mfma_f32_16x16x32_bf16 v[58:61], v[164:167], v[188:191], v[58:61]
	v_mfma_f32_16x16x32_bf16 v[46:49], v[156:159], v[196:199], v[46:49]
	v_mfma_f32_16x16x32_bf16 v[42:45], v[164:167], v[196:199], v[42:45]
	v_mfma_f32_16x16x32_bf16 v[30:33], v[156:159], v[204:207], v[30:33]
	v_mfma_f32_16x16x32_bf16 v[26:29], v[164:167], v[204:207], v[26:29]
	v_mfma_f32_16x16x32_bf16 v[14:17], v[156:159], v[212:215], v[14:17]
	v_mfma_f32_16x16x32_bf16 v[10:13], v[164:167], v[212:215], v[10:13]
	s_setprio 2
	s_setprio 0
	v_mfma_f32_16x16x32_bf16 v[54:57], v[168:171], v[184:187], v[54:57]
	v_mfma_f32_16x16x32_bf16 v[50:53], v[176:179], v[184:187], v[50:53]
	v_mfma_f32_16x16x32_bf16 v[38:41], v[168:171], v[192:195], v[38:41]
	v_mfma_f32_16x16x32_bf16 v[34:37], v[176:179], v[192:195], v[34:37]
	v_mfma_f32_16x16x32_bf16 v[22:25], v[168:171], v[200:203], v[22:25]
	v_mfma_f32_16x16x32_bf16 v[18:21], v[176:179], v[200:203], v[18:21]
	v_mfma_f32_16x16x32_bf16 v[6:9], v[168:171], v[208:211], v[6:9]
	v_mfma_f32_16x16x32_bf16 v[2:5], v[176:179], v[208:211], v[2:5]
	v_mfma_f32_16x16x32_bf16 v[54:57], v[172:175], v[188:191], v[54:57]
	v_mfma_f32_16x16x32_bf16 v[50:53], v[180:183], v[188:191], v[50:53]
	v_mfma_f32_16x16x32_bf16 v[38:41], v[172:175], v[196:199], v[38:41]
	v_mfma_f32_16x16x32_bf16 v[34:37], v[180:183], v[196:199], v[34:37]
	v_mfma_f32_16x16x32_bf16 v[22:25], v[172:175], v[204:207], v[22:25]
	v_mfma_f32_16x16x32_bf16 v[18:21], v[180:183], v[204:207], v[18:21]
	v_mfma_f32_16x16x32_bf16 v[6:9], v[172:175], v[212:215], v[6:9]
	v_mfma_f32_16x16x32_bf16 v[2:5], v[180:183], v[212:215], v[2:5]
	s_setprio 2
	s_barrier
; #define PG8_STAGE(bufoff, gbase, voff) do { _Pragma("unroll") for (int _i = 0; _i < 2; ++_i) \
;         __builtin_amdgcn_global_load_lds((const unsigned*)((const char*)(gbase) + (voff)[_i]), (LAS unsigned*)(lds + (bufoff) + ldsw + _i * 8192), 16, 0, 0); } while (0)
; #define PG8_LDA(dst, b, h) do { _Pragma("unroll") for (int m = 0; m < 4; ++m) _Pragma("unroll") for (int k = 0; k < 2; ++k) dst[m][k] = *(const LAS bf16x8*)(lds + PG8_SA(b, h) + aoff + m * 2048 + k * 1024); } while (0)
; #define PG8_LDB(dst, b, h) do { _Pragma("unroll") for (int n = 0; n < 2; ++n) _Pragma("unroll") for (int k = 0; k < 2; ++k) dst[n][k] = *(const LAS bf16x8*)(lds + PG8_SB(b, h) + boff + n * 2048 + k * 1024); } while (0)
; #define PG8_MMA(ai, bj, At, Bt) do { __builtin_amdgcn_s_setprio(1); _Pragma("unroll") for (int m = 0; m < 4; ++m) _Pragma("unroll") for (int n = 0; n < 2; ++n) _Pragma("unroll") for (int k = 0; k < 2; ++k) \
;         acc[ai][bj][m][n] = __builtin_amdgcn_mfma_f32_16x16x32_bf16(Bt[n][k], At[m][k], acc[ai][bj][m][n], 0, 0, 0); __builtin_amdgcn_s_setprio(0); } while (0)
; #define PG8_WAIT_V(n) asm volatile("s_waitcnt vmcnt(" #n ")" ::: "memory")
; #define PG8_WAIT_L(n) asm volatile("s_waitcnt lgkmcnt(" #n ")" ::: "memory")
; #define PG8_BAR __builtin_amdgcn_s_barrier()
; #define PG8_SCHED __builtin_amdgcn_sched_barrier(0)
; template <class Epi>
; __device__ __forceinline__ void gemm_phase(LAS unsigned char* lds, const Gemm g, int G, int c, const Epi& E) {
;     ...
;             PG8_LDB(B0, 1, 0); PG8_LDB(B1, 1, 1); PG8_SCHED; PG8_LDA(At, 1, 0); PG8_STAGE(PG8_SA(0, 1), a2 + hstepA, voffA);
;             PG8_WAIT_V(8); PG8_WAIT_L(0); PG8_BAR; PG8_MMA(0, 0, At, B0); PG8_MMA(0, 1, At, B1); PG8_BAR; PG8_SCHED;
	s_add_i32 s33, 0, 0x18000
	s_add_i32 s62, 0, 0x1c000
	v_add_u32_e32 v164, s33, v147
	v_add_u32_e32 v180, s62, v147
	ds_read_b128 v[152:155], v164
	ds_read_b128 v[156:159], v164 offset:1024
	ds_read_b128 v[160:163], v164 offset:2048
	ds_read_b128 v[164:167], v164 offset:3072
	ds_read_b128 v[168:171], v180
	ds_read_b128 v[172:175], v180 offset:1024
	ds_read_b128 v[176:179], v180 offset:2048
	ds_read_b128 v[180:183], v180 offset:3072
	s_add_u32 s40, s40, 0x40000
	s_addc_u32 s41, s41, 0
	s_mov_b32 m0, s47
	v_lshl_add_u64 v[224:225], s[40:41], 0, v[136:137]
	ds_read_b128 v[184:187], v150 offset:32768
	ds_read_b128 v[188:191], v150 offset:33792
	ds_read_b128 v[192:195], v150 offset:34816
	ds_read_b128 v[196:199], v150 offset:35840
	ds_read_b128 v[200:203], v150 offset:36864
	ds_read_b128 v[204:207], v150 offset:37888
	ds_read_b128 v[208:211], v150 offset:38912
	ds_read_b128 v[212:215], v150 offset:39936
	global_load_lds_dwordx4 v[224:225], off
	v_lshl_add_u64 v[224:225], s[40:41], 0, v[132:133]
	s_mov_b32 m0, s52
	s_nop 0
	global_load_lds_dwordx4 v[224:225], off
	s_waitcnt vmcnt(8)
	s_waitcnt lgkmcnt(0)
	s_barrier
	s_setprio 0
	v_mfma_f32_16x16x32_bf16 v[126:129], v[152:155], v[184:187], v[126:129]
	v_mfma_f32_16x16x32_bf16 v[122:125], v[160:163], v[184:187], v[122:125]
	v_mfma_f32_16x16x32_bf16 v[110:113], v[152:155], v[192:195], v[110:113]
	v_mfma_f32_16x16x32_bf16 v[106:109], v[160:163], v[192:195], v[106:109]
	v_mfma_f32_16x16x32_bf16 v[94:97], v[152:155], v[200:203], v[94:97]
	v_mfma_f32_16x16x32_bf16 v[90:93], v[160:163], v[200:203], v[90:93]
	v_mfma_f32_16x16x32_bf16 v[78:81], v[152:155], v[208:211], v[78:81]
	v_mfma_f32_16x16x32_bf16 v[74:77], v[160:163], v[208:211], v[74:77]
	v_mfma_f32_16x16x32_bf16 v[126:129], v[156:159], v[188:191], v[126:129]
	v_mfma_f32_16x16x32_bf16 v[122:125], v[164:167], v[188:191], v[122:125]
	v_mfma_f32_16x16x32_bf16 v[110:113], v[156:159], v[196:199], v[110:113]
	v_mfma_f32_16x16x32_bf16 v[106:109], v[164:167], v[196:199], v[106:109]
	v_mfma_f32_16x16x32_bf16 v[94:97], v[156:159], v[204:207], v[94:97]
	v_mfma_f32_16x16x32_bf16 v[90:93], v[164:167], v[204:207], v[90:93]
	v_mfma_f32_16x16x32_bf16 v[78:81], v[156:159], v[212:215], v[78:81]
	v_mfma_f32_16x16x32_bf16 v[74:77], v[164:167], v[212:215], v[74:77]
	s_setprio 2
	s_setprio 0
	v_mfma_f32_16x16x32_bf16 v[118:121], v[168:171], v[184:187], v[118:121]
	v_mfma_f32_16x16x32_bf16 v[114:117], v[176:179], v[184:187], v[114:117]
	v_mfma_f32_16x16x32_bf16 v[102:105], v[168:171], v[192:195], v[102:105]
	v_mfma_f32_16x16x32_bf16 v[98:101], v[176:179], v[192:195], v[98:101]
	v_mfma_f32_16x16x32_bf16 v[86:89], v[168:171], v[200:203], v[86:89]
	v_mfma_f32_16x16x32_bf16 v[82:85], v[176:179], v[200:203], v[82:85]
	v_mfma_f32_16x16x32_bf16 v[70:73], v[168:171], v[208:211], v[70:73]
	v_mfma_f32_16x16x32_bf16 v[66:69], v[176:179], v[208:211], v[66:69]
	v_mfma_f32_16x16x32_bf16 v[118:121], v[172:175], v[188:191], v[118:121]
	v_mfma_f32_16x16x32_bf16 v[114:117], v[180:183], v[188:191], v[114:117]
	v_mfma_f32_16x16x32_bf16 v[102:105], v[172:175], v[196:199], v[102:105]
	v_mfma_f32_16x16x32_bf16 v[98:101], v[180:183], v[196:199], v[98:101]
	v_mfma_f32_16x16x32_bf16 v[86:89], v[172:175], v[204:207], v[86:89]
	v_mfma_f32_16x16x32_bf16 v[82:85], v[180:183], v[204:207], v[82:85]
	v_mfma_f32_16x16x32_bf16 v[70:73], v[172:175], v[212:215], v[70:73]
	v_mfma_f32_16x16x32_bf16 v[66:69], v[180:183], v[212:215], v[66:69]
	s_setprio 2
	s_barrier
; #define PG8_STAGE(bufoff, gbase, voff) do { _Pragma("unroll") for (int _i = 0; _i < 2; ++_i) \
;         __builtin_amdgcn_global_load_lds((const unsigned*)((const char*)(gbase) + (voff)[_i]), (LAS unsigned*)(lds + (bufoff) + ldsw + _i * 8192), 16, 0, 0); } while (0)
; #define PG8_LDA(dst, b, h) do { _Pragma("unroll") for (int m = 0; m < 4; ++m) _Pragma("unroll") for (int k = 0; k < 2; ++k) dst[m][k] = *(const LAS bf16x8*)(lds + PG8_SA(b, h) + aoff + m * 2048 + k * 1024); } while (0)
; #define PG8_MMA(ai, bj, At, Bt) do { __builtin_amdgcn_s_setprio(1); _Pragma("unroll") for (int m = 0; m < 4; ++m) _Pragma("unroll") for (int n = 0; n < 2; ++n) _Pragma("unroll") for (int k = 0; k < 2; ++k) \
;         acc[ai][bj][m][n] = __builtin_amdgcn_mfma_f32_16x16x32_bf16(Bt[n][k], At[m][k], acc[ai][bj][m][n], 0, 0, 0); __builtin_amdgcn_s_setprio(0); } while (0)
; #define PG8_WAIT_V(n) asm volatile("s_waitcnt vmcnt(" #n ")" ::: "memory")
; #define PG8_WAIT_L(n) asm volatile("s_waitcnt lgkmcnt(" #n ")" ::: "memory")
; #define PG8_BAR __builtin_amdgcn_s_barrier()
; #define PG8_SCHED __builtin_amdgcn_sched_barrier(0)
; template <class Epi>
; __device__ __forceinline__ void gemm_phase(LAS unsigned char* lds, const Gemm g, int G, int c, const Epi& E) {
;     ...
;         for (int t = 0; t < nt; t += 2) {
;     ...
;             PG8_LDA(At, 1, 1); PG8_STAGE(PG8_SB(1, 0), b3, voffB); PG8_STAGE(PG8_SB(1, 1), b3 + hstepB, voffB); PG8_STAGE(PG8_SA(1, 0), a3, voffA);
;             PG8_WAIT_V(8); PG8_WAIT_L(0); PG8_BAR; PG8_MMA(1, 0, At, B0); PG8_MMA(1, 1, At, B1); PG8_BAR; PG8_SCHED;
;         }
;         if (wr == 0) PG8_BAR;
	s_add_i32 s33, s33, s46
	v_lshl_add_u64 v[216:217], v[216:217], 0, s[12:13]
	s_mov_b32 m0, s33
	ds_read_b128 v[184:187], v150 offset:49152
	ds_read_b128 v[188:191], v150 offset:50176
	ds_read_b128 v[192:195], v150 offset:51200
	ds_read_b128 v[196:199], v150 offset:52224
	ds_read_b128 v[200:203], v150 offset:53248
	ds_read_b128 v[204:207], v150 offset:54272
	ds_read_b128 v[208:211], v150 offset:55296
	ds_read_b128 v[212:215], v150 offset:56320
	global_load_lds_dwordx4 v[216:217], off
	s_add_i32 m0, s33, 0x2000
	s_add_u32 s38, s38, 0x40080
	v_lshl_add_u64 v[216:217], v[218:219], 0, s[12:13]
	s_addc_u32 s39, s39, 0
	s_add_i32 s33, s62, s46
	global_load_lds_dwordx4 v[216:217], off
	v_lshl_add_u64 v[216:217], s[38:39], 0, v[134:135]
	s_mov_b32 m0, s33
	s_nop 0
	global_load_lds_dwordx4 v[216:217], off
	v_lshl_add_u64 v[216:217], s[38:39], 0, v[130:131]
	s_add_i32 m0, s33, 0x2000
	s_nop 0
	global_load_lds_dwordx4 v[216:217], off
	v_lshl_add_u64 v[216:217], v[220:221], 0, s[12:13]
	s_mov_b32 m0, s57
	s_nop 0
	global_load_lds_dwordx4 v[216:217], off
	v_lshl_add_u64 v[216:217], v[222:223], 0, s[12:13]
	s_mov_b32 m0, s58
	s_nop 0
	global_load_lds_dwordx4 v[216:217], off
	s_waitcnt vmcnt(8)
	s_waitcnt lgkmcnt(0)
	s_barrier
	s_setprio 0
	v_mfma_f32_16x16x32_bf16 v[62:65], v[152:155], v[184:187], v[62:65]
	v_mfma_f32_16x16x32_bf16 v[58:61], v[160:163], v[184:187], v[58:61]
	v_mfma_f32_16x16x32_bf16 v[46:49], v[152:155], v[192:195], v[46:49]
	v_mfma_f32_16x16x32_bf16 v[42:45], v[160:163], v[192:195], v[42:45]
	v_mfma_f32_16x16x32_bf16 v[30:33], v[152:155], v[200:203], v[30:33]
	v_mfma_f32_16x16x32_bf16 v[26:29], v[160:163], v[200:203], v[26:29]
	v_mfma_f32_16x16x32_bf16 v[14:17], v[152:155], v[208:211], v[14:17]
	v_mfma_f32_16x16x32_bf16 v[10:13], v[160:163], v[208:211], v[10:13]
	v_mfma_f32_16x16x32_bf16 v[62:65], v[156:159], v[188:191], v[62:65]
	v_mfma_f32_16x16x32_bf16 v[58:61], v[164:167], v[188:191], v[58:61]
	v_mfma_f32_16x16x32_bf16 v[46:49], v[156:159], v[196:199], v[46:49]
	v_mfma_f32_16x16x32_bf16 v[42:45], v[164:167], v[196:199], v[42:45]
	v_mfma_f32_16x16x32_bf16 v[30:33], v[156:159], v[204:207], v[30:33]
	v_mfma_f32_16x16x32_bf16 v[26:29], v[164:167], v[204:207], v[26:29]
	v_mfma_f32_16x16x32_bf16 v[14:17], v[156:159], v[212:215], v[14:17]
	v_mfma_f32_16x16x32_bf16 v[10:13], v[164:167], v[212:215], v[10:13]
	s_setprio 2
	s_setprio 0
	v_mfma_f32_16x16x32_bf16 v[54:57], v[168:171], v[184:187], v[54:57]
	v_mfma_f32_16x16x32_bf16 v[50:53], v[176:179], v[184:187], v[50:53]
	v_mfma_f32_16x16x32_bf16 v[38:41], v[168:171], v[192:195], v[38:41]
	v_mfma_f32_16x16x32_bf16 v[34:37], v[176:179], v[192:195], v[34:37]
	v_mfma_f32_16x16x32_bf16 v[22:25], v[168:171], v[200:203], v[22:25]
	v_mfma_f32_16x16x32_bf16 v[18:21], v[176:179], v[200:203], v[18:21]
	v_mfma_f32_16x16x32_bf16 v[6:9], v[168:171], v[208:211], v[6:9]
	v_mfma_f32_16x16x32_bf16 v[2:5], v[176:179], v[208:211], v[2:5]
	v_mfma_f32_16x16x32_bf16 v[54:57], v[172:175], v[188:191], v[54:57]
	v_mfma_f32_16x16x32_bf16 v[50:53], v[180:183], v[188:191], v[50:53]
	v_mfma_f32_16x16x32_bf16 v[38:41], v[172:175], v[196:199], v[38:41]
	v_mfma_f32_16x16x32_bf16 v[34:37], v[180:183], v[196:199], v[34:37]
	v_mfma_f32_16x16x32_bf16 v[22:25], v[172:175], v[204:207], v[22:25]
	v_mfma_f32_16x16x32_bf16 v[18:21], v[180:183], v[204:207], v[18:21]
	v_mfma_f32_16x16x32_bf16 v[6:9], v[172:175], v[212:215], v[6:9]
	v_mfma_f32_16x16x32_bf16 v[2:5], v[180:183], v[212:215], v[2:5]
	s_setprio 2
	s_add_i32 s80, s80, 2
	s_add_u32 s4, s4, 0x100
	s_addc_u32 s5, s5, 0
	s_add_u32 s78, s78, 0x100
	s_addc_u32 s79, s79, 0
	s_cmp_gt_u32 s80, 13
	s_barrier
	s_cbranch_scc0 .LBB0_1058
	s_and_b64 vcc, exec, s[14:15]
	s_cbranch_vccz .LBB0_1061
	s_barrier

; #define PG8_STAGE(bufoff, gbase, voff) do { _Pragma("unroll") for (int _i = 0; _i < 2; ++_i) \
;         __builtin_amdgcn_global_load_lds((const unsigned*)((const char*)(gbase) + (voff)[_i]), (LAS unsigned*)(lds + (bufoff) + ldsw + _i * 8192), 16, 0, 0); } while (0)
; #define PG8_LDA(dst, b, h) do { _Pragma("unroll") for (int m = 0; m < 4; ++m) _Pragma("unroll") for (int k = 0; k < 2; ++k) dst[m][k] = *(const LAS bf16x8*)(lds + PG8_SA(b, h) + aoff + m * 2048 + k * 1024); } while (0)
; #define PG8_LDB(dst, b, h) do { _Pragma("unroll") for (int n = 0; n < 2; ++n) _Pragma("unroll") for (int k = 0; k < 2; ++k) dst[n][k] = *(const LAS bf16x8*)(lds + PG8_SB(b, h) + boff + n * 2048 + k * 1024); } while (0)
; #define PG8_MMA(ai, bj, At, Bt) do { __builtin_amdgcn_s_setprio(1); _Pragma("unroll") for (int m = 0; m < 4; ++m) _Pragma("unroll") for (int n = 0; n < 2; ++n) _Pragma("unroll") for (int k = 0; k < 2; ++k) \
;         acc[ai][bj][m][n] = __builtin_amdgcn_mfma_f32_16x16x32_bf16(Bt[n][k], At[m][k], acc[ai][bj][m][n], 0, 0, 0); __builtin_amdgcn_s_setprio(0); } while (0)
; template <class Epi>
; __device__ __forceinline__ void gemm_phase(LAS unsigned char* lds, const Gemm g, int G, int c, const Epi& E) {
;     ...
;         const bool has_next = S.next(ui + 1, nxt);
;         const char* nA = has_next ? (const char*)(g.A + (size_t)nxt.pb * g.sA) + (size_t)nxt.pm * 2 * hstepA : cA;
;         const char* nB = has_next ? (const char*)(g.Bt + (size_t)nxt.pb * g.sB) + (size_t)nxt.pn * 2 * hstepB : cB;
; #pragma nounroll
;         for (int t = 0; t < nt; t += 2) {
;             const bool last = (t == nt - 2);
;             const char* a1 = cA + (size_t)(t + 1) * kstep;
;             const char* a2 = last ? nA : cA + (size_t)(t + 2) * kstep; const char* b2 = last ? nB : cB + (size_t)(t + 2) * kstep;
;             const char* a3 = a2 + kstep; const char* b3 = b2 + kstep;
;             PG8_LDB(B0, 0, 0); PG8_LDB(B1, 0, 1); PG8_SCHED; PG8_LDA(At, 0, 0); PG8_STAGE(PG8_SA(1, 1), a1 + hstepA, voffA);
;             PG8_WAIT_V(8); PG8_WAIT_L(0); PG8_BAR; PG8_MMA(0, 0, At, B0); PG8_MMA(0, 1, At, B1); PG8_BAR; PG8_SCHED;
;             PG8_LDA(At, 0, 1); PG8_STAGE(PG8_SB(0, 0), b2, voffB); PG8_STAGE(PG8_SB(0, 1), b2 + hstepB, voffB); PG8_STAGE(PG8_SA(0, 0), a2, voffA);
;             PG8_WAIT_V(8); PG8_WAIT_L(0); PG8_BAR; PG8_MMA(1, 0, At, B0); PG8_MMA(1, 1, At, B1); PG8_BAR; PG8_SCHED;
.LBB0_1142:
	s_add_u32 s66, s18, 0x100
	s_addc_u32 s67, s19, 0
	s_mov_b32 s68, -2
	s_waitcnt vmcnt(0)
	ds_read_b128 v[122:125], v168
	ds_read_b128 v[126:129], v168 offset:1024
	ds_read_b128 v[130:133], v168 offset:2048
	ds_read_b128 v[134:137], v168 offset:3072
	ds_read_b128 v[162:165], v169
	ds_read_b128 v[172:175], v169 offset:1024
	ds_read_b128 v[176:179], v169 offset:2048
	ds_read_b128 v[180:183], v169 offset:3072
	s_add_u32 s18, s16, 0x100
	s_addc_u32 s19, s17, 0
	s_cmp_eq_u32 s68, 40
	s_cselect_b32 s23, s5, s19
	s_cselect_b32 s22, s4, s18
	s_cselect_b32 s21, s15, s67
	s_cselect_b32 s20, s14, s66
	v_lshl_add_u64 v[216:217], s[16:17], 0, v[154:155]
	s_add_i32 m0, s38, 0xc000
	ds_read_b128 v[184:187], v170
	ds_read_b128 v[188:191], v170 offset:1024
	ds_read_b128 v[192:195], v170 offset:2048
	ds_read_b128 v[196:199], v170 offset:3072
	ds_read_b128 v[200:203], v170 offset:4096
	ds_read_b128 v[204:207], v170 offset:5120
	ds_read_b128 v[208:211], v170 offset:6144
	ds_read_b128 v[212:215], v170 offset:7168
	global_load_lds_dwordx4 v[216:217], off
	v_lshl_add_u64 v[216:217], s[16:17], 0, v[156:157]
	s_add_i32 m0, s38, 0xe000
	s_nop 0
	global_load_lds_dwordx4 v[216:217], off
	s_waitcnt vmcnt(8)
	s_waitcnt lgkmcnt(0)
	s_barrier
	s_setprio 0
	v_mfma_f32_16x16x32_bf16 v[142:145], v[122:125], v[184:187], 0
	v_mfma_f32_16x16x32_bf16 v[138:141], v[130:133], v[184:187], 0
	v_mfma_f32_16x16x32_bf16 v[118:121], v[122:125], v[192:195], 0
	v_mfma_f32_16x16x32_bf16 v[106:109], v[130:133], v[192:195], 0
	v_mfma_f32_16x16x32_bf16 v[102:105], v[122:125], v[200:203], 0
	v_mfma_f32_16x16x32_bf16 v[90:93], v[130:133], v[200:203], 0
	v_mfma_f32_16x16x32_bf16 v[86:89], v[122:125], v[208:211], 0
	v_mfma_f32_16x16x32_bf16 v[74:77], v[130:133], v[208:211], 0
	v_mfma_f32_16x16x32_bf16 v[142:145], v[126:129], v[188:191], v[142:145]
	v_mfma_f32_16x16x32_bf16 v[138:141], v[134:137], v[188:191], v[138:141]
	v_mfma_f32_16x16x32_bf16 v[118:121], v[126:129], v[196:199], v[118:121]
	v_mfma_f32_16x16x32_bf16 v[106:109], v[134:137], v[196:199], v[106:109]
	v_mfma_f32_16x16x32_bf16 v[102:105], v[126:129], v[204:207], v[102:105]
	v_mfma_f32_16x16x32_bf16 v[90:93], v[134:137], v[204:207], v[90:93]
	v_mfma_f32_16x16x32_bf16 v[86:89], v[126:129], v[212:215], v[86:89]
	v_mfma_f32_16x16x32_bf16 v[74:77], v[134:137], v[212:215], v[74:77]
	s_setprio 2
	s_setprio 0
	v_mfma_f32_16x16x32_bf16 v[114:117], v[162:165], v[184:187], 0
	v_mfma_f32_16x16x32_bf16 v[110:113], v[176:179], v[184:187], 0
	v_mfma_f32_16x16x32_bf16 v[98:101], v[162:165], v[192:195], 0
	v_mfma_f32_16x16x32_bf16 v[94:97], v[176:179], v[192:195], 0
	v_mfma_f32_16x16x32_bf16 v[82:85], v[162:165], v[200:203], 0
	v_mfma_f32_16x16x32_bf16 v[78:81], v[176:179], v[200:203], 0
	v_mfma_f32_16x16x32_bf16 v[70:73], v[162:165], v[208:211], 0
	v_mfma_f32_16x16x32_bf16 v[66:69], v[176:179], v[208:211], 0
	v_mfma_f32_16x16x32_bf16 v[114:117], v[172:175], v[188:191], v[114:117]
	v_mfma_f32_16x16x32_bf16 v[110:113], v[180:183], v[188:191], v[110:113]
	v_mfma_f32_16x16x32_bf16 v[98:101], v[172:175], v[196:199], v[98:101]
	v_mfma_f32_16x16x32_bf16 v[94:97], v[180:183], v[196:199], v[94:97]
	v_mfma_f32_16x16x32_bf16 v[82:85], v[172:175], v[204:207], v[82:85]
	v_mfma_f32_16x16x32_bf16 v[78:81], v[180:183], v[204:207], v[78:81]
	v_mfma_f32_16x16x32_bf16 v[70:73], v[172:175], v[212:215], v[70:73]
	v_mfma_f32_16x16x32_bf16 v[66:69], v[180:183], v[212:215], v[66:69]
	s_setprio 2
	s_barrier
	s_add_i32 s16, s54, s36
	v_lshl_add_u64 v[216:217], s[20:21], 0, v[150:151]
	s_mov_b32 m0, s16
	ds_read_b128 v[184:187], v170 offset:16384
	ds_read_b128 v[188:191], v170 offset:17408
	ds_read_b128 v[192:195], v170 offset:18432
	ds_read_b128 v[196:199], v170 offset:19456
	ds_read_b128 v[200:203], v170 offset:20480
	ds_read_b128 v[204:207], v170 offset:21504
	ds_read_b128 v[208:211], v170 offset:22528
	ds_read_b128 v[212:215], v170 offset:23552
	global_load_lds_dwordx4 v[216:217], off
	s_add_i32 m0, s16, 0x2000
	s_add_u32 s16, s20, 0xb0000
	v_lshl_add_u64 v[218:219], s[20:21], 0, v[146:147]
	s_addc_u32 s17, s21, 0
	s_add_i32 s33, s55, s36
	global_load_lds_dwordx4 v[218:219], off
	v_lshl_add_u64 v[220:221], s[16:17], 0, v[150:151]
	s_mov_b32 m0, s33
	v_lshl_add_u64 v[222:223], s[22:23], 0, v[148:149]
	global_load_lds_dwordx4 v[220:221], off
	v_lshl_add_u64 v[220:221], s[16:17], 0, v[146:147]
	s_add_i32 m0, s33, 0x2000
	s_nop 0
	global_load_lds_dwordx4 v[220:221], off
	v_lshl_add_u64 v[220:221], s[22:23], 0, v[152:153]
	s_mov_b32 m0, s38
	s_nop 0
	global_load_lds_dwordx4 v[220:221], off
	s_mov_b32 m0, s39
	s_nop 0
	global_load_lds_dwordx4 v[222:223], off
	s_waitcnt vmcnt(8)
	s_waitcnt lgkmcnt(0)
	s_barrier
; #define PG8_STAGE(bufoff, gbase, voff) do { _Pragma("unroll") for (int _i = 0; _i < 2; ++_i) \
;         __builtin_amdgcn_global_load_lds((const unsigned*)((const char*)(gbase) + (voff)[_i]), (LAS unsigned*)(lds + (bufoff) + ldsw + _i * 8192), 16, 0, 0); } while (0)
; #define PG8_LDA(dst, b, h) do { _Pragma("unroll") for (int m = 0; m < 4; ++m) _Pragma("unroll") for (int k = 0; k < 2; ++k) dst[m][k] = *(const LAS bf16x8*)(lds + PG8_SA(b, h) + aoff + m * 2048 + k * 1024); } while (0)
; #define PG8_LDB(dst, b, h) do { _Pragma("unroll") for (int n = 0; n < 2; ++n) _Pragma("unroll") for (int k = 0; k < 2; ++k) dst[n][k] = *(const LAS bf16x8*)(lds + PG8_SB(b, h) + boff + n * 2048 + k * 1024); } while (0)
; #define PG8_MMA(ai, bj, At, Bt) do { __builtin_amdgcn_s_setprio(1); _Pragma("unroll") for (int m = 0; m < 4; ++m) _Pragma("unroll") for (int n = 0; n < 2; ++n) _Pragma("unroll") for (int k = 0; k < 2; ++k) \
;         acc[ai][bj][m][n] = __builtin_amdgcn_mfma_f32_16x16x32_bf16(Bt[n][k], At[m][k], acc[ai][bj][m][n], 0, 0, 0); __builtin_amdgcn_s_setprio(0); } while (0)
; #define PG8_WAIT_V(n) asm volatile("s_waitcnt vmcnt(" #n ")" ::: "memory")
; #define PG8_WAIT_L(n) asm volatile("s_waitcnt lgkmcnt(" #n ")" ::: "memory")
; #define PG8_BAR __builtin_amdgcn_s_barrier()
; #define PG8_SCHED __builtin_amdgcn_sched_barrier(0)
; template <class Epi>
; __device__ __forceinline__ void gemm_phase(LAS unsigned char* lds, const Gemm g, int G, int c, const Epi& E) {
;     ...
;             PG8_WAIT_V(8); PG8_WAIT_L(0); PG8_BAR; PG8_MMA(1, 0, At, B0); PG8_MMA(1, 1, At, B1); PG8_BAR; PG8_SCHED;
;             PG8_LDB(B0, 1, 0); PG8_LDB(B1, 1, 1); PG8_SCHED; PG8_LDA(At, 1, 0); PG8_STAGE(PG8_SA(0, 1), a2 + hstepA, voffA);
;             PG8_WAIT_V(8); PG8_WAIT_L(0); PG8_BAR; PG8_MMA(0, 0, At, B0); PG8_MMA(0, 1, At, B1); PG8_BAR; PG8_SCHED;
	s_setprio 0
	v_mfma_f32_16x16x32_bf16 v[62:65], v[122:125], v[184:187], 0
	v_mfma_f32_16x16x32_bf16 v[58:61], v[130:133], v[184:187], 0
	v_mfma_f32_16x16x32_bf16 v[54:57], v[122:125], v[192:195], 0
	v_mfma_f32_16x16x32_bf16 v[42:45], v[130:133], v[192:195], 0
	v_mfma_f32_16x16x32_bf16 v[38:41], v[122:125], v[200:203], 0
	v_mfma_f32_16x16x32_bf16 v[26:29], v[130:133], v[200:203], 0
	v_mfma_f32_16x16x32_bf16 v[22:25], v[122:125], v[208:211], 0
	v_mfma_f32_16x16x32_bf16 v[10:13], v[130:133], v[208:211], 0
	v_mfma_f32_16x16x32_bf16 v[62:65], v[126:129], v[188:191], v[62:65]
	v_mfma_f32_16x16x32_bf16 v[58:61], v[134:137], v[188:191], v[58:61]
	v_mfma_f32_16x16x32_bf16 v[54:57], v[126:129], v[196:199], v[54:57]
	v_mfma_f32_16x16x32_bf16 v[42:45], v[134:137], v[196:199], v[42:45]
	v_mfma_f32_16x16x32_bf16 v[38:41], v[126:129], v[204:207], v[38:41]
	v_mfma_f32_16x16x32_bf16 v[26:29], v[134:137], v[204:207], v[26:29]
	v_mfma_f32_16x16x32_bf16 v[22:25], v[126:129], v[212:215], v[22:25]
	v_mfma_f32_16x16x32_bf16 v[10:13], v[134:137], v[212:215], v[10:13]
	s_setprio 2
	s_setprio 0
	v_mfma_f32_16x16x32_bf16 v[50:53], v[162:165], v[184:187], 0
	v_mfma_f32_16x16x32_bf16 v[46:49], v[176:179], v[184:187], 0
	v_mfma_f32_16x16x32_bf16 v[34:37], v[162:165], v[192:195], 0
	v_mfma_f32_16x16x32_bf16 v[30:33], v[176:179], v[192:195], 0
	v_mfma_f32_16x16x32_bf16 v[18:21], v[162:165], v[200:203], 0
	v_mfma_f32_16x16x32_bf16 v[14:17], v[176:179], v[200:203], 0
	v_mfma_f32_16x16x32_bf16 v[6:9], v[162:165], v[208:211], 0
	v_mfma_f32_16x16x32_bf16 v[2:5], v[176:179], v[208:211], 0
	v_mfma_f32_16x16x32_bf16 v[50:53], v[172:175], v[188:191], v[50:53]
	v_mfma_f32_16x16x32_bf16 v[46:49], v[180:183], v[188:191], v[46:49]
	v_mfma_f32_16x16x32_bf16 v[34:37], v[172:175], v[196:199], v[34:37]
	v_mfma_f32_16x16x32_bf16 v[30:33], v[180:183], v[196:199], v[30:33]
	v_mfma_f32_16x16x32_bf16 v[18:21], v[172:175], v[204:207], v[18:21]
	v_mfma_f32_16x16x32_bf16 v[14:17], v[180:183], v[204:207], v[14:17]
	v_mfma_f32_16x16x32_bf16 v[6:9], v[172:175], v[212:215], v[6:9]
	v_mfma_f32_16x16x32_bf16 v[2:5], v[180:183], v[212:215], v[2:5]
	s_setprio 2
	s_barrier
	s_add_i32 s33, 0, 0x18000
	s_add_i32 s62, 0, 0x1c000
	v_add_u32_e32 v134, s33, v167
	v_add_u32_e32 v171, s62, v167
	ds_read_b128 v[122:125], v134
	ds_read_b128 v[126:129], v134 offset:1024
	ds_read_b128 v[130:133], v134 offset:2048
	ds_read_b128 v[134:137], v134 offset:3072
	ds_read_b128 v[162:165], v171
	ds_read_b128 v[172:175], v171 offset:1024
	ds_read_b128 v[176:179], v171 offset:2048
	ds_read_b128 v[180:183], v171 offset:3072
	s_add_u32 s16, s22, 0xb0000
	s_addc_u32 s17, s23, 0
	s_mov_b32 m0, s40
	v_lshl_add_u64 v[224:225], s[16:17], 0, v[152:153]
	ds_read_b128 v[184:187], v170 offset:32768
	ds_read_b128 v[188:191], v170 offset:33792
	ds_read_b128 v[192:195], v170 offset:34816
	ds_read_b128 v[196:199], v170 offset:35840
	ds_read_b128 v[200:203], v170 offset:36864
	ds_read_b128 v[204:207], v170 offset:37888
	ds_read_b128 v[208:211], v170 offset:38912
	ds_read_b128 v[212:215], v170 offset:39936
	global_load_lds_dwordx4 v[224:225], off
	v_lshl_add_u64 v[224:225], s[16:17], 0, v[148:149]
	s_mov_b32 m0, s41
	s_nop 0
	global_load_lds_dwordx4 v[224:225], off
	s_waitcnt vmcnt(8)
	s_waitcnt lgkmcnt(0)
	s_barrier
	s_setprio 0
	v_mfma_f32_16x16x32_bf16 v[142:145], v[122:125], v[184:187], v[142:145]
	v_mfma_f32_16x16x32_bf16 v[138:141], v[130:133], v[184:187], v[138:141]
	v_mfma_f32_16x16x32_bf16 v[118:121], v[122:125], v[192:195], v[118:121]
	v_mfma_f32_16x16x32_bf16 v[106:109], v[130:133], v[192:195], v[106:109]
	v_mfma_f32_16x16x32_bf16 v[102:105], v[122:125], v[200:203], v[102:105]
	v_mfma_f32_16x16x32_bf16 v[90:93], v[130:133], v[200:203], v[90:93]
	v_mfma_f32_16x16x32_bf16 v[86:89], v[122:125], v[208:211], v[86:89]
	v_mfma_f32_16x16x32_bf16 v[74:77], v[130:133], v[208:211], v[74:77]
	v_mfma_f32_16x16x32_bf16 v[142:145], v[126:129], v[188:191], v[142:145]
	v_mfma_f32_16x16x32_bf16 v[138:141], v[134:137], v[188:191], v[138:141]
	v_mfma_f32_16x16x32_bf16 v[118:121], v[126:129], v[196:199], v[118:121]
	v_mfma_f32_16x16x32_bf16 v[106:109], v[134:137], v[196:199], v[106:109]
	v_mfma_f32_16x16x32_bf16 v[102:105], v[126:129], v[204:207], v[102:105]
	v_mfma_f32_16x16x32_bf16 v[90:93], v[134:137], v[204:207], v[90:93]
	v_mfma_f32_16x16x32_bf16 v[86:89], v[126:129], v[212:215], v[86:89]
	v_mfma_f32_16x16x32_bf16 v[74:77], v[134:137], v[212:215], v[74:77]
	s_setprio 2
	s_setprio 0
	v_mfma_f32_16x16x32_bf16 v[114:117], v[162:165], v[184:187], v[114:117]
	v_mfma_f32_16x16x32_bf16 v[110:113], v[176:179], v[184:187], v[110:113]
	v_mfma_f32_16x16x32_bf16 v[98:101], v[162:165], v[192:195], v[98:101]
	v_mfma_f32_16x16x32_bf16 v[94:97], v[176:179], v[192:195], v[94:97]
	v_mfma_f32_16x16x32_bf16 v[82:85], v[162:165], v[200:203], v[82:85]
	v_mfma_f32_16x16x32_bf16 v[78:81], v[176:179], v[200:203], v[78:81]
	v_mfma_f32_16x16x32_bf16 v[70:73], v[162:165], v[208:211], v[70:73]
	v_mfma_f32_16x16x32_bf16 v[66:69], v[176:179], v[208:211], v[66:69]
	v_mfma_f32_16x16x32_bf16 v[114:117], v[172:175], v[188:191], v[114:117]
	v_mfma_f32_16x16x32_bf16 v[110:113], v[180:183], v[188:191], v[110:113]
	v_mfma_f32_16x16x32_bf16 v[98:101], v[172:175], v[196:199], v[98:101]
	v_mfma_f32_16x16x32_bf16 v[94:97], v[180:183], v[196:199], v[94:97]
	v_mfma_f32_16x16x32_bf16 v[82:85], v[172:175], v[204:207], v[82:85]
	v_mfma_f32_16x16x32_bf16 v[78:81], v[180:183], v[204:207], v[78:81]
	v_mfma_f32_16x16x32_bf16 v[70:73], v[172:175], v[212:215], v[70:73]
	v_mfma_f32_16x16x32_bf16 v[66:69], v[180:183], v[212:215], v[66:69]
	s_setprio 2
	s_barrier
; #define PG8_STAGE(bufoff, gbase, voff) do { _Pragma("unroll") for (int _i = 0; _i < 2; ++_i) \
;         __builtin_amdgcn_global_load_lds((const unsigned*)((const char*)(gbase) + (voff)[_i]), (LAS unsigned*)(lds + (bufoff) + ldsw + _i * 8192), 16, 0, 0); } while (0)
; #define PG8_LDA(dst, b, h) do { _Pragma("unroll") for (int m = 0; m < 4; ++m) _Pragma("unroll") for (int k = 0; k < 2; ++k) dst[m][k] = *(const LAS bf16x8*)(lds + PG8_SA(b, h) + aoff + m * 2048 + k * 1024); } while (0)
; #define PG8_LDB(dst, b, h) do { _Pragma("unroll") for (int n = 0; n < 2; ++n) _Pragma("unroll") for (int k = 0; k < 2; ++k) dst[n][k] = *(const LAS bf16x8*)(lds + PG8_SB(b, h) + boff + n * 2048 + k * 1024); } while (0)
; #define PG8_WAIT_V(n) asm volatile("s_waitcnt vmcnt(" #n ")" ::: "memory")
; #define PG8_WAIT_L(n) asm volatile("s_waitcnt lgkmcnt(" #n ")" ::: "memory")
; template <class Epi>
; __device__ __forceinline__ void gemm_phase(LAS unsigned char* lds, const Gemm g, int G, int c, const Epi& E) {
;     ...
;         for (int t = 0; t < nt; t += 2) {
;             const bool last = (t == nt - 2);
;             const char* a1 = cA + (size_t)(t + 1) * kstep;
;             const char* a2 = last ? nA : cA + (size_t)(t + 2) * kstep; const char* b2 = last ? nB : cB + (size_t)(t + 2) * kstep;
;             const char* a3 = a2 + kstep; const char* b3 = b2 + kstep;
;             PG8_LDB(B0, 0, 0); PG8_LDB(B1, 0, 1); PG8_SCHED; PG8_LDA(At, 0, 0); PG8_STAGE(PG8_SA(1, 1), a1 + hstepA, voffA);
;             PG8_WAIT_V(8); PG8_WAIT_L(0); PG8_BAR; PG8_MMA(0, 0, At, B0); PG8_MMA(0, 1, At, B1); PG8_BAR; PG8_SCHED;
;             PG8_LDA(At, 0, 1); PG8_STAGE(PG8_SB(0, 0), b2, voffB); PG8_STAGE(PG8_SB(0, 1), b2 + hstepB, voffB); PG8_STAGE(PG8_SA(0, 0), a2, voffA);
;             PG8_WAIT_V(8); PG8_WAIT_L(0); PG8_BAR; PG8_MMA(1, 0, At, B0); PG8_MMA(1, 1, At, B1); PG8_BAR; PG8_SCHED;
;             PG8_LDB(B0, 1, 0); PG8_LDB(B1, 1, 1); PG8_SCHED; PG8_LDA(At, 1, 0); PG8_STAGE(PG8_SA(0, 1), a2 + hstepA, voffA);
;             PG8_WAIT_V(8); PG8_WAIT_L(0); PG8_BAR; PG8_MMA(0, 0, At, B0); PG8_MMA(0, 1, At, B1); PG8_BAR; PG8_SCHED;
;             PG8_LDA(At, 1, 1); PG8_STAGE(PG8_SB(1, 0), b3, voffB); PG8_STAGE(PG8_SB(1, 1), b3 + hstepB, voffB); PG8_STAGE(PG8_SA(1, 0), a3, voffA);
;             PG8_WAIT_V(8); PG8_WAIT_L(0); PG8_BAR; PG8_MMA(1, 0, At, B0); PG8_MMA(1, 1, At, B1); PG8_BAR; PG8_SCHED;
	s_add_i32 s16, s33, s36
	v_lshl_add_u64 v[216:217], v[216:217], 0, s[10:11]
	s_mov_b32 m0, s16
	ds_read_b128 v[184:187], v170 offset:49152
	ds_read_b128 v[188:191], v170 offset:50176
	ds_read_b128 v[192:195], v170 offset:51200
	ds_read_b128 v[196:199], v170 offset:52224
	ds_read_b128 v[200:203], v170 offset:53248
	ds_read_b128 v[204:207], v170 offset:54272
	ds_read_b128 v[208:211], v170 offset:55296
	ds_read_b128 v[212:215], v170 offset:56320
	global_load_lds_dwordx4 v[216:217], off
	s_add_i32 m0, s16, 0x2000
	s_add_u32 s16, s20, 0xb0080
	v_lshl_add_u64 v[216:217], v[218:219], 0, s[10:11]
	s_addc_u32 s17, s21, 0
	s_add_i32 s20, s62, s36
	global_load_lds_dwordx4 v[216:217], off
	v_lshl_add_u64 v[216:217], s[16:17], 0, v[150:151]
	s_mov_b32 m0, s20
	s_nop 0
	global_load_lds_dwordx4 v[216:217], off
	v_lshl_add_u64 v[216:217], s[16:17], 0, v[146:147]
	s_add_i32 m0, s20, 0x2000
	s_nop 0
	global_load_lds_dwordx4 v[216:217], off
	v_lshl_add_u64 v[216:217], v[220:221], 0, s[10:11]
	s_mov_b32 m0, s47
	s_nop 0
	global_load_lds_dwordx4 v[216:217], off
	v_lshl_add_u64 v[216:217], v[222:223], 0, s[10:11]
	s_mov_b32 m0, s52
	s_nop 0
	global_load_lds_dwordx4 v[216:217], off
	s_waitcnt vmcnt(8)
	s_waitcnt lgkmcnt(0)
	s_barrier
	s_setprio 0
	v_mfma_f32_16x16x32_bf16 v[62:65], v[122:125], v[184:187], v[62:65]
	v_mfma_f32_16x16x32_bf16 v[58:61], v[130:133], v[184:187], v[58:61]
	v_mfma_f32_16x16x32_bf16 v[54:57], v[122:125], v[192:195], v[54:57]
	v_mfma_f32_16x16x32_bf16 v[42:45], v[130:133], v[192:195], v[42:45]
	v_mfma_f32_16x16x32_bf16 v[38:41], v[122:125], v[200:203], v[38:41]
	v_mfma_f32_16x16x32_bf16 v[26:29], v[130:133], v[200:203], v[26:29]
	v_mfma_f32_16x16x32_bf16 v[22:25], v[122:125], v[208:211], v[22:25]
	v_mfma_f32_16x16x32_bf16 v[10:13], v[130:133], v[208:211], v[10:13]
	v_mfma_f32_16x16x32_bf16 v[62:65], v[126:129], v[188:191], v[62:65]
	v_mfma_f32_16x16x32_bf16 v[58:61], v[134:137], v[188:191], v[58:61]
	v_mfma_f32_16x16x32_bf16 v[54:57], v[126:129], v[196:199], v[54:57]
	v_mfma_f32_16x16x32_bf16 v[42:45], v[134:137], v[196:199], v[42:45]
	v_mfma_f32_16x16x32_bf16 v[38:41], v[126:129], v[204:207], v[38:41]
	v_mfma_f32_16x16x32_bf16 v[26:29], v[134:137], v[204:207], v[26:29]
	v_mfma_f32_16x16x32_bf16 v[22:25], v[126:129], v[212:215], v[22:25]
	v_mfma_f32_16x16x32_bf16 v[10:13], v[134:137], v[212:215], v[10:13]
	s_setprio 2
	s_setprio 0
	v_mfma_f32_16x16x32_bf16 v[50:53], v[162:165], v[184:187], v[50:53]
	v_mfma_f32_16x16x32_bf16 v[46:49], v[176:179], v[184:187], v[46:49]
	v_mfma_f32_16x16x32_bf16 v[34:37], v[162:165], v[192:195], v[34:37]
	v_mfma_f32_16x16x32_bf16 v[30:33], v[176:179], v[192:195], v[30:33]
	v_mfma_f32_16x16x32_bf16 v[18:21], v[162:165], v[200:203], v[18:21]
	v_mfma_f32_16x16x32_bf16 v[14:17], v[176:179], v[200:203], v[14:17]
	v_mfma_f32_16x16x32_bf16 v[6:9], v[162:165], v[208:211], v[6:9]
	v_mfma_f32_16x16x32_bf16 v[2:5], v[176:179], v[208:211], v[2:5]
	v_mfma_f32_16x16x32_bf16 v[50:53], v[172:175], v[188:191], v[50:53]
	v_mfma_f32_16x16x32_bf16 v[46:49], v[180:183], v[188:191], v[46:49]
	v_mfma_f32_16x16x32_bf16 v[34:37], v[172:175], v[196:199], v[34:37]
	v_mfma_f32_16x16x32_bf16 v[30:33], v[180:183], v[196:199], v[30:33]
	v_mfma_f32_16x16x32_bf16 v[18:21], v[172:175], v[204:207], v[18:21]
	v_mfma_f32_16x16x32_bf16 v[14:17], v[180:183], v[204:207], v[14:17]
	v_mfma_f32_16x16x32_bf16 v[6:9], v[172:175], v[212:215], v[6:9]
	v_mfma_f32_16x16x32_bf16 v[2:5], v[180:183], v[212:215], v[2:5]
	s_setprio 2
	s_add_i32 s68, s68, 2
	s_add_u32 s66, s66, 0x100
	s_addc_u32 s67, s67, 0
	s_cmp_gt_u32 s68, 41
	s_mov_b64 s[16:17], s[18:19]
	s_barrier
	s_cbranch_scc0 .LBB0_1143
.LBB0_1143:
	ds_read_b128 v[122:125], v168
	ds_read_b128 v[126:129], v168 offset:1024
	ds_read_b128 v[130:133], v168 offset:2048
	ds_read_b128 v[134:137], v168 offset:3072
	ds_read_b128 v[162:165], v169
	ds_read_b128 v[172:175], v169 offset:1024
	ds_read_b128 v[176:179], v169 offset:2048
	ds_read_b128 v[180:183], v169 offset:3072
	s_add_u32 s18, s16, 0x100
	s_addc_u32 s19, s17, 0
	s_cmp_eq_u32 s68, 40
	s_cselect_b32 s23, s5, s19
	s_cselect_b32 s22, s4, s18
	s_cselect_b32 s21, s15, s67
	s_cselect_b32 s20, s14, s66
	v_lshl_add_u64 v[216:217], s[16:17], 0, v[154:155]
	s_add_i32 m0, s38, 0xc000
	ds_read_b128 v[184:187], v170
	ds_read_b128 v[188:191], v170 offset:1024
	ds_read_b128 v[192:195], v170 offset:2048
	ds_read_b128 v[196:199], v170 offset:3072
	ds_read_b128 v[200:203], v170 offset:4096
	ds_read_b128 v[204:207], v170 offset:5120
	ds_read_b128 v[208:211], v170 offset:6144
	ds_read_b128 v[212:215], v170 offset:7168
	global_load_lds_dwordx4 v[216:217], off
	v_lshl_add_u64 v[216:217], s[16:17], 0, v[156:157]
	s_add_i32 m0, s38, 0xe000
	s_nop 0
	global_load_lds_dwordx4 v[216:217], off
	s_waitcnt vmcnt(8)
	s_waitcnt lgkmcnt(0)
	s_barrier
; #define PG8_STAGE(bufoff, gbase, voff) do { _Pragma("unroll") for (int _i = 0; _i < 2; ++_i) \
;         __builtin_amdgcn_global_load_lds((const unsigned*)((const char*)(gbase) + (voff)[_i]), (LAS unsigned*)(lds + (bufoff) + ldsw + _i * 8192), 16, 0, 0); } while (0)
; #define PG8_LDA(dst, b, h) do { _Pragma("unroll") for (int m = 0; m < 4; ++m) _Pragma("unroll") for (int k = 0; k < 2; ++k) dst[m][k] = *(const LAS bf16x8*)(lds + PG8_SA(b, h) + aoff + m * 2048 + k * 1024); } while (0)
; #define PG8_MMA(ai, bj, At, Bt) do { __builtin_amdgcn_s_setprio(1); _Pragma("unroll") for (int m = 0; m < 4; ++m) _Pragma("unroll") for (int n = 0; n < 2; ++n) _Pragma("unroll") for (int k = 0; k < 2; ++k) \
;         acc[ai][bj][m][n] = __builtin_amdgcn_mfma_f32_16x16x32_bf16(Bt[n][k], At[m][k], acc[ai][bj][m][n], 0, 0, 0); __builtin_amdgcn_s_setprio(0); } while (0)
; #define PG8_WAIT_V(n) asm volatile("s_waitcnt vmcnt(" #n ")" ::: "memory")
; #define PG8_WAIT_L(n) asm volatile("s_waitcnt lgkmcnt(" #n ")" ::: "memory")
; #define PG8_BAR __builtin_amdgcn_s_barrier()
; #define PG8_SCHED __builtin_amdgcn_sched_barrier(0)
; template <class Epi>
; __device__ __forceinline__ void gemm_phase(LAS unsigned char* lds, const Gemm g, int G, int c, const Epi& E) {
;     ...
;             PG8_WAIT_V(8); PG8_WAIT_L(0); PG8_BAR; PG8_MMA(0, 0, At, B0); PG8_MMA(0, 1, At, B1); PG8_BAR; PG8_SCHED;
;             PG8_LDA(At, 0, 1); PG8_STAGE(PG8_SB(0, 0), b2, voffB); PG8_STAGE(PG8_SB(0, 1), b2 + hstepB, voffB); PG8_STAGE(PG8_SA(0, 0), a2, voffA);
;             PG8_WAIT_V(8); PG8_WAIT_L(0); PG8_BAR; PG8_MMA(1, 0, At, B0); PG8_MMA(1, 1, At, B1); PG8_BAR; PG8_SCHED;
	s_setprio 0
	v_mfma_f32_16x16x32_bf16 v[142:145], v[122:125], v[184:187], v[142:145]
	v_mfma_f32_16x16x32_bf16 v[138:141], v[130:133], v[184:187], v[138:141]
	v_mfma_f32_16x16x32_bf16 v[118:121], v[122:125], v[192:195], v[118:121]
	v_mfma_f32_16x16x32_bf16 v[106:109], v[130:133], v[192:195], v[106:109]
	v_mfma_f32_16x16x32_bf16 v[102:105], v[122:125], v[200:203], v[102:105]
	v_mfma_f32_16x16x32_bf16 v[90:93], v[130:133], v[200:203], v[90:93]
	v_mfma_f32_16x16x32_bf16 v[86:89], v[122:125], v[208:211], v[86:89]
	v_mfma_f32_16x16x32_bf16 v[74:77], v[130:133], v[208:211], v[74:77]
	v_mfma_f32_16x16x32_bf16 v[142:145], v[126:129], v[188:191], v[142:145]
	v_mfma_f32_16x16x32_bf16 v[138:141], v[134:137], v[188:191], v[138:141]
	v_mfma_f32_16x16x32_bf16 v[118:121], v[126:129], v[196:199], v[118:121]
	v_mfma_f32_16x16x32_bf16 v[106:109], v[134:137], v[196:199], v[106:109]
	v_mfma_f32_16x16x32_bf16 v[102:105], v[126:129], v[204:207], v[102:105]
	v_mfma_f32_16x16x32_bf16 v[90:93], v[134:137], v[204:207], v[90:93]
	v_mfma_f32_16x16x32_bf16 v[86:89], v[126:129], v[212:215], v[86:89]
	v_mfma_f32_16x16x32_bf16 v[74:77], v[134:137], v[212:215], v[74:77]
	s_setprio 2
	s_setprio 0
	v_mfma_f32_16x16x32_bf16 v[114:117], v[162:165], v[184:187], v[114:117]
	v_mfma_f32_16x16x32_bf16 v[110:113], v[176:179], v[184:187], v[110:113]
	v_mfma_f32_16x16x32_bf16 v[98:101], v[162:165], v[192:195], v[98:101]
	v_mfma_f32_16x16x32_bf16 v[94:97], v[176:179], v[192:195], v[94:97]
	v_mfma_f32_16x16x32_bf16 v[82:85], v[162:165], v[200:203], v[82:85]
	v_mfma_f32_16x16x32_bf16 v[78:81], v[176:179], v[200:203], v[78:81]
	v_mfma_f32_16x16x32_bf16 v[70:73], v[162:165], v[208:211], v[70:73]
	v_mfma_f32_16x16x32_bf16 v[66:69], v[176:179], v[208:211], v[66:69]
	v_mfma_f32_16x16x32_bf16 v[114:117], v[172:175], v[188:191], v[114:117]
	v_mfma_f32_16x16x32_bf16 v[110:113], v[180:183], v[188:191], v[110:113]
	v_mfma_f32_16x16x32_bf16 v[98:101], v[172:175], v[196:199], v[98:101]
	v_mfma_f32_16x16x32_bf16 v[94:97], v[180:183], v[196:199], v[94:97]
	v_mfma_f32_16x16x32_bf16 v[82:85], v[172:175], v[204:207], v[82:85]
	v_mfma_f32_16x16x32_bf16 v[78:81], v[180:183], v[204:207], v[78:81]
	v_mfma_f32_16x16x32_bf16 v[70:73], v[172:175], v[212:215], v[70:73]
	v_mfma_f32_16x16x32_bf16 v[66:69], v[180:183], v[212:215], v[66:69]
	s_setprio 2
	s_barrier
	s_add_i32 s16, s54, s36
	v_lshl_add_u64 v[216:217], s[20:21], 0, v[150:151]
	s_mov_b32 m0, s16
	ds_read_b128 v[184:187], v170 offset:16384
	ds_read_b128 v[188:191], v170 offset:17408
	ds_read_b128 v[192:195], v170 offset:18432
	ds_read_b128 v[196:199], v170 offset:19456
	ds_read_b128 v[200:203], v170 offset:20480
	ds_read_b128 v[204:207], v170 offset:21504
	ds_read_b128 v[208:211], v170 offset:22528
	ds_read_b128 v[212:215], v170 offset:23552
	global_load_lds_dwordx4 v[216:217], off
	s_add_i32 m0, s16, 0x2000
	s_add_u32 s16, s20, 0xb0000
	v_lshl_add_u64 v[218:219], s[20:21], 0, v[146:147]
	s_addc_u32 s17, s21, 0
	s_add_i32 s33, s55, s36
	global_load_lds_dwordx4 v[218:219], off
	v_lshl_add_u64 v[220:221], s[16:17], 0, v[150:151]
	s_mov_b32 m0, s33
	v_lshl_add_u64 v[222:223], s[22:23], 0, v[148:149]
	global_load_lds_dwordx4 v[220:221], off
	v_lshl_add_u64 v[220:221], s[16:17], 0, v[146:147]
	s_add_i32 m0, s33, 0x2000
	s_nop 0
	global_load_lds_dwordx4 v[220:221], off
	v_lshl_add_u64 v[220:221], s[22:23], 0, v[152:153]
	s_mov_b32 m0, s38
	s_nop 0
	global_load_lds_dwordx4 v[220:221], off
	s_mov_b32 m0, s39
	s_nop 0
	global_load_lds_dwordx4 v[222:223], off
	s_waitcnt vmcnt(8)
	s_waitcnt lgkmcnt(0)
	s_barrier
	s_setprio 0
	v_mfma_f32_16x16x32_bf16 v[62:65], v[122:125], v[184:187], v[62:65]
	v_mfma_f32_16x16x32_bf16 v[58:61], v[130:133], v[184:187], v[58:61]
	v_mfma_f32_16x16x32_bf16 v[54:57], v[122:125], v[192:195], v[54:57]
	v_mfma_f32_16x16x32_bf16 v[42:45], v[130:133], v[192:195], v[42:45]
	v_mfma_f32_16x16x32_bf16 v[38:41], v[122:125], v[200:203], v[38:41]
	v_mfma_f32_16x16x32_bf16 v[26:29], v[130:133], v[200:203], v[26:29]
	v_mfma_f32_16x16x32_bf16 v[22:25], v[122:125], v[208:211], v[22:25]
	v_mfma_f32_16x16x32_bf16 v[10:13], v[130:133], v[208:211], v[10:13]
	v_mfma_f32_16x16x32_bf16 v[62:65], v[126:129], v[188:191], v[62:65]
	v_mfma_f32_16x16x32_bf16 v[58:61], v[134:137], v[188:191], v[58:61]
	v_mfma_f32_16x16x32_bf16 v[54:57], v[126:129], v[196:199], v[54:57]
	v_mfma_f32_16x16x32_bf16 v[42:45], v[134:137], v[196:199], v[42:45]
	v_mfma_f32_16x16x32_bf16 v[38:41], v[126:129], v[204:207], v[38:41]
	v_mfma_f32_16x16x32_bf16 v[26:29], v[134:137], v[204:207], v[26:29]
	v_mfma_f32_16x16x32_bf16 v[22:25], v[126:129], v[212:215], v[22:25]
	v_mfma_f32_16x16x32_bf16 v[10:13], v[134:137], v[212:215], v[10:13]
	s_setprio 2
	s_setprio 0
	v_mfma_f32_16x16x32_bf16 v[50:53], v[162:165], v[184:187], v[50:53]
	v_mfma_f32_16x16x32_bf16 v[46:49], v[176:179], v[184:187], v[46:49]
	v_mfma_f32_16x16x32_bf16 v[34:37], v[162:165], v[192:195], v[34:37]
	v_mfma_f32_16x16x32_bf16 v[30:33], v[176:179], v[192:195], v[30:33]
	v_mfma_f32_16x16x32_bf16 v[18:21], v[162:165], v[200:203], v[18:21]
	v_mfma_f32_16x16x32_bf16 v[14:17], v[176:179], v[200:203], v[14:17]
	v_mfma_f32_16x16x32_bf16 v[6:9], v[162:165], v[208:211], v[6:9]
	v_mfma_f32_16x16x32_bf16 v[2:5], v[176:179], v[208:211], v[2:5]
	v_mfma_f32_16x16x32_bf16 v[50:53], v[172:175], v[188:191], v[50:53]
	v_mfma_f32_16x16x32_bf16 v[46:49], v[180:183], v[188:191], v[46:49]
	v_mfma_f32_16x16x32_bf16 v[34:37], v[172:175], v[196:199], v[34:37]
	v_mfma_f32_16x16x32_bf16 v[30:33], v[180:183], v[196:199], v[30:33]
	v_mfma_f32_16x16x32_bf16 v[18:21], v[172:175], v[204:207], v[18:21]
	v_mfma_f32_16x16x32_bf16 v[14:17], v[180:183], v[204:207], v[14:17]
	v_mfma_f32_16x16x32_bf16 v[6:9], v[172:175], v[212:215], v[6:9]
	v_mfma_f32_16x16x32_bf16 v[2:5], v[180:183], v[212:215], v[2:5]
	s_setprio 2
	s_barrier
; #define PG8_STAGE(bufoff, gbase, voff) do { _Pragma("unroll") for (int _i = 0; _i < 2; ++_i) \
;         __builtin_amdgcn_global_load_lds((const unsigned*)((const char*)(gbase) + (voff)[_i]), (LAS unsigned*)(lds + (bufoff) + ldsw + _i * 8192), 16, 0, 0); } while (0)
; #define PG8_LDA(dst, b, h) do { _Pragma("unroll") for (int m = 0; m < 4; ++m) _Pragma("unroll") for (int k = 0; k < 2; ++k) dst[m][k] = *(const LAS bf16x8*)(lds + PG8_SA(b, h) + aoff + m * 2048 + k * 1024); } while (0)
; #define PG8_LDB(dst, b, h) do { _Pragma("unroll") for (int n = 0; n < 2; ++n) _Pragma("unroll") for (int k = 0; k < 2; ++k) dst[n][k] = *(const LAS bf16x8*)(lds + PG8_SB(b, h) + boff + n * 2048 + k * 1024); } while (0)
; #define PG8_MMA(ai, bj, At, Bt) do { __builtin_amdgcn_s_setprio(1); _Pragma("unroll") for (int m = 0; m < 4; ++m) _Pragma("unroll") for (int n = 0; n < 2; ++n) _Pragma("unroll") for (int k = 0; k < 2; ++k) \
;         acc[ai][bj][m][n] = __builtin_amdgcn_mfma_f32_16x16x32_bf16(Bt[n][k], At[m][k], acc[ai][bj][m][n], 0, 0, 0); __builtin_amdgcn_s_setprio(0); } while (0)
; #define PG8_WAIT_V(n) asm volatile("s_waitcnt vmcnt(" #n ")" ::: "memory")
; #define PG8_WAIT_L(n) asm volatile("s_waitcnt lgkmcnt(" #n ")" ::: "memory")
; #define PG8_BAR __builtin_amdgcn_s_barrier()
; #define PG8_SCHED __builtin_amdgcn_sched_barrier(0)
; template <class Epi>
; __device__ __forceinline__ void gemm_phase(LAS unsigned char* lds, const Gemm g, int G, int c, const Epi& E) {
;     ...
;             PG8_LDB(B0, 1, 0); PG8_LDB(B1, 1, 1); PG8_SCHED; PG8_LDA(At, 1, 0); PG8_STAGE(PG8_SA(0, 1), a2 + hstepA, voffA);
;             PG8_WAIT_V(8); PG8_WAIT_L(0); PG8_BAR; PG8_MMA(0, 0, At, B0); PG8_MMA(0, 1, At, B1); PG8_BAR; PG8_SCHED;
	s_add_i32 s33, 0, 0x18000
	s_add_i32 s62, 0, 0x1c000
	v_add_u32_e32 v134, s33, v167
	v_add_u32_e32 v171, s62, v167
	ds_read_b128 v[122:125], v134
	ds_read_b128 v[126:129], v134 offset:1024
	ds_read_b128 v[130:133], v134 offset:2048
	ds_read_b128 v[134:137], v134 offset:3072
	ds_read_b128 v[162:165], v171
	ds_read_b128 v[172:175], v171 offset:1024
	ds_read_b128 v[176:179], v171 offset:2048
	ds_read_b128 v[180:183], v171 offset:3072
	s_add_u32 s16, s22, 0xb0000
	s_addc_u32 s17, s23, 0
	s_mov_b32 m0, s40
	v_lshl_add_u64 v[224:225], s[16:17], 0, v[152:153]
	ds_read_b128 v[184:187], v170 offset:32768
	ds_read_b128 v[188:191], v170 offset:33792
	ds_read_b128 v[192:195], v170 offset:34816
	ds_read_b128 v[196:199], v170 offset:35840
	ds_read_b128 v[200:203], v170 offset:36864
	ds_read_b128 v[204:207], v170 offset:37888
	ds_read_b128 v[208:211], v170 offset:38912
	ds_read_b128 v[212:215], v170 offset:39936
	global_load_lds_dwordx4 v[224:225], off
	v_lshl_add_u64 v[224:225], s[16:17], 0, v[148:149]
	s_mov_b32 m0, s41
	s_nop 0
	global_load_lds_dwordx4 v[224:225], off
	s_waitcnt vmcnt(8)
	s_waitcnt lgkmcnt(0)
	s_barrier
	s_setprio 0
	v_mfma_f32_16x16x32_bf16 v[142:145], v[122:125], v[184:187], v[142:145]
	v_mfma_f32_16x16x32_bf16 v[138:141], v[130:133], v[184:187], v[138:141]
	v_mfma_f32_16x16x32_bf16 v[118:121], v[122:125], v[192:195], v[118:121]
	v_mfma_f32_16x16x32_bf16 v[106:109], v[130:133], v[192:195], v[106:109]
	v_mfma_f32_16x16x32_bf16 v[102:105], v[122:125], v[200:203], v[102:105]
	v_mfma_f32_16x16x32_bf16 v[90:93], v[130:133], v[200:203], v[90:93]
	v_mfma_f32_16x16x32_bf16 v[86:89], v[122:125], v[208:211], v[86:89]
	v_mfma_f32_16x16x32_bf16 v[74:77], v[130:133], v[208:211], v[74:77]
	v_mfma_f32_16x16x32_bf16 v[142:145], v[126:129], v[188:191], v[142:145]
	v_mfma_f32_16x16x32_bf16 v[138:141], v[134:137], v[188:191], v[138:141]
	v_mfma_f32_16x16x32_bf16 v[118:121], v[126:129], v[196:199], v[118:121]
	v_mfma_f32_16x16x32_bf16 v[106:109], v[134:137], v[196:199], v[106:109]
	v_mfma_f32_16x16x32_bf16 v[102:105], v[126:129], v[204:207], v[102:105]
	v_mfma_f32_16x16x32_bf16 v[90:93], v[134:137], v[204:207], v[90:93]
	v_mfma_f32_16x16x32_bf16 v[86:89], v[126:129], v[212:215], v[86:89]
	v_mfma_f32_16x16x32_bf16 v[74:77], v[134:137], v[212:215], v[74:77]
	s_setprio 2
	s_setprio 0
	v_mfma_f32_16x16x32_bf16 v[114:117], v[162:165], v[184:187], v[114:117]
	v_mfma_f32_16x16x32_bf16 v[110:113], v[176:179], v[184:187], v[110:113]
	v_mfma_f32_16x16x32_bf16 v[98:101], v[162:165], v[192:195], v[98:101]
	v_mfma_f32_16x16x32_bf16 v[94:97], v[176:179], v[192:195], v[94:97]
	v_mfma_f32_16x16x32_bf16 v[82:85], v[162:165], v[200:203], v[82:85]
	v_mfma_f32_16x16x32_bf16 v[78:81], v[176:179], v[200:203], v[78:81]
	v_mfma_f32_16x16x32_bf16 v[70:73], v[162:165], v[208:211], v[70:73]
	v_mfma_f32_16x16x32_bf16 v[66:69], v[176:179], v[208:211], v[66:69]
	v_mfma_f32_16x16x32_bf16 v[114:117], v[172:175], v[188:191], v[114:117]
	v_mfma_f32_16x16x32_bf16 v[110:113], v[180:183], v[188:191], v[110:113]
	v_mfma_f32_16x16x32_bf16 v[98:101], v[172:175], v[196:199], v[98:101]
	v_mfma_f32_16x16x32_bf16 v[94:97], v[180:183], v[196:199], v[94:97]
	v_mfma_f32_16x16x32_bf16 v[82:85], v[172:175], v[204:207], v[82:85]
	v_mfma_f32_16x16x32_bf16 v[78:81], v[180:183], v[204:207], v[78:81]
	v_mfma_f32_16x16x32_bf16 v[70:73], v[172:175], v[212:215], v[70:73]
	v_mfma_f32_16x16x32_bf16 v[66:69], v[180:183], v[212:215], v[66:69]
	s_setprio 2
	s_barrier
; #define PG8_STAGE(bufoff, gbase, voff) do { _Pragma("unroll") for (int _i = 0; _i < 2; ++_i) \
;         __builtin_amdgcn_global_load_lds((const unsigned*)((const char*)(gbase) + (voff)[_i]), (LAS unsigned*)(lds + (bufoff) + ldsw + _i * 8192), 16, 0, 0); } while (0)
; #define PG8_LDA(dst, b, h) do { _Pragma("unroll") for (int m = 0; m < 4; ++m) _Pragma("unroll") for (int k = 0; k < 2; ++k) dst[m][k] = *(const LAS bf16x8*)(lds + PG8_SA(b, h) + aoff + m * 2048 + k * 1024); } while (0)
; #define PG8_MMA(ai, bj, At, Bt) do { __builtin_amdgcn_s_setprio(1); _Pragma("unroll") for (int m = 0; m < 4; ++m) _Pragma("unroll") for (int n = 0; n < 2; ++n) _Pragma("unroll") for (int k = 0; k < 2; ++k) \
;         acc[ai][bj][m][n] = __builtin_amdgcn_mfma_f32_16x16x32_bf16(Bt[n][k], At[m][k], acc[ai][bj][m][n], 0, 0, 0); __builtin_amdgcn_s_setprio(0); } while (0)
; #define PG8_WAIT_V(n) asm volatile("s_waitcnt vmcnt(" #n ")" ::: "memory")
; #define PG8_WAIT_L(n) asm volatile("s_waitcnt lgkmcnt(" #n ")" ::: "memory")
; #define PG8_BAR __builtin_amdgcn_s_barrier()
; #define PG8_SCHED __builtin_amdgcn_sched_barrier(0)
; template <class Epi>
; __device__ __forceinline__ void gemm_phase(LAS unsigned char* lds, const Gemm g, int G, int c, const Epi& E) {
;     ...
;         for (int t = 0; t < nt; t += 2) {
;     ...
;             PG8_LDA(At, 1, 1); PG8_STAGE(PG8_SB(1, 0), b3, voffB); PG8_STAGE(PG8_SB(1, 1), b3 + hstepB, voffB); PG8_STAGE(PG8_SA(1, 0), a3, voffA);
;             PG8_WAIT_V(8); PG8_WAIT_L(0); PG8_BAR; PG8_MMA(1, 0, At, B0); PG8_MMA(1, 1, At, B1); PG8_BAR; PG8_SCHED;
;         }
;         if (wr == 0) PG8_BAR;
	s_add_i32 s16, s33, s36
	v_lshl_add_u64 v[216:217], v[216:217], 0, s[10:11]
	s_mov_b32 m0, s16
	ds_read_b128 v[184:187], v170 offset:49152
	ds_read_b128 v[188:191], v170 offset:50176
	ds_read_b128 v[192:195], v170 offset:51200
	ds_read_b128 v[196:199], v170 offset:52224
	ds_read_b128 v[200:203], v170 offset:53248
	ds_read_b128 v[204:207], v170 offset:54272
	ds_read_b128 v[208:211], v170 offset:55296
	ds_read_b128 v[212:215], v170 offset:56320
	global_load_lds_dwordx4 v[216:217], off
	s_add_i32 m0, s16, 0x2000
	s_add_u32 s16, s20, 0xb0080
	v_lshl_add_u64 v[216:217], v[218:219], 0, s[10:11]
	s_addc_u32 s17, s21, 0
	s_add_i32 s20, s62, s36
	global_load_lds_dwordx4 v[216:217], off
	v_lshl_add_u64 v[216:217], s[16:17], 0, v[150:151]
	s_mov_b32 m0, s20
	s_nop 0
	global_load_lds_dwordx4 v[216:217], off
	v_lshl_add_u64 v[216:217], s[16:17], 0, v[146:147]
	s_add_i32 m0, s20, 0x2000
	s_nop 0
	global_load_lds_dwordx4 v[216:217], off
	v_lshl_add_u64 v[216:217], v[220:221], 0, s[10:11]
	s_mov_b32 m0, s47
	s_nop 0
	global_load_lds_dwordx4 v[216:217], off
	v_lshl_add_u64 v[216:217], v[222:223], 0, s[10:11]
	s_mov_b32 m0, s52
	s_nop 0
	global_load_lds_dwordx4 v[216:217], off
	s_waitcnt vmcnt(8)
	s_waitcnt lgkmcnt(0)
	s_barrier
	s_setprio 0
	v_mfma_f32_16x16x32_bf16 v[62:65], v[122:125], v[184:187], v[62:65]
	v_mfma_f32_16x16x32_bf16 v[58:61], v[130:133], v[184:187], v[58:61]
	v_mfma_f32_16x16x32_bf16 v[54:57], v[122:125], v[192:195], v[54:57]
	v_mfma_f32_16x16x32_bf16 v[42:45], v[130:133], v[192:195], v[42:45]
	v_mfma_f32_16x16x32_bf16 v[38:41], v[122:125], v[200:203], v[38:41]
	v_mfma_f32_16x16x32_bf16 v[26:29], v[130:133], v[200:203], v[26:29]
	v_mfma_f32_16x16x32_bf16 v[22:25], v[122:125], v[208:211], v[22:25]
	v_mfma_f32_16x16x32_bf16 v[10:13], v[130:133], v[208:211], v[10:13]
	v_mfma_f32_16x16x32_bf16 v[62:65], v[126:129], v[188:191], v[62:65]
	v_mfma_f32_16x16x32_bf16 v[58:61], v[134:137], v[188:191], v[58:61]
	v_mfma_f32_16x16x32_bf16 v[54:57], v[126:129], v[196:199], v[54:57]
	v_mfma_f32_16x16x32_bf16 v[42:45], v[134:137], v[196:199], v[42:45]
	v_mfma_f32_16x16x32_bf16 v[38:41], v[126:129], v[204:207], v[38:41]
	v_mfma_f32_16x16x32_bf16 v[26:29], v[134:137], v[204:207], v[26:29]
	v_mfma_f32_16x16x32_bf16 v[22:25], v[126:129], v[212:215], v[22:25]
	v_mfma_f32_16x16x32_bf16 v[10:13], v[134:137], v[212:215], v[10:13]
	s_setprio 2
	s_setprio 0
	v_mfma_f32_16x16x32_bf16 v[50:53], v[162:165], v[184:187], v[50:53]
	v_mfma_f32_16x16x32_bf16 v[46:49], v[176:179], v[184:187], v[46:49]
	v_mfma_f32_16x16x32_bf16 v[34:37], v[162:165], v[192:195], v[34:37]
	v_mfma_f32_16x16x32_bf16 v[30:33], v[176:179], v[192:195], v[30:33]
	v_mfma_f32_16x16x32_bf16 v[18:21], v[162:165], v[200:203], v[18:21]
	v_mfma_f32_16x16x32_bf16 v[14:17], v[176:179], v[200:203], v[14:17]
	v_mfma_f32_16x16x32_bf16 v[6:9], v[162:165], v[208:211], v[6:9]
	v_mfma_f32_16x16x32_bf16 v[2:5], v[176:179], v[208:211], v[2:5]
	v_mfma_f32_16x16x32_bf16 v[50:53], v[172:175], v[188:191], v[50:53]
	v_mfma_f32_16x16x32_bf16 v[46:49], v[180:183], v[188:191], v[46:49]
	v_mfma_f32_16x16x32_bf16 v[34:37], v[172:175], v[196:199], v[34:37]
	v_mfma_f32_16x16x32_bf16 v[30:33], v[180:183], v[196:199], v[30:33]
	v_mfma_f32_16x16x32_bf16 v[18:21], v[172:175], v[204:207], v[18:21]
	v_mfma_f32_16x16x32_bf16 v[14:17], v[180:183], v[204:207], v[14:17]
	v_mfma_f32_16x16x32_bf16 v[6:9], v[172:175], v[212:215], v[6:9]
	v_mfma_f32_16x16x32_bf16 v[2:5], v[180:183], v[212:215], v[2:5]
	s_setprio 2
	s_add_i32 s68, s68, 2
	s_add_u32 s66, s66, 0x100
	s_addc_u32 s67, s67, 0
	s_cmp_gt_u32 s68, 41
	s_mov_b64 s[16:17], s[18:19]
	s_barrier
	s_cbranch_scc0 .LBB0_1143
	s_and_b64 vcc, exec, s[12:13]
	s_cbranch_vccz .LBB0_1146
	s_barrier

; #define PG8_STAGE(bufoff, gbase, voff) do { _Pragma("unroll") for (int _i = 0; _i < 2; ++_i) \
;         __builtin_amdgcn_global_load_lds((const unsigned*)((const char*)(gbase) + (voff)[_i]), (LAS unsigned*)(lds + (bufoff) + ldsw + _i * 8192), 16, 0, 0); } while (0)
; #define PG8_LDA(dst, b, h) do { _Pragma("unroll") for (int m = 0; m < 4; ++m) _Pragma("unroll") for (int k = 0; k < 2; ++k) dst[m][k] = *(const LAS bf16x8*)(lds + PG8_SA(b, h) + aoff + m * 2048 + k * 1024); } while (0)
; #define PG8_LDB(dst, b, h) do { _Pragma("unroll") for (int n = 0; n < 2; ++n) _Pragma("unroll") for (int k = 0; k < 2; ++k) dst[n][k] = *(const LAS bf16x8*)(lds + PG8_SB(b, h) + boff + n * 2048 + k * 1024); } while (0)
; #define PG8_MMA(ai, bj, At, Bt) do { __builtin_amdgcn_s_setprio(1); _Pragma("unroll") for (int m = 0; m < 4; ++m) _Pragma("unroll") for (int n = 0; n < 2; ++n) _Pragma("unroll") for (int k = 0; k < 2; ++k) \
;         acc[ai][bj][m][n] = __builtin_amdgcn_mfma_f32_16x16x32_bf16(Bt[n][k], At[m][k], acc[ai][bj][m][n], 0, 0, 0); __builtin_amdgcn_s_setprio(0); } while (0)
; template <class Epi>
; __device__ __forceinline__ void gemm_phase(LAS unsigned char* lds, const Gemm g, int G, int c, const Epi& E) {
;     ...
;         const bool has_next = S.next(ui + 1, nxt);
;         const char* nA = has_next ? (const char*)(g.A + (size_t)nxt.pb * g.sA) + (size_t)nxt.pm * 2 * hstepA : cA;
;         const char* nB = has_next ? (const char*)(g.Bt + (size_t)nxt.pb * g.sB) + (size_t)nxt.pn * 2 * hstepB : cB;
; #pragma nounroll
;         for (int t = 0; t < nt; t += 2) {
;             const bool last = (t == nt - 2);
;             const char* a1 = cA + (size_t)(t + 1) * kstep;
;             const char* a2 = last ? nA : cA + (size_t)(t + 2) * kstep; const char* b2 = last ? nB : cB + (size_t)(t + 2) * kstep;
;             const char* a3 = a2 + kstep; const char* b3 = b2 + kstep;
;             PG8_LDB(B0, 0, 0); PG8_LDB(B1, 0, 1); PG8_SCHED; PG8_LDA(At, 0, 0); PG8_STAGE(PG8_SA(1, 1), a1 + hstepA, voffA);
;             PG8_WAIT_V(8); PG8_WAIT_L(0); PG8_BAR; PG8_MMA(0, 0, At, B0); PG8_MMA(0, 1, At, B1); PG8_BAR; PG8_SCHED;
;             PG8_LDA(At, 0, 1); PG8_STAGE(PG8_SB(0, 0), b2, voffB); PG8_STAGE(PG8_SB(0, 1), b2 + hstepB, voffB); PG8_STAGE(PG8_SA(0, 0), a2, voffA);
;             PG8_WAIT_V(8); PG8_WAIT_L(0); PG8_BAR; PG8_MMA(1, 0, At, B0); PG8_MMA(1, 1, At, B1); PG8_BAR; PG8_SCHED;
.LBB0_1296:
	s_ashr_i32 s39, s38, 31
	s_lshl_b64 s[44:45], s[38:39], 19
	s_add_u32 s44, s54, s44
	s_addc_u32 s45, s55, s45
	s_and_b64 s[4:5], s[4:5], exec
	s_cselect_b32 s7, s45, s47
	s_cselect_b32 s39, s44, s46
	s_add_u32 s4, s48, 0x40080
	s_addc_u32 s5, s49, 0
	s_add_u32 s41, s46, 0x100
	s_addc_u32 s80, s47, 0
	s_mov_b32 s81, -2
	s_waitcnt lgkmcnt(0)
	ds_read_b128 v[146:149], v152
	ds_read_b128 v[158:161], v152 offset:1024
	ds_read_b128 v[162:165], v152 offset:2048
	ds_read_b128 v[166:169], v152 offset:3072
	ds_read_b128 v[170:173], v153
	ds_read_b128 v[174:177], v153 offset:1024
	ds_read_b128 v[178:181], v153 offset:2048
	ds_read_b128 v[182:185], v153 offset:3072
	s_add_u32 s33, s4, 0xfffc0080
	s_addc_u32 s46, s5, -1
	s_cmp_eq_u32 s81, 12
	s_cselect_b32 s49, s43, s46
	s_cselect_b32 s48, s42, s33
	s_cselect_b32 s47, s7, s80
	s_cselect_b32 s46, s39, s41
	v_lshl_add_u64 v[218:219], s[4:5], 0, v[138:139]
	s_add_i32 m0, s11, 0xc000
	ds_read_b128 v[186:189], v154
	ds_read_b128 v[190:193], v154 offset:1024
	ds_read_b128 v[194:197], v154 offset:2048
	ds_read_b128 v[198:201], v154 offset:3072
	ds_read_b128 v[202:205], v154 offset:4096
	ds_read_b128 v[206:209], v154 offset:5120
	ds_read_b128 v[210:213], v154 offset:6144
	ds_read_b128 v[214:217], v154 offset:7168
	global_load_lds_dwordx4 v[218:219], off
	v_lshl_add_u64 v[218:219], s[4:5], 0, v[140:141]
	s_add_i32 m0, s11, 0xe000
	s_nop 0
	global_load_lds_dwordx4 v[218:219], off
	s_waitcnt vmcnt(8)
	s_waitcnt lgkmcnt(0)
	s_barrier
	s_setprio 0
	v_mfma_f32_16x16x32_bf16 v[126:129], v[146:149], v[186:189], 0
	v_mfma_f32_16x16x32_bf16 v[122:125], v[162:165], v[186:189], 0
	v_mfma_f32_16x16x32_bf16 v[110:113], v[146:149], v[194:197], 0
	v_mfma_f32_16x16x32_bf16 v[106:109], v[162:165], v[194:197], 0
	v_mfma_f32_16x16x32_bf16 v[94:97], v[146:149], v[202:205], 0
	v_mfma_f32_16x16x32_bf16 v[90:93], v[162:165], v[202:205], 0
	v_mfma_f32_16x16x32_bf16 v[78:81], v[146:149], v[210:213], 0
	v_mfma_f32_16x16x32_bf16 v[74:77], v[162:165], v[210:213], 0
	v_mfma_f32_16x16x32_bf16 v[126:129], v[158:161], v[190:193], v[126:129]
	v_mfma_f32_16x16x32_bf16 v[122:125], v[166:169], v[190:193], v[122:125]
	v_mfma_f32_16x16x32_bf16 v[110:113], v[158:161], v[198:201], v[110:113]
	v_mfma_f32_16x16x32_bf16 v[106:109], v[166:169], v[198:201], v[106:109]
	v_mfma_f32_16x16x32_bf16 v[94:97], v[158:161], v[206:209], v[94:97]
	v_mfma_f32_16x16x32_bf16 v[90:93], v[166:169], v[206:209], v[90:93]
	v_mfma_f32_16x16x32_bf16 v[78:81], v[158:161], v[214:217], v[78:81]
	v_mfma_f32_16x16x32_bf16 v[74:77], v[166:169], v[214:217], v[74:77]
	s_setprio 2
	s_setprio 0
	v_mfma_f32_16x16x32_bf16 v[118:121], v[170:173], v[186:189], 0
	v_mfma_f32_16x16x32_bf16 v[114:117], v[178:181], v[186:189], 0
	v_mfma_f32_16x16x32_bf16 v[102:105], v[170:173], v[194:197], 0
	v_mfma_f32_16x16x32_bf16 v[98:101], v[178:181], v[194:197], 0
	v_mfma_f32_16x16x32_bf16 v[86:89], v[170:173], v[202:205], 0
	v_mfma_f32_16x16x32_bf16 v[82:85], v[178:181], v[202:205], 0
	v_mfma_f32_16x16x32_bf16 v[70:73], v[170:173], v[210:213], 0
	v_mfma_f32_16x16x32_bf16 v[66:69], v[178:181], v[210:213], 0
	v_mfma_f32_16x16x32_bf16 v[118:121], v[174:177], v[190:193], v[118:121]
	v_mfma_f32_16x16x32_bf16 v[114:117], v[182:185], v[190:193], v[114:117]
	v_mfma_f32_16x16x32_bf16 v[102:105], v[174:177], v[198:201], v[102:105]
	v_mfma_f32_16x16x32_bf16 v[98:101], v[182:185], v[198:201], v[98:101]
	v_mfma_f32_16x16x32_bf16 v[86:89], v[174:177], v[206:209], v[86:89]
	v_mfma_f32_16x16x32_bf16 v[82:85], v[182:185], v[206:209], v[82:85]
	v_mfma_f32_16x16x32_bf16 v[70:73], v[174:177], v[214:217], v[70:73]
	v_mfma_f32_16x16x32_bf16 v[66:69], v[182:185], v[214:217], v[66:69]
	s_setprio 2
	s_barrier
	s_add_i32 s33, s71, s56
	v_lshl_add_u64 v[218:219], s[46:47], 0, v[132:133]
	s_mov_b32 m0, s33
	ds_read_b128 v[186:189], v154 offset:16384
	ds_read_b128 v[190:193], v154 offset:17408
	ds_read_b128 v[194:197], v154 offset:18432
	ds_read_b128 v[198:201], v154 offset:19456
	ds_read_b128 v[202:205], v154 offset:20480
	ds_read_b128 v[206:209], v154 offset:21504
	ds_read_b128 v[210:213], v154 offset:22528
	ds_read_b128 v[214:217], v154 offset:23552
	global_load_lds_dwordx4 v[218:219], off
	s_add_i32 m0, s33, 0x2000
	s_add_u32 s62, s46, 0x40000
	v_lshl_add_u64 v[220:221], s[46:47], 0, v[136:137]
	s_addc_u32 s63, s47, 0
	s_add_i32 s33, s72, s56
	global_load_lds_dwordx4 v[220:221], off
	v_lshl_add_u64 v[222:223], s[62:63], 0, v[132:133]
	s_mov_b32 m0, s33
	v_lshl_add_u64 v[224:225], s[48:49], 0, v[134:135]
	global_load_lds_dwordx4 v[222:223], off
	v_lshl_add_u64 v[222:223], s[62:63], 0, v[136:137]
	s_add_i32 m0, s33, 0x2000
	s_nop 0
	global_load_lds_dwordx4 v[222:223], off
	v_lshl_add_u64 v[222:223], s[48:49], 0, v[130:131]
	s_mov_b32 m0, s11
	s_nop 0
	global_load_lds_dwordx4 v[222:223], off
	s_mov_b32 m0, s57
	s_nop 0
	global_load_lds_dwordx4 v[224:225], off
	s_waitcnt vmcnt(8)
	s_waitcnt lgkmcnt(0)
	s_barrier
; #define PG8_STAGE(bufoff, gbase, voff) do { _Pragma("unroll") for (int _i = 0; _i < 2; ++_i) \
;         __builtin_amdgcn_global_load_lds((const unsigned*)((const char*)(gbase) + (voff)[_i]), (LAS unsigned*)(lds + (bufoff) + ldsw + _i * 8192), 16, 0, 0); } while (0)
; #define PG8_LDA(dst, b, h) do { _Pragma("unroll") for (int m = 0; m < 4; ++m) _Pragma("unroll") for (int k = 0; k < 2; ++k) dst[m][k] = *(const LAS bf16x8*)(lds + PG8_SA(b, h) + aoff + m * 2048 + k * 1024); } while (0)
; #define PG8_LDB(dst, b, h) do { _Pragma("unroll") for (int n = 0; n < 2; ++n) _Pragma("unroll") for (int k = 0; k < 2; ++k) dst[n][k] = *(const LAS bf16x8*)(lds + PG8_SB(b, h) + boff + n * 2048 + k * 1024); } while (0)
; #define PG8_MMA(ai, bj, At, Bt) do { __builtin_amdgcn_s_setprio(1); _Pragma("unroll") for (int m = 0; m < 4; ++m) _Pragma("unroll") for (int n = 0; n < 2; ++n) _Pragma("unroll") for (int k = 0; k < 2; ++k) \
;         acc[ai][bj][m][n] = __builtin_amdgcn_mfma_f32_16x16x32_bf16(Bt[n][k], At[m][k], acc[ai][bj][m][n], 0, 0, 0); __builtin_amdgcn_s_setprio(0); } while (0)
; #define PG8_WAIT_V(n) asm volatile("s_waitcnt vmcnt(" #n ")" ::: "memory")
; #define PG8_WAIT_L(n) asm volatile("s_waitcnt lgkmcnt(" #n ")" ::: "memory")
; #define PG8_BAR __builtin_amdgcn_s_barrier()
; #define PG8_SCHED __builtin_amdgcn_sched_barrier(0)
; template <class Epi>
; __device__ __forceinline__ void gemm_phase(LAS unsigned char* lds, const Gemm g, int G, int c, const Epi& E) {
;     ...
;             PG8_WAIT_V(8); PG8_WAIT_L(0); PG8_BAR; PG8_MMA(1, 0, At, B0); PG8_MMA(1, 1, At, B1); PG8_BAR; PG8_SCHED;
;             PG8_LDB(B0, 1, 0); PG8_LDB(B1, 1, 1); PG8_SCHED; PG8_LDA(At, 1, 0); PG8_STAGE(PG8_SA(0, 1), a2 + hstepA, voffA);
;             PG8_WAIT_V(8); PG8_WAIT_L(0); PG8_BAR; PG8_MMA(0, 0, At, B0); PG8_MMA(0, 1, At, B1); PG8_BAR; PG8_SCHED;
	s_setprio 0
	v_mfma_f32_16x16x32_bf16 v[62:65], v[146:149], v[186:189], 0
	v_mfma_f32_16x16x32_bf16 v[58:61], v[162:165], v[186:189], 0
	v_mfma_f32_16x16x32_bf16 v[46:49], v[146:149], v[194:197], 0
	v_mfma_f32_16x16x32_bf16 v[42:45], v[162:165], v[194:197], 0
	v_mfma_f32_16x16x32_bf16 v[30:33], v[146:149], v[202:205], 0
	v_mfma_f32_16x16x32_bf16 v[26:29], v[162:165], v[202:205], 0
	v_mfma_f32_16x16x32_bf16 v[14:17], v[146:149], v[210:213], 0
	v_mfma_f32_16x16x32_bf16 v[10:13], v[162:165], v[210:213], 0
	v_mfma_f32_16x16x32_bf16 v[62:65], v[158:161], v[190:193], v[62:65]
	v_mfma_f32_16x16x32_bf16 v[58:61], v[166:169], v[190:193], v[58:61]
	v_mfma_f32_16x16x32_bf16 v[46:49], v[158:161], v[198:201], v[46:49]
	v_mfma_f32_16x16x32_bf16 v[42:45], v[166:169], v[198:201], v[42:45]
	v_mfma_f32_16x16x32_bf16 v[30:33], v[158:161], v[206:209], v[30:33]
	v_mfma_f32_16x16x32_bf16 v[26:29], v[166:169], v[206:209], v[26:29]
	v_mfma_f32_16x16x32_bf16 v[14:17], v[158:161], v[214:217], v[14:17]
	v_mfma_f32_16x16x32_bf16 v[10:13], v[166:169], v[214:217], v[10:13]
	s_setprio 2
	s_setprio 0
	v_mfma_f32_16x16x32_bf16 v[54:57], v[170:173], v[186:189], 0
	v_mfma_f32_16x16x32_bf16 v[50:53], v[178:181], v[186:189], 0
	v_mfma_f32_16x16x32_bf16 v[38:41], v[170:173], v[194:197], 0
	v_mfma_f32_16x16x32_bf16 v[34:37], v[178:181], v[194:197], 0
	v_mfma_f32_16x16x32_bf16 v[22:25], v[170:173], v[202:205], 0
	v_mfma_f32_16x16x32_bf16 v[18:21], v[178:181], v[202:205], 0
	v_mfma_f32_16x16x32_bf16 v[6:9], v[170:173], v[210:213], 0
	v_mfma_f32_16x16x32_bf16 v[2:5], v[178:181], v[210:213], 0
	v_mfma_f32_16x16x32_bf16 v[54:57], v[174:177], v[190:193], v[54:57]
	v_mfma_f32_16x16x32_bf16 v[50:53], v[182:185], v[190:193], v[50:53]
	v_mfma_f32_16x16x32_bf16 v[38:41], v[174:177], v[198:201], v[38:41]
	v_mfma_f32_16x16x32_bf16 v[34:37], v[182:185], v[198:201], v[34:37]
	v_mfma_f32_16x16x32_bf16 v[22:25], v[174:177], v[206:209], v[22:25]
	v_mfma_f32_16x16x32_bf16 v[18:21], v[182:185], v[206:209], v[18:21]
	v_mfma_f32_16x16x32_bf16 v[6:9], v[174:177], v[214:217], v[6:9]
	v_mfma_f32_16x16x32_bf16 v[2:5], v[182:185], v[214:217], v[2:5]
	s_setprio 2
	s_barrier
	s_add_i32 s33, 0, 0x18000
	v_add_u32_e32 v157, s33, v151
	s_add_i32 s62, 0, 0x1c000
	ds_read_b128 v[146:149], v157
	ds_read_b128 v[158:161], v157 offset:1024
	ds_read_b128 v[162:165], v157 offset:2048
	ds_read_b128 v[166:169], v157 offset:3072
	v_add_u32_e32 v157, s62, v151
	ds_read_b128 v[170:173], v157
	ds_read_b128 v[174:177], v157 offset:1024
	ds_read_b128 v[178:181], v157 offset:2048
	ds_read_b128 v[182:185], v157 offset:3072
	s_add_u32 s48, s48, 0x40000
	s_addc_u32 s49, s49, 0
	s_mov_b32 m0, s58
	v_lshl_add_u64 v[226:227], s[48:49], 0, v[130:131]
	ds_read_b128 v[186:189], v154 offset:32768
	ds_read_b128 v[190:193], v154 offset:33792
	ds_read_b128 v[194:197], v154 offset:34816
	ds_read_b128 v[198:201], v154 offset:35840
	ds_read_b128 v[202:205], v154 offset:36864
	ds_read_b128 v[206:209], v154 offset:37888
	ds_read_b128 v[210:213], v154 offset:38912
	ds_read_b128 v[214:217], v154 offset:39936
	global_load_lds_dwordx4 v[226:227], off
	v_lshl_add_u64 v[226:227], s[48:49], 0, v[134:135]
	s_mov_b32 m0, s59
	s_nop 0
	global_load_lds_dwordx4 v[226:227], off
	s_waitcnt vmcnt(8)
	s_waitcnt lgkmcnt(0)
	s_barrier
	s_setprio 0
	v_mfma_f32_16x16x32_bf16 v[126:129], v[146:149], v[186:189], v[126:129]
	v_mfma_f32_16x16x32_bf16 v[122:125], v[162:165], v[186:189], v[122:125]
	v_mfma_f32_16x16x32_bf16 v[110:113], v[146:149], v[194:197], v[110:113]
	v_mfma_f32_16x16x32_bf16 v[106:109], v[162:165], v[194:197], v[106:109]
	v_mfma_f32_16x16x32_bf16 v[94:97], v[146:149], v[202:205], v[94:97]
	v_mfma_f32_16x16x32_bf16 v[90:93], v[162:165], v[202:205], v[90:93]
	v_mfma_f32_16x16x32_bf16 v[78:81], v[146:149], v[210:213], v[78:81]
	v_mfma_f32_16x16x32_bf16 v[74:77], v[162:165], v[210:213], v[74:77]
	v_mfma_f32_16x16x32_bf16 v[126:129], v[158:161], v[190:193], v[126:129]
	v_mfma_f32_16x16x32_bf16 v[122:125], v[166:169], v[190:193], v[122:125]
	v_mfma_f32_16x16x32_bf16 v[110:113], v[158:161], v[198:201], v[110:113]
	v_mfma_f32_16x16x32_bf16 v[106:109], v[166:169], v[198:201], v[106:109]
	v_mfma_f32_16x16x32_bf16 v[94:97], v[158:161], v[206:209], v[94:97]
	v_mfma_f32_16x16x32_bf16 v[90:93], v[166:169], v[206:209], v[90:93]
	v_mfma_f32_16x16x32_bf16 v[78:81], v[158:161], v[214:217], v[78:81]
	v_mfma_f32_16x16x32_bf16 v[74:77], v[166:169], v[214:217], v[74:77]
	s_setprio 2
	s_setprio 0
	v_mfma_f32_16x16x32_bf16 v[118:121], v[170:173], v[186:189], v[118:121]
	v_mfma_f32_16x16x32_bf16 v[114:117], v[178:181], v[186:189], v[114:117]
	v_mfma_f32_16x16x32_bf16 v[102:105], v[170:173], v[194:197], v[102:105]
	v_mfma_f32_16x16x32_bf16 v[98:101], v[178:181], v[194:197], v[98:101]
	v_mfma_f32_16x16x32_bf16 v[86:89], v[170:173], v[202:205], v[86:89]
	v_mfma_f32_16x16x32_bf16 v[82:85], v[178:181], v[202:205], v[82:85]
	v_mfma_f32_16x16x32_bf16 v[70:73], v[170:173], v[210:213], v[70:73]
	v_mfma_f32_16x16x32_bf16 v[66:69], v[178:181], v[210:213], v[66:69]
	v_mfma_f32_16x16x32_bf16 v[118:121], v[174:177], v[190:193], v[118:121]
	v_mfma_f32_16x16x32_bf16 v[114:117], v[182:185], v[190:193], v[114:117]
	v_mfma_f32_16x16x32_bf16 v[102:105], v[174:177], v[198:201], v[102:105]
	v_mfma_f32_16x16x32_bf16 v[98:101], v[182:185], v[198:201], v[98:101]
	v_mfma_f32_16x16x32_bf16 v[86:89], v[174:177], v[206:209], v[86:89]
	v_mfma_f32_16x16x32_bf16 v[82:85], v[182:185], v[206:209], v[82:85]
	v_mfma_f32_16x16x32_bf16 v[70:73], v[174:177], v[214:217], v[70:73]
	v_mfma_f32_16x16x32_bf16 v[66:69], v[182:185], v[214:217], v[66:69]
	s_setprio 2
	s_barrier
; #define PG8_STAGE(bufoff, gbase, voff) do { _Pragma("unroll") for (int _i = 0; _i < 2; ++_i) \
;         __builtin_amdgcn_global_load_lds((const unsigned*)((const char*)(gbase) + (voff)[_i]), (LAS unsigned*)(lds + (bufoff) + ldsw + _i * 8192), 16, 0, 0); } while (0)
; #define PG8_LDA(dst, b, h) do { _Pragma("unroll") for (int m = 0; m < 4; ++m) _Pragma("unroll") for (int k = 0; k < 2; ++k) dst[m][k] = *(const LAS bf16x8*)(lds + PG8_SA(b, h) + aoff + m * 2048 + k * 1024); } while (0)
; #define PG8_LDB(dst, b, h) do { _Pragma("unroll") for (int n = 0; n < 2; ++n) _Pragma("unroll") for (int k = 0; k < 2; ++k) dst[n][k] = *(const LAS bf16x8*)(lds + PG8_SB(b, h) + boff + n * 2048 + k * 1024); } while (0)
; #define PG8_WAIT_V(n) asm volatile("s_waitcnt vmcnt(" #n ")" ::: "memory")
; #define PG8_WAIT_L(n) asm volatile("s_waitcnt lgkmcnt(" #n ")" ::: "memory")
; template <class Epi>
; __device__ __forceinline__ void gemm_phase(LAS unsigned char* lds, const Gemm g, int G, int c, const Epi& E) {
;     ...
;         for (int t = 0; t < nt; t += 2) {
;             const bool last = (t == nt - 2);
;             const char* a1 = cA + (size_t)(t + 1) * kstep;
;             const char* a2 = last ? nA : cA + (size_t)(t + 2) * kstep; const char* b2 = last ? nB : cB + (size_t)(t + 2) * kstep;
;             const char* a3 = a2 + kstep; const char* b3 = b2 + kstep;
;             PG8_LDB(B0, 0, 0); PG8_LDB(B1, 0, 1); PG8_SCHED; PG8_LDA(At, 0, 0); PG8_STAGE(PG8_SA(1, 1), a1 + hstepA, voffA);
;             PG8_WAIT_V(8); PG8_WAIT_L(0); PG8_BAR; PG8_MMA(0, 0, At, B0); PG8_MMA(0, 1, At, B1); PG8_BAR; PG8_SCHED;
;             PG8_LDA(At, 0, 1); PG8_STAGE(PG8_SB(0, 0), b2, voffB); PG8_STAGE(PG8_SB(0, 1), b2 + hstepB, voffB); PG8_STAGE(PG8_SA(0, 0), a2, voffA);
;             PG8_WAIT_V(8); PG8_WAIT_L(0); PG8_BAR; PG8_MMA(1, 0, At, B0); PG8_MMA(1, 1, At, B1); PG8_BAR; PG8_SCHED;
;             PG8_LDB(B0, 1, 0); PG8_LDB(B1, 1, 1); PG8_SCHED; PG8_LDA(At, 1, 0); PG8_STAGE(PG8_SA(0, 1), a2 + hstepA, voffA);
;             PG8_WAIT_V(8); PG8_WAIT_L(0); PG8_BAR; PG8_MMA(0, 0, At, B0); PG8_MMA(0, 1, At, B1); PG8_BAR; PG8_SCHED;
;             PG8_LDA(At, 1, 1); PG8_STAGE(PG8_SB(1, 0), b3, voffB); PG8_STAGE(PG8_SB(1, 1), b3 + hstepB, voffB); PG8_STAGE(PG8_SA(1, 0), a3, voffA);
;             PG8_WAIT_V(8); PG8_WAIT_L(0); PG8_BAR; PG8_MMA(1, 0, At, B0); PG8_MMA(1, 1, At, B1); PG8_BAR; PG8_SCHED;
	s_add_i32 s33, s33, s56
	v_lshl_add_u64 v[218:219], v[218:219], 0, s[20:21]
	s_mov_b32 m0, s33
	ds_read_b128 v[186:189], v154 offset:49152
	ds_read_b128 v[190:193], v154 offset:50176
	ds_read_b128 v[194:197], v154 offset:51200
	ds_read_b128 v[198:201], v154 offset:52224
	ds_read_b128 v[202:205], v154 offset:53248
	ds_read_b128 v[206:209], v154 offset:54272
	ds_read_b128 v[210:213], v154 offset:55296
	ds_read_b128 v[214:217], v154 offset:56320
	global_load_lds_dwordx4 v[218:219], off
	s_add_i32 m0, s33, 0x2000
	s_add_u32 s46, s46, 0x40080
	v_lshl_add_u64 v[218:219], v[220:221], 0, s[20:21]
	s_addc_u32 s47, s47, 0
	s_add_i32 s33, s62, s56
	global_load_lds_dwordx4 v[218:219], off
	v_lshl_add_u64 v[218:219], s[46:47], 0, v[132:133]
	s_mov_b32 m0, s33
	s_nop 0
	global_load_lds_dwordx4 v[218:219], off
	v_lshl_add_u64 v[218:219], s[46:47], 0, v[136:137]
	s_add_i32 m0, s33, 0x2000
	s_nop 0
	global_load_lds_dwordx4 v[218:219], off
	v_lshl_add_u64 v[218:219], v[222:223], 0, s[20:21]
	s_mov_b32 m0, s67
	s_nop 0
	global_load_lds_dwordx4 v[218:219], off
	v_lshl_add_u64 v[218:219], v[224:225], 0, s[20:21]
	s_mov_b32 m0, s68
	s_nop 0
	global_load_lds_dwordx4 v[218:219], off
	s_waitcnt vmcnt(8)
	s_waitcnt lgkmcnt(0)
	s_barrier
	s_setprio 0
	v_mfma_f32_16x16x32_bf16 v[62:65], v[146:149], v[186:189], v[62:65]
	v_mfma_f32_16x16x32_bf16 v[58:61], v[162:165], v[186:189], v[58:61]
	v_mfma_f32_16x16x32_bf16 v[46:49], v[146:149], v[194:197], v[46:49]
	v_mfma_f32_16x16x32_bf16 v[42:45], v[162:165], v[194:197], v[42:45]
	v_mfma_f32_16x16x32_bf16 v[30:33], v[146:149], v[202:205], v[30:33]
	v_mfma_f32_16x16x32_bf16 v[26:29], v[162:165], v[202:205], v[26:29]
	v_mfma_f32_16x16x32_bf16 v[14:17], v[146:149], v[210:213], v[14:17]
	v_mfma_f32_16x16x32_bf16 v[10:13], v[162:165], v[210:213], v[10:13]
	v_mfma_f32_16x16x32_bf16 v[62:65], v[158:161], v[190:193], v[62:65]
	v_mfma_f32_16x16x32_bf16 v[58:61], v[166:169], v[190:193], v[58:61]
	v_mfma_f32_16x16x32_bf16 v[46:49], v[158:161], v[198:201], v[46:49]
	v_mfma_f32_16x16x32_bf16 v[42:45], v[166:169], v[198:201], v[42:45]
	v_mfma_f32_16x16x32_bf16 v[30:33], v[158:161], v[206:209], v[30:33]
	v_mfma_f32_16x16x32_bf16 v[26:29], v[166:169], v[206:209], v[26:29]
	v_mfma_f32_16x16x32_bf16 v[14:17], v[158:161], v[214:217], v[14:17]
	v_mfma_f32_16x16x32_bf16 v[10:13], v[166:169], v[214:217], v[10:13]
	s_setprio 2
	s_setprio 0
	v_mfma_f32_16x16x32_bf16 v[54:57], v[170:173], v[186:189], v[54:57]
	v_mfma_f32_16x16x32_bf16 v[50:53], v[178:181], v[186:189], v[50:53]
	v_mfma_f32_16x16x32_bf16 v[38:41], v[170:173], v[194:197], v[38:41]
	v_mfma_f32_16x16x32_bf16 v[34:37], v[178:181], v[194:197], v[34:37]
	v_mfma_f32_16x16x32_bf16 v[22:25], v[170:173], v[202:205], v[22:25]
	v_mfma_f32_16x16x32_bf16 v[18:21], v[178:181], v[202:205], v[18:21]
	v_mfma_f32_16x16x32_bf16 v[6:9], v[170:173], v[210:213], v[6:9]
	v_mfma_f32_16x16x32_bf16 v[2:5], v[178:181], v[210:213], v[2:5]
	v_mfma_f32_16x16x32_bf16 v[54:57], v[174:177], v[190:193], v[54:57]
	v_mfma_f32_16x16x32_bf16 v[50:53], v[182:185], v[190:193], v[50:53]
	v_mfma_f32_16x16x32_bf16 v[38:41], v[174:177], v[198:201], v[38:41]
	v_mfma_f32_16x16x32_bf16 v[34:37], v[182:185], v[198:201], v[34:37]
	v_mfma_f32_16x16x32_bf16 v[22:25], v[174:177], v[206:209], v[22:25]
	v_mfma_f32_16x16x32_bf16 v[18:21], v[182:185], v[206:209], v[18:21]
	v_mfma_f32_16x16x32_bf16 v[6:9], v[174:177], v[214:217], v[6:9]
	v_mfma_f32_16x16x32_bf16 v[2:5], v[182:185], v[214:217], v[2:5]
	s_setprio 2
	s_add_i32 s81, s81, 2
	s_add_u32 s4, s4, 0x100
	s_addc_u32 s5, s5, 0
	s_add_u32 s41, s41, 0x100
	s_addc_u32 s80, s80, 0
	s_cmp_gt_u32 s81, 13
	s_barrier
	s_cbranch_scc0 .LBB0_1297
.LBB0_1297:
	ds_read_b128 v[146:149], v152
	ds_read_b128 v[158:161], v152 offset:1024
	ds_read_b128 v[162:165], v152 offset:2048
	ds_read_b128 v[166:169], v152 offset:3072
	ds_read_b128 v[170:173], v153
	ds_read_b128 v[174:177], v153 offset:1024
	ds_read_b128 v[178:181], v153 offset:2048
	ds_read_b128 v[182:185], v153 offset:3072
	s_add_u32 s33, s4, 0xfffc0080
	s_addc_u32 s46, s5, -1
	s_cmp_eq_u32 s81, 12
	s_cselect_b32 s49, s43, s46
	s_cselect_b32 s48, s42, s33
	s_cselect_b32 s47, s7, s80
	s_cselect_b32 s46, s39, s41
	v_lshl_add_u64 v[218:219], s[4:5], 0, v[138:139]
	s_add_i32 m0, s11, 0xc000
	ds_read_b128 v[186:189], v154
	ds_read_b128 v[190:193], v154 offset:1024
	ds_read_b128 v[194:197], v154 offset:2048
	ds_read_b128 v[198:201], v154 offset:3072
	ds_read_b128 v[202:205], v154 offset:4096
	ds_read_b128 v[206:209], v154 offset:5120
	ds_read_b128 v[210:213], v154 offset:6144
	ds_read_b128 v[214:217], v154 offset:7168
	global_load_lds_dwordx4 v[218:219], off
	v_lshl_add_u64 v[218:219], s[4:5], 0, v[140:141]
	s_add_i32 m0, s11, 0xe000
	s_nop 0
	global_load_lds_dwordx4 v[218:219], off
	s_waitcnt vmcnt(8)
	s_waitcnt lgkmcnt(0)
	s_barrier
; #define PG8_STAGE(bufoff, gbase, voff) do { _Pragma("unroll") for (int _i = 0; _i < 2; ++_i) \
;         __builtin_amdgcn_global_load_lds((const unsigned*)((const char*)(gbase) + (voff)[_i]), (LAS unsigned*)(lds + (bufoff) + ldsw + _i * 8192), 16, 0, 0); } while (0)
; #define PG8_LDA(dst, b, h) do { _Pragma("unroll") for (int m = 0; m < 4; ++m) _Pragma("unroll") for (int k = 0; k < 2; ++k) dst[m][k] = *(const LAS bf16x8*)(lds + PG8_SA(b, h) + aoff + m * 2048 + k * 1024); } while (0)
; #define PG8_MMA(ai, bj, At, Bt) do { __builtin_amdgcn_s_setprio(1); _Pragma("unroll") for (int m = 0; m < 4; ++m) _Pragma("unroll") for (int n = 0; n < 2; ++n) _Pragma("unroll") for (int k = 0; k < 2; ++k) \
;         acc[ai][bj][m][n] = __builtin_amdgcn_mfma_f32_16x16x32_bf16(Bt[n][k], At[m][k], acc[ai][bj][m][n], 0, 0, 0); __builtin_amdgcn_s_setprio(0); } while (0)
; #define PG8_WAIT_V(n) asm volatile("s_waitcnt vmcnt(" #n ")" ::: "memory")
; #define PG8_WAIT_L(n) asm volatile("s_waitcnt lgkmcnt(" #n ")" ::: "memory")
; #define PG8_BAR __builtin_amdgcn_s_barrier()
; #define PG8_SCHED __builtin_amdgcn_sched_barrier(0)
; template <class Epi>
; __device__ __forceinline__ void gemm_phase(LAS unsigned char* lds, const Gemm g, int G, int c, const Epi& E) {
;     ...
;             PG8_WAIT_V(8); PG8_WAIT_L(0); PG8_BAR; PG8_MMA(0, 0, At, B0); PG8_MMA(0, 1, At, B1); PG8_BAR; PG8_SCHED;
;             PG8_LDA(At, 0, 1); PG8_STAGE(PG8_SB(0, 0), b2, voffB); PG8_STAGE(PG8_SB(0, 1), b2 + hstepB, voffB); PG8_STAGE(PG8_SA(0, 0), a2, voffA);
;             PG8_WAIT_V(8); PG8_WAIT_L(0); PG8_BAR; PG8_MMA(1, 0, At, B0); PG8_MMA(1, 1, At, B1); PG8_BAR; PG8_SCHED;
	s_setprio 0
	v_mfma_f32_16x16x32_bf16 v[126:129], v[146:149], v[186:189], v[126:129]
	v_mfma_f32_16x16x32_bf16 v[122:125], v[162:165], v[186:189], v[122:125]
	v_mfma_f32_16x16x32_bf16 v[110:113], v[146:149], v[194:197], v[110:113]
	v_mfma_f32_16x16x32_bf16 v[106:109], v[162:165], v[194:197], v[106:109]
	v_mfma_f32_16x16x32_bf16 v[94:97], v[146:149], v[202:205], v[94:97]
	v_mfma_f32_16x16x32_bf16 v[90:93], v[162:165], v[202:205], v[90:93]
	v_mfma_f32_16x16x32_bf16 v[78:81], v[146:149], v[210:213], v[78:81]
	v_mfma_f32_16x16x32_bf16 v[74:77], v[162:165], v[210:213], v[74:77]
	v_mfma_f32_16x16x32_bf16 v[126:129], v[158:161], v[190:193], v[126:129]
	v_mfma_f32_16x16x32_bf16 v[122:125], v[166:169], v[190:193], v[122:125]
	v_mfma_f32_16x16x32_bf16 v[110:113], v[158:161], v[198:201], v[110:113]
	v_mfma_f32_16x16x32_bf16 v[106:109], v[166:169], v[198:201], v[106:109]
	v_mfma_f32_16x16x32_bf16 v[94:97], v[158:161], v[206:209], v[94:97]
	v_mfma_f32_16x16x32_bf16 v[90:93], v[166:169], v[206:209], v[90:93]
	v_mfma_f32_16x16x32_bf16 v[78:81], v[158:161], v[214:217], v[78:81]
	v_mfma_f32_16x16x32_bf16 v[74:77], v[166:169], v[214:217], v[74:77]
	s_setprio 2
	s_setprio 0
	v_mfma_f32_16x16x32_bf16 v[118:121], v[170:173], v[186:189], v[118:121]
	v_mfma_f32_16x16x32_bf16 v[114:117], v[178:181], v[186:189], v[114:117]
	v_mfma_f32_16x16x32_bf16 v[102:105], v[170:173], v[194:197], v[102:105]
	v_mfma_f32_16x16x32_bf16 v[98:101], v[178:181], v[194:197], v[98:101]
	v_mfma_f32_16x16x32_bf16 v[86:89], v[170:173], v[202:205], v[86:89]
	v_mfma_f32_16x16x32_bf16 v[82:85], v[178:181], v[202:205], v[82:85]
	v_mfma_f32_16x16x32_bf16 v[70:73], v[170:173], v[210:213], v[70:73]
	v_mfma_f32_16x16x32_bf16 v[66:69], v[178:181], v[210:213], v[66:69]
	v_mfma_f32_16x16x32_bf16 v[118:121], v[174:177], v[190:193], v[118:121]
	v_mfma_f32_16x16x32_bf16 v[114:117], v[182:185], v[190:193], v[114:117]
	v_mfma_f32_16x16x32_bf16 v[102:105], v[174:177], v[198:201], v[102:105]
	v_mfma_f32_16x16x32_bf16 v[98:101], v[182:185], v[198:201], v[98:101]
	v_mfma_f32_16x16x32_bf16 v[86:89], v[174:177], v[206:209], v[86:89]
	v_mfma_f32_16x16x32_bf16 v[82:85], v[182:185], v[206:209], v[82:85]
	v_mfma_f32_16x16x32_bf16 v[70:73], v[174:177], v[214:217], v[70:73]
	v_mfma_f32_16x16x32_bf16 v[66:69], v[182:185], v[214:217], v[66:69]
	s_setprio 2
	s_barrier
	s_add_i32 s33, s71, s56
	v_lshl_add_u64 v[218:219], s[46:47], 0, v[132:133]
	s_mov_b32 m0, s33
	ds_read_b128 v[186:189], v154 offset:16384
	ds_read_b128 v[190:193], v154 offset:17408
	ds_read_b128 v[194:197], v154 offset:18432
	ds_read_b128 v[198:201], v154 offset:19456
	ds_read_b128 v[202:205], v154 offset:20480
	ds_read_b128 v[206:209], v154 offset:21504
	ds_read_b128 v[210:213], v154 offset:22528
	ds_read_b128 v[214:217], v154 offset:23552
	global_load_lds_dwordx4 v[218:219], off
	s_add_i32 m0, s33, 0x2000
	s_add_u32 s62, s46, 0x40000
	v_lshl_add_u64 v[220:221], s[46:47], 0, v[136:137]
	s_addc_u32 s63, s47, 0
	s_add_i32 s33, s72, s56
	global_load_lds_dwordx4 v[220:221], off
	v_lshl_add_u64 v[222:223], s[62:63], 0, v[132:133]
	s_mov_b32 m0, s33
	v_lshl_add_u64 v[224:225], s[48:49], 0, v[134:135]
	global_load_lds_dwordx4 v[222:223], off
	v_lshl_add_u64 v[222:223], s[62:63], 0, v[136:137]
	s_add_i32 m0, s33, 0x2000
	s_nop 0
	global_load_lds_dwordx4 v[222:223], off
	v_lshl_add_u64 v[222:223], s[48:49], 0, v[130:131]
	s_mov_b32 m0, s11
	s_nop 0
	global_load_lds_dwordx4 v[222:223], off
	s_mov_b32 m0, s57
	s_nop 0
	global_load_lds_dwordx4 v[224:225], off
	s_waitcnt vmcnt(8)
	s_waitcnt lgkmcnt(0)
	s_barrier
	s_setprio 0
	v_mfma_f32_16x16x32_bf16 v[62:65], v[146:149], v[186:189], v[62:65]
	v_mfma_f32_16x16x32_bf16 v[58:61], v[162:165], v[186:189], v[58:61]
	v_mfma_f32_16x16x32_bf16 v[46:49], v[146:149], v[194:197], v[46:49]
	v_mfma_f32_16x16x32_bf16 v[42:45], v[162:165], v[194:197], v[42:45]
	v_mfma_f32_16x16x32_bf16 v[30:33], v[146:149], v[202:205], v[30:33]
	v_mfma_f32_16x16x32_bf16 v[26:29], v[162:165], v[202:205], v[26:29]
	v_mfma_f32_16x16x32_bf16 v[14:17], v[146:149], v[210:213], v[14:17]
	v_mfma_f32_16x16x32_bf16 v[10:13], v[162:165], v[210:213], v[10:13]
	v_mfma_f32_16x16x32_bf16 v[62:65], v[158:161], v[190:193], v[62:65]
	v_mfma_f32_16x16x32_bf16 v[58:61], v[166:169], v[190:193], v[58:61]
	v_mfma_f32_16x16x32_bf16 v[46:49], v[158:161], v[198:201], v[46:49]
	v_mfma_f32_16x16x32_bf16 v[42:45], v[166:169], v[198:201], v[42:45]
	v_mfma_f32_16x16x32_bf16 v[30:33], v[158:161], v[206:209], v[30:33]
	v_mfma_f32_16x16x32_bf16 v[26:29], v[166:169], v[206:209], v[26:29]
	v_mfma_f32_16x16x32_bf16 v[14:17], v[158:161], v[214:217], v[14:17]
	v_mfma_f32_16x16x32_bf16 v[10:13], v[166:169], v[214:217], v[10:13]
	s_setprio 2
	s_setprio 0
	v_mfma_f32_16x16x32_bf16 v[54:57], v[170:173], v[186:189], v[54:57]
	v_mfma_f32_16x16x32_bf16 v[50:53], v[178:181], v[186:189], v[50:53]
	v_mfma_f32_16x16x32_bf16 v[38:41], v[170:173], v[194:197], v[38:41]
	v_mfma_f32_16x16x32_bf16 v[34:37], v[178:181], v[194:197], v[34:37]
	v_mfma_f32_16x16x32_bf16 v[22:25], v[170:173], v[202:205], v[22:25]
	v_mfma_f32_16x16x32_bf16 v[18:21], v[178:181], v[202:205], v[18:21]
	v_mfma_f32_16x16x32_bf16 v[6:9], v[170:173], v[210:213], v[6:9]
	v_mfma_f32_16x16x32_bf16 v[2:5], v[178:181], v[210:213], v[2:5]
	v_mfma_f32_16x16x32_bf16 v[54:57], v[174:177], v[190:193], v[54:57]
	v_mfma_f32_16x16x32_bf16 v[50:53], v[182:185], v[190:193], v[50:53]
	v_mfma_f32_16x16x32_bf16 v[38:41], v[174:177], v[198:201], v[38:41]
	v_mfma_f32_16x16x32_bf16 v[34:37], v[182:185], v[198:201], v[34:37]
	v_mfma_f32_16x16x32_bf16 v[22:25], v[174:177], v[206:209], v[22:25]
	v_mfma_f32_16x16x32_bf16 v[18:21], v[182:185], v[206:209], v[18:21]
	v_mfma_f32_16x16x32_bf16 v[6:9], v[174:177], v[214:217], v[6:9]
	v_mfma_f32_16x16x32_bf16 v[2:5], v[182:185], v[214:217], v[2:5]
	s_setprio 2
	s_barrier
; #define PG8_STAGE(bufoff, gbase, voff) do { _Pragma("unroll") for (int _i = 0; _i < 2; ++_i) \
;         __builtin_amdgcn_global_load_lds((const unsigned*)((const char*)(gbase) + (voff)[_i]), (LAS unsigned*)(lds + (bufoff) + ldsw + _i * 8192), 16, 0, 0); } while (0)
; #define PG8_LDA(dst, b, h) do { _Pragma("unroll") for (int m = 0; m < 4; ++m) _Pragma("unroll") for (int k = 0; k < 2; ++k) dst[m][k] = *(const LAS bf16x8*)(lds + PG8_SA(b, h) + aoff + m * 2048 + k * 1024); } while (0)
; #define PG8_LDB(dst, b, h) do { _Pragma("unroll") for (int n = 0; n < 2; ++n) _Pragma("unroll") for (int k = 0; k < 2; ++k) dst[n][k] = *(const LAS bf16x8*)(lds + PG8_SB(b, h) + boff + n * 2048 + k * 1024); } while (0)
; #define PG8_MMA(ai, bj, At, Bt) do { __builtin_amdgcn_s_setprio(1); _Pragma("unroll") for (int m = 0; m < 4; ++m) _Pragma("unroll") for (int n = 0; n < 2; ++n) _Pragma("unroll") for (int k = 0; k < 2; ++k) \
;         acc[ai][bj][m][n] = __builtin_amdgcn_mfma_f32_16x16x32_bf16(Bt[n][k], At[m][k], acc[ai][bj][m][n], 0, 0, 0); __builtin_amdgcn_s_setprio(0); } while (0)
; #define PG8_WAIT_V(n) asm volatile("s_waitcnt vmcnt(" #n ")" ::: "memory")
; #define PG8_WAIT_L(n) asm volatile("s_waitcnt lgkmcnt(" #n ")" ::: "memory")
; #define PG8_BAR __builtin_amdgcn_s_barrier()
; #define PG8_SCHED __builtin_amdgcn_sched_barrier(0)
; template <class Epi>
; __device__ __forceinline__ void gemm_phase(LAS unsigned char* lds, const Gemm g, int G, int c, const Epi& E) {
;     ...
;             PG8_LDB(B0, 1, 0); PG8_LDB(B1, 1, 1); PG8_SCHED; PG8_LDA(At, 1, 0); PG8_STAGE(PG8_SA(0, 1), a2 + hstepA, voffA);
;             PG8_WAIT_V(8); PG8_WAIT_L(0); PG8_BAR; PG8_MMA(0, 0, At, B0); PG8_MMA(0, 1, At, B1); PG8_BAR; PG8_SCHED;
	s_add_i32 s33, 0, 0x18000
	v_add_u32_e32 v157, s33, v151
	s_add_i32 s62, 0, 0x1c000
	ds_read_b128 v[146:149], v157
	ds_read_b128 v[158:161], v157 offset:1024
	ds_read_b128 v[162:165], v157 offset:2048
	ds_read_b128 v[166:169], v157 offset:3072
	v_add_u32_e32 v157, s62, v151
	ds_read_b128 v[170:173], v157
	ds_read_b128 v[174:177], v157 offset:1024
	ds_read_b128 v[178:181], v157 offset:2048
	ds_read_b128 v[182:185], v157 offset:3072
	s_add_u32 s48, s48, 0x40000
	s_addc_u32 s49, s49, 0
	s_mov_b32 m0, s58
	v_lshl_add_u64 v[226:227], s[48:49], 0, v[130:131]
	ds_read_b128 v[186:189], v154 offset:32768
	ds_read_b128 v[190:193], v154 offset:33792
	ds_read_b128 v[194:197], v154 offset:34816
	ds_read_b128 v[198:201], v154 offset:35840
	ds_read_b128 v[202:205], v154 offset:36864
	ds_read_b128 v[206:209], v154 offset:37888
	ds_read_b128 v[210:213], v154 offset:38912
	ds_read_b128 v[214:217], v154 offset:39936
	global_load_lds_dwordx4 v[226:227], off
	v_lshl_add_u64 v[226:227], s[48:49], 0, v[134:135]
	s_mov_b32 m0, s59
	s_nop 0
	global_load_lds_dwordx4 v[226:227], off
	s_waitcnt vmcnt(8)
	s_waitcnt lgkmcnt(0)
	s_barrier
	s_setprio 0
	v_mfma_f32_16x16x32_bf16 v[126:129], v[146:149], v[186:189], v[126:129]
	v_mfma_f32_16x16x32_bf16 v[122:125], v[162:165], v[186:189], v[122:125]
	v_mfma_f32_16x16x32_bf16 v[110:113], v[146:149], v[194:197], v[110:113]
	v_mfma_f32_16x16x32_bf16 v[106:109], v[162:165], v[194:197], v[106:109]
	v_mfma_f32_16x16x32_bf16 v[94:97], v[146:149], v[202:205], v[94:97]
	v_mfma_f32_16x16x32_bf16 v[90:93], v[162:165], v[202:205], v[90:93]
	v_mfma_f32_16x16x32_bf16 v[78:81], v[146:149], v[210:213], v[78:81]
	v_mfma_f32_16x16x32_bf16 v[74:77], v[162:165], v[210:213], v[74:77]
	v_mfma_f32_16x16x32_bf16 v[126:129], v[158:161], v[190:193], v[126:129]
	v_mfma_f32_16x16x32_bf16 v[122:125], v[166:169], v[190:193], v[122:125]
	v_mfma_f32_16x16x32_bf16 v[110:113], v[158:161], v[198:201], v[110:113]
	v_mfma_f32_16x16x32_bf16 v[106:109], v[166:169], v[198:201], v[106:109]
	v_mfma_f32_16x16x32_bf16 v[94:97], v[158:161], v[206:209], v[94:97]
	v_mfma_f32_16x16x32_bf16 v[90:93], v[166:169], v[206:209], v[90:93]
	v_mfma_f32_16x16x32_bf16 v[78:81], v[158:161], v[214:217], v[78:81]
	v_mfma_f32_16x16x32_bf16 v[74:77], v[166:169], v[214:217], v[74:77]
	s_setprio 2
	s_setprio 0
	v_mfma_f32_16x16x32_bf16 v[118:121], v[170:173], v[186:189], v[118:121]
	v_mfma_f32_16x16x32_bf16 v[114:117], v[178:181], v[186:189], v[114:117]
	v_mfma_f32_16x16x32_bf16 v[102:105], v[170:173], v[194:197], v[102:105]
	v_mfma_f32_16x16x32_bf16 v[98:101], v[178:181], v[194:197], v[98:101]
	v_mfma_f32_16x16x32_bf16 v[86:89], v[170:173], v[202:205], v[86:89]
	v_mfma_f32_16x16x32_bf16 v[82:85], v[178:181], v[202:205], v[82:85]
	v_mfma_f32_16x16x32_bf16 v[70:73], v[170:173], v[210:213], v[70:73]
	v_mfma_f32_16x16x32_bf16 v[66:69], v[178:181], v[210:213], v[66:69]
	v_mfma_f32_16x16x32_bf16 v[118:121], v[174:177], v[190:193], v[118:121]
	v_mfma_f32_16x16x32_bf16 v[114:117], v[182:185], v[190:193], v[114:117]
	v_mfma_f32_16x16x32_bf16 v[102:105], v[174:177], v[198:201], v[102:105]
	v_mfma_f32_16x16x32_bf16 v[98:101], v[182:185], v[198:201], v[98:101]
	v_mfma_f32_16x16x32_bf16 v[86:89], v[174:177], v[206:209], v[86:89]
	v_mfma_f32_16x16x32_bf16 v[82:85], v[182:185], v[206:209], v[82:85]
	v_mfma_f32_16x16x32_bf16 v[70:73], v[174:177], v[214:217], v[70:73]
	v_mfma_f32_16x16x32_bf16 v[66:69], v[182:185], v[214:217], v[66:69]
	s_setprio 2
	s_barrier
; #define PG8_STAGE(bufoff, gbase, voff) do { _Pragma("unroll") for (int _i = 0; _i < 2; ++_i) \
;         __builtin_amdgcn_global_load_lds((const unsigned*)((const char*)(gbase) + (voff)[_i]), (LAS unsigned*)(lds + (bufoff) + ldsw + _i * 8192), 16, 0, 0); } while (0)
; #define PG8_LDA(dst, b, h) do { _Pragma("unroll") for (int m = 0; m < 4; ++m) _Pragma("unroll") for (int k = 0; k < 2; ++k) dst[m][k] = *(const LAS bf16x8*)(lds + PG8_SA(b, h) + aoff + m * 2048 + k * 1024); } while (0)
; #define PG8_MMA(ai, bj, At, Bt) do { __builtin_amdgcn_s_setprio(1); _Pragma("unroll") for (int m = 0; m < 4; ++m) _Pragma("unroll") for (int n = 0; n < 2; ++n) _Pragma("unroll") for (int k = 0; k < 2; ++k) \
;         acc[ai][bj][m][n] = __builtin_amdgcn_mfma_f32_16x16x32_bf16(Bt[n][k], At[m][k], acc[ai][bj][m][n], 0, 0, 0); __builtin_amdgcn_s_setprio(0); } while (0)
; #define PG8_WAIT_V(n) asm volatile("s_waitcnt vmcnt(" #n ")" ::: "memory")
; #define PG8_WAIT_L(n) asm volatile("s_waitcnt lgkmcnt(" #n ")" ::: "memory")
; #define PG8_BAR __builtin_amdgcn_s_barrier()
; #define PG8_SCHED __builtin_amdgcn_sched_barrier(0)
; template <class Epi>
; __device__ __forceinline__ void gemm_phase(LAS unsigned char* lds, const Gemm g, int G, int c, const Epi& E) {
;     ...
;         for (int t = 0; t < nt; t += 2) {
;     ...
;             PG8_LDA(At, 1, 1); PG8_STAGE(PG8_SB(1, 0), b3, voffB); PG8_STAGE(PG8_SB(1, 1), b3 + hstepB, voffB); PG8_STAGE(PG8_SA(1, 0), a3, voffA);
;             PG8_WAIT_V(8); PG8_WAIT_L(0); PG8_BAR; PG8_MMA(1, 0, At, B0); PG8_MMA(1, 1, At, B1); PG8_BAR; PG8_SCHED;
;         }
;         if (wr == 0) PG8_BAR;
	s_add_i32 s33, s33, s56
	v_lshl_add_u64 v[218:219], v[218:219], 0, s[20:21]
	s_mov_b32 m0, s33
	ds_read_b128 v[186:189], v154 offset:49152
	ds_read_b128 v[190:193], v154 offset:50176
	ds_read_b128 v[194:197], v154 offset:51200
	ds_read_b128 v[198:201], v154 offset:52224
	ds_read_b128 v[202:205], v154 offset:53248
	ds_read_b128 v[206:209], v154 offset:54272
	ds_read_b128 v[210:213], v154 offset:55296
	ds_read_b128 v[214:217], v154 offset:56320
	global_load_lds_dwordx4 v[218:219], off
	s_add_i32 m0, s33, 0x2000
	s_add_u32 s46, s46, 0x40080
	v_lshl_add_u64 v[218:219], v[220:221], 0, s[20:21]
	s_addc_u32 s47, s47, 0
	s_add_i32 s33, s62, s56
	global_load_lds_dwordx4 v[218:219], off
	v_lshl_add_u64 v[218:219], s[46:47], 0, v[132:133]
	s_mov_b32 m0, s33
	s_nop 0
	global_load_lds_dwordx4 v[218:219], off
	v_lshl_add_u64 v[218:219], s[46:47], 0, v[136:137]
	s_add_i32 m0, s33, 0x2000
	s_nop 0
	global_load_lds_dwordx4 v[218:219], off
	v_lshl_add_u64 v[218:219], v[222:223], 0, s[20:21]
	s_mov_b32 m0, s67
	s_nop 0
	global_load_lds_dwordx4 v[218:219], off
	v_lshl_add_u64 v[218:219], v[224:225], 0, s[20:21]
	s_mov_b32 m0, s68
	s_nop 0
	global_load_lds_dwordx4 v[218:219], off
	s_waitcnt vmcnt(8)
	s_waitcnt lgkmcnt(0)
	s_barrier
	s_setprio 0
	v_mfma_f32_16x16x32_bf16 v[62:65], v[146:149], v[186:189], v[62:65]
	v_mfma_f32_16x16x32_bf16 v[58:61], v[162:165], v[186:189], v[58:61]
	v_mfma_f32_16x16x32_bf16 v[46:49], v[146:149], v[194:197], v[46:49]
	v_mfma_f32_16x16x32_bf16 v[42:45], v[162:165], v[194:197], v[42:45]
	v_mfma_f32_16x16x32_bf16 v[30:33], v[146:149], v[202:205], v[30:33]
	v_mfma_f32_16x16x32_bf16 v[26:29], v[162:165], v[202:205], v[26:29]
	v_mfma_f32_16x16x32_bf16 v[14:17], v[146:149], v[210:213], v[14:17]
	v_mfma_f32_16x16x32_bf16 v[10:13], v[162:165], v[210:213], v[10:13]
	v_mfma_f32_16x16x32_bf16 v[62:65], v[158:161], v[190:193], v[62:65]
	v_mfma_f32_16x16x32_bf16 v[58:61], v[166:169], v[190:193], v[58:61]
	v_mfma_f32_16x16x32_bf16 v[46:49], v[158:161], v[198:201], v[46:49]
	v_mfma_f32_16x16x32_bf16 v[42:45], v[166:169], v[198:201], v[42:45]
	v_mfma_f32_16x16x32_bf16 v[30:33], v[158:161], v[206:209], v[30:33]
	v_mfma_f32_16x16x32_bf16 v[26:29], v[166:169], v[206:209], v[26:29]
	v_mfma_f32_16x16x32_bf16 v[14:17], v[158:161], v[214:217], v[14:17]
	v_mfma_f32_16x16x32_bf16 v[10:13], v[166:169], v[214:217], v[10:13]
	s_setprio 2
	s_setprio 0
	v_mfma_f32_16x16x32_bf16 v[54:57], v[170:173], v[186:189], v[54:57]
	v_mfma_f32_16x16x32_bf16 v[50:53], v[178:181], v[186:189], v[50:53]
	v_mfma_f32_16x16x32_bf16 v[38:41], v[170:173], v[194:197], v[38:41]
	v_mfma_f32_16x16x32_bf16 v[34:37], v[178:181], v[194:197], v[34:37]
	v_mfma_f32_16x16x32_bf16 v[22:25], v[170:173], v[202:205], v[22:25]
	v_mfma_f32_16x16x32_bf16 v[18:21], v[178:181], v[202:205], v[18:21]
	v_mfma_f32_16x16x32_bf16 v[6:9], v[170:173], v[210:213], v[6:9]
	v_mfma_f32_16x16x32_bf16 v[2:5], v[178:181], v[210:213], v[2:5]
	v_mfma_f32_16x16x32_bf16 v[54:57], v[174:177], v[190:193], v[54:57]
	v_mfma_f32_16x16x32_bf16 v[50:53], v[182:185], v[190:193], v[50:53]
	v_mfma_f32_16x16x32_bf16 v[38:41], v[174:177], v[198:201], v[38:41]
	v_mfma_f32_16x16x32_bf16 v[34:37], v[182:185], v[198:201], v[34:37]
	v_mfma_f32_16x16x32_bf16 v[22:25], v[174:177], v[206:209], v[22:25]
	v_mfma_f32_16x16x32_bf16 v[18:21], v[182:185], v[206:209], v[18:21]
	v_mfma_f32_16x16x32_bf16 v[6:9], v[174:177], v[214:217], v[6:9]
	v_mfma_f32_16x16x32_bf16 v[2:5], v[182:185], v[214:217], v[2:5]
	s_setprio 2
	s_add_i32 s81, s81, 2
	s_add_u32 s4, s4, 0x100
	s_addc_u32 s5, s5, 0
	s_add_u32 s41, s41, 0x100
	s_addc_u32 s80, s80, 0
	s_cmp_gt_u32 s81, 13
	s_barrier
	s_cbranch_scc0 .LBB0_1297
	s_and_b64 vcc, exec, s[22:23]
	s_cbranch_vccz .LBB0_1300
	s_barrier

; #define PG8_STAGE(bufoff, gbase, voff) do { _Pragma("unroll") for (int _i = 0; _i < 2; ++_i) \
;         __builtin_amdgcn_global_load_lds((const unsigned*)((const char*)(gbase) + (voff)[_i]), (LAS unsigned*)(lds + (bufoff) + ldsw + _i * 8192), 16, 0, 0); } while (0)
; #define PG8_LDA(dst, b, h) do { _Pragma("unroll") for (int m = 0; m < 4; ++m) _Pragma("unroll") for (int k = 0; k < 2; ++k) dst[m][k] = *(const LAS bf16x8*)(lds + PG8_SA(b, h) + aoff + m * 2048 + k * 1024); } while (0)
; #define PG8_LDB(dst, b, h) do { _Pragma("unroll") for (int n = 0; n < 2; ++n) _Pragma("unroll") for (int k = 0; k < 2; ++k) dst[n][k] = *(const LAS bf16x8*)(lds + PG8_SB(b, h) + boff + n * 2048 + k * 1024); } while (0)
; #define PG8_MMA(ai, bj, At, Bt) do { __builtin_amdgcn_s_setprio(1); _Pragma("unroll") for (int m = 0; m < 4; ++m) _Pragma("unroll") for (int n = 0; n < 2; ++n) _Pragma("unroll") for (int k = 0; k < 2; ++k) \
;         acc[ai][bj][m][n] = __builtin_amdgcn_mfma_f32_16x16x32_bf16(Bt[n][k], At[m][k], acc[ai][bj][m][n], 0, 0, 0); __builtin_amdgcn_s_setprio(0); } while (0)
; template <class Epi>
; __device__ __forceinline__ void gemm_phase(LAS unsigned char* lds, const Gemm g, int G, int c, const Epi& E) {
;     ...
;         const bool has_next = S.next(ui + 1, nxt);
;         const char* nA = has_next ? (const char*)(g.A + (size_t)nxt.pb * g.sA) + (size_t)nxt.pm * 2 * hstepA : cA;
;         const char* nB = has_next ? (const char*)(g.Bt + (size_t)nxt.pb * g.sB) + (size_t)nxt.pn * 2 * hstepB : cB;
; #pragma nounroll
;         for (int t = 0; t < nt; t += 2) {
;             const bool last = (t == nt - 2);
;             const char* a1 = cA + (size_t)(t + 1) * kstep;
;             const char* a2 = last ? nA : cA + (size_t)(t + 2) * kstep; const char* b2 = last ? nB : cB + (size_t)(t + 2) * kstep;
;             const char* a3 = a2 + kstep; const char* b3 = b2 + kstep;
;             PG8_LDB(B0, 0, 0); PG8_LDB(B1, 0, 1); PG8_SCHED; PG8_LDA(At, 0, 0); PG8_STAGE(PG8_SA(1, 1), a1 + hstepA, voffA);
;             PG8_WAIT_V(8); PG8_WAIT_L(0); PG8_BAR; PG8_MMA(0, 0, At, B0); PG8_MMA(0, 1, At, B1); PG8_BAR; PG8_SCHED;
;             PG8_LDA(At, 0, 1); PG8_STAGE(PG8_SB(0, 0), b2, voffB); PG8_STAGE(PG8_SB(0, 1), b2 + hstepB, voffB); PG8_STAGE(PG8_SA(0, 0), a2, voffA);
;             PG8_WAIT_V(8); PG8_WAIT_L(0); PG8_BAR; PG8_MMA(1, 0, At, B0); PG8_MMA(1, 1, At, B1); PG8_BAR; PG8_SCHED;
.LBB0_1824:
	s_ashr_i32 s15, s14, 31
	s_lshl_b64 s[18:19], s[14:15], 21
	s_add_u32 s18, s34, s18
	s_addc_u32 s19, s35, s19
	s_and_b64 s[24:25], s[2:3], exec
	s_cselect_b32 s15, s19, s41
	s_cselect_b32 s63, s18, s40
	s_ashr_i32 s11, s10, 31
	s_lshl_b64 s[24:25], s[10:11], 21
	s_add_u32 s11, s46, s24
	s_addc_u32 s33, s47, s25
	s_ashr_i32 s13, s12, 31
	s_lshl_b64 s[24:25], s[12:13], 21
	s_add_u32 s24, s11, s24
	s_addc_u32 s25, s33, s25
	s_and_b64 s[44:45], s[2:3], exec
	s_cselect_b32 s11, s25, s43
	s_cselect_b32 s13, s24, s42
	s_add_u32 s40, s40, 0x100080
	s_addc_u32 s41, s41, 0
	s_add_u32 s66, s42, 0x100
	s_addc_u32 s67, s43, 0
	s_mov_b32 s68, -2
	ds_read_b128 v[146:149], v152
	ds_read_b128 v[156:159], v152 offset:1024
	ds_read_b128 v[160:163], v152 offset:2048
	ds_read_b128 v[164:167], v152 offset:3072
	ds_read_b128 v[168:171], v153
	ds_read_b128 v[172:175], v153 offset:1024
	ds_read_b128 v[176:179], v153 offset:2048
	ds_read_b128 v[180:183], v153 offset:3072
	s_add_u32 s33, s40, 0xfff00080
	s_addc_u32 s42, s41, -1
	s_cmp_eq_u32 s68, 60
	s_cselect_b32 s45, s15, s42
	s_cselect_b32 s44, s63, s33
	s_cselect_b32 s43, s11, s67
	s_cselect_b32 s42, s13, s66
	v_lshl_add_u64 v[216:217], s[40:41], 0, v[138:139]
	s_add_i32 m0, s17, 0xc000
	ds_read_b128 v[184:187], v154
	ds_read_b128 v[188:191], v154 offset:1024
	ds_read_b128 v[192:195], v154 offset:2048
	ds_read_b128 v[196:199], v154 offset:3072
	ds_read_b128 v[200:203], v154 offset:4096
	ds_read_b128 v[204:207], v154 offset:5120
	ds_read_b128 v[208:211], v154 offset:6144
	ds_read_b128 v[212:215], v154 offset:7168
	global_load_lds_dwordx4 v[216:217], off
	v_lshl_add_u64 v[216:217], s[40:41], 0, v[140:141]
	s_add_i32 m0, s17, 0xe000
	s_nop 0
	global_load_lds_dwordx4 v[216:217], off
	s_waitcnt vmcnt(8)
	s_waitcnt lgkmcnt(0)
	s_barrier
	s_setprio 0
	v_mfma_f32_16x16x32_bf16 v[126:129], v[146:149], v[184:187], 0
	v_mfma_f32_16x16x32_bf16 v[122:125], v[160:163], v[184:187], 0
	v_mfma_f32_16x16x32_bf16 v[118:121], v[146:149], v[192:195], 0
	v_mfma_f32_16x16x32_bf16 v[110:113], v[160:163], v[192:195], 0
	v_mfma_f32_16x16x32_bf16 v[102:105], v[146:149], v[200:203], 0
	v_mfma_f32_16x16x32_bf16 v[94:97], v[160:163], v[200:203], 0
	v_mfma_f32_16x16x32_bf16 v[86:89], v[146:149], v[208:211], 0
	v_mfma_f32_16x16x32_bf16 v[78:81], v[160:163], v[208:211], 0
	v_mfma_f32_16x16x32_bf16 v[126:129], v[156:159], v[188:191], v[126:129]
	v_mfma_f32_16x16x32_bf16 v[122:125], v[164:167], v[188:191], v[122:125]
	v_mfma_f32_16x16x32_bf16 v[118:121], v[156:159], v[196:199], v[118:121]
	v_mfma_f32_16x16x32_bf16 v[110:113], v[164:167], v[196:199], v[110:113]
	v_mfma_f32_16x16x32_bf16 v[102:105], v[156:159], v[204:207], v[102:105]
	v_mfma_f32_16x16x32_bf16 v[94:97], v[164:167], v[204:207], v[94:97]
	v_mfma_f32_16x16x32_bf16 v[86:89], v[156:159], v[212:215], v[86:89]
	v_mfma_f32_16x16x32_bf16 v[78:81], v[164:167], v[212:215], v[78:81]
	s_setprio 2
	s_setprio 0
	v_mfma_f32_16x16x32_bf16 v[114:117], v[168:171], v[184:187], 0
	v_mfma_f32_16x16x32_bf16 v[106:109], v[176:179], v[184:187], 0
	v_mfma_f32_16x16x32_bf16 v[98:101], v[168:171], v[192:195], 0
	v_mfma_f32_16x16x32_bf16 v[90:93], v[176:179], v[192:195], 0
	v_mfma_f32_16x16x32_bf16 v[82:85], v[168:171], v[200:203], 0
	v_mfma_f32_16x16x32_bf16 v[74:77], v[176:179], v[200:203], 0
	v_mfma_f32_16x16x32_bf16 v[70:73], v[168:171], v[208:211], 0
	v_mfma_f32_16x16x32_bf16 v[66:69], v[176:179], v[208:211], 0
	v_mfma_f32_16x16x32_bf16 v[114:117], v[172:175], v[188:191], v[114:117]
	v_mfma_f32_16x16x32_bf16 v[106:109], v[180:183], v[188:191], v[106:109]
	v_mfma_f32_16x16x32_bf16 v[98:101], v[172:175], v[196:199], v[98:101]
	v_mfma_f32_16x16x32_bf16 v[90:93], v[180:183], v[196:199], v[90:93]
	v_mfma_f32_16x16x32_bf16 v[82:85], v[172:175], v[204:207], v[82:85]
	v_mfma_f32_16x16x32_bf16 v[74:77], v[180:183], v[204:207], v[74:77]
	v_mfma_f32_16x16x32_bf16 v[70:73], v[172:175], v[212:215], v[70:73]
	v_mfma_f32_16x16x32_bf16 v[66:69], v[180:183], v[212:215], v[66:69]
	s_setprio 2
	s_barrier
	s_add_i32 s33, s61, s52
	v_lshl_add_u64 v[216:217], s[42:43], 0, v[134:135]
	s_mov_b32 m0, s33
	ds_read_b128 v[184:187], v154 offset:16384
	ds_read_b128 v[188:191], v154 offset:17408
	ds_read_b128 v[192:195], v154 offset:18432
	ds_read_b128 v[196:199], v154 offset:19456
	ds_read_b128 v[200:203], v154 offset:20480
	ds_read_b128 v[204:207], v154 offset:21504
	ds_read_b128 v[208:211], v154 offset:22528
	ds_read_b128 v[212:215], v154 offset:23552
	global_load_lds_dwordx4 v[216:217], off
	s_add_i32 m0, s33, 0x2000
	s_add_u32 s64, s42, 0x100000
	v_lshl_add_u64 v[218:219], s[42:43], 0, v[130:131]
	s_addc_u32 s65, s43, 0
	s_add_i32 s33, s62, s52
	global_load_lds_dwordx4 v[218:219], off
	v_lshl_add_u64 v[220:221], s[64:65], 0, v[134:135]
	s_mov_b32 m0, s33
	v_lshl_add_u64 v[222:223], s[44:45], 0, v[132:133]
	global_load_lds_dwordx4 v[220:221], off
	v_lshl_add_u64 v[220:221], s[64:65], 0, v[130:131]
	s_add_i32 m0, s33, 0x2000
	s_nop 0
	global_load_lds_dwordx4 v[220:221], off
	v_lshl_add_u64 v[220:221], s[44:45], 0, v[136:137]
	s_mov_b32 m0, s17
	s_nop 0
	global_load_lds_dwordx4 v[220:221], off
	s_mov_b32 m0, s37
	s_nop 0
	global_load_lds_dwordx4 v[222:223], off
	s_waitcnt vmcnt(8)
	s_waitcnt lgkmcnt(0)
	s_barrier
; #define PG8_STAGE(bufoff, gbase, voff) do { _Pragma("unroll") for (int _i = 0; _i < 2; ++_i) \
;         __builtin_amdgcn_global_load_lds((const unsigned*)((const char*)(gbase) + (voff)[_i]), (LAS unsigned*)(lds + (bufoff) + ldsw + _i * 8192), 16, 0, 0); } while (0)
; #define PG8_LDA(dst, b, h) do { _Pragma("unroll") for (int m = 0; m < 4; ++m) _Pragma("unroll") for (int k = 0; k < 2; ++k) dst[m][k] = *(const LAS bf16x8*)(lds + PG8_SA(b, h) + aoff + m * 2048 + k * 1024); } while (0)
; #define PG8_LDB(dst, b, h) do { _Pragma("unroll") for (int n = 0; n < 2; ++n) _Pragma("unroll") for (int k = 0; k < 2; ++k) dst[n][k] = *(const LAS bf16x8*)(lds + PG8_SB(b, h) + boff + n * 2048 + k * 1024); } while (0)
; #define PG8_MMA(ai, bj, At, Bt) do { __builtin_amdgcn_s_setprio(1); _Pragma("unroll") for (int m = 0; m < 4; ++m) _Pragma("unroll") for (int n = 0; n < 2; ++n) _Pragma("unroll") for (int k = 0; k < 2; ++k) \
;         acc[ai][bj][m][n] = __builtin_amdgcn_mfma_f32_16x16x32_bf16(Bt[n][k], At[m][k], acc[ai][bj][m][n], 0, 0, 0); __builtin_amdgcn_s_setprio(0); } while (0)
; #define PG8_WAIT_V(n) asm volatile("s_waitcnt vmcnt(" #n ")" ::: "memory")
; #define PG8_WAIT_L(n) asm volatile("s_waitcnt lgkmcnt(" #n ")" ::: "memory")
; #define PG8_BAR __builtin_amdgcn_s_barrier()
; #define PG8_SCHED __builtin_amdgcn_sched_barrier(0)
; template <class Epi>
; __device__ __forceinline__ void gemm_phase(LAS unsigned char* lds, const Gemm g, int G, int c, const Epi& E) {
;     ...
;             PG8_WAIT_V(8); PG8_WAIT_L(0); PG8_BAR; PG8_MMA(1, 0, At, B0); PG8_MMA(1, 1, At, B1); PG8_BAR; PG8_SCHED;
;             PG8_LDB(B0, 1, 0); PG8_LDB(B1, 1, 1); PG8_SCHED; PG8_LDA(At, 1, 0); PG8_STAGE(PG8_SA(0, 1), a2 + hstepA, voffA);
;             PG8_WAIT_V(8); PG8_WAIT_L(0); PG8_BAR; PG8_MMA(0, 0, At, B0); PG8_MMA(0, 1, At, B1); PG8_BAR; PG8_SCHED;
	s_setprio 0
	v_mfma_f32_16x16x32_bf16 v[62:65], v[146:149], v[184:187], 0
	v_mfma_f32_16x16x32_bf16 v[58:61], v[160:163], v[184:187], 0
	v_mfma_f32_16x16x32_bf16 v[54:57], v[146:149], v[192:195], 0
	v_mfma_f32_16x16x32_bf16 v[46:49], v[160:163], v[192:195], 0
	v_mfma_f32_16x16x32_bf16 v[38:41], v[146:149], v[200:203], 0
	v_mfma_f32_16x16x32_bf16 v[30:33], v[160:163], v[200:203], 0
	v_mfma_f32_16x16x32_bf16 v[22:25], v[146:149], v[208:211], 0
	v_mfma_f32_16x16x32_bf16 v[14:17], v[160:163], v[208:211], 0
	v_mfma_f32_16x16x32_bf16 v[62:65], v[156:159], v[188:191], v[62:65]
	v_mfma_f32_16x16x32_bf16 v[58:61], v[164:167], v[188:191], v[58:61]
	v_mfma_f32_16x16x32_bf16 v[54:57], v[156:159], v[196:199], v[54:57]
	v_mfma_f32_16x16x32_bf16 v[46:49], v[164:167], v[196:199], v[46:49]
	v_mfma_f32_16x16x32_bf16 v[38:41], v[156:159], v[204:207], v[38:41]
	v_mfma_f32_16x16x32_bf16 v[30:33], v[164:167], v[204:207], v[30:33]
	v_mfma_f32_16x16x32_bf16 v[22:25], v[156:159], v[212:215], v[22:25]
	v_mfma_f32_16x16x32_bf16 v[14:17], v[164:167], v[212:215], v[14:17]
	s_setprio 2
	s_setprio 0
	v_mfma_f32_16x16x32_bf16 v[50:53], v[168:171], v[184:187], 0
	v_mfma_f32_16x16x32_bf16 v[42:45], v[176:179], v[184:187], 0
	v_mfma_f32_16x16x32_bf16 v[34:37], v[168:171], v[192:195], 0
	v_mfma_f32_16x16x32_bf16 v[26:29], v[176:179], v[192:195], 0
	v_mfma_f32_16x16x32_bf16 v[18:21], v[168:171], v[200:203], 0
	v_mfma_f32_16x16x32_bf16 v[10:13], v[176:179], v[200:203], 0
	v_mfma_f32_16x16x32_bf16 v[6:9], v[168:171], v[208:211], 0
	v_mfma_f32_16x16x32_bf16 v[2:5], v[176:179], v[208:211], 0
	v_mfma_f32_16x16x32_bf16 v[50:53], v[172:175], v[188:191], v[50:53]
	v_mfma_f32_16x16x32_bf16 v[42:45], v[180:183], v[188:191], v[42:45]
	v_mfma_f32_16x16x32_bf16 v[34:37], v[172:175], v[196:199], v[34:37]
	v_mfma_f32_16x16x32_bf16 v[26:29], v[180:183], v[196:199], v[26:29]
	v_mfma_f32_16x16x32_bf16 v[18:21], v[172:175], v[204:207], v[18:21]
	v_mfma_f32_16x16x32_bf16 v[10:13], v[180:183], v[204:207], v[10:13]
	v_mfma_f32_16x16x32_bf16 v[6:9], v[172:175], v[212:215], v[6:9]
	v_mfma_f32_16x16x32_bf16 v[2:5], v[180:183], v[212:215], v[2:5]
	s_setprio 2
	s_barrier
	s_add_i32 s33, 0, 0x18000
	v_add_u32_e32 v155, s33, v151
	s_add_i32 s64, 0, 0x1c000
	ds_read_b128 v[146:149], v155
	ds_read_b128 v[156:159], v155 offset:1024
	ds_read_b128 v[160:163], v155 offset:2048
	ds_read_b128 v[164:167], v155 offset:3072
	v_add_u32_e32 v155, s64, v151
	ds_read_b128 v[168:171], v155
	ds_read_b128 v[172:175], v155 offset:1024
	ds_read_b128 v[176:179], v155 offset:2048
	ds_read_b128 v[180:183], v155 offset:3072
	s_add_u32 s44, s44, 0x100000
	s_addc_u32 s45, s45, 0
	s_mov_b32 m0, s39
	v_lshl_add_u64 v[226:227], s[44:45], 0, v[136:137]
	ds_read_b128 v[184:187], v154 offset:32768
	ds_read_b128 v[188:191], v154 offset:33792
	ds_read_b128 v[192:195], v154 offset:34816
	ds_read_b128 v[196:199], v154 offset:35840
	ds_read_b128 v[200:203], v154 offset:36864
	ds_read_b128 v[204:207], v154 offset:37888
	ds_read_b128 v[208:211], v154 offset:38912
	ds_read_b128 v[212:215], v154 offset:39936
	global_load_lds_dwordx4 v[226:227], off
	v_lshl_add_u64 v[226:227], s[44:45], 0, v[132:133]
	s_mov_b32 m0, s53
	s_nop 0
	global_load_lds_dwordx4 v[226:227], off
	s_waitcnt vmcnt(8)
	s_waitcnt lgkmcnt(0)
	s_barrier
	s_setprio 0
	v_mfma_f32_16x16x32_bf16 v[126:129], v[146:149], v[184:187], v[126:129]
	v_mfma_f32_16x16x32_bf16 v[122:125], v[160:163], v[184:187], v[122:125]
	v_mfma_f32_16x16x32_bf16 v[118:121], v[146:149], v[192:195], v[118:121]
	v_mfma_f32_16x16x32_bf16 v[110:113], v[160:163], v[192:195], v[110:113]
	v_mfma_f32_16x16x32_bf16 v[102:105], v[146:149], v[200:203], v[102:105]
	v_mfma_f32_16x16x32_bf16 v[94:97], v[160:163], v[200:203], v[94:97]
	v_mfma_f32_16x16x32_bf16 v[86:89], v[146:149], v[208:211], v[86:89]
	v_mfma_f32_16x16x32_bf16 v[78:81], v[160:163], v[208:211], v[78:81]
	v_mfma_f32_16x16x32_bf16 v[126:129], v[156:159], v[188:191], v[126:129]
	v_mfma_f32_16x16x32_bf16 v[122:125], v[164:167], v[188:191], v[122:125]
	v_mfma_f32_16x16x32_bf16 v[118:121], v[156:159], v[196:199], v[118:121]
	v_mfma_f32_16x16x32_bf16 v[110:113], v[164:167], v[196:199], v[110:113]
	v_mfma_f32_16x16x32_bf16 v[102:105], v[156:159], v[204:207], v[102:105]
	v_mfma_f32_16x16x32_bf16 v[94:97], v[164:167], v[204:207], v[94:97]
	v_mfma_f32_16x16x32_bf16 v[86:89], v[156:159], v[212:215], v[86:89]
	v_mfma_f32_16x16x32_bf16 v[78:81], v[164:167], v[212:215], v[78:81]
	s_setprio 2
	s_setprio 0
	v_mfma_f32_16x16x32_bf16 v[114:117], v[168:171], v[184:187], v[114:117]
	v_mfma_f32_16x16x32_bf16 v[106:109], v[176:179], v[184:187], v[106:109]
	v_mfma_f32_16x16x32_bf16 v[98:101], v[168:171], v[192:195], v[98:101]
	v_mfma_f32_16x16x32_bf16 v[90:93], v[176:179], v[192:195], v[90:93]
	v_mfma_f32_16x16x32_bf16 v[82:85], v[168:171], v[200:203], v[82:85]
	v_mfma_f32_16x16x32_bf16 v[74:77], v[176:179], v[200:203], v[74:77]
	v_mfma_f32_16x16x32_bf16 v[70:73], v[168:171], v[208:211], v[70:73]
	v_mfma_f32_16x16x32_bf16 v[66:69], v[176:179], v[208:211], v[66:69]
	v_mfma_f32_16x16x32_bf16 v[114:117], v[172:175], v[188:191], v[114:117]
	v_mfma_f32_16x16x32_bf16 v[106:109], v[180:183], v[188:191], v[106:109]
	v_mfma_f32_16x16x32_bf16 v[98:101], v[172:175], v[196:199], v[98:101]
	v_mfma_f32_16x16x32_bf16 v[90:93], v[180:183], v[196:199], v[90:93]
	v_mfma_f32_16x16x32_bf16 v[82:85], v[172:175], v[204:207], v[82:85]
	v_mfma_f32_16x16x32_bf16 v[74:77], v[180:183], v[204:207], v[74:77]
	v_mfma_f32_16x16x32_bf16 v[70:73], v[172:175], v[212:215], v[70:73]
	v_mfma_f32_16x16x32_bf16 v[66:69], v[180:183], v[212:215], v[66:69]
	s_setprio 2
	s_barrier
; #define PG8_STAGE(bufoff, gbase, voff) do { _Pragma("unroll") for (int _i = 0; _i < 2; ++_i) \
;         __builtin_amdgcn_global_load_lds((const unsigned*)((const char*)(gbase) + (voff)[_i]), (LAS unsigned*)(lds + (bufoff) + ldsw + _i * 8192), 16, 0, 0); } while (0)
; #define PG8_LDA(dst, b, h) do { _Pragma("unroll") for (int m = 0; m < 4; ++m) _Pragma("unroll") for (int k = 0; k < 2; ++k) dst[m][k] = *(const LAS bf16x8*)(lds + PG8_SA(b, h) + aoff + m * 2048 + k * 1024); } while (0)
; #define PG8_LDB(dst, b, h) do { _Pragma("unroll") for (int n = 0; n < 2; ++n) _Pragma("unroll") for (int k = 0; k < 2; ++k) dst[n][k] = *(const LAS bf16x8*)(lds + PG8_SB(b, h) + boff + n * 2048 + k * 1024); } while (0)
; #define PG8_WAIT_V(n) asm volatile("s_waitcnt vmcnt(" #n ")" ::: "memory")
; #define PG8_WAIT_L(n) asm volatile("s_waitcnt lgkmcnt(" #n ")" ::: "memory")
; template <class Epi>
; __device__ __forceinline__ void gemm_phase(LAS unsigned char* lds, const Gemm g, int G, int c, const Epi& E) {
;     ...
;         for (int t = 0; t < nt; t += 2) {
;             const bool last = (t == nt - 2);
;             const char* a1 = cA + (size_t)(t + 1) * kstep;
;             const char* a2 = last ? nA : cA + (size_t)(t + 2) * kstep; const char* b2 = last ? nB : cB + (size_t)(t + 2) * kstep;
;             const char* a3 = a2 + kstep; const char* b3 = b2 + kstep;
;             PG8_LDB(B0, 0, 0); PG8_LDB(B1, 0, 1); PG8_SCHED; PG8_LDA(At, 0, 0); PG8_STAGE(PG8_SA(1, 1), a1 + hstepA, voffA);
;             PG8_WAIT_V(8); PG8_WAIT_L(0); PG8_BAR; PG8_MMA(0, 0, At, B0); PG8_MMA(0, 1, At, B1); PG8_BAR; PG8_SCHED;
;             PG8_LDA(At, 0, 1); PG8_STAGE(PG8_SB(0, 0), b2, voffB); PG8_STAGE(PG8_SB(0, 1), b2 + hstepB, voffB); PG8_STAGE(PG8_SA(0, 0), a2, voffA);
;             PG8_WAIT_V(8); PG8_WAIT_L(0); PG8_BAR; PG8_MMA(1, 0, At, B0); PG8_MMA(1, 1, At, B1); PG8_BAR; PG8_SCHED;
;             PG8_LDB(B0, 1, 0); PG8_LDB(B1, 1, 1); PG8_SCHED; PG8_LDA(At, 1, 0); PG8_STAGE(PG8_SA(0, 1), a2 + hstepA, voffA);
;             PG8_WAIT_V(8); PG8_WAIT_L(0); PG8_BAR; PG8_MMA(0, 0, At, B0); PG8_MMA(0, 1, At, B1); PG8_BAR; PG8_SCHED;
;             PG8_LDA(At, 1, 1); PG8_STAGE(PG8_SB(1, 0), b3, voffB); PG8_STAGE(PG8_SB(1, 1), b3 + hstepB, voffB); PG8_STAGE(PG8_SA(1, 0), a3, voffA);
;             PG8_WAIT_V(8); PG8_WAIT_L(0); PG8_BAR; PG8_MMA(1, 0, At, B0); PG8_MMA(1, 1, At, B1); PG8_BAR; PG8_SCHED;
	s_add_i32 s33, s33, s52
	v_lshl_add_u64 v[216:217], v[216:217], 0, s[6:7]
	s_mov_b32 m0, s33
	ds_read_b128 v[184:187], v154 offset:49152
	ds_read_b128 v[188:191], v154 offset:50176
	ds_read_b128 v[192:195], v154 offset:51200
	ds_read_b128 v[196:199], v154 offset:52224
	ds_read_b128 v[200:203], v154 offset:53248
	ds_read_b128 v[204:207], v154 offset:54272
	ds_read_b128 v[208:211], v154 offset:55296
	ds_read_b128 v[212:215], v154 offset:56320
	global_load_lds_dwordx4 v[216:217], off
	s_add_i32 m0, s33, 0x2000
	s_add_u32 s42, s42, 0x100080
	v_lshl_add_u64 v[216:217], v[218:219], 0, s[6:7]
	s_addc_u32 s43, s43, 0
	s_add_i32 s33, s64, s52
	global_load_lds_dwordx4 v[216:217], off
	v_lshl_add_u64 v[216:217], s[42:43], 0, v[134:135]
	s_mov_b32 m0, s33
	s_nop 0
	global_load_lds_dwordx4 v[216:217], off
	v_lshl_add_u64 v[216:217], s[42:43], 0, v[130:131]
	s_add_i32 m0, s33, 0x2000
	s_nop 0
	global_load_lds_dwordx4 v[216:217], off
	v_lshl_add_u64 v[216:217], v[220:221], 0, s[6:7]
	s_mov_b32 m0, s59
	s_nop 0
	global_load_lds_dwordx4 v[216:217], off
	v_lshl_add_u64 v[216:217], v[222:223], 0, s[6:7]
	s_mov_b32 m0, s60
	s_nop 0
	global_load_lds_dwordx4 v[216:217], off
	s_waitcnt vmcnt(8)
	s_waitcnt lgkmcnt(0)
	s_barrier
	s_setprio 0
	v_mfma_f32_16x16x32_bf16 v[62:65], v[146:149], v[184:187], v[62:65]
	v_mfma_f32_16x16x32_bf16 v[58:61], v[160:163], v[184:187], v[58:61]
	v_mfma_f32_16x16x32_bf16 v[54:57], v[146:149], v[192:195], v[54:57]
	v_mfma_f32_16x16x32_bf16 v[46:49], v[160:163], v[192:195], v[46:49]
	v_mfma_f32_16x16x32_bf16 v[38:41], v[146:149], v[200:203], v[38:41]
	v_mfma_f32_16x16x32_bf16 v[30:33], v[160:163], v[200:203], v[30:33]
	v_mfma_f32_16x16x32_bf16 v[22:25], v[146:149], v[208:211], v[22:25]
	v_mfma_f32_16x16x32_bf16 v[14:17], v[160:163], v[208:211], v[14:17]
	v_mfma_f32_16x16x32_bf16 v[62:65], v[156:159], v[188:191], v[62:65]
	v_mfma_f32_16x16x32_bf16 v[58:61], v[164:167], v[188:191], v[58:61]
	v_mfma_f32_16x16x32_bf16 v[54:57], v[156:159], v[196:199], v[54:57]
	v_mfma_f32_16x16x32_bf16 v[46:49], v[164:167], v[196:199], v[46:49]
	v_mfma_f32_16x16x32_bf16 v[38:41], v[156:159], v[204:207], v[38:41]
	v_mfma_f32_16x16x32_bf16 v[30:33], v[164:167], v[204:207], v[30:33]
	v_mfma_f32_16x16x32_bf16 v[22:25], v[156:159], v[212:215], v[22:25]
	v_mfma_f32_16x16x32_bf16 v[14:17], v[164:167], v[212:215], v[14:17]
	s_setprio 2
	s_setprio 0
	v_mfma_f32_16x16x32_bf16 v[50:53], v[168:171], v[184:187], v[50:53]
	v_mfma_f32_16x16x32_bf16 v[42:45], v[176:179], v[184:187], v[42:45]
	v_mfma_f32_16x16x32_bf16 v[34:37], v[168:171], v[192:195], v[34:37]
	v_mfma_f32_16x16x32_bf16 v[26:29], v[176:179], v[192:195], v[26:29]
	v_mfma_f32_16x16x32_bf16 v[18:21], v[168:171], v[200:203], v[18:21]
	v_mfma_f32_16x16x32_bf16 v[10:13], v[176:179], v[200:203], v[10:13]
	v_mfma_f32_16x16x32_bf16 v[6:9], v[168:171], v[208:211], v[6:9]
	v_mfma_f32_16x16x32_bf16 v[2:5], v[176:179], v[208:211], v[2:5]
	v_mfma_f32_16x16x32_bf16 v[50:53], v[172:175], v[188:191], v[50:53]
	v_mfma_f32_16x16x32_bf16 v[42:45], v[180:183], v[188:191], v[42:45]
	v_mfma_f32_16x16x32_bf16 v[34:37], v[172:175], v[196:199], v[34:37]
	v_mfma_f32_16x16x32_bf16 v[26:29], v[180:183], v[196:199], v[26:29]
	v_mfma_f32_16x16x32_bf16 v[18:21], v[172:175], v[204:207], v[18:21]
	v_mfma_f32_16x16x32_bf16 v[10:13], v[180:183], v[204:207], v[10:13]
	v_mfma_f32_16x16x32_bf16 v[6:9], v[172:175], v[212:215], v[6:9]
	v_mfma_f32_16x16x32_bf16 v[2:5], v[180:183], v[212:215], v[2:5]
	s_setprio 2
	s_add_i32 s68, s68, 2
	s_add_u32 s40, s40, 0x100
	s_addc_u32 s41, s41, 0
	s_add_u32 s66, s66, 0x100
	s_addc_u32 s67, s67, 0
	s_cmp_gt_u32 s68, 61
	s_barrier
	s_cbranch_scc0 .LBB0_1825
.LBB0_1825:
	ds_read_b128 v[146:149], v152
	ds_read_b128 v[156:159], v152 offset:1024
	ds_read_b128 v[160:163], v152 offset:2048
	ds_read_b128 v[164:167], v152 offset:3072
	ds_read_b128 v[168:171], v153
	ds_read_b128 v[172:175], v153 offset:1024
	ds_read_b128 v[176:179], v153 offset:2048
	ds_read_b128 v[180:183], v153 offset:3072
	s_add_u32 s33, s40, 0xfff00080
	s_addc_u32 s42, s41, -1
	s_cmp_eq_u32 s68, 60
	s_cselect_b32 s45, s15, s42
	s_cselect_b32 s44, s63, s33
	s_cselect_b32 s43, s11, s67
	s_cselect_b32 s42, s13, s66
	v_lshl_add_u64 v[216:217], s[40:41], 0, v[138:139]
	s_add_i32 m0, s17, 0xc000
	ds_read_b128 v[184:187], v154
	ds_read_b128 v[188:191], v154 offset:1024
	ds_read_b128 v[192:195], v154 offset:2048
	ds_read_b128 v[196:199], v154 offset:3072
	ds_read_b128 v[200:203], v154 offset:4096
	ds_read_b128 v[204:207], v154 offset:5120
	ds_read_b128 v[208:211], v154 offset:6144
	ds_read_b128 v[212:215], v154 offset:7168
	global_load_lds_dwordx4 v[216:217], off
	v_lshl_add_u64 v[216:217], s[40:41], 0, v[140:141]
	s_add_i32 m0, s17, 0xe000
	s_nop 0
	global_load_lds_dwordx4 v[216:217], off
	s_waitcnt vmcnt(8)
	s_waitcnt lgkmcnt(0)
	s_barrier
; #define PG8_STAGE(bufoff, gbase, voff) do { _Pragma("unroll") for (int _i = 0; _i < 2; ++_i) \
;         __builtin_amdgcn_global_load_lds((const unsigned*)((const char*)(gbase) + (voff)[_i]), (LAS unsigned*)(lds + (bufoff) + ldsw + _i * 8192), 16, 0, 0); } while (0)
; #define PG8_LDA(dst, b, h) do { _Pragma("unroll") for (int m = 0; m < 4; ++m) _Pragma("unroll") for (int k = 0; k < 2; ++k) dst[m][k] = *(const LAS bf16x8*)(lds + PG8_SA(b, h) + aoff + m * 2048 + k * 1024); } while (0)
; #define PG8_MMA(ai, bj, At, Bt) do { __builtin_amdgcn_s_setprio(1); _Pragma("unroll") for (int m = 0; m < 4; ++m) _Pragma("unroll") for (int n = 0; n < 2; ++n) _Pragma("unroll") for (int k = 0; k < 2; ++k) \
;         acc[ai][bj][m][n] = __builtin_amdgcn_mfma_f32_16x16x32_bf16(Bt[n][k], At[m][k], acc[ai][bj][m][n], 0, 0, 0); __builtin_amdgcn_s_setprio(0); } while (0)
; #define PG8_WAIT_V(n) asm volatile("s_waitcnt vmcnt(" #n ")" ::: "memory")
; #define PG8_WAIT_L(n) asm volatile("s_waitcnt lgkmcnt(" #n ")" ::: "memory")
; #define PG8_BAR __builtin_amdgcn_s_barrier()
; #define PG8_SCHED __builtin_amdgcn_sched_barrier(0)
; template <class Epi>
; __device__ __forceinline__ void gemm_phase(LAS unsigned char* lds, const Gemm g, int G, int c, const Epi& E) {
;     ...
;             PG8_WAIT_V(8); PG8_WAIT_L(0); PG8_BAR; PG8_MMA(0, 0, At, B0); PG8_MMA(0, 1, At, B1); PG8_BAR; PG8_SCHED;
;             PG8_LDA(At, 0, 1); PG8_STAGE(PG8_SB(0, 0), b2, voffB); PG8_STAGE(PG8_SB(0, 1), b2 + hstepB, voffB); PG8_STAGE(PG8_SA(0, 0), a2, voffA);
;             PG8_WAIT_V(8); PG8_WAIT_L(0); PG8_BAR; PG8_MMA(1, 0, At, B0); PG8_MMA(1, 1, At, B1); PG8_BAR; PG8_SCHED;
	s_setprio 0
	v_mfma_f32_16x16x32_bf16 v[126:129], v[146:149], v[184:187], v[126:129]
	v_mfma_f32_16x16x32_bf16 v[122:125], v[160:163], v[184:187], v[122:125]
	v_mfma_f32_16x16x32_bf16 v[118:121], v[146:149], v[192:195], v[118:121]
	v_mfma_f32_16x16x32_bf16 v[110:113], v[160:163], v[192:195], v[110:113]
	v_mfma_f32_16x16x32_bf16 v[102:105], v[146:149], v[200:203], v[102:105]
	v_mfma_f32_16x16x32_bf16 v[94:97], v[160:163], v[200:203], v[94:97]
	v_mfma_f32_16x16x32_bf16 v[86:89], v[146:149], v[208:211], v[86:89]
	v_mfma_f32_16x16x32_bf16 v[78:81], v[160:163], v[208:211], v[78:81]
	v_mfma_f32_16x16x32_bf16 v[126:129], v[156:159], v[188:191], v[126:129]
	v_mfma_f32_16x16x32_bf16 v[122:125], v[164:167], v[188:191], v[122:125]
	v_mfma_f32_16x16x32_bf16 v[118:121], v[156:159], v[196:199], v[118:121]
	v_mfma_f32_16x16x32_bf16 v[110:113], v[164:167], v[196:199], v[110:113]
	v_mfma_f32_16x16x32_bf16 v[102:105], v[156:159], v[204:207], v[102:105]
	v_mfma_f32_16x16x32_bf16 v[94:97], v[164:167], v[204:207], v[94:97]
	v_mfma_f32_16x16x32_bf16 v[86:89], v[156:159], v[212:215], v[86:89]
	v_mfma_f32_16x16x32_bf16 v[78:81], v[164:167], v[212:215], v[78:81]
	s_setprio 2
	s_setprio 0
	v_mfma_f32_16x16x32_bf16 v[114:117], v[168:171], v[184:187], v[114:117]
	v_mfma_f32_16x16x32_bf16 v[106:109], v[176:179], v[184:187], v[106:109]
	v_mfma_f32_16x16x32_bf16 v[98:101], v[168:171], v[192:195], v[98:101]
	v_mfma_f32_16x16x32_bf16 v[90:93], v[176:179], v[192:195], v[90:93]
	v_mfma_f32_16x16x32_bf16 v[82:85], v[168:171], v[200:203], v[82:85]
	v_mfma_f32_16x16x32_bf16 v[74:77], v[176:179], v[200:203], v[74:77]
	v_mfma_f32_16x16x32_bf16 v[70:73], v[168:171], v[208:211], v[70:73]
	v_mfma_f32_16x16x32_bf16 v[66:69], v[176:179], v[208:211], v[66:69]
	v_mfma_f32_16x16x32_bf16 v[114:117], v[172:175], v[188:191], v[114:117]
	v_mfma_f32_16x16x32_bf16 v[106:109], v[180:183], v[188:191], v[106:109]
	v_mfma_f32_16x16x32_bf16 v[98:101], v[172:175], v[196:199], v[98:101]
	v_mfma_f32_16x16x32_bf16 v[90:93], v[180:183], v[196:199], v[90:93]
	v_mfma_f32_16x16x32_bf16 v[82:85], v[172:175], v[204:207], v[82:85]
	v_mfma_f32_16x16x32_bf16 v[74:77], v[180:183], v[204:207], v[74:77]
	v_mfma_f32_16x16x32_bf16 v[70:73], v[172:175], v[212:215], v[70:73]
	v_mfma_f32_16x16x32_bf16 v[66:69], v[180:183], v[212:215], v[66:69]
	s_setprio 2
	s_barrier
	s_add_i32 s33, s61, s52
	v_lshl_add_u64 v[216:217], s[42:43], 0, v[134:135]
	s_mov_b32 m0, s33
	ds_read_b128 v[184:187], v154 offset:16384
	ds_read_b128 v[188:191], v154 offset:17408
	ds_read_b128 v[192:195], v154 offset:18432
	ds_read_b128 v[196:199], v154 offset:19456
	ds_read_b128 v[200:203], v154 offset:20480
	ds_read_b128 v[204:207], v154 offset:21504
	ds_read_b128 v[208:211], v154 offset:22528
	ds_read_b128 v[212:215], v154 offset:23552
	global_load_lds_dwordx4 v[216:217], off
	s_add_i32 m0, s33, 0x2000
	s_add_u32 s64, s42, 0x100000
	v_lshl_add_u64 v[218:219], s[42:43], 0, v[130:131]
	s_addc_u32 s65, s43, 0
	s_add_i32 s33, s62, s52
	global_load_lds_dwordx4 v[218:219], off
	v_lshl_add_u64 v[220:221], s[64:65], 0, v[134:135]
	s_mov_b32 m0, s33
	v_lshl_add_u64 v[222:223], s[44:45], 0, v[132:133]
	global_load_lds_dwordx4 v[220:221], off
	v_lshl_add_u64 v[220:221], s[64:65], 0, v[130:131]
	s_add_i32 m0, s33, 0x2000
	s_nop 0
	global_load_lds_dwordx4 v[220:221], off
	v_lshl_add_u64 v[220:221], s[44:45], 0, v[136:137]
	s_mov_b32 m0, s17
	s_nop 0
	global_load_lds_dwordx4 v[220:221], off
	s_mov_b32 m0, s37
	s_nop 0
	global_load_lds_dwordx4 v[222:223], off
	s_waitcnt vmcnt(8)
	s_waitcnt lgkmcnt(0)
	s_barrier
	s_setprio 0
	v_mfma_f32_16x16x32_bf16 v[62:65], v[146:149], v[184:187], v[62:65]
	v_mfma_f32_16x16x32_bf16 v[58:61], v[160:163], v[184:187], v[58:61]
	v_mfma_f32_16x16x32_bf16 v[54:57], v[146:149], v[192:195], v[54:57]
	v_mfma_f32_16x16x32_bf16 v[46:49], v[160:163], v[192:195], v[46:49]
	v_mfma_f32_16x16x32_bf16 v[38:41], v[146:149], v[200:203], v[38:41]
	v_mfma_f32_16x16x32_bf16 v[30:33], v[160:163], v[200:203], v[30:33]
	v_mfma_f32_16x16x32_bf16 v[22:25], v[146:149], v[208:211], v[22:25]
	v_mfma_f32_16x16x32_bf16 v[14:17], v[160:163], v[208:211], v[14:17]
	v_mfma_f32_16x16x32_bf16 v[62:65], v[156:159], v[188:191], v[62:65]
	v_mfma_f32_16x16x32_bf16 v[58:61], v[164:167], v[188:191], v[58:61]
	v_mfma_f32_16x16x32_bf16 v[54:57], v[156:159], v[196:199], v[54:57]
	v_mfma_f32_16x16x32_bf16 v[46:49], v[164:167], v[196:199], v[46:49]
	v_mfma_f32_16x16x32_bf16 v[38:41], v[156:159], v[204:207], v[38:41]
	v_mfma_f32_16x16x32_bf16 v[30:33], v[164:167], v[204:207], v[30:33]
	v_mfma_f32_16x16x32_bf16 v[22:25], v[156:159], v[212:215], v[22:25]
	v_mfma_f32_16x16x32_bf16 v[14:17], v[164:167], v[212:215], v[14:17]
	s_setprio 2
	s_setprio 0
	v_mfma_f32_16x16x32_bf16 v[50:53], v[168:171], v[184:187], v[50:53]
	v_mfma_f32_16x16x32_bf16 v[42:45], v[176:179], v[184:187], v[42:45]
	v_mfma_f32_16x16x32_bf16 v[34:37], v[168:171], v[192:195], v[34:37]
	v_mfma_f32_16x16x32_bf16 v[26:29], v[176:179], v[192:195], v[26:29]
	v_mfma_f32_16x16x32_bf16 v[18:21], v[168:171], v[200:203], v[18:21]
	v_mfma_f32_16x16x32_bf16 v[10:13], v[176:179], v[200:203], v[10:13]
	v_mfma_f32_16x16x32_bf16 v[6:9], v[168:171], v[208:211], v[6:9]
	v_mfma_f32_16x16x32_bf16 v[2:5], v[176:179], v[208:211], v[2:5]
	v_mfma_f32_16x16x32_bf16 v[50:53], v[172:175], v[188:191], v[50:53]
	v_mfma_f32_16x16x32_bf16 v[42:45], v[180:183], v[188:191], v[42:45]
	v_mfma_f32_16x16x32_bf16 v[34:37], v[172:175], v[196:199], v[34:37]
	v_mfma_f32_16x16x32_bf16 v[26:29], v[180:183], v[196:199], v[26:29]
	v_mfma_f32_16x16x32_bf16 v[18:21], v[172:175], v[204:207], v[18:21]
	v_mfma_f32_16x16x32_bf16 v[10:13], v[180:183], v[204:207], v[10:13]
	v_mfma_f32_16x16x32_bf16 v[6:9], v[172:175], v[212:215], v[6:9]
	v_mfma_f32_16x16x32_bf16 v[2:5], v[180:183], v[212:215], v[2:5]
	s_setprio 2
	s_barrier
; #define PG8_STAGE(bufoff, gbase, voff) do { _Pragma("unroll") for (int _i = 0; _i < 2; ++_i) \
;         __builtin_amdgcn_global_load_lds((const unsigned*)((const char*)(gbase) + (voff)[_i]), (LAS unsigned*)(lds + (bufoff) + ldsw + _i * 8192), 16, 0, 0); } while (0)
; #define PG8_LDA(dst, b, h) do { _Pragma("unroll") for (int m = 0; m < 4; ++m) _Pragma("unroll") for (int k = 0; k < 2; ++k) dst[m][k] = *(const LAS bf16x8*)(lds + PG8_SA(b, h) + aoff + m * 2048 + k * 1024); } while (0)
; #define PG8_LDB(dst, b, h) do { _Pragma("unroll") for (int n = 0; n < 2; ++n) _Pragma("unroll") for (int k = 0; k < 2; ++k) dst[n][k] = *(const LAS bf16x8*)(lds + PG8_SB(b, h) + boff + n * 2048 + k * 1024); } while (0)
; #define PG8_MMA(ai, bj, At, Bt) do { __builtin_amdgcn_s_setprio(1); _Pragma("unroll") for (int m = 0; m < 4; ++m) _Pragma("unroll") for (int n = 0; n < 2; ++n) _Pragma("unroll") for (int k = 0; k < 2; ++k) \
;         acc[ai][bj][m][n] = __builtin_amdgcn_mfma_f32_16x16x32_bf16(Bt[n][k], At[m][k], acc[ai][bj][m][n], 0, 0, 0); __builtin_amdgcn_s_setprio(0); } while (0)
; #define PG8_WAIT_V(n) asm volatile("s_waitcnt vmcnt(" #n ")" ::: "memory")
; #define PG8_WAIT_L(n) asm volatile("s_waitcnt lgkmcnt(" #n ")" ::: "memory")
; #define PG8_BAR __builtin_amdgcn_s_barrier()
; #define PG8_SCHED __builtin_amdgcn_sched_barrier(0)
; template <class Epi>
; __device__ __forceinline__ void gemm_phase(LAS unsigned char* lds, const Gemm g, int G, int c, const Epi& E) {
;     ...
;             PG8_LDB(B0, 1, 0); PG8_LDB(B1, 1, 1); PG8_SCHED; PG8_LDA(At, 1, 0); PG8_STAGE(PG8_SA(0, 1), a2 + hstepA, voffA);
;             PG8_WAIT_V(8); PG8_WAIT_L(0); PG8_BAR; PG8_MMA(0, 0, At, B0); PG8_MMA(0, 1, At, B1); PG8_BAR; PG8_SCHED;
	s_add_i32 s33, 0, 0x18000
	v_add_u32_e32 v155, s33, v151
	s_add_i32 s64, 0, 0x1c000
	ds_read_b128 v[146:149], v155
	ds_read_b128 v[156:159], v155 offset:1024
	ds_read_b128 v[160:163], v155 offset:2048
	ds_read_b128 v[164:167], v155 offset:3072
	v_add_u32_e32 v155, s64, v151
	ds_read_b128 v[168:171], v155
	ds_read_b128 v[172:175], v155 offset:1024
	ds_read_b128 v[176:179], v155 offset:2048
	ds_read_b128 v[180:183], v155 offset:3072
	s_add_u32 s44, s44, 0x100000
	s_addc_u32 s45, s45, 0
	s_mov_b32 m0, s39
	v_lshl_add_u64 v[226:227], s[44:45], 0, v[136:137]
	ds_read_b128 v[184:187], v154 offset:32768
	ds_read_b128 v[188:191], v154 offset:33792
	ds_read_b128 v[192:195], v154 offset:34816
	ds_read_b128 v[196:199], v154 offset:35840
	ds_read_b128 v[200:203], v154 offset:36864
	ds_read_b128 v[204:207], v154 offset:37888
	ds_read_b128 v[208:211], v154 offset:38912
	ds_read_b128 v[212:215], v154 offset:39936
	global_load_lds_dwordx4 v[226:227], off
	v_lshl_add_u64 v[226:227], s[44:45], 0, v[132:133]
	s_mov_b32 m0, s53
	s_nop 0
	global_load_lds_dwordx4 v[226:227], off
	s_waitcnt vmcnt(8)
	s_waitcnt lgkmcnt(0)
	s_barrier
	s_setprio 0
	v_mfma_f32_16x16x32_bf16 v[126:129], v[146:149], v[184:187], v[126:129]
	v_mfma_f32_16x16x32_bf16 v[122:125], v[160:163], v[184:187], v[122:125]
	v_mfma_f32_16x16x32_bf16 v[118:121], v[146:149], v[192:195], v[118:121]
	v_mfma_f32_16x16x32_bf16 v[110:113], v[160:163], v[192:195], v[110:113]
	v_mfma_f32_16x16x32_bf16 v[102:105], v[146:149], v[200:203], v[102:105]
	v_mfma_f32_16x16x32_bf16 v[94:97], v[160:163], v[200:203], v[94:97]
	v_mfma_f32_16x16x32_bf16 v[86:89], v[146:149], v[208:211], v[86:89]
	v_mfma_f32_16x16x32_bf16 v[78:81], v[160:163], v[208:211], v[78:81]
	v_mfma_f32_16x16x32_bf16 v[126:129], v[156:159], v[188:191], v[126:129]
	v_mfma_f32_16x16x32_bf16 v[122:125], v[164:167], v[188:191], v[122:125]
	v_mfma_f32_16x16x32_bf16 v[118:121], v[156:159], v[196:199], v[118:121]
	v_mfma_f32_16x16x32_bf16 v[110:113], v[164:167], v[196:199], v[110:113]
	v_mfma_f32_16x16x32_bf16 v[102:105], v[156:159], v[204:207], v[102:105]
	v_mfma_f32_16x16x32_bf16 v[94:97], v[164:167], v[204:207], v[94:97]
	v_mfma_f32_16x16x32_bf16 v[86:89], v[156:159], v[212:215], v[86:89]
	v_mfma_f32_16x16x32_bf16 v[78:81], v[164:167], v[212:215], v[78:81]
	s_setprio 2
	s_setprio 0
	v_mfma_f32_16x16x32_bf16 v[114:117], v[168:171], v[184:187], v[114:117]
	v_mfma_f32_16x16x32_bf16 v[106:109], v[176:179], v[184:187], v[106:109]
	v_mfma_f32_16x16x32_bf16 v[98:101], v[168:171], v[192:195], v[98:101]
	v_mfma_f32_16x16x32_bf16 v[90:93], v[176:179], v[192:195], v[90:93]
	v_mfma_f32_16x16x32_bf16 v[82:85], v[168:171], v[200:203], v[82:85]
	v_mfma_f32_16x16x32_bf16 v[74:77], v[176:179], v[200:203], v[74:77]
	v_mfma_f32_16x16x32_bf16 v[70:73], v[168:171], v[208:211], v[70:73]
	v_mfma_f32_16x16x32_bf16 v[66:69], v[176:179], v[208:211], v[66:69]
	v_mfma_f32_16x16x32_bf16 v[114:117], v[172:175], v[188:191], v[114:117]
	v_mfma_f32_16x16x32_bf16 v[106:109], v[180:183], v[188:191], v[106:109]
	v_mfma_f32_16x16x32_bf16 v[98:101], v[172:175], v[196:199], v[98:101]
	v_mfma_f32_16x16x32_bf16 v[90:93], v[180:183], v[196:199], v[90:93]
	v_mfma_f32_16x16x32_bf16 v[82:85], v[172:175], v[204:207], v[82:85]
	v_mfma_f32_16x16x32_bf16 v[74:77], v[180:183], v[204:207], v[74:77]
	v_mfma_f32_16x16x32_bf16 v[70:73], v[172:175], v[212:215], v[70:73]
	v_mfma_f32_16x16x32_bf16 v[66:69], v[180:183], v[212:215], v[66:69]
	s_setprio 2
	s_barrier
; #define PG8_STAGE(bufoff, gbase, voff) do { _Pragma("unroll") for (int _i = 0; _i < 2; ++_i) \
;         __builtin_amdgcn_global_load_lds((const unsigned*)((const char*)(gbase) + (voff)[_i]), (LAS unsigned*)(lds + (bufoff) + ldsw + _i * 8192), 16, 0, 0); } while (0)
; #define PG8_LDA(dst, b, h) do { _Pragma("unroll") for (int m = 0; m < 4; ++m) _Pragma("unroll") for (int k = 0; k < 2; ++k) dst[m][k] = *(const LAS bf16x8*)(lds + PG8_SA(b, h) + aoff + m * 2048 + k * 1024); } while (0)
; #define PG8_MMA(ai, bj, At, Bt) do { __builtin_amdgcn_s_setprio(1); _Pragma("unroll") for (int m = 0; m < 4; ++m) _Pragma("unroll") for (int n = 0; n < 2; ++n) _Pragma("unroll") for (int k = 0; k < 2; ++k) \
;         acc[ai][bj][m][n] = __builtin_amdgcn_mfma_f32_16x16x32_bf16(Bt[n][k], At[m][k], acc[ai][bj][m][n], 0, 0, 0); __builtin_amdgcn_s_setprio(0); } while (0)
; #define PG8_WAIT_V(n) asm volatile("s_waitcnt vmcnt(" #n ")" ::: "memory")
; #define PG8_WAIT_L(n) asm volatile("s_waitcnt lgkmcnt(" #n ")" ::: "memory")
; #define PG8_BAR __builtin_amdgcn_s_barrier()
; #define PG8_SCHED __builtin_amdgcn_sched_barrier(0)
; template <class Epi>
; __device__ __forceinline__ void gemm_phase(LAS unsigned char* lds, const Gemm g, int G, int c, const Epi& E) {
;     ...
;             PG8_LDA(At, 1, 1); PG8_STAGE(PG8_SB(1, 0), b3, voffB); PG8_STAGE(PG8_SB(1, 1), b3 + hstepB, voffB); PG8_STAGE(PG8_SA(1, 0), a3, voffA);
;             PG8_WAIT_V(8); PG8_WAIT_L(0); PG8_BAR; PG8_MMA(1, 0, At, B0); PG8_MMA(1, 1, At, B1); PG8_BAR; PG8_SCHED;
;         }
;         if (wr == 0) PG8_BAR;
	s_add_i32 s33, s33, s52
	v_lshl_add_u64 v[216:217], v[216:217], 0, s[6:7]
	s_mov_b32 m0, s33
	ds_read_b128 v[184:187], v154 offset:49152
	ds_read_b128 v[188:191], v154 offset:50176
	ds_read_b128 v[192:195], v154 offset:51200
	ds_read_b128 v[196:199], v154 offset:52224
	ds_read_b128 v[200:203], v154 offset:53248
	ds_read_b128 v[204:207], v154 offset:54272
	ds_read_b128 v[208:211], v154 offset:55296
	ds_read_b128 v[212:215], v154 offset:56320
	global_load_lds_dwordx4 v[216:217], off
	s_add_i32 m0, s33, 0x2000
	s_add_u32 s42, s42, 0x100080
	v_lshl_add_u64 v[216:217], v[218:219], 0, s[6:7]
	s_addc_u32 s43, s43, 0
	s_add_i32 s33, s64, s52
	global_load_lds_dwordx4 v[216:217], off
	v_lshl_add_u64 v[216:217], s[42:43], 0, v[134:135]
	s_mov_b32 m0, s33
	s_nop 0
	global_load_lds_dwordx4 v[216:217], off
	v_lshl_add_u64 v[216:217], s[42:43], 0, v[130:131]
	s_add_i32 m0, s33, 0x2000
	s_nop 0
	global_load_lds_dwordx4 v[216:217], off
	v_lshl_add_u64 v[216:217], v[220:221], 0, s[6:7]
	s_mov_b32 m0, s59
	s_nop 0
	global_load_lds_dwordx4 v[216:217], off
	v_lshl_add_u64 v[216:217], v[222:223], 0, s[6:7]
	s_mov_b32 m0, s60
	s_nop 0
	global_load_lds_dwordx4 v[216:217], off
	s_waitcnt vmcnt(8)
	s_waitcnt lgkmcnt(0)
	s_barrier
	s_setprio 0
	v_mfma_f32_16x16x32_bf16 v[62:65], v[146:149], v[184:187], v[62:65]
	v_mfma_f32_16x16x32_bf16 v[58:61], v[160:163], v[184:187], v[58:61]
	v_mfma_f32_16x16x32_bf16 v[54:57], v[146:149], v[192:195], v[54:57]
	v_mfma_f32_16x16x32_bf16 v[46:49], v[160:163], v[192:195], v[46:49]
	v_mfma_f32_16x16x32_bf16 v[38:41], v[146:149], v[200:203], v[38:41]
	v_mfma_f32_16x16x32_bf16 v[30:33], v[160:163], v[200:203], v[30:33]
	v_mfma_f32_16x16x32_bf16 v[22:25], v[146:149], v[208:211], v[22:25]
	v_mfma_f32_16x16x32_bf16 v[14:17], v[160:163], v[208:211], v[14:17]
	v_mfma_f32_16x16x32_bf16 v[62:65], v[156:159], v[188:191], v[62:65]
	v_mfma_f32_16x16x32_bf16 v[58:61], v[164:167], v[188:191], v[58:61]
	v_mfma_f32_16x16x32_bf16 v[54:57], v[156:159], v[196:199], v[54:57]
	v_mfma_f32_16x16x32_bf16 v[46:49], v[164:167], v[196:199], v[46:49]
	v_mfma_f32_16x16x32_bf16 v[38:41], v[156:159], v[204:207], v[38:41]
	v_mfma_f32_16x16x32_bf16 v[30:33], v[164:167], v[204:207], v[30:33]
	v_mfma_f32_16x16x32_bf16 v[22:25], v[156:159], v[212:215], v[22:25]
	v_mfma_f32_16x16x32_bf16 v[14:17], v[164:167], v[212:215], v[14:17]
	s_setprio 2
	s_setprio 0
	v_mfma_f32_16x16x32_bf16 v[50:53], v[168:171], v[184:187], v[50:53]
	v_mfma_f32_16x16x32_bf16 v[42:45], v[176:179], v[184:187], v[42:45]
	v_mfma_f32_16x16x32_bf16 v[34:37], v[168:171], v[192:195], v[34:37]
	v_mfma_f32_16x16x32_bf16 v[26:29], v[176:179], v[192:195], v[26:29]
	v_mfma_f32_16x16x32_bf16 v[18:21], v[168:171], v[200:203], v[18:21]
	v_mfma_f32_16x16x32_bf16 v[10:13], v[176:179], v[200:203], v[10:13]
	v_mfma_f32_16x16x32_bf16 v[6:9], v[168:171], v[208:211], v[6:9]
	v_mfma_f32_16x16x32_bf16 v[2:5], v[176:179], v[208:211], v[2:5]
	v_mfma_f32_16x16x32_bf16 v[50:53], v[172:175], v[188:191], v[50:53]
	v_mfma_f32_16x16x32_bf16 v[42:45], v[180:183], v[188:191], v[42:45]
	v_mfma_f32_16x16x32_bf16 v[34:37], v[172:175], v[196:199], v[34:37]
	v_mfma_f32_16x16x32_bf16 v[26:29], v[180:183], v[196:199], v[26:29]
	v_mfma_f32_16x16x32_bf16 v[18:21], v[172:175], v[204:207], v[18:21]
	v_mfma_f32_16x16x32_bf16 v[10:13], v[180:183], v[204:207], v[10:13]
	v_mfma_f32_16x16x32_bf16 v[6:9], v[172:175], v[212:215], v[6:9]
	v_mfma_f32_16x16x32_bf16 v[2:5], v[180:183], v[212:215], v[2:5]
	s_setprio 2
	s_add_i32 s68, s68, 2
	s_add_u32 s40, s40, 0x100
	s_addc_u32 s41, s41, 0
	s_add_u32 s66, s66, 0x100
	s_addc_u32 s67, s67, 0
	s_cmp_gt_u32 s68, 61
	s_barrier
	s_cbranch_scc0 .LBB0_1825
	s_and_b64 vcc, exec, s[8:9]
	s_cbranch_vccz .LBB0_1828
	s_barrier

; #define PG8_STAGE(bufoff, gbase, voff) do { _Pragma("unroll") for (int _i = 0; _i < 2; ++_i) \
;         __builtin_amdgcn_global_load_lds((const unsigned*)((const char*)(gbase) + (voff)[_i]), (LAS unsigned*)(lds + (bufoff) + ldsw + _i * 8192), 16, 0, 0); } while (0)
; #define PG8_LDA(dst, b, h) do { _Pragma("unroll") for (int m = 0; m < 4; ++m) _Pragma("unroll") for (int k = 0; k < 2; ++k) dst[m][k] = *(const LAS bf16x8*)(lds + PG8_SA(b, h) + aoff + m * 2048 + k * 1024); } while (0)
; #define PG8_LDB(dst, b, h) do { _Pragma("unroll") for (int n = 0; n < 2; ++n) _Pragma("unroll") for (int k = 0; k < 2; ++k) dst[n][k] = *(const LAS bf16x8*)(lds + PG8_SB(b, h) + boff + n * 2048 + k * 1024); } while (0)
; #define PG8_MMA(ai, bj, At, Bt) do { __builtin_amdgcn_s_setprio(1); _Pragma("unroll") for (int m = 0; m < 4; ++m) _Pragma("unroll") for (int n = 0; n < 2; ++n) _Pragma("unroll") for (int k = 0; k < 2; ++k) \
;         acc[ai][bj][m][n] = __builtin_amdgcn_mfma_f32_16x16x32_bf16(Bt[n][k], At[m][k], acc[ai][bj][m][n], 0, 0, 0); __builtin_amdgcn_s_setprio(0); } while (0)
; template <class Epi>
; __device__ __forceinline__ void gemm_phase(LAS unsigned char* lds, const Gemm g, int G, int c, const Epi& E) {
;     ...
;         const bool has_next = S.next(ui + 1, nxt);
;         const char* nA = has_next ? (const char*)(g.A + (size_t)nxt.pb * g.sA) + (size_t)nxt.pm * 2 * hstepA : cA;
;         const char* nB = has_next ? (const char*)(g.Bt + (size_t)nxt.pb * g.sB) + (size_t)nxt.pn * 2 * hstepB : cB;
; #pragma nounroll
;         for (int t = 0; t < nt; t += 2) {
;             const bool last = (t == nt - 2);
;             const char* a1 = cA + (size_t)(t + 1) * kstep;
;             const char* a2 = last ? nA : cA + (size_t)(t + 2) * kstep; const char* b2 = last ? nB : cB + (size_t)(t + 2) * kstep;
;             const char* a3 = a2 + kstep; const char* b3 = b2 + kstep;
;             PG8_LDB(B0, 0, 0); PG8_LDB(B1, 0, 1); PG8_SCHED; PG8_LDA(At, 0, 0); PG8_STAGE(PG8_SA(1, 1), a1 + hstepA, voffA);
;             PG8_WAIT_V(8); PG8_WAIT_L(0); PG8_BAR; PG8_MMA(0, 0, At, B0); PG8_MMA(0, 1, At, B1); PG8_BAR; PG8_SCHED;
;             PG8_LDA(At, 0, 1); PG8_STAGE(PG8_SB(0, 0), b2, voffB); PG8_STAGE(PG8_SB(0, 1), b2 + hstepB, voffB); PG8_STAGE(PG8_SA(0, 0), a2, voffA);
;             PG8_WAIT_V(8); PG8_WAIT_L(0); PG8_BAR; PG8_MMA(1, 0, At, B0); PG8_MMA(1, 1, At, B1); PG8_BAR; PG8_SCHED;
.LBB0_1930:
	s_ashr_i32 s15, s14, 31
	s_lshl_b64 s[20:21], s[14:15], 19
	s_add_u32 s20, s40, s20
	s_addc_u32 s21, s41, s21
	s_and_b64 s[4:5], s[4:5], exec
	s_cselect_b32 s15, s21, s37
	s_cselect_b32 s17, s20, s36
	s_add_u32 s4, s38, 0x40080
	s_addc_u32 s5, s39, 0
	s_add_u32 s60, s36, 0x100
	s_addc_u32 s61, s37, 0
	s_mov_b32 s62, -2
	s_waitcnt vmcnt(0)
	ds_read_b128 v[122:125], v168
	ds_read_b128 v[126:129], v168 offset:1024
	ds_read_b128 v[130:133], v168 offset:2048
	ds_read_b128 v[134:137], v168 offset:3072
	ds_read_b128 v[162:165], v169
	ds_read_b128 v[172:175], v169 offset:1024
	ds_read_b128 v[176:179], v169 offset:2048
	ds_read_b128 v[180:183], v169 offset:3072
	s_add_u32 s33, s4, 0xfffc0080
	s_addc_u32 s36, s5, -1
	s_cmp_eq_u32 s62, 12
	s_cselect_b32 s39, s19, s36
	s_cselect_b32 s38, s18, s33
	s_cselect_b32 s37, s15, s61
	s_cselect_b32 s36, s17, s60
	v_lshl_add_u64 v[216:217], s[4:5], 0, v[154:155]
	s_add_i32 m0, s23, 0xc000
	ds_read_b128 v[184:187], v170
	ds_read_b128 v[188:191], v170 offset:1024
	ds_read_b128 v[192:195], v170 offset:2048
	ds_read_b128 v[196:199], v170 offset:3072
	ds_read_b128 v[200:203], v170 offset:4096
	ds_read_b128 v[204:207], v170 offset:5120
	ds_read_b128 v[208:211], v170 offset:6144
	ds_read_b128 v[212:215], v170 offset:7168
	global_load_lds_dwordx4 v[216:217], off
	v_lshl_add_u64 v[216:217], s[4:5], 0, v[156:157]
	s_add_i32 m0, s23, 0xe000
	s_nop 0
	global_load_lds_dwordx4 v[216:217], off
	s_waitcnt vmcnt(8)
	s_waitcnt lgkmcnt(0)
	s_barrier
	s_setprio 0
	v_mfma_f32_16x16x32_bf16 v[142:145], v[122:125], v[184:187], 0
	v_mfma_f32_16x16x32_bf16 v[138:141], v[130:133], v[184:187], 0
	v_mfma_f32_16x16x32_bf16 v[118:121], v[122:125], v[192:195], 0
	v_mfma_f32_16x16x32_bf16 v[106:109], v[130:133], v[192:195], 0
	v_mfma_f32_16x16x32_bf16 v[102:105], v[122:125], v[200:203], 0
	v_mfma_f32_16x16x32_bf16 v[90:93], v[130:133], v[200:203], 0
	v_mfma_f32_16x16x32_bf16 v[86:89], v[122:125], v[208:211], 0
	v_mfma_f32_16x16x32_bf16 v[74:77], v[130:133], v[208:211], 0
	v_mfma_f32_16x16x32_bf16 v[142:145], v[126:129], v[188:191], v[142:145]
	v_mfma_f32_16x16x32_bf16 v[138:141], v[134:137], v[188:191], v[138:141]
	v_mfma_f32_16x16x32_bf16 v[118:121], v[126:129], v[196:199], v[118:121]
	v_mfma_f32_16x16x32_bf16 v[106:109], v[134:137], v[196:199], v[106:109]
	v_mfma_f32_16x16x32_bf16 v[102:105], v[126:129], v[204:207], v[102:105]
	v_mfma_f32_16x16x32_bf16 v[90:93], v[134:137], v[204:207], v[90:93]
	v_mfma_f32_16x16x32_bf16 v[86:89], v[126:129], v[212:215], v[86:89]
	v_mfma_f32_16x16x32_bf16 v[74:77], v[134:137], v[212:215], v[74:77]
	s_setprio 2
	s_setprio 0
	v_mfma_f32_16x16x32_bf16 v[114:117], v[162:165], v[184:187], 0
	v_mfma_f32_16x16x32_bf16 v[110:113], v[176:179], v[184:187], 0
	v_mfma_f32_16x16x32_bf16 v[98:101], v[162:165], v[192:195], 0
	v_mfma_f32_16x16x32_bf16 v[94:97], v[176:179], v[192:195], 0
	v_mfma_f32_16x16x32_bf16 v[82:85], v[162:165], v[200:203], 0
	v_mfma_f32_16x16x32_bf16 v[78:81], v[176:179], v[200:203], 0
	v_mfma_f32_16x16x32_bf16 v[70:73], v[162:165], v[208:211], 0
	v_mfma_f32_16x16x32_bf16 v[66:69], v[176:179], v[208:211], 0
	v_mfma_f32_16x16x32_bf16 v[114:117], v[172:175], v[188:191], v[114:117]
	v_mfma_f32_16x16x32_bf16 v[110:113], v[180:183], v[188:191], v[110:113]
	v_mfma_f32_16x16x32_bf16 v[98:101], v[172:175], v[196:199], v[98:101]
	v_mfma_f32_16x16x32_bf16 v[94:97], v[180:183], v[196:199], v[94:97]
	v_mfma_f32_16x16x32_bf16 v[82:85], v[172:175], v[204:207], v[82:85]
	v_mfma_f32_16x16x32_bf16 v[78:81], v[180:183], v[204:207], v[78:81]
	v_mfma_f32_16x16x32_bf16 v[70:73], v[172:175], v[212:215], v[70:73]
	v_mfma_f32_16x16x32_bf16 v[66:69], v[180:183], v[212:215], v[66:69]
	s_setprio 2
	s_barrier
	s_add_i32 s33, s56, s42
	v_lshl_add_u64 v[216:217], s[36:37], 0, v[150:151]
	s_mov_b32 m0, s33
	ds_read_b128 v[184:187], v170 offset:16384
	ds_read_b128 v[188:191], v170 offset:17408
	ds_read_b128 v[192:195], v170 offset:18432
	ds_read_b128 v[196:199], v170 offset:19456
	ds_read_b128 v[200:203], v170 offset:20480
	ds_read_b128 v[204:207], v170 offset:21504
	ds_read_b128 v[208:211], v170 offset:22528
	ds_read_b128 v[212:215], v170 offset:23552
	global_load_lds_dwordx4 v[216:217], off
	s_add_i32 m0, s33, 0x2000
	s_add_u32 s64, s36, 0x40000
	v_lshl_add_u64 v[218:219], s[36:37], 0, v[146:147]
	s_addc_u32 s65, s37, 0
	s_add_i32 s33, s57, s42
	global_load_lds_dwordx4 v[218:219], off
	v_lshl_add_u64 v[220:221], s[64:65], 0, v[150:151]
	s_mov_b32 m0, s33
	v_lshl_add_u64 v[222:223], s[38:39], 0, v[148:149]
	global_load_lds_dwordx4 v[220:221], off
	v_lshl_add_u64 v[220:221], s[64:65], 0, v[146:147]
	s_add_i32 m0, s33, 0x2000
	s_nop 0
	global_load_lds_dwordx4 v[220:221], off
	v_lshl_add_u64 v[220:221], s[38:39], 0, v[152:153]
	s_mov_b32 m0, s23
	s_nop 0
	global_load_lds_dwordx4 v[220:221], off
	s_mov_b32 m0, s25
	s_nop 0
	global_load_lds_dwordx4 v[222:223], off
	s_waitcnt vmcnt(8)
	s_waitcnt lgkmcnt(0)
	s_barrier
; #define PG8_STAGE(bufoff, gbase, voff) do { _Pragma("unroll") for (int _i = 0; _i < 2; ++_i) \
;         __builtin_amdgcn_global_load_lds((const unsigned*)((const char*)(gbase) + (voff)[_i]), (LAS unsigned*)(lds + (bufoff) + ldsw + _i * 8192), 16, 0, 0); } while (0)
; #define PG8_LDA(dst, b, h) do { _Pragma("unroll") for (int m = 0; m < 4; ++m) _Pragma("unroll") for (int k = 0; k < 2; ++k) dst[m][k] = *(const LAS bf16x8*)(lds + PG8_SA(b, h) + aoff + m * 2048 + k * 1024); } while (0)
; #define PG8_LDB(dst, b, h) do { _Pragma("unroll") for (int n = 0; n < 2; ++n) _Pragma("unroll") for (int k = 0; k < 2; ++k) dst[n][k] = *(const LAS bf16x8*)(lds + PG8_SB(b, h) + boff + n * 2048 + k * 1024); } while (0)
; #define PG8_MMA(ai, bj, At, Bt) do { __builtin_amdgcn_s_setprio(1); _Pragma("unroll") for (int m = 0; m < 4; ++m) _Pragma("unroll") for (int n = 0; n < 2; ++n) _Pragma("unroll") for (int k = 0; k < 2; ++k) \
;         acc[ai][bj][m][n] = __builtin_amdgcn_mfma_f32_16x16x32_bf16(Bt[n][k], At[m][k], acc[ai][bj][m][n], 0, 0, 0); __builtin_amdgcn_s_setprio(0); } while (0)
; #define PG8_WAIT_V(n) asm volatile("s_waitcnt vmcnt(" #n ")" ::: "memory")
; #define PG8_WAIT_L(n) asm volatile("s_waitcnt lgkmcnt(" #n ")" ::: "memory")
; #define PG8_BAR __builtin_amdgcn_s_barrier()
; #define PG8_SCHED __builtin_amdgcn_sched_barrier(0)
; template <class Epi>
; __device__ __forceinline__ void gemm_phase(LAS unsigned char* lds, const Gemm g, int G, int c, const Epi& E) {
;     ...
;             PG8_WAIT_V(8); PG8_WAIT_L(0); PG8_BAR; PG8_MMA(1, 0, At, B0); PG8_MMA(1, 1, At, B1); PG8_BAR; PG8_SCHED;
;             PG8_LDB(B0, 1, 0); PG8_LDB(B1, 1, 1); PG8_SCHED; PG8_LDA(At, 1, 0); PG8_STAGE(PG8_SA(0, 1), a2 + hstepA, voffA);
;             PG8_WAIT_V(8); PG8_WAIT_L(0); PG8_BAR; PG8_MMA(0, 0, At, B0); PG8_MMA(0, 1, At, B1); PG8_BAR; PG8_SCHED;
	s_setprio 0
	v_mfma_f32_16x16x32_bf16 v[62:65], v[122:125], v[184:187], 0
	v_mfma_f32_16x16x32_bf16 v[58:61], v[130:133], v[184:187], 0
	v_mfma_f32_16x16x32_bf16 v[54:57], v[122:125], v[192:195], 0
	v_mfma_f32_16x16x32_bf16 v[42:45], v[130:133], v[192:195], 0
	v_mfma_f32_16x16x32_bf16 v[38:41], v[122:125], v[200:203], 0
	v_mfma_f32_16x16x32_bf16 v[26:29], v[130:133], v[200:203], 0
	v_mfma_f32_16x16x32_bf16 v[22:25], v[122:125], v[208:211], 0
	v_mfma_f32_16x16x32_bf16 v[10:13], v[130:133], v[208:211], 0
	v_mfma_f32_16x16x32_bf16 v[62:65], v[126:129], v[188:191], v[62:65]
	v_mfma_f32_16x16x32_bf16 v[58:61], v[134:137], v[188:191], v[58:61]
	v_mfma_f32_16x16x32_bf16 v[54:57], v[126:129], v[196:199], v[54:57]
	v_mfma_f32_16x16x32_bf16 v[42:45], v[134:137], v[196:199], v[42:45]
	v_mfma_f32_16x16x32_bf16 v[38:41], v[126:129], v[204:207], v[38:41]
	v_mfma_f32_16x16x32_bf16 v[26:29], v[134:137], v[204:207], v[26:29]
	v_mfma_f32_16x16x32_bf16 v[22:25], v[126:129], v[212:215], v[22:25]
	v_mfma_f32_16x16x32_bf16 v[10:13], v[134:137], v[212:215], v[10:13]
	s_setprio 2
	s_setprio 0
	v_mfma_f32_16x16x32_bf16 v[50:53], v[162:165], v[184:187], 0
	v_mfma_f32_16x16x32_bf16 v[46:49], v[176:179], v[184:187], 0
	v_mfma_f32_16x16x32_bf16 v[34:37], v[162:165], v[192:195], 0
	v_mfma_f32_16x16x32_bf16 v[30:33], v[176:179], v[192:195], 0
	v_mfma_f32_16x16x32_bf16 v[18:21], v[162:165], v[200:203], 0
	v_mfma_f32_16x16x32_bf16 v[14:17], v[176:179], v[200:203], 0
	v_mfma_f32_16x16x32_bf16 v[6:9], v[162:165], v[208:211], 0
	v_mfma_f32_16x16x32_bf16 v[2:5], v[176:179], v[208:211], 0
	v_mfma_f32_16x16x32_bf16 v[50:53], v[172:175], v[188:191], v[50:53]
	v_mfma_f32_16x16x32_bf16 v[46:49], v[180:183], v[188:191], v[46:49]
	v_mfma_f32_16x16x32_bf16 v[34:37], v[172:175], v[196:199], v[34:37]
	v_mfma_f32_16x16x32_bf16 v[30:33], v[180:183], v[196:199], v[30:33]
	v_mfma_f32_16x16x32_bf16 v[18:21], v[172:175], v[204:207], v[18:21]
	v_mfma_f32_16x16x32_bf16 v[14:17], v[180:183], v[204:207], v[14:17]
	v_mfma_f32_16x16x32_bf16 v[6:9], v[172:175], v[212:215], v[6:9]
	v_mfma_f32_16x16x32_bf16 v[2:5], v[180:183], v[212:215], v[2:5]
	s_setprio 2
	s_barrier
	s_add_i32 s33, 0, 0x18000
	s_add_i32 s63, 0, 0x1c000
	v_add_u32_e32 v134, s33, v167
	v_add_u32_e32 v171, s63, v167
	ds_read_b128 v[122:125], v134
	ds_read_b128 v[126:129], v134 offset:1024
	ds_read_b128 v[130:133], v134 offset:2048
	ds_read_b128 v[134:137], v134 offset:3072
	ds_read_b128 v[162:165], v171
	ds_read_b128 v[172:175], v171 offset:1024
	ds_read_b128 v[176:179], v171 offset:2048
	ds_read_b128 v[180:183], v171 offset:3072
	s_add_u32 s38, s38, 0x40000
	s_addc_u32 s39, s39, 0
	s_mov_b32 m0, s44
	v_lshl_add_u64 v[224:225], s[38:39], 0, v[152:153]
	ds_read_b128 v[184:187], v170 offset:32768
	ds_read_b128 v[188:191], v170 offset:33792
	ds_read_b128 v[192:195], v170 offset:34816
	ds_read_b128 v[196:199], v170 offset:35840
	ds_read_b128 v[200:203], v170 offset:36864
	ds_read_b128 v[204:207], v170 offset:37888
	ds_read_b128 v[208:211], v170 offset:38912
	ds_read_b128 v[212:215], v170 offset:39936
	global_load_lds_dwordx4 v[224:225], off
	v_lshl_add_u64 v[224:225], s[38:39], 0, v[148:149]
	s_mov_b32 m0, s45
	s_nop 0
	global_load_lds_dwordx4 v[224:225], off
	s_waitcnt vmcnt(8)
	s_waitcnt lgkmcnt(0)
	s_barrier
	s_setprio 0
	v_mfma_f32_16x16x32_bf16 v[142:145], v[122:125], v[184:187], v[142:145]
	v_mfma_f32_16x16x32_bf16 v[138:141], v[130:133], v[184:187], v[138:141]
	v_mfma_f32_16x16x32_bf16 v[118:121], v[122:125], v[192:195], v[118:121]
	v_mfma_f32_16x16x32_bf16 v[106:109], v[130:133], v[192:195], v[106:109]
	v_mfma_f32_16x16x32_bf16 v[102:105], v[122:125], v[200:203], v[102:105]
	v_mfma_f32_16x16x32_bf16 v[90:93], v[130:133], v[200:203], v[90:93]
	v_mfma_f32_16x16x32_bf16 v[86:89], v[122:125], v[208:211], v[86:89]
	v_mfma_f32_16x16x32_bf16 v[74:77], v[130:133], v[208:211], v[74:77]
	v_mfma_f32_16x16x32_bf16 v[142:145], v[126:129], v[188:191], v[142:145]
	v_mfma_f32_16x16x32_bf16 v[138:141], v[134:137], v[188:191], v[138:141]
	v_mfma_f32_16x16x32_bf16 v[118:121], v[126:129], v[196:199], v[118:121]
	v_mfma_f32_16x16x32_bf16 v[106:109], v[134:137], v[196:199], v[106:109]
	v_mfma_f32_16x16x32_bf16 v[102:105], v[126:129], v[204:207], v[102:105]
	v_mfma_f32_16x16x32_bf16 v[90:93], v[134:137], v[204:207], v[90:93]
	v_mfma_f32_16x16x32_bf16 v[86:89], v[126:129], v[212:215], v[86:89]
	v_mfma_f32_16x16x32_bf16 v[74:77], v[134:137], v[212:215], v[74:77]
	s_setprio 2
	s_setprio 0
	v_mfma_f32_16x16x32_bf16 v[114:117], v[162:165], v[184:187], v[114:117]
	v_mfma_f32_16x16x32_bf16 v[110:113], v[176:179], v[184:187], v[110:113]
	v_mfma_f32_16x16x32_bf16 v[98:101], v[162:165], v[192:195], v[98:101]
	v_mfma_f32_16x16x32_bf16 v[94:97], v[176:179], v[192:195], v[94:97]
	v_mfma_f32_16x16x32_bf16 v[82:85], v[162:165], v[200:203], v[82:85]
	v_mfma_f32_16x16x32_bf16 v[78:81], v[176:179], v[200:203], v[78:81]
	v_mfma_f32_16x16x32_bf16 v[70:73], v[162:165], v[208:211], v[70:73]
	v_mfma_f32_16x16x32_bf16 v[66:69], v[176:179], v[208:211], v[66:69]
	v_mfma_f32_16x16x32_bf16 v[114:117], v[172:175], v[188:191], v[114:117]
	v_mfma_f32_16x16x32_bf16 v[110:113], v[180:183], v[188:191], v[110:113]
	v_mfma_f32_16x16x32_bf16 v[98:101], v[172:175], v[196:199], v[98:101]
	v_mfma_f32_16x16x32_bf16 v[94:97], v[180:183], v[196:199], v[94:97]
	v_mfma_f32_16x16x32_bf16 v[82:85], v[172:175], v[204:207], v[82:85]
	v_mfma_f32_16x16x32_bf16 v[78:81], v[180:183], v[204:207], v[78:81]
	v_mfma_f32_16x16x32_bf16 v[70:73], v[172:175], v[212:215], v[70:73]
	v_mfma_f32_16x16x32_bf16 v[66:69], v[180:183], v[212:215], v[66:69]
	s_setprio 2
	s_barrier
; #define PG8_STAGE(bufoff, gbase, voff) do { _Pragma("unroll") for (int _i = 0; _i < 2; ++_i) \
;         __builtin_amdgcn_global_load_lds((const unsigned*)((const char*)(gbase) + (voff)[_i]), (LAS unsigned*)(lds + (bufoff) + ldsw + _i * 8192), 16, 0, 0); } while (0)
; #define PG8_LDA(dst, b, h) do { _Pragma("unroll") for (int m = 0; m < 4; ++m) _Pragma("unroll") for (int k = 0; k < 2; ++k) dst[m][k] = *(const LAS bf16x8*)(lds + PG8_SA(b, h) + aoff + m * 2048 + k * 1024); } while (0)
; #define PG8_LDB(dst, b, h) do { _Pragma("unroll") for (int n = 0; n < 2; ++n) _Pragma("unroll") for (int k = 0; k < 2; ++k) dst[n][k] = *(const LAS bf16x8*)(lds + PG8_SB(b, h) + boff + n * 2048 + k * 1024); } while (0)
; #define PG8_MMA(ai, bj, At, Bt) do { __builtin_amdgcn_s_setprio(1); _Pragma("unroll") for (int m = 0; m < 4; ++m) _Pragma("unroll") for (int n = 0; n < 2; ++n) _Pragma("unroll") for (int k = 0; k < 2; ++k) \
;         acc[ai][bj][m][n] = __builtin_amdgcn_mfma_f32_16x16x32_bf16(Bt[n][k], At[m][k], acc[ai][bj][m][n], 0, 0, 0); __builtin_amdgcn_s_setprio(0); } while (0)
; #define PG8_WAIT_V(n) asm volatile("s_waitcnt vmcnt(" #n ")" ::: "memory")
; #define PG8_BAR __builtin_amdgcn_s_barrier()
; template <class Epi>
; __device__ __forceinline__ void gemm_phase(LAS unsigned char* lds, const Gemm g, int G, int c, const Epi& E) {
;     ...
;             PG8_LDB(B0, 0, 0); PG8_LDB(B1, 0, 1); PG8_SCHED; PG8_LDA(At, 0, 0); PG8_STAGE(PG8_SA(1, 1), a1 + hstepA, voffA);
;             PG8_WAIT_V(8); PG8_WAIT_L(0); PG8_BAR; PG8_MMA(0, 0, At, B0); PG8_MMA(0, 1, At, B1); PG8_BAR; PG8_SCHED;
;             PG8_LDA(At, 0, 1); PG8_STAGE(PG8_SB(0, 0), b2, voffB); PG8_STAGE(PG8_SB(0, 1), b2 + hstepB, voffB); PG8_STAGE(PG8_SA(0, 0), a2, voffA);
;             PG8_WAIT_V(8); PG8_WAIT_L(0); PG8_BAR; PG8_MMA(1, 0, At, B0); PG8_MMA(1, 1, At, B1); PG8_BAR; PG8_SCHED;
;             PG8_LDB(B0, 1, 0); PG8_LDB(B1, 1, 1); PG8_SCHED; PG8_LDA(At, 1, 0); PG8_STAGE(PG8_SA(0, 1), a2 + hstepA, voffA);
;             PG8_WAIT_V(8); PG8_WAIT_L(0); PG8_BAR; PG8_MMA(0, 0, At, B0); PG8_MMA(0, 1, At, B1); PG8_BAR; PG8_SCHED;
;             PG8_LDA(At, 1, 1); PG8_STAGE(PG8_SB(1, 0), b3, voffB); PG8_STAGE(PG8_SB(1, 1), b3 + hstepB, voffB); PG8_STAGE(PG8_SA(1, 0), a3, voffA);
;             PG8_WAIT_V(8); PG8_WAIT_L(0); PG8_BAR; PG8_MMA(1, 0, At, B0); PG8_MMA(1, 1, At, B1); PG8_BAR; PG8_SCHED;
;         }
	s_add_i32 s33, s33, s42
	v_lshl_add_u64 v[216:217], v[216:217], 0, s[10:11]
	s_mov_b32 m0, s33
	ds_read_b128 v[184:187], v170 offset:49152
	ds_read_b128 v[188:191], v170 offset:50176
	ds_read_b128 v[192:195], v170 offset:51200
	ds_read_b128 v[196:199], v170 offset:52224
	ds_read_b128 v[200:203], v170 offset:53248
	ds_read_b128 v[204:207], v170 offset:54272
	ds_read_b128 v[208:211], v170 offset:55296
	ds_read_b128 v[212:215], v170 offset:56320
	global_load_lds_dwordx4 v[216:217], off
	s_add_i32 m0, s33, 0x2000
	s_add_u32 s36, s36, 0x40080
	v_lshl_add_u64 v[216:217], v[218:219], 0, s[10:11]
	s_addc_u32 s37, s37, 0
	s_add_i32 s33, s63, s42
	global_load_lds_dwordx4 v[216:217], off
	v_lshl_add_u64 v[216:217], s[36:37], 0, v[150:151]
	s_mov_b32 m0, s33
	s_nop 0
	global_load_lds_dwordx4 v[216:217], off
	v_lshl_add_u64 v[216:217], s[36:37], 0, v[146:147]
	s_add_i32 m0, s33, 0x2000
	s_nop 0
	global_load_lds_dwordx4 v[216:217], off
	v_lshl_add_u64 v[216:217], v[220:221], 0, s[10:11]
	s_mov_b32 m0, s53
	s_nop 0
	global_load_lds_dwordx4 v[216:217], off
	v_lshl_add_u64 v[216:217], v[222:223], 0, s[10:11]
	s_mov_b32 m0, s54
	s_nop 0
	global_load_lds_dwordx4 v[216:217], off
	s_waitcnt vmcnt(8)
	s_waitcnt lgkmcnt(0)
	s_barrier
	s_setprio 0
	v_mfma_f32_16x16x32_bf16 v[62:65], v[122:125], v[184:187], v[62:65]
	v_mfma_f32_16x16x32_bf16 v[58:61], v[130:133], v[184:187], v[58:61]
	v_mfma_f32_16x16x32_bf16 v[54:57], v[122:125], v[192:195], v[54:57]
	v_mfma_f32_16x16x32_bf16 v[42:45], v[130:133], v[192:195], v[42:45]
	v_mfma_f32_16x16x32_bf16 v[38:41], v[122:125], v[200:203], v[38:41]
	v_mfma_f32_16x16x32_bf16 v[26:29], v[130:133], v[200:203], v[26:29]
	v_mfma_f32_16x16x32_bf16 v[22:25], v[122:125], v[208:211], v[22:25]
	v_mfma_f32_16x16x32_bf16 v[10:13], v[130:133], v[208:211], v[10:13]
	v_mfma_f32_16x16x32_bf16 v[62:65], v[126:129], v[188:191], v[62:65]
	v_mfma_f32_16x16x32_bf16 v[58:61], v[134:137], v[188:191], v[58:61]
	v_mfma_f32_16x16x32_bf16 v[54:57], v[126:129], v[196:199], v[54:57]
	v_mfma_f32_16x16x32_bf16 v[42:45], v[134:137], v[196:199], v[42:45]
	v_mfma_f32_16x16x32_bf16 v[38:41], v[126:129], v[204:207], v[38:41]
	v_mfma_f32_16x16x32_bf16 v[26:29], v[134:137], v[204:207], v[26:29]
	v_mfma_f32_16x16x32_bf16 v[22:25], v[126:129], v[212:215], v[22:25]
	v_mfma_f32_16x16x32_bf16 v[10:13], v[134:137], v[212:215], v[10:13]
	s_setprio 2
	s_setprio 0
	v_mfma_f32_16x16x32_bf16 v[50:53], v[162:165], v[184:187], v[50:53]
	v_mfma_f32_16x16x32_bf16 v[46:49], v[176:179], v[184:187], v[46:49]
	v_mfma_f32_16x16x32_bf16 v[34:37], v[162:165], v[192:195], v[34:37]
	v_mfma_f32_16x16x32_bf16 v[30:33], v[176:179], v[192:195], v[30:33]
	v_mfma_f32_16x16x32_bf16 v[18:21], v[162:165], v[200:203], v[18:21]
	v_mfma_f32_16x16x32_bf16 v[14:17], v[176:179], v[200:203], v[14:17]
	v_mfma_f32_16x16x32_bf16 v[6:9], v[162:165], v[208:211], v[6:9]
	v_mfma_f32_16x16x32_bf16 v[2:5], v[176:179], v[208:211], v[2:5]
	v_mfma_f32_16x16x32_bf16 v[50:53], v[172:175], v[188:191], v[50:53]
	v_mfma_f32_16x16x32_bf16 v[46:49], v[180:183], v[188:191], v[46:49]
	v_mfma_f32_16x16x32_bf16 v[34:37], v[172:175], v[196:199], v[34:37]
	v_mfma_f32_16x16x32_bf16 v[30:33], v[180:183], v[196:199], v[30:33]
	v_mfma_f32_16x16x32_bf16 v[18:21], v[172:175], v[204:207], v[18:21]
	v_mfma_f32_16x16x32_bf16 v[14:17], v[180:183], v[204:207], v[14:17]
	v_mfma_f32_16x16x32_bf16 v[6:9], v[172:175], v[212:215], v[6:9]
	v_mfma_f32_16x16x32_bf16 v[2:5], v[180:183], v[212:215], v[2:5]
	s_setprio 2
	s_add_i32 s62, s62, 2
	s_add_u32 s4, s4, 0x100
	s_addc_u32 s5, s5, 0
	s_add_u32 s60, s60, 0x100
	s_addc_u32 s61, s61, 0
	s_cmp_gt_u32 s62, 13
	s_barrier
	s_cbranch_scc0 .LBB0_1931
.LBB0_1931:
	ds_read_b128 v[122:125], v168
	ds_read_b128 v[126:129], v168 offset:1024
	ds_read_b128 v[130:133], v168 offset:2048
	ds_read_b128 v[134:137], v168 offset:3072
	ds_read_b128 v[162:165], v169
	ds_read_b128 v[172:175], v169 offset:1024
	ds_read_b128 v[176:179], v169 offset:2048
	ds_read_b128 v[180:183], v169 offset:3072
	s_add_u32 s33, s4, 0xfffc0080
	s_addc_u32 s36, s5, -1
	s_cmp_eq_u32 s62, 12
	s_cselect_b32 s39, s19, s36
	s_cselect_b32 s38, s18, s33
	s_cselect_b32 s37, s15, s61
	s_cselect_b32 s36, s17, s60
	v_lshl_add_u64 v[216:217], s[4:5], 0, v[154:155]
	s_add_i32 m0, s23, 0xc000
	ds_read_b128 v[184:187], v170
	ds_read_b128 v[188:191], v170 offset:1024
	ds_read_b128 v[192:195], v170 offset:2048
	ds_read_b128 v[196:199], v170 offset:3072
	ds_read_b128 v[200:203], v170 offset:4096
	ds_read_b128 v[204:207], v170 offset:5120
	ds_read_b128 v[208:211], v170 offset:6144
	ds_read_b128 v[212:215], v170 offset:7168
	global_load_lds_dwordx4 v[216:217], off
	v_lshl_add_u64 v[216:217], s[4:5], 0, v[156:157]
	s_add_i32 m0, s23, 0xe000
	s_nop 0
	global_load_lds_dwordx4 v[216:217], off
	s_waitcnt vmcnt(8)
	s_waitcnt lgkmcnt(0)
	s_barrier
; #define PG8_STAGE(bufoff, gbase, voff) do { _Pragma("unroll") for (int _i = 0; _i < 2; ++_i) \
;         __builtin_amdgcn_global_load_lds((const unsigned*)((const char*)(gbase) + (voff)[_i]), (LAS unsigned*)(lds + (bufoff) + ldsw + _i * 8192), 16, 0, 0); } while (0)
; #define PG8_LDA(dst, b, h) do { _Pragma("unroll") for (int m = 0; m < 4; ++m) _Pragma("unroll") for (int k = 0; k < 2; ++k) dst[m][k] = *(const LAS bf16x8*)(lds + PG8_SA(b, h) + aoff + m * 2048 + k * 1024); } while (0)
; #define PG8_MMA(ai, bj, At, Bt) do { __builtin_amdgcn_s_setprio(1); _Pragma("unroll") for (int m = 0; m < 4; ++m) _Pragma("unroll") for (int n = 0; n < 2; ++n) _Pragma("unroll") for (int k = 0; k < 2; ++k) \
;         acc[ai][bj][m][n] = __builtin_amdgcn_mfma_f32_16x16x32_bf16(Bt[n][k], At[m][k], acc[ai][bj][m][n], 0, 0, 0); __builtin_amdgcn_s_setprio(0); } while (0)
; #define PG8_WAIT_V(n) asm volatile("s_waitcnt vmcnt(" #n ")" ::: "memory")
; #define PG8_WAIT_L(n) asm volatile("s_waitcnt lgkmcnt(" #n ")" ::: "memory")
; #define PG8_BAR __builtin_amdgcn_s_barrier()
; #define PG8_SCHED __builtin_amdgcn_sched_barrier(0)
; template <class Epi>
; __device__ __forceinline__ void gemm_phase(LAS unsigned char* lds, const Gemm g, int G, int c, const Epi& E) {
;     ...
;             PG8_WAIT_V(8); PG8_WAIT_L(0); PG8_BAR; PG8_MMA(0, 0, At, B0); PG8_MMA(0, 1, At, B1); PG8_BAR; PG8_SCHED;
;             PG8_LDA(At, 0, 1); PG8_STAGE(PG8_SB(0, 0), b2, voffB); PG8_STAGE(PG8_SB(0, 1), b2 + hstepB, voffB); PG8_STAGE(PG8_SA(0, 0), a2, voffA);
;             PG8_WAIT_V(8); PG8_WAIT_L(0); PG8_BAR; PG8_MMA(1, 0, At, B0); PG8_MMA(1, 1, At, B1); PG8_BAR; PG8_SCHED;
	s_setprio 0
	v_mfma_f32_16x16x32_bf16 v[142:145], v[122:125], v[184:187], v[142:145]
	v_mfma_f32_16x16x32_bf16 v[138:141], v[130:133], v[184:187], v[138:141]
	v_mfma_f32_16x16x32_bf16 v[118:121], v[122:125], v[192:195], v[118:121]
	v_mfma_f32_16x16x32_bf16 v[106:109], v[130:133], v[192:195], v[106:109]
	v_mfma_f32_16x16x32_bf16 v[102:105], v[122:125], v[200:203], v[102:105]
	v_mfma_f32_16x16x32_bf16 v[90:93], v[130:133], v[200:203], v[90:93]
	v_mfma_f32_16x16x32_bf16 v[86:89], v[122:125], v[208:211], v[86:89]
	v_mfma_f32_16x16x32_bf16 v[74:77], v[130:133], v[208:211], v[74:77]
	v_mfma_f32_16x16x32_bf16 v[142:145], v[126:129], v[188:191], v[142:145]
	v_mfma_f32_16x16x32_bf16 v[138:141], v[134:137], v[188:191], v[138:141]
	v_mfma_f32_16x16x32_bf16 v[118:121], v[126:129], v[196:199], v[118:121]
	v_mfma_f32_16x16x32_bf16 v[106:109], v[134:137], v[196:199], v[106:109]
	v_mfma_f32_16x16x32_bf16 v[102:105], v[126:129], v[204:207], v[102:105]
	v_mfma_f32_16x16x32_bf16 v[90:93], v[134:137], v[204:207], v[90:93]
	v_mfma_f32_16x16x32_bf16 v[86:89], v[126:129], v[212:215], v[86:89]
	v_mfma_f32_16x16x32_bf16 v[74:77], v[134:137], v[212:215], v[74:77]
	s_setprio 2
	s_setprio 0
	v_mfma_f32_16x16x32_bf16 v[114:117], v[162:165], v[184:187], v[114:117]
	v_mfma_f32_16x16x32_bf16 v[110:113], v[176:179], v[184:187], v[110:113]
	v_mfma_f32_16x16x32_bf16 v[98:101], v[162:165], v[192:195], v[98:101]
	v_mfma_f32_16x16x32_bf16 v[94:97], v[176:179], v[192:195], v[94:97]
	v_mfma_f32_16x16x32_bf16 v[82:85], v[162:165], v[200:203], v[82:85]
	v_mfma_f32_16x16x32_bf16 v[78:81], v[176:179], v[200:203], v[78:81]
	v_mfma_f32_16x16x32_bf16 v[70:73], v[162:165], v[208:211], v[70:73]
	v_mfma_f32_16x16x32_bf16 v[66:69], v[176:179], v[208:211], v[66:69]
	v_mfma_f32_16x16x32_bf16 v[114:117], v[172:175], v[188:191], v[114:117]
	v_mfma_f32_16x16x32_bf16 v[110:113], v[180:183], v[188:191], v[110:113]
	v_mfma_f32_16x16x32_bf16 v[98:101], v[172:175], v[196:199], v[98:101]
	v_mfma_f32_16x16x32_bf16 v[94:97], v[180:183], v[196:199], v[94:97]
	v_mfma_f32_16x16x32_bf16 v[82:85], v[172:175], v[204:207], v[82:85]
	v_mfma_f32_16x16x32_bf16 v[78:81], v[180:183], v[204:207], v[78:81]
	v_mfma_f32_16x16x32_bf16 v[70:73], v[172:175], v[212:215], v[70:73]
	v_mfma_f32_16x16x32_bf16 v[66:69], v[180:183], v[212:215], v[66:69]
	s_setprio 2
	s_barrier
	s_add_i32 s33, s56, s42
	v_lshl_add_u64 v[216:217], s[36:37], 0, v[150:151]
	s_mov_b32 m0, s33
	ds_read_b128 v[184:187], v170 offset:16384
	ds_read_b128 v[188:191], v170 offset:17408
	ds_read_b128 v[192:195], v170 offset:18432
	ds_read_b128 v[196:199], v170 offset:19456
	ds_read_b128 v[200:203], v170 offset:20480
	ds_read_b128 v[204:207], v170 offset:21504
	ds_read_b128 v[208:211], v170 offset:22528
	ds_read_b128 v[212:215], v170 offset:23552
	global_load_lds_dwordx4 v[216:217], off
	s_add_i32 m0, s33, 0x2000
	s_add_u32 s64, s36, 0x40000
	v_lshl_add_u64 v[218:219], s[36:37], 0, v[146:147]
	s_addc_u32 s65, s37, 0
	s_add_i32 s33, s57, s42
	global_load_lds_dwordx4 v[218:219], off
	v_lshl_add_u64 v[220:221], s[64:65], 0, v[150:151]
	s_mov_b32 m0, s33
	v_lshl_add_u64 v[222:223], s[38:39], 0, v[148:149]
	global_load_lds_dwordx4 v[220:221], off
	v_lshl_add_u64 v[220:221], s[64:65], 0, v[146:147]
	s_add_i32 m0, s33, 0x2000
	s_nop 0
	global_load_lds_dwordx4 v[220:221], off
	v_lshl_add_u64 v[220:221], s[38:39], 0, v[152:153]
	s_mov_b32 m0, s23
	s_nop 0
	global_load_lds_dwordx4 v[220:221], off
	s_mov_b32 m0, s25
	s_nop 0
	global_load_lds_dwordx4 v[222:223], off
	s_waitcnt vmcnt(8)
	s_waitcnt lgkmcnt(0)
	s_barrier
	s_setprio 0
	v_mfma_f32_16x16x32_bf16 v[62:65], v[122:125], v[184:187], v[62:65]
	v_mfma_f32_16x16x32_bf16 v[58:61], v[130:133], v[184:187], v[58:61]
	v_mfma_f32_16x16x32_bf16 v[54:57], v[122:125], v[192:195], v[54:57]
	v_mfma_f32_16x16x32_bf16 v[42:45], v[130:133], v[192:195], v[42:45]
	v_mfma_f32_16x16x32_bf16 v[38:41], v[122:125], v[200:203], v[38:41]
	v_mfma_f32_16x16x32_bf16 v[26:29], v[130:133], v[200:203], v[26:29]
	v_mfma_f32_16x16x32_bf16 v[22:25], v[122:125], v[208:211], v[22:25]
	v_mfma_f32_16x16x32_bf16 v[10:13], v[130:133], v[208:211], v[10:13]
	v_mfma_f32_16x16x32_bf16 v[62:65], v[126:129], v[188:191], v[62:65]
	v_mfma_f32_16x16x32_bf16 v[58:61], v[134:137], v[188:191], v[58:61]
	v_mfma_f32_16x16x32_bf16 v[54:57], v[126:129], v[196:199], v[54:57]
	v_mfma_f32_16x16x32_bf16 v[42:45], v[134:137], v[196:199], v[42:45]
	v_mfma_f32_16x16x32_bf16 v[38:41], v[126:129], v[204:207], v[38:41]
	v_mfma_f32_16x16x32_bf16 v[26:29], v[134:137], v[204:207], v[26:29]
	v_mfma_f32_16x16x32_bf16 v[22:25], v[126:129], v[212:215], v[22:25]
	v_mfma_f32_16x16x32_bf16 v[10:13], v[134:137], v[212:215], v[10:13]
	s_setprio 2
	s_setprio 0
	v_mfma_f32_16x16x32_bf16 v[50:53], v[162:165], v[184:187], v[50:53]
	v_mfma_f32_16x16x32_bf16 v[46:49], v[176:179], v[184:187], v[46:49]
	v_mfma_f32_16x16x32_bf16 v[34:37], v[162:165], v[192:195], v[34:37]
	v_mfma_f32_16x16x32_bf16 v[30:33], v[176:179], v[192:195], v[30:33]
	v_mfma_f32_16x16x32_bf16 v[18:21], v[162:165], v[200:203], v[18:21]
	v_mfma_f32_16x16x32_bf16 v[14:17], v[176:179], v[200:203], v[14:17]
	v_mfma_f32_16x16x32_bf16 v[6:9], v[162:165], v[208:211], v[6:9]
	v_mfma_f32_16x16x32_bf16 v[2:5], v[176:179], v[208:211], v[2:5]
	v_mfma_f32_16x16x32_bf16 v[50:53], v[172:175], v[188:191], v[50:53]
	v_mfma_f32_16x16x32_bf16 v[46:49], v[180:183], v[188:191], v[46:49]
	v_mfma_f32_16x16x32_bf16 v[34:37], v[172:175], v[196:199], v[34:37]
	v_mfma_f32_16x16x32_bf16 v[30:33], v[180:183], v[196:199], v[30:33]
	v_mfma_f32_16x16x32_bf16 v[18:21], v[172:175], v[204:207], v[18:21]
	v_mfma_f32_16x16x32_bf16 v[14:17], v[180:183], v[204:207], v[14:17]
	v_mfma_f32_16x16x32_bf16 v[6:9], v[172:175], v[212:215], v[6:9]
	v_mfma_f32_16x16x32_bf16 v[2:5], v[180:183], v[212:215], v[2:5]
	s_setprio 2
	s_barrier
; #define PG8_STAGE(bufoff, gbase, voff) do { _Pragma("unroll") for (int _i = 0; _i < 2; ++_i) \
;         __builtin_amdgcn_global_load_lds((const unsigned*)((const char*)(gbase) + (voff)[_i]), (LAS unsigned*)(lds + (bufoff) + ldsw + _i * 8192), 16, 0, 0); } while (0)
; #define PG8_LDA(dst, b, h) do { _Pragma("unroll") for (int m = 0; m < 4; ++m) _Pragma("unroll") for (int k = 0; k < 2; ++k) dst[m][k] = *(const LAS bf16x8*)(lds + PG8_SA(b, h) + aoff + m * 2048 + k * 1024); } while (0)
; #define PG8_LDB(dst, b, h) do { _Pragma("unroll") for (int n = 0; n < 2; ++n) _Pragma("unroll") for (int k = 0; k < 2; ++k) dst[n][k] = *(const LAS bf16x8*)(lds + PG8_SB(b, h) + boff + n * 2048 + k * 1024); } while (0)
; #define PG8_MMA(ai, bj, At, Bt) do { __builtin_amdgcn_s_setprio(1); _Pragma("unroll") for (int m = 0; m < 4; ++m) _Pragma("unroll") for (int n = 0; n < 2; ++n) _Pragma("unroll") for (int k = 0; k < 2; ++k) \
;         acc[ai][bj][m][n] = __builtin_amdgcn_mfma_f32_16x16x32_bf16(Bt[n][k], At[m][k], acc[ai][bj][m][n], 0, 0, 0); __builtin_amdgcn_s_setprio(0); } while (0)
; #define PG8_WAIT_V(n) asm volatile("s_waitcnt vmcnt(" #n ")" ::: "memory")
; #define PG8_WAIT_L(n) asm volatile("s_waitcnt lgkmcnt(" #n ")" ::: "memory")
; #define PG8_BAR __builtin_amdgcn_s_barrier()
; #define PG8_SCHED __builtin_amdgcn_sched_barrier(0)
; template <class Epi>
; __device__ __forceinline__ void gemm_phase(LAS unsigned char* lds, const Gemm g, int G, int c, const Epi& E) {
;     ...
;             PG8_LDB(B0, 1, 0); PG8_LDB(B1, 1, 1); PG8_SCHED; PG8_LDA(At, 1, 0); PG8_STAGE(PG8_SA(0, 1), a2 + hstepA, voffA);
;             PG8_WAIT_V(8); PG8_WAIT_L(0); PG8_BAR; PG8_MMA(0, 0, At, B0); PG8_MMA(0, 1, At, B1); PG8_BAR; PG8_SCHED;
	s_add_i32 s33, 0, 0x18000
	s_add_i32 s63, 0, 0x1c000
	v_add_u32_e32 v134, s33, v167
	v_add_u32_e32 v171, s63, v167
	ds_read_b128 v[122:125], v134
	ds_read_b128 v[126:129], v134 offset:1024
	ds_read_b128 v[130:133], v134 offset:2048
	ds_read_b128 v[134:137], v134 offset:3072
	ds_read_b128 v[162:165], v171
	ds_read_b128 v[172:175], v171 offset:1024
	ds_read_b128 v[176:179], v171 offset:2048
	ds_read_b128 v[180:183], v171 offset:3072
	s_add_u32 s38, s38, 0x40000
	s_addc_u32 s39, s39, 0
	s_mov_b32 m0, s44
	v_lshl_add_u64 v[224:225], s[38:39], 0, v[152:153]
	ds_read_b128 v[184:187], v170 offset:32768
	ds_read_b128 v[188:191], v170 offset:33792
	ds_read_b128 v[192:195], v170 offset:34816
	ds_read_b128 v[196:199], v170 offset:35840
	ds_read_b128 v[200:203], v170 offset:36864
	ds_read_b128 v[204:207], v170 offset:37888
	ds_read_b128 v[208:211], v170 offset:38912
	ds_read_b128 v[212:215], v170 offset:39936
	global_load_lds_dwordx4 v[224:225], off
	v_lshl_add_u64 v[224:225], s[38:39], 0, v[148:149]
	s_mov_b32 m0, s45
	s_nop 0
	global_load_lds_dwordx4 v[224:225], off
	s_waitcnt vmcnt(8)
	s_waitcnt lgkmcnt(0)
	s_barrier
	s_setprio 0
	v_mfma_f32_16x16x32_bf16 v[142:145], v[122:125], v[184:187], v[142:145]
	v_mfma_f32_16x16x32_bf16 v[138:141], v[130:133], v[184:187], v[138:141]
	v_mfma_f32_16x16x32_bf16 v[118:121], v[122:125], v[192:195], v[118:121]
	v_mfma_f32_16x16x32_bf16 v[106:109], v[130:133], v[192:195], v[106:109]
	v_mfma_f32_16x16x32_bf16 v[102:105], v[122:125], v[200:203], v[102:105]
	v_mfma_f32_16x16x32_bf16 v[90:93], v[130:133], v[200:203], v[90:93]
	v_mfma_f32_16x16x32_bf16 v[86:89], v[122:125], v[208:211], v[86:89]
	v_mfma_f32_16x16x32_bf16 v[74:77], v[130:133], v[208:211], v[74:77]
	v_mfma_f32_16x16x32_bf16 v[142:145], v[126:129], v[188:191], v[142:145]
	v_mfma_f32_16x16x32_bf16 v[138:141], v[134:137], v[188:191], v[138:141]
	v_mfma_f32_16x16x32_bf16 v[118:121], v[126:129], v[196:199], v[118:121]
	v_mfma_f32_16x16x32_bf16 v[106:109], v[134:137], v[196:199], v[106:109]
	v_mfma_f32_16x16x32_bf16 v[102:105], v[126:129], v[204:207], v[102:105]
	v_mfma_f32_16x16x32_bf16 v[90:93], v[134:137], v[204:207], v[90:93]
	v_mfma_f32_16x16x32_bf16 v[86:89], v[126:129], v[212:215], v[86:89]
	v_mfma_f32_16x16x32_bf16 v[74:77], v[134:137], v[212:215], v[74:77]
	s_setprio 2
	s_setprio 0
	v_mfma_f32_16x16x32_bf16 v[114:117], v[162:165], v[184:187], v[114:117]
	v_mfma_f32_16x16x32_bf16 v[110:113], v[176:179], v[184:187], v[110:113]
	v_mfma_f32_16x16x32_bf16 v[98:101], v[162:165], v[192:195], v[98:101]
	v_mfma_f32_16x16x32_bf16 v[94:97], v[176:179], v[192:195], v[94:97]
	v_mfma_f32_16x16x32_bf16 v[82:85], v[162:165], v[200:203], v[82:85]
	v_mfma_f32_16x16x32_bf16 v[78:81], v[176:179], v[200:203], v[78:81]
	v_mfma_f32_16x16x32_bf16 v[70:73], v[162:165], v[208:211], v[70:73]
	v_mfma_f32_16x16x32_bf16 v[66:69], v[176:179], v[208:211], v[66:69]
	v_mfma_f32_16x16x32_bf16 v[114:117], v[172:175], v[188:191], v[114:117]
	v_mfma_f32_16x16x32_bf16 v[110:113], v[180:183], v[188:191], v[110:113]
	v_mfma_f32_16x16x32_bf16 v[98:101], v[172:175], v[196:199], v[98:101]
	v_mfma_f32_16x16x32_bf16 v[94:97], v[180:183], v[196:199], v[94:97]
	v_mfma_f32_16x16x32_bf16 v[82:85], v[172:175], v[204:207], v[82:85]
	v_mfma_f32_16x16x32_bf16 v[78:81], v[180:183], v[204:207], v[78:81]
	v_mfma_f32_16x16x32_bf16 v[70:73], v[172:175], v[212:215], v[70:73]
	v_mfma_f32_16x16x32_bf16 v[66:69], v[180:183], v[212:215], v[66:69]
	s_setprio 2
	s_barrier
; #define PG8_STAGE(bufoff, gbase, voff) do { _Pragma("unroll") for (int _i = 0; _i < 2; ++_i) \
;         __builtin_amdgcn_global_load_lds((const unsigned*)((const char*)(gbase) + (voff)[_i]), (LAS unsigned*)(lds + (bufoff) + ldsw + _i * 8192), 16, 0, 0); } while (0)
; #define PG8_LDA(dst, b, h) do { _Pragma("unroll") for (int m = 0; m < 4; ++m) _Pragma("unroll") for (int k = 0; k < 2; ++k) dst[m][k] = *(const LAS bf16x8*)(lds + PG8_SA(b, h) + aoff + m * 2048 + k * 1024); } while (0)
; #define PG8_MMA(ai, bj, At, Bt) do { __builtin_amdgcn_s_setprio(1); _Pragma("unroll") for (int m = 0; m < 4; ++m) _Pragma("unroll") for (int n = 0; n < 2; ++n) _Pragma("unroll") for (int k = 0; k < 2; ++k) \
;         acc[ai][bj][m][n] = __builtin_amdgcn_mfma_f32_16x16x32_bf16(Bt[n][k], At[m][k], acc[ai][bj][m][n], 0, 0, 0); __builtin_amdgcn_s_setprio(0); } while (0)
; #define PG8_WAIT_V(n) asm volatile("s_waitcnt vmcnt(" #n ")" ::: "memory")
; #define PG8_WAIT_L(n) asm volatile("s_waitcnt lgkmcnt(" #n ")" ::: "memory")
; #define PG8_BAR __builtin_amdgcn_s_barrier()
; #define PG8_SCHED __builtin_amdgcn_sched_barrier(0)
; template <class Epi>
; __device__ __forceinline__ void gemm_phase(LAS unsigned char* lds, const Gemm g, int G, int c, const Epi& E) {
;     ...
;             PG8_LDA(At, 1, 1); PG8_STAGE(PG8_SB(1, 0), b3, voffB); PG8_STAGE(PG8_SB(1, 1), b3 + hstepB, voffB); PG8_STAGE(PG8_SA(1, 0), a3, voffA);
;             PG8_WAIT_V(8); PG8_WAIT_L(0); PG8_BAR; PG8_MMA(1, 0, At, B0); PG8_MMA(1, 1, At, B1); PG8_BAR; PG8_SCHED;
;         }
;         if (wr == 0) PG8_BAR;
	s_add_i32 s33, s33, s42
	v_lshl_add_u64 v[216:217], v[216:217], 0, s[10:11]
	s_mov_b32 m0, s33
	ds_read_b128 v[184:187], v170 offset:49152
	ds_read_b128 v[188:191], v170 offset:50176
	ds_read_b128 v[192:195], v170 offset:51200
	ds_read_b128 v[196:199], v170 offset:52224
	ds_read_b128 v[200:203], v170 offset:53248
	ds_read_b128 v[204:207], v170 offset:54272
	ds_read_b128 v[208:211], v170 offset:55296
	ds_read_b128 v[212:215], v170 offset:56320
	global_load_lds_dwordx4 v[216:217], off
	s_add_i32 m0, s33, 0x2000
	s_add_u32 s36, s36, 0x40080
	v_lshl_add_u64 v[216:217], v[218:219], 0, s[10:11]
	s_addc_u32 s37, s37, 0
	s_add_i32 s33, s63, s42
	global_load_lds_dwordx4 v[216:217], off
	v_lshl_add_u64 v[216:217], s[36:37], 0, v[150:151]
	s_mov_b32 m0, s33
	s_nop 0
	global_load_lds_dwordx4 v[216:217], off
	v_lshl_add_u64 v[216:217], s[36:37], 0, v[146:147]
	s_add_i32 m0, s33, 0x2000
	s_nop 0
	global_load_lds_dwordx4 v[216:217], off
	v_lshl_add_u64 v[216:217], v[220:221], 0, s[10:11]
	s_mov_b32 m0, s53
	s_nop 0
	global_load_lds_dwordx4 v[216:217], off
	v_lshl_add_u64 v[216:217], v[222:223], 0, s[10:11]
	s_mov_b32 m0, s54
	s_nop 0
	global_load_lds_dwordx4 v[216:217], off
	s_waitcnt vmcnt(8)
	s_waitcnt lgkmcnt(0)
	s_barrier
	s_setprio 0
	v_mfma_f32_16x16x32_bf16 v[62:65], v[122:125], v[184:187], v[62:65]
	v_mfma_f32_16x16x32_bf16 v[58:61], v[130:133], v[184:187], v[58:61]
	v_mfma_f32_16x16x32_bf16 v[54:57], v[122:125], v[192:195], v[54:57]
	v_mfma_f32_16x16x32_bf16 v[42:45], v[130:133], v[192:195], v[42:45]
	v_mfma_f32_16x16x32_bf16 v[38:41], v[122:125], v[200:203], v[38:41]
	v_mfma_f32_16x16x32_bf16 v[26:29], v[130:133], v[200:203], v[26:29]
	v_mfma_f32_16x16x32_bf16 v[22:25], v[122:125], v[208:211], v[22:25]
	v_mfma_f32_16x16x32_bf16 v[10:13], v[130:133], v[208:211], v[10:13]
	v_mfma_f32_16x16x32_bf16 v[62:65], v[126:129], v[188:191], v[62:65]
	v_mfma_f32_16x16x32_bf16 v[58:61], v[134:137], v[188:191], v[58:61]
	v_mfma_f32_16x16x32_bf16 v[54:57], v[126:129], v[196:199], v[54:57]
	v_mfma_f32_16x16x32_bf16 v[42:45], v[134:137], v[196:199], v[42:45]
	v_mfma_f32_16x16x32_bf16 v[38:41], v[126:129], v[204:207], v[38:41]
	v_mfma_f32_16x16x32_bf16 v[26:29], v[134:137], v[204:207], v[26:29]
	v_mfma_f32_16x16x32_bf16 v[22:25], v[126:129], v[212:215], v[22:25]
	v_mfma_f32_16x16x32_bf16 v[10:13], v[134:137], v[212:215], v[10:13]
	s_setprio 2
	s_setprio 0
	v_mfma_f32_16x16x32_bf16 v[50:53], v[162:165], v[184:187], v[50:53]
	v_mfma_f32_16x16x32_bf16 v[46:49], v[176:179], v[184:187], v[46:49]
	v_mfma_f32_16x16x32_bf16 v[34:37], v[162:165], v[192:195], v[34:37]
	v_mfma_f32_16x16x32_bf16 v[30:33], v[176:179], v[192:195], v[30:33]
	v_mfma_f32_16x16x32_bf16 v[18:21], v[162:165], v[200:203], v[18:21]
	v_mfma_f32_16x16x32_bf16 v[14:17], v[176:179], v[200:203], v[14:17]
	v_mfma_f32_16x16x32_bf16 v[6:9], v[162:165], v[208:211], v[6:9]
	v_mfma_f32_16x16x32_bf16 v[2:5], v[176:179], v[208:211], v[2:5]
	v_mfma_f32_16x16x32_bf16 v[50:53], v[172:175], v[188:191], v[50:53]
	v_mfma_f32_16x16x32_bf16 v[46:49], v[180:183], v[188:191], v[46:49]
	v_mfma_f32_16x16x32_bf16 v[34:37], v[172:175], v[196:199], v[34:37]
	v_mfma_f32_16x16x32_bf16 v[30:33], v[180:183], v[196:199], v[30:33]
	v_mfma_f32_16x16x32_bf16 v[18:21], v[172:175], v[204:207], v[18:21]
	v_mfma_f32_16x16x32_bf16 v[14:17], v[180:183], v[204:207], v[14:17]
	v_mfma_f32_16x16x32_bf16 v[6:9], v[172:175], v[212:215], v[6:9]
	v_mfma_f32_16x16x32_bf16 v[2:5], v[180:183], v[212:215], v[2:5]
	s_setprio 2
	s_add_i32 s62, s62, 2
	s_add_u32 s4, s4, 0x100
	s_addc_u32 s5, s5, 0
	s_add_u32 s60, s60, 0x100
	s_addc_u32 s61, s61, 0
	s_cmp_gt_u32 s62, 13
	s_barrier
	s_cbranch_scc0 .LBB0_1931
	s_and_b64 vcc, exec, s[12:13]
	s_cbranch_vccz .LBB0_1934
	s_barrier

; #define PG8_STAGE(bufoff, gbase, voff) do { _Pragma("unroll") for (int _i = 0; _i < 2; ++_i) \
;         __builtin_amdgcn_global_load_lds((const unsigned*)((const char*)(gbase) + (voff)[_i]), (LAS unsigned*)(lds + (bufoff) + ldsw + _i * 8192), 16, 0, 0); } while (0)
; #define PG8_LDA(dst, b, h) do { _Pragma("unroll") for (int m = 0; m < 4; ++m) _Pragma("unroll") for (int k = 0; k < 2; ++k) dst[m][k] = *(const LAS bf16x8*)(lds + PG8_SA(b, h) + aoff + m * 2048 + k * 1024); } while (0)
; #define PG8_LDB(dst, b, h) do { _Pragma("unroll") for (int n = 0; n < 2; ++n) _Pragma("unroll") for (int k = 0; k < 2; ++k) dst[n][k] = *(const LAS bf16x8*)(lds + PG8_SB(b, h) + boff + n * 2048 + k * 1024); } while (0)
; #define PG8_MMA(ai, bj, At, Bt) do { __builtin_amdgcn_s_setprio(1); _Pragma("unroll") for (int m = 0; m < 4; ++m) _Pragma("unroll") for (int n = 0; n < 2; ++n) _Pragma("unroll") for (int k = 0; k < 2; ++k) \
;         acc[ai][bj][m][n] = __builtin_amdgcn_mfma_f32_16x16x32_bf16(Bt[n][k], At[m][k], acc[ai][bj][m][n], 0, 0, 0); __builtin_amdgcn_s_setprio(0); } while (0)
; template <class Epi>
; __device__ __forceinline__ void gemm_phase(LAS unsigned char* lds, const Gemm g, int G, int c, const Epi& E) {
;     ...
;         const bool has_next = S.next(ui + 1, nxt);
;         const char* nA = has_next ? (const char*)(g.A + (size_t)nxt.pb * g.sA) + (size_t)nxt.pm * 2 * hstepA : cA;
;         const char* nB = has_next ? (const char*)(g.Bt + (size_t)nxt.pb * g.sB) + (size_t)nxt.pn * 2 * hstepB : cB;
; #pragma nounroll
;         for (int t = 0; t < nt; t += 2) {
;             const bool last = (t == nt - 2);
;             const char* a1 = cA + (size_t)(t + 1) * kstep;
;             const char* a2 = last ? nA : cA + (size_t)(t + 2) * kstep; const char* b2 = last ? nB : cB + (size_t)(t + 2) * kstep;
;             const char* a3 = a2 + kstep; const char* b3 = b2 + kstep;
;             PG8_LDB(B0, 0, 0); PG8_LDB(B1, 0, 1); PG8_SCHED; PG8_LDA(At, 0, 0); PG8_STAGE(PG8_SA(1, 1), a1 + hstepA, voffA);
;             PG8_WAIT_V(8); PG8_WAIT_L(0); PG8_BAR; PG8_MMA(0, 0, At, B0); PG8_MMA(0, 1, At, B1); PG8_BAR; PG8_SCHED;
;             PG8_LDA(At, 0, 1); PG8_STAGE(PG8_SB(0, 0), b2, voffB); PG8_STAGE(PG8_SB(0, 1), b2 + hstepB, voffB); PG8_STAGE(PG8_SA(0, 0), a2, voffA);
;             PG8_WAIT_V(8); PG8_WAIT_L(0); PG8_BAR; PG8_MMA(1, 0, At, B0); PG8_MMA(1, 1, At, B1); PG8_BAR; PG8_SCHED;
.LBB0_2083:
	s_ashr_i32 s17, s16, 31
	s_lshl_b64 s[22:23], s[16:17], 19
	s_add_u32 s22, s43, s22
	s_addc_u32 s23, s44, s23
	s_and_b64 s[4:5], s[4:5], exec
	s_cselect_b32 s17, s23, s39
	s_cselect_b32 s19, s22, s38
	s_add_u32 s4, s40, 0x40080
	s_addc_u32 s5, s41, 0
	s_add_u32 s66, s38, 0x100
	s_addc_u32 s67, s39, 0
	s_mov_b32 s68, -2
	ds_read_b128 v[152:155], v148
	ds_read_b128 v[156:159], v148 offset:1024
	ds_read_b128 v[160:163], v148 offset:2048
	ds_read_b128 v[164:167], v148 offset:3072
	ds_read_b128 v[168:171], v149
	ds_read_b128 v[172:175], v149 offset:1024
	ds_read_b128 v[176:179], v149 offset:2048
	ds_read_b128 v[180:183], v149 offset:3072
	s_add_u32 s33, s4, 0xfffc0080
	s_addc_u32 s38, s5, -1
	s_cmp_eq_u32 s68, 12
	s_cselect_b32 s41, s21, s38
	s_cselect_b32 s40, s20, s33
	s_cselect_b32 s39, s17, s67
	s_cselect_b32 s38, s19, s66
	v_lshl_add_u64 v[216:217], s[4:5], 0, v[138:139]
	s_add_i32 m0, s25, 0xc000
	ds_read_b128 v[184:187], v150
	ds_read_b128 v[188:191], v150 offset:1024
	ds_read_b128 v[192:195], v150 offset:2048
	ds_read_b128 v[196:199], v150 offset:3072
	ds_read_b128 v[200:203], v150 offset:4096
	ds_read_b128 v[204:207], v150 offset:5120
	ds_read_b128 v[208:211], v150 offset:6144
	ds_read_b128 v[212:215], v150 offset:7168
	global_load_lds_dwordx4 v[216:217], off
	v_lshl_add_u64 v[216:217], s[4:5], 0, v[140:141]
	s_add_i32 m0, s25, 0xe000
	s_nop 0
	global_load_lds_dwordx4 v[216:217], off
	s_waitcnt vmcnt(8)
	s_waitcnt lgkmcnt(0)
	s_barrier
	s_setprio 0
	v_mfma_f32_16x16x32_bf16 v[126:129], v[152:155], v[184:187], 0
	v_mfma_f32_16x16x32_bf16 v[122:125], v[160:163], v[184:187], 0
	v_mfma_f32_16x16x32_bf16 v[110:113], v[152:155], v[192:195], 0
	v_mfma_f32_16x16x32_bf16 v[106:109], v[160:163], v[192:195], 0
	v_mfma_f32_16x16x32_bf16 v[94:97], v[152:155], v[200:203], 0
	v_mfma_f32_16x16x32_bf16 v[90:93], v[160:163], v[200:203], 0
	v_mfma_f32_16x16x32_bf16 v[78:81], v[152:155], v[208:211], 0
	v_mfma_f32_16x16x32_bf16 v[74:77], v[160:163], v[208:211], 0
	v_mfma_f32_16x16x32_bf16 v[126:129], v[156:159], v[188:191], v[126:129]
	v_mfma_f32_16x16x32_bf16 v[122:125], v[164:167], v[188:191], v[122:125]
	v_mfma_f32_16x16x32_bf16 v[110:113], v[156:159], v[196:199], v[110:113]
	v_mfma_f32_16x16x32_bf16 v[106:109], v[164:167], v[196:199], v[106:109]
	v_mfma_f32_16x16x32_bf16 v[94:97], v[156:159], v[204:207], v[94:97]
	v_mfma_f32_16x16x32_bf16 v[90:93], v[164:167], v[204:207], v[90:93]
	v_mfma_f32_16x16x32_bf16 v[78:81], v[156:159], v[212:215], v[78:81]
	v_mfma_f32_16x16x32_bf16 v[74:77], v[164:167], v[212:215], v[74:77]
	s_setprio 2
	s_setprio 0
	v_mfma_f32_16x16x32_bf16 v[118:121], v[168:171], v[184:187], 0
	v_mfma_f32_16x16x32_bf16 v[114:117], v[176:179], v[184:187], 0
	v_mfma_f32_16x16x32_bf16 v[102:105], v[168:171], v[192:195], 0
	v_mfma_f32_16x16x32_bf16 v[98:101], v[176:179], v[192:195], 0
	v_mfma_f32_16x16x32_bf16 v[86:89], v[168:171], v[200:203], 0
	v_mfma_f32_16x16x32_bf16 v[82:85], v[176:179], v[200:203], 0
	v_mfma_f32_16x16x32_bf16 v[70:73], v[168:171], v[208:211], 0
	v_mfma_f32_16x16x32_bf16 v[66:69], v[176:179], v[208:211], 0
	v_mfma_f32_16x16x32_bf16 v[118:121], v[172:175], v[188:191], v[118:121]
	v_mfma_f32_16x16x32_bf16 v[114:117], v[180:183], v[188:191], v[114:117]
	v_mfma_f32_16x16x32_bf16 v[102:105], v[172:175], v[196:199], v[102:105]
	v_mfma_f32_16x16x32_bf16 v[98:101], v[180:183], v[196:199], v[98:101]
	v_mfma_f32_16x16x32_bf16 v[86:89], v[172:175], v[204:207], v[86:89]
	v_mfma_f32_16x16x32_bf16 v[82:85], v[180:183], v[204:207], v[82:85]
	v_mfma_f32_16x16x32_bf16 v[70:73], v[172:175], v[212:215], v[70:73]
	v_mfma_f32_16x16x32_bf16 v[66:69], v[180:183], v[212:215], v[66:69]
	s_setprio 2
	s_barrier
	s_add_i32 s33, s56, s46
	v_lshl_add_u64 v[216:217], s[38:39], 0, v[134:135]
	s_mov_b32 m0, s33
	ds_read_b128 v[184:187], v150 offset:16384
	ds_read_b128 v[188:191], v150 offset:17408
	ds_read_b128 v[192:195], v150 offset:18432
	ds_read_b128 v[196:199], v150 offset:19456
	ds_read_b128 v[200:203], v150 offset:20480
	ds_read_b128 v[204:207], v150 offset:21504
	ds_read_b128 v[208:211], v150 offset:22528
	ds_read_b128 v[212:215], v150 offset:23552
	global_load_lds_dwordx4 v[216:217], off
	s_add_i32 m0, s33, 0x2000
	s_add_u32 s70, s38, 0x40000
	v_lshl_add_u64 v[218:219], s[38:39], 0, v[130:131]
	s_addc_u32 s71, s39, 0
	s_add_i32 s33, s57, s46
	global_load_lds_dwordx4 v[218:219], off
	v_lshl_add_u64 v[220:221], s[70:71], 0, v[134:135]
	s_mov_b32 m0, s33
	v_lshl_add_u64 v[222:223], s[40:41], 0, v[132:133]
	global_load_lds_dwordx4 v[220:221], off
	v_lshl_add_u64 v[220:221], s[70:71], 0, v[130:131]
	s_add_i32 m0, s33, 0x2000
	s_nop 0
	global_load_lds_dwordx4 v[220:221], off
	v_lshl_add_u64 v[220:221], s[40:41], 0, v[136:137]
	s_mov_b32 m0, s25
	s_nop 0
	global_load_lds_dwordx4 v[220:221], off
	s_mov_b32 m0, s37
	s_nop 0
	global_load_lds_dwordx4 v[222:223], off
	s_waitcnt vmcnt(8)
	s_waitcnt lgkmcnt(0)
	s_barrier
; #define PG8_STAGE(bufoff, gbase, voff) do { _Pragma("unroll") for (int _i = 0; _i < 2; ++_i) \
;         __builtin_amdgcn_global_load_lds((const unsigned*)((const char*)(gbase) + (voff)[_i]), (LAS unsigned*)(lds + (bufoff) + ldsw + _i * 8192), 16, 0, 0); } while (0)
; #define PG8_LDA(dst, b, h) do { _Pragma("unroll") for (int m = 0; m < 4; ++m) _Pragma("unroll") for (int k = 0; k < 2; ++k) dst[m][k] = *(const LAS bf16x8*)(lds + PG8_SA(b, h) + aoff + m * 2048 + k * 1024); } while (0)
; #define PG8_LDB(dst, b, h) do { _Pragma("unroll") for (int n = 0; n < 2; ++n) _Pragma("unroll") for (int k = 0; k < 2; ++k) dst[n][k] = *(const LAS bf16x8*)(lds + PG8_SB(b, h) + boff + n * 2048 + k * 1024); } while (0)
; #define PG8_MMA(ai, bj, At, Bt) do { __builtin_amdgcn_s_setprio(1); _Pragma("unroll") for (int m = 0; m < 4; ++m) _Pragma("unroll") for (int n = 0; n < 2; ++n) _Pragma("unroll") for (int k = 0; k < 2; ++k) \
;         acc[ai][bj][m][n] = __builtin_amdgcn_mfma_f32_16x16x32_bf16(Bt[n][k], At[m][k], acc[ai][bj][m][n], 0, 0, 0); __builtin_amdgcn_s_setprio(0); } while (0)
; #define PG8_WAIT_V(n) asm volatile("s_waitcnt vmcnt(" #n ")" ::: "memory")
; #define PG8_WAIT_L(n) asm volatile("s_waitcnt lgkmcnt(" #n ")" ::: "memory")
; #define PG8_BAR __builtin_amdgcn_s_barrier()
; #define PG8_SCHED __builtin_amdgcn_sched_barrier(0)
; template <class Epi>
; __device__ __forceinline__ void gemm_phase(LAS unsigned char* lds, const Gemm g, int G, int c, const Epi& E) {
;     ...
;             PG8_WAIT_V(8); PG8_WAIT_L(0); PG8_BAR; PG8_MMA(1, 0, At, B0); PG8_MMA(1, 1, At, B1); PG8_BAR; PG8_SCHED;
;             PG8_LDB(B0, 1, 0); PG8_LDB(B1, 1, 1); PG8_SCHED; PG8_LDA(At, 1, 0); PG8_STAGE(PG8_SA(0, 1), a2 + hstepA, voffA);
;             PG8_WAIT_V(8); PG8_WAIT_L(0); PG8_BAR; PG8_MMA(0, 0, At, B0); PG8_MMA(0, 1, At, B1); PG8_BAR; PG8_SCHED;
	s_setprio 0
	v_mfma_f32_16x16x32_bf16 v[62:65], v[152:155], v[184:187], 0
	v_mfma_f32_16x16x32_bf16 v[58:61], v[160:163], v[184:187], 0
	v_mfma_f32_16x16x32_bf16 v[46:49], v[152:155], v[192:195], 0
	v_mfma_f32_16x16x32_bf16 v[42:45], v[160:163], v[192:195], 0
	v_mfma_f32_16x16x32_bf16 v[30:33], v[152:155], v[200:203], 0
	v_mfma_f32_16x16x32_bf16 v[26:29], v[160:163], v[200:203], 0
	v_mfma_f32_16x16x32_bf16 v[14:17], v[152:155], v[208:211], 0
	v_mfma_f32_16x16x32_bf16 v[10:13], v[160:163], v[208:211], 0
	v_mfma_f32_16x16x32_bf16 v[62:65], v[156:159], v[188:191], v[62:65]
	v_mfma_f32_16x16x32_bf16 v[58:61], v[164:167], v[188:191], v[58:61]
	v_mfma_f32_16x16x32_bf16 v[46:49], v[156:159], v[196:199], v[46:49]
	v_mfma_f32_16x16x32_bf16 v[42:45], v[164:167], v[196:199], v[42:45]
	v_mfma_f32_16x16x32_bf16 v[30:33], v[156:159], v[204:207], v[30:33]
	v_mfma_f32_16x16x32_bf16 v[26:29], v[164:167], v[204:207], v[26:29]
	v_mfma_f32_16x16x32_bf16 v[14:17], v[156:159], v[212:215], v[14:17]
	v_mfma_f32_16x16x32_bf16 v[10:13], v[164:167], v[212:215], v[10:13]
	s_setprio 2
	s_setprio 0
	v_mfma_f32_16x16x32_bf16 v[54:57], v[168:171], v[184:187], 0
	v_mfma_f32_16x16x32_bf16 v[50:53], v[176:179], v[184:187], 0
	v_mfma_f32_16x16x32_bf16 v[38:41], v[168:171], v[192:195], 0
	v_mfma_f32_16x16x32_bf16 v[34:37], v[176:179], v[192:195], 0
	v_mfma_f32_16x16x32_bf16 v[22:25], v[168:171], v[200:203], 0
	v_mfma_f32_16x16x32_bf16 v[18:21], v[176:179], v[200:203], 0
	v_mfma_f32_16x16x32_bf16 v[6:9], v[168:171], v[208:211], 0
	v_mfma_f32_16x16x32_bf16 v[2:5], v[176:179], v[208:211], 0
	v_mfma_f32_16x16x32_bf16 v[54:57], v[172:175], v[188:191], v[54:57]
	v_mfma_f32_16x16x32_bf16 v[50:53], v[180:183], v[188:191], v[50:53]
	v_mfma_f32_16x16x32_bf16 v[38:41], v[172:175], v[196:199], v[38:41]
	v_mfma_f32_16x16x32_bf16 v[34:37], v[180:183], v[196:199], v[34:37]
	v_mfma_f32_16x16x32_bf16 v[22:25], v[172:175], v[204:207], v[22:25]
	v_mfma_f32_16x16x32_bf16 v[18:21], v[180:183], v[204:207], v[18:21]
	v_mfma_f32_16x16x32_bf16 v[6:9], v[172:175], v[212:215], v[6:9]
	v_mfma_f32_16x16x32_bf16 v[2:5], v[180:183], v[212:215], v[2:5]
	s_setprio 2
	s_barrier
	s_add_i32 s33, 0, 0x18000
	s_add_i32 s69, 0, 0x1c000
	v_add_u32_e32 v164, s33, v147
	v_add_u32_e32 v180, s69, v147
	ds_read_b128 v[152:155], v164
	ds_read_b128 v[156:159], v164 offset:1024
	ds_read_b128 v[160:163], v164 offset:2048
	ds_read_b128 v[164:167], v164 offset:3072
	ds_read_b128 v[168:171], v180
	ds_read_b128 v[172:175], v180 offset:1024
	ds_read_b128 v[176:179], v180 offset:2048
	ds_read_b128 v[180:183], v180 offset:3072
	s_add_u32 s40, s40, 0x40000
	s_addc_u32 s41, s41, 0
	s_mov_b32 m0, s47
	v_lshl_add_u64 v[224:225], s[40:41], 0, v[136:137]
	ds_read_b128 v[184:187], v150 offset:32768
	ds_read_b128 v[188:191], v150 offset:33792
	ds_read_b128 v[192:195], v150 offset:34816
	ds_read_b128 v[196:199], v150 offset:35840
	ds_read_b128 v[200:203], v150 offset:36864
	ds_read_b128 v[204:207], v150 offset:37888
	ds_read_b128 v[208:211], v150 offset:38912
	ds_read_b128 v[212:215], v150 offset:39936
	global_load_lds_dwordx4 v[224:225], off
	v_lshl_add_u64 v[224:225], s[40:41], 0, v[132:133]
	s_mov_b32 m0, s48
	s_nop 0
	global_load_lds_dwordx4 v[224:225], off
	s_waitcnt vmcnt(8)
	s_waitcnt lgkmcnt(0)
	s_barrier
	s_setprio 0
	v_mfma_f32_16x16x32_bf16 v[126:129], v[152:155], v[184:187], v[126:129]
	v_mfma_f32_16x16x32_bf16 v[122:125], v[160:163], v[184:187], v[122:125]
	v_mfma_f32_16x16x32_bf16 v[110:113], v[152:155], v[192:195], v[110:113]
	v_mfma_f32_16x16x32_bf16 v[106:109], v[160:163], v[192:195], v[106:109]
	v_mfma_f32_16x16x32_bf16 v[94:97], v[152:155], v[200:203], v[94:97]
	v_mfma_f32_16x16x32_bf16 v[90:93], v[160:163], v[200:203], v[90:93]
	v_mfma_f32_16x16x32_bf16 v[78:81], v[152:155], v[208:211], v[78:81]
	v_mfma_f32_16x16x32_bf16 v[74:77], v[160:163], v[208:211], v[74:77]
	v_mfma_f32_16x16x32_bf16 v[126:129], v[156:159], v[188:191], v[126:129]
	v_mfma_f32_16x16x32_bf16 v[122:125], v[164:167], v[188:191], v[122:125]
	v_mfma_f32_16x16x32_bf16 v[110:113], v[156:159], v[196:199], v[110:113]
	v_mfma_f32_16x16x32_bf16 v[106:109], v[164:167], v[196:199], v[106:109]
	v_mfma_f32_16x16x32_bf16 v[94:97], v[156:159], v[204:207], v[94:97]
	v_mfma_f32_16x16x32_bf16 v[90:93], v[164:167], v[204:207], v[90:93]
	v_mfma_f32_16x16x32_bf16 v[78:81], v[156:159], v[212:215], v[78:81]
	v_mfma_f32_16x16x32_bf16 v[74:77], v[164:167], v[212:215], v[74:77]
	s_setprio 2
	s_setprio 0
	v_mfma_f32_16x16x32_bf16 v[118:121], v[168:171], v[184:187], v[118:121]
	v_mfma_f32_16x16x32_bf16 v[114:117], v[176:179], v[184:187], v[114:117]
	v_mfma_f32_16x16x32_bf16 v[102:105], v[168:171], v[192:195], v[102:105]
	v_mfma_f32_16x16x32_bf16 v[98:101], v[176:179], v[192:195], v[98:101]
	v_mfma_f32_16x16x32_bf16 v[86:89], v[168:171], v[200:203], v[86:89]
	v_mfma_f32_16x16x32_bf16 v[82:85], v[176:179], v[200:203], v[82:85]
	v_mfma_f32_16x16x32_bf16 v[70:73], v[168:171], v[208:211], v[70:73]
	v_mfma_f32_16x16x32_bf16 v[66:69], v[176:179], v[208:211], v[66:69]
	v_mfma_f32_16x16x32_bf16 v[118:121], v[172:175], v[188:191], v[118:121]
	v_mfma_f32_16x16x32_bf16 v[114:117], v[180:183], v[188:191], v[114:117]
	v_mfma_f32_16x16x32_bf16 v[102:105], v[172:175], v[196:199], v[102:105]
	v_mfma_f32_16x16x32_bf16 v[98:101], v[180:183], v[196:199], v[98:101]
	v_mfma_f32_16x16x32_bf16 v[86:89], v[172:175], v[204:207], v[86:89]
	v_mfma_f32_16x16x32_bf16 v[82:85], v[180:183], v[204:207], v[82:85]
	v_mfma_f32_16x16x32_bf16 v[70:73], v[172:175], v[212:215], v[70:73]
	v_mfma_f32_16x16x32_bf16 v[66:69], v[180:183], v[212:215], v[66:69]
	s_setprio 2
	s_barrier
; #define PG8_STAGE(bufoff, gbase, voff) do { _Pragma("unroll") for (int _i = 0; _i < 2; ++_i) \
;         __builtin_amdgcn_global_load_lds((const unsigned*)((const char*)(gbase) + (voff)[_i]), (LAS unsigned*)(lds + (bufoff) + ldsw + _i * 8192), 16, 0, 0); } while (0)
; #define PG8_LDA(dst, b, h) do { _Pragma("unroll") for (int m = 0; m < 4; ++m) _Pragma("unroll") for (int k = 0; k < 2; ++k) dst[m][k] = *(const LAS bf16x8*)(lds + PG8_SA(b, h) + aoff + m * 2048 + k * 1024); } while (0)
; #define PG8_LDB(dst, b, h) do { _Pragma("unroll") for (int n = 0; n < 2; ++n) _Pragma("unroll") for (int k = 0; k < 2; ++k) dst[n][k] = *(const LAS bf16x8*)(lds + PG8_SB(b, h) + boff + n * 2048 + k * 1024); } while (0)
; #define PG8_MMA(ai, bj, At, Bt) do { __builtin_amdgcn_s_setprio(1); _Pragma("unroll") for (int m = 0; m < 4; ++m) _Pragma("unroll") for (int n = 0; n < 2; ++n) _Pragma("unroll") for (int k = 0; k < 2; ++k) \
;         acc[ai][bj][m][n] = __builtin_amdgcn_mfma_f32_16x16x32_bf16(Bt[n][k], At[m][k], acc[ai][bj][m][n], 0, 0, 0); __builtin_amdgcn_s_setprio(0); } while (0)
; #define PG8_WAIT_V(n) asm volatile("s_waitcnt vmcnt(" #n ")" ::: "memory")
; #define PG8_BAR __builtin_amdgcn_s_barrier()
; template <class Epi>
; __device__ __forceinline__ void gemm_phase(LAS unsigned char* lds, const Gemm g, int G, int c, const Epi& E) {
;     ...
;             PG8_LDB(B0, 0, 0); PG8_LDB(B1, 0, 1); PG8_SCHED; PG8_LDA(At, 0, 0); PG8_STAGE(PG8_SA(1, 1), a1 + hstepA, voffA);
;             PG8_WAIT_V(8); PG8_WAIT_L(0); PG8_BAR; PG8_MMA(0, 0, At, B0); PG8_MMA(0, 1, At, B1); PG8_BAR; PG8_SCHED;
;             PG8_LDA(At, 0, 1); PG8_STAGE(PG8_SB(0, 0), b2, voffB); PG8_STAGE(PG8_SB(0, 1), b2 + hstepB, voffB); PG8_STAGE(PG8_SA(0, 0), a2, voffA);
;             PG8_WAIT_V(8); PG8_WAIT_L(0); PG8_BAR; PG8_MMA(1, 0, At, B0); PG8_MMA(1, 1, At, B1); PG8_BAR; PG8_SCHED;
;             PG8_LDB(B0, 1, 0); PG8_LDB(B1, 1, 1); PG8_SCHED; PG8_LDA(At, 1, 0); PG8_STAGE(PG8_SA(0, 1), a2 + hstepA, voffA);
;             PG8_WAIT_V(8); PG8_WAIT_L(0); PG8_BAR; PG8_MMA(0, 0, At, B0); PG8_MMA(0, 1, At, B1); PG8_BAR; PG8_SCHED;
;             PG8_LDA(At, 1, 1); PG8_STAGE(PG8_SB(1, 0), b3, voffB); PG8_STAGE(PG8_SB(1, 1), b3 + hstepB, voffB); PG8_STAGE(PG8_SA(1, 0), a3, voffA);
;             PG8_WAIT_V(8); PG8_WAIT_L(0); PG8_BAR; PG8_MMA(1, 0, At, B0); PG8_MMA(1, 1, At, B1); PG8_BAR; PG8_SCHED;
;         }
	s_add_i32 s33, s33, s46
	v_lshl_add_u64 v[216:217], v[216:217], 0, s[12:13]
	s_mov_b32 m0, s33
	ds_read_b128 v[184:187], v150 offset:49152
	ds_read_b128 v[188:191], v150 offset:50176
	ds_read_b128 v[192:195], v150 offset:51200
	ds_read_b128 v[196:199], v150 offset:52224
	ds_read_b128 v[200:203], v150 offset:53248
	ds_read_b128 v[204:207], v150 offset:54272
	ds_read_b128 v[208:211], v150 offset:55296
	ds_read_b128 v[212:215], v150 offset:56320
	global_load_lds_dwordx4 v[216:217], off
	s_add_i32 m0, s33, 0x2000
	s_add_u32 s38, s38, 0x40080
	v_lshl_add_u64 v[216:217], v[218:219], 0, s[12:13]
	s_addc_u32 s39, s39, 0
	s_add_i32 s33, s69, s46
	global_load_lds_dwordx4 v[216:217], off
	v_lshl_add_u64 v[216:217], s[38:39], 0, v[134:135]
	s_mov_b32 m0, s33
	s_nop 0
	global_load_lds_dwordx4 v[216:217], off
	v_lshl_add_u64 v[216:217], s[38:39], 0, v[130:131]
	s_add_i32 m0, s33, 0x2000
	s_nop 0
	global_load_lds_dwordx4 v[216:217], off
	v_lshl_add_u64 v[216:217], v[220:221], 0, s[12:13]
	s_mov_b32 m0, s53
	s_nop 0
	global_load_lds_dwordx4 v[216:217], off
	v_lshl_add_u64 v[216:217], v[222:223], 0, s[12:13]
	s_mov_b32 m0, s54
	s_nop 0
	global_load_lds_dwordx4 v[216:217], off
	s_waitcnt vmcnt(8)
	s_waitcnt lgkmcnt(0)
	s_barrier
	s_setprio 0
	v_mfma_f32_16x16x32_bf16 v[62:65], v[152:155], v[184:187], v[62:65]
	v_mfma_f32_16x16x32_bf16 v[58:61], v[160:163], v[184:187], v[58:61]
	v_mfma_f32_16x16x32_bf16 v[46:49], v[152:155], v[192:195], v[46:49]
	v_mfma_f32_16x16x32_bf16 v[42:45], v[160:163], v[192:195], v[42:45]
	v_mfma_f32_16x16x32_bf16 v[30:33], v[152:155], v[200:203], v[30:33]
	v_mfma_f32_16x16x32_bf16 v[26:29], v[160:163], v[200:203], v[26:29]
	v_mfma_f32_16x16x32_bf16 v[14:17], v[152:155], v[208:211], v[14:17]
	v_mfma_f32_16x16x32_bf16 v[10:13], v[160:163], v[208:211], v[10:13]
	v_mfma_f32_16x16x32_bf16 v[62:65], v[156:159], v[188:191], v[62:65]
	v_mfma_f32_16x16x32_bf16 v[58:61], v[164:167], v[188:191], v[58:61]
	v_mfma_f32_16x16x32_bf16 v[46:49], v[156:159], v[196:199], v[46:49]
	v_mfma_f32_16x16x32_bf16 v[42:45], v[164:167], v[196:199], v[42:45]
	v_mfma_f32_16x16x32_bf16 v[30:33], v[156:159], v[204:207], v[30:33]
	v_mfma_f32_16x16x32_bf16 v[26:29], v[164:167], v[204:207], v[26:29]
	v_mfma_f32_16x16x32_bf16 v[14:17], v[156:159], v[212:215], v[14:17]
	v_mfma_f32_16x16x32_bf16 v[10:13], v[164:167], v[212:215], v[10:13]
	s_setprio 2
	s_setprio 0
	v_mfma_f32_16x16x32_bf16 v[54:57], v[168:171], v[184:187], v[54:57]
	v_mfma_f32_16x16x32_bf16 v[50:53], v[176:179], v[184:187], v[50:53]
	v_mfma_f32_16x16x32_bf16 v[38:41], v[168:171], v[192:195], v[38:41]
	v_mfma_f32_16x16x32_bf16 v[34:37], v[176:179], v[192:195], v[34:37]
	v_mfma_f32_16x16x32_bf16 v[22:25], v[168:171], v[200:203], v[22:25]
	v_mfma_f32_16x16x32_bf16 v[18:21], v[176:179], v[200:203], v[18:21]
	v_mfma_f32_16x16x32_bf16 v[6:9], v[168:171], v[208:211], v[6:9]
	v_mfma_f32_16x16x32_bf16 v[2:5], v[176:179], v[208:211], v[2:5]
	v_mfma_f32_16x16x32_bf16 v[54:57], v[172:175], v[188:191], v[54:57]
	v_mfma_f32_16x16x32_bf16 v[50:53], v[180:183], v[188:191], v[50:53]
	v_mfma_f32_16x16x32_bf16 v[38:41], v[172:175], v[196:199], v[38:41]
	v_mfma_f32_16x16x32_bf16 v[34:37], v[180:183], v[196:199], v[34:37]
	v_mfma_f32_16x16x32_bf16 v[22:25], v[172:175], v[204:207], v[22:25]
	v_mfma_f32_16x16x32_bf16 v[18:21], v[180:183], v[204:207], v[18:21]
	v_mfma_f32_16x16x32_bf16 v[6:9], v[172:175], v[212:215], v[6:9]
	v_mfma_f32_16x16x32_bf16 v[2:5], v[180:183], v[212:215], v[2:5]
	s_setprio 2
	s_add_i32 s68, s68, 2
	s_add_u32 s4, s4, 0x100
	s_addc_u32 s5, s5, 0
	s_add_u32 s66, s66, 0x100
	s_addc_u32 s67, s67, 0
	s_cmp_gt_u32 s68, 13
	s_barrier
	s_cbranch_scc0 .LBB0_2084
.LBB0_2084:
	ds_read_b128 v[152:155], v148
	ds_read_b128 v[156:159], v148 offset:1024
	ds_read_b128 v[160:163], v148 offset:2048
	ds_read_b128 v[164:167], v148 offset:3072
	ds_read_b128 v[168:171], v149
	ds_read_b128 v[172:175], v149 offset:1024
	ds_read_b128 v[176:179], v149 offset:2048
	ds_read_b128 v[180:183], v149 offset:3072
	s_add_u32 s33, s4, 0xfffc0080
	s_addc_u32 s38, s5, -1
	s_cmp_eq_u32 s68, 12
	s_cselect_b32 s41, s21, s38
	s_cselect_b32 s40, s20, s33
	s_cselect_b32 s39, s17, s67
	s_cselect_b32 s38, s19, s66
	v_lshl_add_u64 v[216:217], s[4:5], 0, v[138:139]
	s_add_i32 m0, s25, 0xc000
	ds_read_b128 v[184:187], v150
	ds_read_b128 v[188:191], v150 offset:1024
	ds_read_b128 v[192:195], v150 offset:2048
	ds_read_b128 v[196:199], v150 offset:3072
	ds_read_b128 v[200:203], v150 offset:4096
	ds_read_b128 v[204:207], v150 offset:5120
	ds_read_b128 v[208:211], v150 offset:6144
	ds_read_b128 v[212:215], v150 offset:7168
	global_load_lds_dwordx4 v[216:217], off
	v_lshl_add_u64 v[216:217], s[4:5], 0, v[140:141]
	s_add_i32 m0, s25, 0xe000
	s_nop 0
	global_load_lds_dwordx4 v[216:217], off
	s_waitcnt vmcnt(8)
	s_waitcnt lgkmcnt(0)
	s_barrier
; #define PG8_STAGE(bufoff, gbase, voff) do { _Pragma("unroll") for (int _i = 0; _i < 2; ++_i) \
;         __builtin_amdgcn_global_load_lds((const unsigned*)((const char*)(gbase) + (voff)[_i]), (LAS unsigned*)(lds + (bufoff) + ldsw + _i * 8192), 16, 0, 0); } while (0)
; #define PG8_LDA(dst, b, h) do { _Pragma("unroll") for (int m = 0; m < 4; ++m) _Pragma("unroll") for (int k = 0; k < 2; ++k) dst[m][k] = *(const LAS bf16x8*)(lds + PG8_SA(b, h) + aoff + m * 2048 + k * 1024); } while (0)
; #define PG8_MMA(ai, bj, At, Bt) do { __builtin_amdgcn_s_setprio(1); _Pragma("unroll") for (int m = 0; m < 4; ++m) _Pragma("unroll") for (int n = 0; n < 2; ++n) _Pragma("unroll") for (int k = 0; k < 2; ++k) \
;         acc[ai][bj][m][n] = __builtin_amdgcn_mfma_f32_16x16x32_bf16(Bt[n][k], At[m][k], acc[ai][bj][m][n], 0, 0, 0); __builtin_amdgcn_s_setprio(0); } while (0)
; #define PG8_WAIT_V(n) asm volatile("s_waitcnt vmcnt(" #n ")" ::: "memory")
; #define PG8_WAIT_L(n) asm volatile("s_waitcnt lgkmcnt(" #n ")" ::: "memory")
; #define PG8_BAR __builtin_amdgcn_s_barrier()
; #define PG8_SCHED __builtin_amdgcn_sched_barrier(0)
; template <class Epi>
; __device__ __forceinline__ void gemm_phase(LAS unsigned char* lds, const Gemm g, int G, int c, const Epi& E) {
;     ...
;             PG8_WAIT_V(8); PG8_WAIT_L(0); PG8_BAR; PG8_MMA(0, 0, At, B0); PG8_MMA(0, 1, At, B1); PG8_BAR; PG8_SCHED;
;             PG8_LDA(At, 0, 1); PG8_STAGE(PG8_SB(0, 0), b2, voffB); PG8_STAGE(PG8_SB(0, 1), b2 + hstepB, voffB); PG8_STAGE(PG8_SA(0, 0), a2, voffA);
;             PG8_WAIT_V(8); PG8_WAIT_L(0); PG8_BAR; PG8_MMA(1, 0, At, B0); PG8_MMA(1, 1, At, B1); PG8_BAR; PG8_SCHED;
	s_setprio 0
	v_mfma_f32_16x16x32_bf16 v[126:129], v[152:155], v[184:187], v[126:129]
	v_mfma_f32_16x16x32_bf16 v[122:125], v[160:163], v[184:187], v[122:125]
	v_mfma_f32_16x16x32_bf16 v[110:113], v[152:155], v[192:195], v[110:113]
	v_mfma_f32_16x16x32_bf16 v[106:109], v[160:163], v[192:195], v[106:109]
	v_mfma_f32_16x16x32_bf16 v[94:97], v[152:155], v[200:203], v[94:97]
	v_mfma_f32_16x16x32_bf16 v[90:93], v[160:163], v[200:203], v[90:93]
	v_mfma_f32_16x16x32_bf16 v[78:81], v[152:155], v[208:211], v[78:81]
	v_mfma_f32_16x16x32_bf16 v[74:77], v[160:163], v[208:211], v[74:77]
	v_mfma_f32_16x16x32_bf16 v[126:129], v[156:159], v[188:191], v[126:129]
	v_mfma_f32_16x16x32_bf16 v[122:125], v[164:167], v[188:191], v[122:125]
	v_mfma_f32_16x16x32_bf16 v[110:113], v[156:159], v[196:199], v[110:113]
	v_mfma_f32_16x16x32_bf16 v[106:109], v[164:167], v[196:199], v[106:109]
	v_mfma_f32_16x16x32_bf16 v[94:97], v[156:159], v[204:207], v[94:97]
	v_mfma_f32_16x16x32_bf16 v[90:93], v[164:167], v[204:207], v[90:93]
	v_mfma_f32_16x16x32_bf16 v[78:81], v[156:159], v[212:215], v[78:81]
	v_mfma_f32_16x16x32_bf16 v[74:77], v[164:167], v[212:215], v[74:77]
	s_setprio 2
	s_setprio 0
	v_mfma_f32_16x16x32_bf16 v[118:121], v[168:171], v[184:187], v[118:121]
	v_mfma_f32_16x16x32_bf16 v[114:117], v[176:179], v[184:187], v[114:117]
	v_mfma_f32_16x16x32_bf16 v[102:105], v[168:171], v[192:195], v[102:105]
	v_mfma_f32_16x16x32_bf16 v[98:101], v[176:179], v[192:195], v[98:101]
	v_mfma_f32_16x16x32_bf16 v[86:89], v[168:171], v[200:203], v[86:89]
	v_mfma_f32_16x16x32_bf16 v[82:85], v[176:179], v[200:203], v[82:85]
	v_mfma_f32_16x16x32_bf16 v[70:73], v[168:171], v[208:211], v[70:73]
	v_mfma_f32_16x16x32_bf16 v[66:69], v[176:179], v[208:211], v[66:69]
	v_mfma_f32_16x16x32_bf16 v[118:121], v[172:175], v[188:191], v[118:121]
	v_mfma_f32_16x16x32_bf16 v[114:117], v[180:183], v[188:191], v[114:117]
	v_mfma_f32_16x16x32_bf16 v[102:105], v[172:175], v[196:199], v[102:105]
	v_mfma_f32_16x16x32_bf16 v[98:101], v[180:183], v[196:199], v[98:101]
	v_mfma_f32_16x16x32_bf16 v[86:89], v[172:175], v[204:207], v[86:89]
	v_mfma_f32_16x16x32_bf16 v[82:85], v[180:183], v[204:207], v[82:85]
	v_mfma_f32_16x16x32_bf16 v[70:73], v[172:175], v[212:215], v[70:73]
	v_mfma_f32_16x16x32_bf16 v[66:69], v[180:183], v[212:215], v[66:69]
	s_setprio 2
	s_barrier
	s_add_i32 s33, s56, s46
	v_lshl_add_u64 v[216:217], s[38:39], 0, v[134:135]
	s_mov_b32 m0, s33
	ds_read_b128 v[184:187], v150 offset:16384
	ds_read_b128 v[188:191], v150 offset:17408
	ds_read_b128 v[192:195], v150 offset:18432
	ds_read_b128 v[196:199], v150 offset:19456
	ds_read_b128 v[200:203], v150 offset:20480
	ds_read_b128 v[204:207], v150 offset:21504
	ds_read_b128 v[208:211], v150 offset:22528
	ds_read_b128 v[212:215], v150 offset:23552
	global_load_lds_dwordx4 v[216:217], off
	s_add_i32 m0, s33, 0x2000
	s_add_u32 s70, s38, 0x40000
	v_lshl_add_u64 v[218:219], s[38:39], 0, v[130:131]
	s_addc_u32 s71, s39, 0
	s_add_i32 s33, s57, s46
	global_load_lds_dwordx4 v[218:219], off
	v_lshl_add_u64 v[220:221], s[70:71], 0, v[134:135]
	s_mov_b32 m0, s33
	v_lshl_add_u64 v[222:223], s[40:41], 0, v[132:133]
	global_load_lds_dwordx4 v[220:221], off
	v_lshl_add_u64 v[220:221], s[70:71], 0, v[130:131]
	s_add_i32 m0, s33, 0x2000
	s_nop 0
	global_load_lds_dwordx4 v[220:221], off
	v_lshl_add_u64 v[220:221], s[40:41], 0, v[136:137]
	s_mov_b32 m0, s25
	s_nop 0
	global_load_lds_dwordx4 v[220:221], off
	s_mov_b32 m0, s37
	s_nop 0
	global_load_lds_dwordx4 v[222:223], off
	s_waitcnt vmcnt(8)
	s_waitcnt lgkmcnt(0)
	s_barrier
	s_setprio 0
	v_mfma_f32_16x16x32_bf16 v[62:65], v[152:155], v[184:187], v[62:65]
	v_mfma_f32_16x16x32_bf16 v[58:61], v[160:163], v[184:187], v[58:61]
	v_mfma_f32_16x16x32_bf16 v[46:49], v[152:155], v[192:195], v[46:49]
	v_mfma_f32_16x16x32_bf16 v[42:45], v[160:163], v[192:195], v[42:45]
	v_mfma_f32_16x16x32_bf16 v[30:33], v[152:155], v[200:203], v[30:33]
	v_mfma_f32_16x16x32_bf16 v[26:29], v[160:163], v[200:203], v[26:29]
	v_mfma_f32_16x16x32_bf16 v[14:17], v[152:155], v[208:211], v[14:17]
	v_mfma_f32_16x16x32_bf16 v[10:13], v[160:163], v[208:211], v[10:13]
	v_mfma_f32_16x16x32_bf16 v[62:65], v[156:159], v[188:191], v[62:65]
	v_mfma_f32_16x16x32_bf16 v[58:61], v[164:167], v[188:191], v[58:61]
	v_mfma_f32_16x16x32_bf16 v[46:49], v[156:159], v[196:199], v[46:49]
	v_mfma_f32_16x16x32_bf16 v[42:45], v[164:167], v[196:199], v[42:45]
	v_mfma_f32_16x16x32_bf16 v[30:33], v[156:159], v[204:207], v[30:33]
	v_mfma_f32_16x16x32_bf16 v[26:29], v[164:167], v[204:207], v[26:29]
	v_mfma_f32_16x16x32_bf16 v[14:17], v[156:159], v[212:215], v[14:17]
	v_mfma_f32_16x16x32_bf16 v[10:13], v[164:167], v[212:215], v[10:13]
	s_setprio 2
	s_setprio 0
	v_mfma_f32_16x16x32_bf16 v[54:57], v[168:171], v[184:187], v[54:57]
	v_mfma_f32_16x16x32_bf16 v[50:53], v[176:179], v[184:187], v[50:53]
	v_mfma_f32_16x16x32_bf16 v[38:41], v[168:171], v[192:195], v[38:41]
	v_mfma_f32_16x16x32_bf16 v[34:37], v[176:179], v[192:195], v[34:37]
	v_mfma_f32_16x16x32_bf16 v[22:25], v[168:171], v[200:203], v[22:25]
	v_mfma_f32_16x16x32_bf16 v[18:21], v[176:179], v[200:203], v[18:21]
	v_mfma_f32_16x16x32_bf16 v[6:9], v[168:171], v[208:211], v[6:9]
	v_mfma_f32_16x16x32_bf16 v[2:5], v[176:179], v[208:211], v[2:5]
	v_mfma_f32_16x16x32_bf16 v[54:57], v[172:175], v[188:191], v[54:57]
	v_mfma_f32_16x16x32_bf16 v[50:53], v[180:183], v[188:191], v[50:53]
	v_mfma_f32_16x16x32_bf16 v[38:41], v[172:175], v[196:199], v[38:41]
	v_mfma_f32_16x16x32_bf16 v[34:37], v[180:183], v[196:199], v[34:37]
	v_mfma_f32_16x16x32_bf16 v[22:25], v[172:175], v[204:207], v[22:25]
	v_mfma_f32_16x16x32_bf16 v[18:21], v[180:183], v[204:207], v[18:21]
	v_mfma_f32_16x16x32_bf16 v[6:9], v[172:175], v[212:215], v[6:9]
	v_mfma_f32_16x16x32_bf16 v[2:5], v[180:183], v[212:215], v[2:5]
	s_setprio 2
	s_barrier
; #define PG8_STAGE(bufoff, gbase, voff) do { _Pragma("unroll") for (int _i = 0; _i < 2; ++_i) \
;         __builtin_amdgcn_global_load_lds((const unsigned*)((const char*)(gbase) + (voff)[_i]), (LAS unsigned*)(lds + (bufoff) + ldsw + _i * 8192), 16, 0, 0); } while (0)
; #define PG8_LDA(dst, b, h) do { _Pragma("unroll") for (int m = 0; m < 4; ++m) _Pragma("unroll") for (int k = 0; k < 2; ++k) dst[m][k] = *(const LAS bf16x8*)(lds + PG8_SA(b, h) + aoff + m * 2048 + k * 1024); } while (0)
; #define PG8_LDB(dst, b, h) do { _Pragma("unroll") for (int n = 0; n < 2; ++n) _Pragma("unroll") for (int k = 0; k < 2; ++k) dst[n][k] = *(const LAS bf16x8*)(lds + PG8_SB(b, h) + boff + n * 2048 + k * 1024); } while (0)
; #define PG8_MMA(ai, bj, At, Bt) do { __builtin_amdgcn_s_setprio(1); _Pragma("unroll") for (int m = 0; m < 4; ++m) _Pragma("unroll") for (int n = 0; n < 2; ++n) _Pragma("unroll") for (int k = 0; k < 2; ++k) \
;         acc[ai][bj][m][n] = __builtin_amdgcn_mfma_f32_16x16x32_bf16(Bt[n][k], At[m][k], acc[ai][bj][m][n], 0, 0, 0); __builtin_amdgcn_s_setprio(0); } while (0)
; #define PG8_WAIT_V(n) asm volatile("s_waitcnt vmcnt(" #n ")" ::: "memory")
; #define PG8_WAIT_L(n) asm volatile("s_waitcnt lgkmcnt(" #n ")" ::: "memory")
; #define PG8_BAR __builtin_amdgcn_s_barrier()
; #define PG8_SCHED __builtin_amdgcn_sched_barrier(0)
; template <class Epi>
; __device__ __forceinline__ void gemm_phase(LAS unsigned char* lds, const Gemm g, int G, int c, const Epi& E) {
;     ...
;             PG8_LDB(B0, 1, 0); PG8_LDB(B1, 1, 1); PG8_SCHED; PG8_LDA(At, 1, 0); PG8_STAGE(PG8_SA(0, 1), a2 + hstepA, voffA);
;             PG8_WAIT_V(8); PG8_WAIT_L(0); PG8_BAR; PG8_MMA(0, 0, At, B0); PG8_MMA(0, 1, At, B1); PG8_BAR; PG8_SCHED;
	s_add_i32 s33, 0, 0x18000
	s_add_i32 s69, 0, 0x1c000
	v_add_u32_e32 v164, s33, v147
	v_add_u32_e32 v180, s69, v147
	ds_read_b128 v[152:155], v164
	ds_read_b128 v[156:159], v164 offset:1024
	ds_read_b128 v[160:163], v164 offset:2048
	ds_read_b128 v[164:167], v164 offset:3072
	ds_read_b128 v[168:171], v180
	ds_read_b128 v[172:175], v180 offset:1024
	ds_read_b128 v[176:179], v180 offset:2048
	ds_read_b128 v[180:183], v180 offset:3072
	s_add_u32 s40, s40, 0x40000
	s_addc_u32 s41, s41, 0
	s_mov_b32 m0, s47
	v_lshl_add_u64 v[224:225], s[40:41], 0, v[136:137]
	ds_read_b128 v[184:187], v150 offset:32768
	ds_read_b128 v[188:191], v150 offset:33792
	ds_read_b128 v[192:195], v150 offset:34816
	ds_read_b128 v[196:199], v150 offset:35840
	ds_read_b128 v[200:203], v150 offset:36864
	ds_read_b128 v[204:207], v150 offset:37888
	ds_read_b128 v[208:211], v150 offset:38912
	ds_read_b128 v[212:215], v150 offset:39936
	global_load_lds_dwordx4 v[224:225], off
	v_lshl_add_u64 v[224:225], s[40:41], 0, v[132:133]
	s_mov_b32 m0, s48
	s_nop 0
	global_load_lds_dwordx4 v[224:225], off
	s_waitcnt vmcnt(8)
	s_waitcnt lgkmcnt(0)
	s_barrier
	s_setprio 0
	v_mfma_f32_16x16x32_bf16 v[126:129], v[152:155], v[184:187], v[126:129]
	v_mfma_f32_16x16x32_bf16 v[122:125], v[160:163], v[184:187], v[122:125]
	v_mfma_f32_16x16x32_bf16 v[110:113], v[152:155], v[192:195], v[110:113]
	v_mfma_f32_16x16x32_bf16 v[106:109], v[160:163], v[192:195], v[106:109]
	v_mfma_f32_16x16x32_bf16 v[94:97], v[152:155], v[200:203], v[94:97]
	v_mfma_f32_16x16x32_bf16 v[90:93], v[160:163], v[200:203], v[90:93]
	v_mfma_f32_16x16x32_bf16 v[78:81], v[152:155], v[208:211], v[78:81]
	v_mfma_f32_16x16x32_bf16 v[74:77], v[160:163], v[208:211], v[74:77]
	v_mfma_f32_16x16x32_bf16 v[126:129], v[156:159], v[188:191], v[126:129]
	v_mfma_f32_16x16x32_bf16 v[122:125], v[164:167], v[188:191], v[122:125]
	v_mfma_f32_16x16x32_bf16 v[110:113], v[156:159], v[196:199], v[110:113]
	v_mfma_f32_16x16x32_bf16 v[106:109], v[164:167], v[196:199], v[106:109]
	v_mfma_f32_16x16x32_bf16 v[94:97], v[156:159], v[204:207], v[94:97]
	v_mfma_f32_16x16x32_bf16 v[90:93], v[164:167], v[204:207], v[90:93]
	v_mfma_f32_16x16x32_bf16 v[78:81], v[156:159], v[212:215], v[78:81]
	v_mfma_f32_16x16x32_bf16 v[74:77], v[164:167], v[212:215], v[74:77]
	s_setprio 2
	s_setprio 0
	v_mfma_f32_16x16x32_bf16 v[118:121], v[168:171], v[184:187], v[118:121]
	v_mfma_f32_16x16x32_bf16 v[114:117], v[176:179], v[184:187], v[114:117]
	v_mfma_f32_16x16x32_bf16 v[102:105], v[168:171], v[192:195], v[102:105]
	v_mfma_f32_16x16x32_bf16 v[98:101], v[176:179], v[192:195], v[98:101]
	v_mfma_f32_16x16x32_bf16 v[86:89], v[168:171], v[200:203], v[86:89]
	v_mfma_f32_16x16x32_bf16 v[82:85], v[176:179], v[200:203], v[82:85]
	v_mfma_f32_16x16x32_bf16 v[70:73], v[168:171], v[208:211], v[70:73]
	v_mfma_f32_16x16x32_bf16 v[66:69], v[176:179], v[208:211], v[66:69]
	v_mfma_f32_16x16x32_bf16 v[118:121], v[172:175], v[188:191], v[118:121]
	v_mfma_f32_16x16x32_bf16 v[114:117], v[180:183], v[188:191], v[114:117]
	v_mfma_f32_16x16x32_bf16 v[102:105], v[172:175], v[196:199], v[102:105]
	v_mfma_f32_16x16x32_bf16 v[98:101], v[180:183], v[196:199], v[98:101]
	v_mfma_f32_16x16x32_bf16 v[86:89], v[172:175], v[204:207], v[86:89]
	v_mfma_f32_16x16x32_bf16 v[82:85], v[180:183], v[204:207], v[82:85]
	v_mfma_f32_16x16x32_bf16 v[70:73], v[172:175], v[212:215], v[70:73]
	v_mfma_f32_16x16x32_bf16 v[66:69], v[180:183], v[212:215], v[66:69]
	s_setprio 2
	s_barrier
; #define PG8_STAGE(bufoff, gbase, voff) do { _Pragma("unroll") for (int _i = 0; _i < 2; ++_i) \
;         __builtin_amdgcn_global_load_lds((const unsigned*)((const char*)(gbase) + (voff)[_i]), (LAS unsigned*)(lds + (bufoff) + ldsw + _i * 8192), 16, 0, 0); } while (0)
; #define PG8_LDA(dst, b, h) do { _Pragma("unroll") for (int m = 0; m < 4; ++m) _Pragma("unroll") for (int k = 0; k < 2; ++k) dst[m][k] = *(const LAS bf16x8*)(lds + PG8_SA(b, h) + aoff + m * 2048 + k * 1024); } while (0)
; #define PG8_MMA(ai, bj, At, Bt) do { __builtin_amdgcn_s_setprio(1); _Pragma("unroll") for (int m = 0; m < 4; ++m) _Pragma("unroll") for (int n = 0; n < 2; ++n) _Pragma("unroll") for (int k = 0; k < 2; ++k) \
;         acc[ai][bj][m][n] = __builtin_amdgcn_mfma_f32_16x16x32_bf16(Bt[n][k], At[m][k], acc[ai][bj][m][n], 0, 0, 0); __builtin_amdgcn_s_setprio(0); } while (0)
; #define PG8_WAIT_V(n) asm volatile("s_waitcnt vmcnt(" #n ")" ::: "memory")
; #define PG8_WAIT_L(n) asm volatile("s_waitcnt lgkmcnt(" #n ")" ::: "memory")
; #define PG8_BAR __builtin_amdgcn_s_barrier()
; #define PG8_SCHED __builtin_amdgcn_sched_barrier(0)
; template <class Epi>
; __device__ __forceinline__ void gemm_phase(LAS unsigned char* lds, const Gemm g, int G, int c, const Epi& E) {
;     ...
;             PG8_LDA(At, 1, 1); PG8_STAGE(PG8_SB(1, 0), b3, voffB); PG8_STAGE(PG8_SB(1, 1), b3 + hstepB, voffB); PG8_STAGE(PG8_SA(1, 0), a3, voffA);
;             PG8_WAIT_V(8); PG8_WAIT_L(0); PG8_BAR; PG8_MMA(1, 0, At, B0); PG8_MMA(1, 1, At, B1); PG8_BAR; PG8_SCHED;
;         }
;         if (wr == 0) PG8_BAR;
	s_add_i32 s33, s33, s46
	v_lshl_add_u64 v[216:217], v[216:217], 0, s[12:13]
	s_mov_b32 m0, s33
	ds_read_b128 v[184:187], v150 offset:49152
	ds_read_b128 v[188:191], v150 offset:50176
	ds_read_b128 v[192:195], v150 offset:51200
	ds_read_b128 v[196:199], v150 offset:52224
	ds_read_b128 v[200:203], v150 offset:53248
	ds_read_b128 v[204:207], v150 offset:54272
	ds_read_b128 v[208:211], v150 offset:55296
	ds_read_b128 v[212:215], v150 offset:56320
	global_load_lds_dwordx4 v[216:217], off
	s_add_i32 m0, s33, 0x2000
	s_add_u32 s38, s38, 0x40080
	v_lshl_add_u64 v[216:217], v[218:219], 0, s[12:13]
	s_addc_u32 s39, s39, 0
	s_add_i32 s33, s69, s46
	global_load_lds_dwordx4 v[216:217], off
	v_lshl_add_u64 v[216:217], s[38:39], 0, v[134:135]
	s_mov_b32 m0, s33
	s_nop 0
	global_load_lds_dwordx4 v[216:217], off
	v_lshl_add_u64 v[216:217], s[38:39], 0, v[130:131]
	s_add_i32 m0, s33, 0x2000
	s_nop 0
	global_load_lds_dwordx4 v[216:217], off
	v_lshl_add_u64 v[216:217], v[220:221], 0, s[12:13]
	s_mov_b32 m0, s53
	s_nop 0
	global_load_lds_dwordx4 v[216:217], off
	v_lshl_add_u64 v[216:217], v[222:223], 0, s[12:13]
	s_mov_b32 m0, s54
	s_nop 0
	global_load_lds_dwordx4 v[216:217], off
	s_waitcnt vmcnt(8)
	s_waitcnt lgkmcnt(0)
	s_barrier
	s_setprio 0
	v_mfma_f32_16x16x32_bf16 v[62:65], v[152:155], v[184:187], v[62:65]
	v_mfma_f32_16x16x32_bf16 v[58:61], v[160:163], v[184:187], v[58:61]
	v_mfma_f32_16x16x32_bf16 v[46:49], v[152:155], v[192:195], v[46:49]
	v_mfma_f32_16x16x32_bf16 v[42:45], v[160:163], v[192:195], v[42:45]
	v_mfma_f32_16x16x32_bf16 v[30:33], v[152:155], v[200:203], v[30:33]
	v_mfma_f32_16x16x32_bf16 v[26:29], v[160:163], v[200:203], v[26:29]
	v_mfma_f32_16x16x32_bf16 v[14:17], v[152:155], v[208:211], v[14:17]
	v_mfma_f32_16x16x32_bf16 v[10:13], v[160:163], v[208:211], v[10:13]
	v_mfma_f32_16x16x32_bf16 v[62:65], v[156:159], v[188:191], v[62:65]
	v_mfma_f32_16x16x32_bf16 v[58:61], v[164:167], v[188:191], v[58:61]
	v_mfma_f32_16x16x32_bf16 v[46:49], v[156:159], v[196:199], v[46:49]
	v_mfma_f32_16x16x32_bf16 v[42:45], v[164:167], v[196:199], v[42:45]
	v_mfma_f32_16x16x32_bf16 v[30:33], v[156:159], v[204:207], v[30:33]
	v_mfma_f32_16x16x32_bf16 v[26:29], v[164:167], v[204:207], v[26:29]
	v_mfma_f32_16x16x32_bf16 v[14:17], v[156:159], v[212:215], v[14:17]
	v_mfma_f32_16x16x32_bf16 v[10:13], v[164:167], v[212:215], v[10:13]
	s_setprio 2
	s_setprio 0
	v_mfma_f32_16x16x32_bf16 v[54:57], v[168:171], v[184:187], v[54:57]
	v_mfma_f32_16x16x32_bf16 v[50:53], v[176:179], v[184:187], v[50:53]
	v_mfma_f32_16x16x32_bf16 v[38:41], v[168:171], v[192:195], v[38:41]
	v_mfma_f32_16x16x32_bf16 v[34:37], v[176:179], v[192:195], v[34:37]
	v_mfma_f32_16x16x32_bf16 v[22:25], v[168:171], v[200:203], v[22:25]
	v_mfma_f32_16x16x32_bf16 v[18:21], v[176:179], v[200:203], v[18:21]
	v_mfma_f32_16x16x32_bf16 v[6:9], v[168:171], v[208:211], v[6:9]
	v_mfma_f32_16x16x32_bf16 v[2:5], v[176:179], v[208:211], v[2:5]
	v_mfma_f32_16x16x32_bf16 v[54:57], v[172:175], v[188:191], v[54:57]
	v_mfma_f32_16x16x32_bf16 v[50:53], v[180:183], v[188:191], v[50:53]
	v_mfma_f32_16x16x32_bf16 v[38:41], v[172:175], v[196:199], v[38:41]
	v_mfma_f32_16x16x32_bf16 v[34:37], v[180:183], v[196:199], v[34:37]
	v_mfma_f32_16x16x32_bf16 v[22:25], v[172:175], v[204:207], v[22:25]
	v_mfma_f32_16x16x32_bf16 v[18:21], v[180:183], v[204:207], v[18:21]
	v_mfma_f32_16x16x32_bf16 v[6:9], v[172:175], v[212:215], v[6:9]
	v_mfma_f32_16x16x32_bf16 v[2:5], v[180:183], v[212:215], v[2:5]
	s_setprio 2
	s_add_i32 s68, s68, 2
	s_add_u32 s4, s4, 0x100
	s_addc_u32 s5, s5, 0
	s_add_u32 s66, s66, 0x100
	s_addc_u32 s67, s67, 0
	s_cmp_gt_u32 s68, 13
	s_barrier
	s_cbranch_scc0 .LBB0_2084
	s_and_b64 vcc, exec, s[14:15]
	s_cbranch_vccz .LBB0_2087
	s_barrier

; #define PG8_STAGE(bufoff, gbase, voff) do { _Pragma("unroll") for (int _i = 0; _i < 2; ++_i) \
;         __builtin_amdgcn_global_load_lds((const unsigned*)((const char*)(gbase) + (voff)[_i]), (LAS unsigned*)(lds + (bufoff) + ldsw + _i * 8192), 16, 0, 0); } while (0)
; #define PG8_LDA(dst, b, h) do { _Pragma("unroll") for (int m = 0; m < 4; ++m) _Pragma("unroll") for (int k = 0; k < 2; ++k) dst[m][k] = *(const LAS bf16x8*)(lds + PG8_SA(b, h) + aoff + m * 2048 + k * 1024); } while (0)
; #define PG8_LDB(dst, b, h) do { _Pragma("unroll") for (int n = 0; n < 2; ++n) _Pragma("unroll") for (int k = 0; k < 2; ++k) dst[n][k] = *(const LAS bf16x8*)(lds + PG8_SB(b, h) + boff + n * 2048 + k * 1024); } while (0)
; #define PG8_MMA(ai, bj, At, Bt) do { __builtin_amdgcn_s_setprio(1); _Pragma("unroll") for (int m = 0; m < 4; ++m) _Pragma("unroll") for (int n = 0; n < 2; ++n) _Pragma("unroll") for (int k = 0; k < 2; ++k) \
;         acc[ai][bj][m][n] = __builtin_amdgcn_mfma_f32_16x16x32_bf16(Bt[n][k], At[m][k], acc[ai][bj][m][n], 0, 0, 0); __builtin_amdgcn_s_setprio(0); } while (0)
; #define PG8_WAIT_V(n) asm volatile("s_waitcnt vmcnt(" #n ")" ::: "memory")
; #define PG8_WAIT_L(n) asm volatile("s_waitcnt lgkmcnt(" #n ")" ::: "memory")
; #define PG8_BAR __builtin_amdgcn_s_barrier()
; #define PG8_SCHED __builtin_amdgcn_sched_barrier(0)
; template <class Epi>
; __device__ __forceinline__ void gemm_phase(LAS unsigned char* lds, const Gemm g, int G, int c, const Epi& E) {
;     ...
;         for (int t = 0; t < nt; t += 2) {
;             const bool last = (t == nt - 2);
;             const char* a1 = cA + (size_t)(t + 1) * kstep;
;             const char* a2 = last ? nA : cA + (size_t)(t + 2) * kstep; const char* b2 = last ? nB : cB + (size_t)(t + 2) * kstep;
;             const char* a3 = a2 + kstep; const char* b3 = b2 + kstep;
;             PG8_LDB(B0, 0, 0); PG8_LDB(B1, 0, 1); PG8_SCHED; PG8_LDA(At, 0, 0); PG8_STAGE(PG8_SA(1, 1), a1 + hstepA, voffA);
;             PG8_WAIT_V(8); PG8_WAIT_L(0); PG8_BAR; PG8_MMA(0, 0, At, B0); PG8_MMA(0, 1, At, B1); PG8_BAR; PG8_SCHED;
;             PG8_LDA(At, 0, 1); PG8_STAGE(PG8_SB(0, 0), b2, voffB); PG8_STAGE(PG8_SB(0, 1), b2 + hstepB, voffB); PG8_STAGE(PG8_SA(0, 0), a2, voffA);
;             PG8_WAIT_V(8); PG8_WAIT_L(0); PG8_BAR; PG8_MMA(1, 0, At, B0); PG8_MMA(1, 1, At, B1); PG8_BAR; PG8_SCHED;
.LBB0_2168:
	s_add_u32 s60, s20, 0x100
	s_addc_u32 s61, s21, 0
	s_mov_b32 s62, -2
	s_waitcnt vmcnt(0)
	ds_read_b128 v[106:109], v168
	ds_read_b128 v[110:113], v168 offset:1024
	ds_read_b128 v[114:117], v168 offset:2048
	ds_read_b128 v[118:121], v168 offset:3072
	ds_read_b128 v[162:165], v169
	ds_read_b128 v[172:175], v169 offset:1024
	ds_read_b128 v[176:179], v169 offset:2048
	ds_read_b128 v[180:183], v169 offset:3072
	s_add_u32 s20, s18, 0x100
	s_addc_u32 s21, s19, 0
	s_cmp_eq_u32 s62, 40
	s_cselect_b32 s25, s5, s21
	s_cselect_b32 s24, s4, s20
	s_cselect_b32 s23, s17, s61
	s_cselect_b32 s22, s16, s60
	v_lshl_add_u64 v[216:217], s[18:19], 0, v[154:155]
	s_add_i32 m0, s40, 0xc000
	ds_read_b128 v[184:187], v170
	ds_read_b128 v[188:191], v170 offset:1024
	ds_read_b128 v[192:195], v170 offset:2048
	ds_read_b128 v[196:199], v170 offset:3072
	ds_read_b128 v[200:203], v170 offset:4096
	ds_read_b128 v[204:207], v170 offset:5120
	ds_read_b128 v[208:211], v170 offset:6144
	ds_read_b128 v[212:215], v170 offset:7168
	global_load_lds_dwordx4 v[216:217], off
	v_lshl_add_u64 v[216:217], s[18:19], 0, v[156:157]
	s_add_i32 m0, s40, 0xe000
	s_nop 0
	global_load_lds_dwordx4 v[216:217], off
	s_waitcnt vmcnt(8)
	s_waitcnt lgkmcnt(0)
	s_barrier
	s_setprio 0
	v_mfma_f32_16x16x32_bf16 v[142:145], v[106:109], v[184:187], 0
	v_mfma_f32_16x16x32_bf16 v[138:141], v[114:117], v[184:187], 0
	v_mfma_f32_16x16x32_bf16 v[126:129], v[106:109], v[192:195], 0
	v_mfma_f32_16x16x32_bf16 v[122:125], v[114:117], v[192:195], 0
	v_mfma_f32_16x16x32_bf16 v[94:97], v[106:109], v[200:203], 0
	v_mfma_f32_16x16x32_bf16 v[90:93], v[114:117], v[200:203], 0
	v_mfma_f32_16x16x32_bf16 v[78:81], v[106:109], v[208:211], 0
	v_mfma_f32_16x16x32_bf16 v[74:77], v[114:117], v[208:211], 0
	v_mfma_f32_16x16x32_bf16 v[142:145], v[110:113], v[188:191], v[142:145]
	v_mfma_f32_16x16x32_bf16 v[138:141], v[118:121], v[188:191], v[138:141]
	v_mfma_f32_16x16x32_bf16 v[126:129], v[110:113], v[196:199], v[126:129]
	v_mfma_f32_16x16x32_bf16 v[122:125], v[118:121], v[196:199], v[122:125]
	v_mfma_f32_16x16x32_bf16 v[94:97], v[110:113], v[204:207], v[94:97]
	v_mfma_f32_16x16x32_bf16 v[90:93], v[118:121], v[204:207], v[90:93]
	v_mfma_f32_16x16x32_bf16 v[78:81], v[110:113], v[212:215], v[78:81]
	v_mfma_f32_16x16x32_bf16 v[74:77], v[118:121], v[212:215], v[74:77]
	s_setprio 2
	s_setprio 0
	v_mfma_f32_16x16x32_bf16 v[134:137], v[162:165], v[184:187], 0
	v_mfma_f32_16x16x32_bf16 v[130:133], v[176:179], v[184:187], 0
	v_mfma_f32_16x16x32_bf16 v[102:105], v[162:165], v[192:195], 0
	v_mfma_f32_16x16x32_bf16 v[98:101], v[176:179], v[192:195], 0
	v_mfma_f32_16x16x32_bf16 v[86:89], v[162:165], v[200:203], 0
	v_mfma_f32_16x16x32_bf16 v[82:85], v[176:179], v[200:203], 0
	v_mfma_f32_16x16x32_bf16 v[70:73], v[162:165], v[208:211], 0
	v_mfma_f32_16x16x32_bf16 v[66:69], v[176:179], v[208:211], 0
	v_mfma_f32_16x16x32_bf16 v[134:137], v[172:175], v[188:191], v[134:137]
	v_mfma_f32_16x16x32_bf16 v[130:133], v[180:183], v[188:191], v[130:133]
	v_mfma_f32_16x16x32_bf16 v[102:105], v[172:175], v[196:199], v[102:105]
	v_mfma_f32_16x16x32_bf16 v[98:101], v[180:183], v[196:199], v[98:101]
	v_mfma_f32_16x16x32_bf16 v[86:89], v[172:175], v[204:207], v[86:89]
	v_mfma_f32_16x16x32_bf16 v[82:85], v[180:183], v[204:207], v[82:85]
	v_mfma_f32_16x16x32_bf16 v[70:73], v[172:175], v[212:215], v[70:73]
	v_mfma_f32_16x16x32_bf16 v[66:69], v[180:183], v[212:215], v[66:69]
	s_setprio 2
	s_barrier
	s_add_i32 s18, s52, s38
	v_lshl_add_u64 v[216:217], s[22:23], 0, v[150:151]
	s_mov_b32 m0, s18
	ds_read_b128 v[184:187], v170 offset:16384
	ds_read_b128 v[188:191], v170 offset:17408
	ds_read_b128 v[192:195], v170 offset:18432
	ds_read_b128 v[196:199], v170 offset:19456
	ds_read_b128 v[200:203], v170 offset:20480
	ds_read_b128 v[204:207], v170 offset:21504
	ds_read_b128 v[208:211], v170 offset:22528
	ds_read_b128 v[212:215], v170 offset:23552
	global_load_lds_dwordx4 v[216:217], off
	s_add_i32 m0, s18, 0x2000
	s_add_u32 s18, s22, 0xb0000
	v_lshl_add_u64 v[218:219], s[22:23], 0, v[146:147]
	s_addc_u32 s19, s23, 0
	s_add_i32 s33, s53, s38
	global_load_lds_dwordx4 v[218:219], off
	v_lshl_add_u64 v[220:221], s[18:19], 0, v[150:151]
	s_mov_b32 m0, s33
	v_lshl_add_u64 v[222:223], s[24:25], 0, v[148:149]
	global_load_lds_dwordx4 v[220:221], off
	v_lshl_add_u64 v[220:221], s[18:19], 0, v[146:147]
	s_add_i32 m0, s33, 0x2000
	s_nop 0
	global_load_lds_dwordx4 v[220:221], off
	v_lshl_add_u64 v[220:221], s[24:25], 0, v[152:153]
	s_mov_b32 m0, s40
	s_nop 0
	global_load_lds_dwordx4 v[220:221], off
	s_mov_b32 m0, s41
	s_nop 0
	global_load_lds_dwordx4 v[222:223], off
	s_waitcnt vmcnt(8)
	s_waitcnt lgkmcnt(0)
	s_barrier
; #define PG8_STAGE(bufoff, gbase, voff) do { _Pragma("unroll") for (int _i = 0; _i < 2; ++_i) \
;         __builtin_amdgcn_global_load_lds((const unsigned*)((const char*)(gbase) + (voff)[_i]), (LAS unsigned*)(lds + (bufoff) + ldsw + _i * 8192), 16, 0, 0); } while (0)
; #define PG8_LDA(dst, b, h) do { _Pragma("unroll") for (int m = 0; m < 4; ++m) _Pragma("unroll") for (int k = 0; k < 2; ++k) dst[m][k] = *(const LAS bf16x8*)(lds + PG8_SA(b, h) + aoff + m * 2048 + k * 1024); } while (0)
; #define PG8_LDB(dst, b, h) do { _Pragma("unroll") for (int n = 0; n < 2; ++n) _Pragma("unroll") for (int k = 0; k < 2; ++k) dst[n][k] = *(const LAS bf16x8*)(lds + PG8_SB(b, h) + boff + n * 2048 + k * 1024); } while (0)
; #define PG8_MMA(ai, bj, At, Bt) do { __builtin_amdgcn_s_setprio(1); _Pragma("unroll") for (int m = 0; m < 4; ++m) _Pragma("unroll") for (int n = 0; n < 2; ++n) _Pragma("unroll") for (int k = 0; k < 2; ++k) \
;         acc[ai][bj][m][n] = __builtin_amdgcn_mfma_f32_16x16x32_bf16(Bt[n][k], At[m][k], acc[ai][bj][m][n], 0, 0, 0); __builtin_amdgcn_s_setprio(0); } while (0)
; #define PG8_WAIT_V(n) asm volatile("s_waitcnt vmcnt(" #n ")" ::: "memory")
; #define PG8_WAIT_L(n) asm volatile("s_waitcnt lgkmcnt(" #n ")" ::: "memory")
; #define PG8_BAR __builtin_amdgcn_s_barrier()
; #define PG8_SCHED __builtin_amdgcn_sched_barrier(0)
; template <class Epi>
; __device__ __forceinline__ void gemm_phase(LAS unsigned char* lds, const Gemm g, int G, int c, const Epi& E) {
;     ...
;             PG8_WAIT_V(8); PG8_WAIT_L(0); PG8_BAR; PG8_MMA(1, 0, At, B0); PG8_MMA(1, 1, At, B1); PG8_BAR; PG8_SCHED;
;             PG8_LDB(B0, 1, 0); PG8_LDB(B1, 1, 1); PG8_SCHED; PG8_LDA(At, 1, 0); PG8_STAGE(PG8_SA(0, 1), a2 + hstepA, voffA);
;             PG8_WAIT_V(8); PG8_WAIT_L(0); PG8_BAR; PG8_MMA(0, 0, At, B0); PG8_MMA(0, 1, At, B1); PG8_BAR; PG8_SCHED;
	s_setprio 0
	v_mfma_f32_16x16x32_bf16 v[62:65], v[106:109], v[184:187], 0
	v_mfma_f32_16x16x32_bf16 v[58:61], v[114:117], v[184:187], 0
	v_mfma_f32_16x16x32_bf16 v[46:49], v[106:109], v[192:195], 0
	v_mfma_f32_16x16x32_bf16 v[42:45], v[114:117], v[192:195], 0
	v_mfma_f32_16x16x32_bf16 v[30:33], v[106:109], v[200:203], 0
	v_mfma_f32_16x16x32_bf16 v[26:29], v[114:117], v[200:203], 0
	v_mfma_f32_16x16x32_bf16 v[14:17], v[106:109], v[208:211], 0
	v_mfma_f32_16x16x32_bf16 v[10:13], v[114:117], v[208:211], 0
	v_mfma_f32_16x16x32_bf16 v[62:65], v[110:113], v[188:191], v[62:65]
	v_mfma_f32_16x16x32_bf16 v[58:61], v[118:121], v[188:191], v[58:61]
	v_mfma_f32_16x16x32_bf16 v[46:49], v[110:113], v[196:199], v[46:49]
	v_mfma_f32_16x16x32_bf16 v[42:45], v[118:121], v[196:199], v[42:45]
	v_mfma_f32_16x16x32_bf16 v[30:33], v[110:113], v[204:207], v[30:33]
	v_mfma_f32_16x16x32_bf16 v[26:29], v[118:121], v[204:207], v[26:29]
	v_mfma_f32_16x16x32_bf16 v[14:17], v[110:113], v[212:215], v[14:17]
	v_mfma_f32_16x16x32_bf16 v[10:13], v[118:121], v[212:215], v[10:13]
	s_setprio 2
	s_setprio 0
	v_mfma_f32_16x16x32_bf16 v[54:57], v[162:165], v[184:187], 0
	v_mfma_f32_16x16x32_bf16 v[50:53], v[176:179], v[184:187], 0
	v_mfma_f32_16x16x32_bf16 v[38:41], v[162:165], v[192:195], 0
	v_mfma_f32_16x16x32_bf16 v[34:37], v[176:179], v[192:195], 0
	v_mfma_f32_16x16x32_bf16 v[22:25], v[162:165], v[200:203], 0
	v_mfma_f32_16x16x32_bf16 v[18:21], v[176:179], v[200:203], 0
	v_mfma_f32_16x16x32_bf16 v[6:9], v[162:165], v[208:211], 0
	v_mfma_f32_16x16x32_bf16 v[2:5], v[176:179], v[208:211], 0
	v_mfma_f32_16x16x32_bf16 v[54:57], v[172:175], v[188:191], v[54:57]
	v_mfma_f32_16x16x32_bf16 v[50:53], v[180:183], v[188:191], v[50:53]
	v_mfma_f32_16x16x32_bf16 v[38:41], v[172:175], v[196:199], v[38:41]
	v_mfma_f32_16x16x32_bf16 v[34:37], v[180:183], v[196:199], v[34:37]
	v_mfma_f32_16x16x32_bf16 v[22:25], v[172:175], v[204:207], v[22:25]
	v_mfma_f32_16x16x32_bf16 v[18:21], v[180:183], v[204:207], v[18:21]
	v_mfma_f32_16x16x32_bf16 v[6:9], v[172:175], v[212:215], v[6:9]
	v_mfma_f32_16x16x32_bf16 v[2:5], v[180:183], v[212:215], v[2:5]
	s_setprio 2
	s_barrier
	s_add_i32 s33, 0, 0x18000
	s_add_i32 s63, 0, 0x1c000
	v_add_u32_e32 v118, s33, v167
	v_add_u32_e32 v171, s63, v167
	ds_read_b128 v[106:109], v118
	ds_read_b128 v[110:113], v118 offset:1024
	ds_read_b128 v[114:117], v118 offset:2048
	ds_read_b128 v[118:121], v118 offset:3072
	ds_read_b128 v[162:165], v171
	ds_read_b128 v[172:175], v171 offset:1024
	ds_read_b128 v[176:179], v171 offset:2048
	ds_read_b128 v[180:183], v171 offset:3072
	s_add_u32 s18, s24, 0xb0000
	s_addc_u32 s19, s25, 0
	s_mov_b32 m0, s42
	v_lshl_add_u64 v[224:225], s[18:19], 0, v[152:153]
	ds_read_b128 v[184:187], v170 offset:32768
	ds_read_b128 v[188:191], v170 offset:33792
	ds_read_b128 v[192:195], v170 offset:34816
	ds_read_b128 v[196:199], v170 offset:35840
	ds_read_b128 v[200:203], v170 offset:36864
	ds_read_b128 v[204:207], v170 offset:37888
	ds_read_b128 v[208:211], v170 offset:38912
	ds_read_b128 v[212:215], v170 offset:39936
	global_load_lds_dwordx4 v[224:225], off
	v_lshl_add_u64 v[224:225], s[18:19], 0, v[148:149]
	s_mov_b32 m0, s43
	s_nop 0
	global_load_lds_dwordx4 v[224:225], off
	s_waitcnt vmcnt(8)
	s_waitcnt lgkmcnt(0)
	s_barrier
	s_setprio 0
	v_mfma_f32_16x16x32_bf16 v[142:145], v[106:109], v[184:187], v[142:145]
	v_mfma_f32_16x16x32_bf16 v[138:141], v[114:117], v[184:187], v[138:141]
	v_mfma_f32_16x16x32_bf16 v[126:129], v[106:109], v[192:195], v[126:129]
	v_mfma_f32_16x16x32_bf16 v[122:125], v[114:117], v[192:195], v[122:125]
	v_mfma_f32_16x16x32_bf16 v[94:97], v[106:109], v[200:203], v[94:97]
	v_mfma_f32_16x16x32_bf16 v[90:93], v[114:117], v[200:203], v[90:93]
	v_mfma_f32_16x16x32_bf16 v[78:81], v[106:109], v[208:211], v[78:81]
	v_mfma_f32_16x16x32_bf16 v[74:77], v[114:117], v[208:211], v[74:77]
	v_mfma_f32_16x16x32_bf16 v[142:145], v[110:113], v[188:191], v[142:145]
	v_mfma_f32_16x16x32_bf16 v[138:141], v[118:121], v[188:191], v[138:141]
	v_mfma_f32_16x16x32_bf16 v[126:129], v[110:113], v[196:199], v[126:129]
	v_mfma_f32_16x16x32_bf16 v[122:125], v[118:121], v[196:199], v[122:125]
	v_mfma_f32_16x16x32_bf16 v[94:97], v[110:113], v[204:207], v[94:97]
	v_mfma_f32_16x16x32_bf16 v[90:93], v[118:121], v[204:207], v[90:93]
	v_mfma_f32_16x16x32_bf16 v[78:81], v[110:113], v[212:215], v[78:81]
	v_mfma_f32_16x16x32_bf16 v[74:77], v[118:121], v[212:215], v[74:77]
	s_setprio 2
	s_setprio 0
	v_mfma_f32_16x16x32_bf16 v[134:137], v[162:165], v[184:187], v[134:137]
	v_mfma_f32_16x16x32_bf16 v[130:133], v[176:179], v[184:187], v[130:133]
	v_mfma_f32_16x16x32_bf16 v[102:105], v[162:165], v[192:195], v[102:105]
	v_mfma_f32_16x16x32_bf16 v[98:101], v[176:179], v[192:195], v[98:101]
	v_mfma_f32_16x16x32_bf16 v[86:89], v[162:165], v[200:203], v[86:89]
	v_mfma_f32_16x16x32_bf16 v[82:85], v[176:179], v[200:203], v[82:85]
	v_mfma_f32_16x16x32_bf16 v[70:73], v[162:165], v[208:211], v[70:73]
	v_mfma_f32_16x16x32_bf16 v[66:69], v[176:179], v[208:211], v[66:69]
	v_mfma_f32_16x16x32_bf16 v[134:137], v[172:175], v[188:191], v[134:137]
	v_mfma_f32_16x16x32_bf16 v[130:133], v[180:183], v[188:191], v[130:133]
	v_mfma_f32_16x16x32_bf16 v[102:105], v[172:175], v[196:199], v[102:105]
	v_mfma_f32_16x16x32_bf16 v[98:101], v[180:183], v[196:199], v[98:101]
	v_mfma_f32_16x16x32_bf16 v[86:89], v[172:175], v[204:207], v[86:89]
	v_mfma_f32_16x16x32_bf16 v[82:85], v[180:183], v[204:207], v[82:85]
	v_mfma_f32_16x16x32_bf16 v[70:73], v[172:175], v[212:215], v[70:73]
	v_mfma_f32_16x16x32_bf16 v[66:69], v[180:183], v[212:215], v[66:69]
	s_setprio 2
	s_barrier
; #define PG8_STAGE(bufoff, gbase, voff) do { _Pragma("unroll") for (int _i = 0; _i < 2; ++_i) \
;         __builtin_amdgcn_global_load_lds((const unsigned*)((const char*)(gbase) + (voff)[_i]), (LAS unsigned*)(lds + (bufoff) + ldsw + _i * 8192), 16, 0, 0); } while (0)
; #define PG8_LDA(dst, b, h) do { _Pragma("unroll") for (int m = 0; m < 4; ++m) _Pragma("unroll") for (int k = 0; k < 2; ++k) dst[m][k] = *(const LAS bf16x8*)(lds + PG8_SA(b, h) + aoff + m * 2048 + k * 1024); } while (0)
; #define PG8_LDB(dst, b, h) do { _Pragma("unroll") for (int n = 0; n < 2; ++n) _Pragma("unroll") for (int k = 0; k < 2; ++k) dst[n][k] = *(const LAS bf16x8*)(lds + PG8_SB(b, h) + boff + n * 2048 + k * 1024); } while (0)
; #define PG8_MMA(ai, bj, At, Bt) do { __builtin_amdgcn_s_setprio(1); _Pragma("unroll") for (int m = 0; m < 4; ++m) _Pragma("unroll") for (int n = 0; n < 2; ++n) _Pragma("unroll") for (int k = 0; k < 2; ++k) \
;         acc[ai][bj][m][n] = __builtin_amdgcn_mfma_f32_16x16x32_bf16(Bt[n][k], At[m][k], acc[ai][bj][m][n], 0, 0, 0); __builtin_amdgcn_s_setprio(0); } while (0)
; #define PG8_WAIT_V(n) asm volatile("s_waitcnt vmcnt(" #n ")" ::: "memory")
; #define PG8_BAR __builtin_amdgcn_s_barrier()
; template <class Epi>
; __device__ __forceinline__ void gemm_phase(LAS unsigned char* lds, const Gemm g, int G, int c, const Epi& E) {
;     ...
;             PG8_LDB(B0, 0, 0); PG8_LDB(B1, 0, 1); PG8_SCHED; PG8_LDA(At, 0, 0); PG8_STAGE(PG8_SA(1, 1), a1 + hstepA, voffA);
;             PG8_WAIT_V(8); PG8_WAIT_L(0); PG8_BAR; PG8_MMA(0, 0, At, B0); PG8_MMA(0, 1, At, B1); PG8_BAR; PG8_SCHED;
;             PG8_LDA(At, 0, 1); PG8_STAGE(PG8_SB(0, 0), b2, voffB); PG8_STAGE(PG8_SB(0, 1), b2 + hstepB, voffB); PG8_STAGE(PG8_SA(0, 0), a2, voffA);
;             PG8_WAIT_V(8); PG8_WAIT_L(0); PG8_BAR; PG8_MMA(1, 0, At, B0); PG8_MMA(1, 1, At, B1); PG8_BAR; PG8_SCHED;
;             PG8_LDB(B0, 1, 0); PG8_LDB(B1, 1, 1); PG8_SCHED; PG8_LDA(At, 1, 0); PG8_STAGE(PG8_SA(0, 1), a2 + hstepA, voffA);
;             PG8_WAIT_V(8); PG8_WAIT_L(0); PG8_BAR; PG8_MMA(0, 0, At, B0); PG8_MMA(0, 1, At, B1); PG8_BAR; PG8_SCHED;
;             PG8_LDA(At, 1, 1); PG8_STAGE(PG8_SB(1, 0), b3, voffB); PG8_STAGE(PG8_SB(1, 1), b3 + hstepB, voffB); PG8_STAGE(PG8_SA(1, 0), a3, voffA);
;             PG8_WAIT_V(8); PG8_WAIT_L(0); PG8_BAR; PG8_MMA(1, 0, At, B0); PG8_MMA(1, 1, At, B1); PG8_BAR; PG8_SCHED;
;         }
	s_add_i32 s18, s33, s38
	v_lshl_add_u64 v[216:217], v[216:217], 0, s[12:13]
	s_mov_b32 m0, s18
	ds_read_b128 v[184:187], v170 offset:49152
	ds_read_b128 v[188:191], v170 offset:50176
	ds_read_b128 v[192:195], v170 offset:51200
	ds_read_b128 v[196:199], v170 offset:52224
	ds_read_b128 v[200:203], v170 offset:53248
	ds_read_b128 v[204:207], v170 offset:54272
	ds_read_b128 v[208:211], v170 offset:55296
	ds_read_b128 v[212:215], v170 offset:56320
	global_load_lds_dwordx4 v[216:217], off
	s_add_i32 m0, s18, 0x2000
	s_add_u32 s18, s22, 0xb0080
	v_lshl_add_u64 v[216:217], v[218:219], 0, s[12:13]
	s_addc_u32 s19, s23, 0
	s_add_i32 s22, s63, s38
	global_load_lds_dwordx4 v[216:217], off
	v_lshl_add_u64 v[216:217], s[18:19], 0, v[150:151]
	s_mov_b32 m0, s22
	s_nop 0
	global_load_lds_dwordx4 v[216:217], off
	v_lshl_add_u64 v[216:217], s[18:19], 0, v[146:147]
	s_add_i32 m0, s22, 0x2000
	s_nop 0
	global_load_lds_dwordx4 v[216:217], off
	v_lshl_add_u64 v[216:217], v[220:221], 0, s[12:13]
	s_mov_b32 m0, s49
	s_nop 0
	global_load_lds_dwordx4 v[216:217], off
	v_lshl_add_u64 v[216:217], v[222:223], 0, s[12:13]
	s_mov_b32 m0, s50
	s_nop 0
	global_load_lds_dwordx4 v[216:217], off
	s_waitcnt vmcnt(8)
	s_waitcnt lgkmcnt(0)
	s_barrier
	s_setprio 0
	v_mfma_f32_16x16x32_bf16 v[62:65], v[106:109], v[184:187], v[62:65]
	v_mfma_f32_16x16x32_bf16 v[58:61], v[114:117], v[184:187], v[58:61]
	v_mfma_f32_16x16x32_bf16 v[46:49], v[106:109], v[192:195], v[46:49]
	v_mfma_f32_16x16x32_bf16 v[42:45], v[114:117], v[192:195], v[42:45]
	v_mfma_f32_16x16x32_bf16 v[30:33], v[106:109], v[200:203], v[30:33]
	v_mfma_f32_16x16x32_bf16 v[26:29], v[114:117], v[200:203], v[26:29]
	v_mfma_f32_16x16x32_bf16 v[14:17], v[106:109], v[208:211], v[14:17]
	v_mfma_f32_16x16x32_bf16 v[10:13], v[114:117], v[208:211], v[10:13]
	v_mfma_f32_16x16x32_bf16 v[62:65], v[110:113], v[188:191], v[62:65]
	v_mfma_f32_16x16x32_bf16 v[58:61], v[118:121], v[188:191], v[58:61]
	v_mfma_f32_16x16x32_bf16 v[46:49], v[110:113], v[196:199], v[46:49]
	v_mfma_f32_16x16x32_bf16 v[42:45], v[118:121], v[196:199], v[42:45]
	v_mfma_f32_16x16x32_bf16 v[30:33], v[110:113], v[204:207], v[30:33]
	v_mfma_f32_16x16x32_bf16 v[26:29], v[118:121], v[204:207], v[26:29]
	v_mfma_f32_16x16x32_bf16 v[14:17], v[110:113], v[212:215], v[14:17]
	v_mfma_f32_16x16x32_bf16 v[10:13], v[118:121], v[212:215], v[10:13]
	s_setprio 2
	s_setprio 0
	v_mfma_f32_16x16x32_bf16 v[54:57], v[162:165], v[184:187], v[54:57]
	v_mfma_f32_16x16x32_bf16 v[50:53], v[176:179], v[184:187], v[50:53]
	v_mfma_f32_16x16x32_bf16 v[38:41], v[162:165], v[192:195], v[38:41]
	v_mfma_f32_16x16x32_bf16 v[34:37], v[176:179], v[192:195], v[34:37]
	v_mfma_f32_16x16x32_bf16 v[22:25], v[162:165], v[200:203], v[22:25]
	v_mfma_f32_16x16x32_bf16 v[18:21], v[176:179], v[200:203], v[18:21]
	v_mfma_f32_16x16x32_bf16 v[6:9], v[162:165], v[208:211], v[6:9]
	v_mfma_f32_16x16x32_bf16 v[2:5], v[176:179], v[208:211], v[2:5]
	v_mfma_f32_16x16x32_bf16 v[54:57], v[172:175], v[188:191], v[54:57]
	v_mfma_f32_16x16x32_bf16 v[50:53], v[180:183], v[188:191], v[50:53]
	v_mfma_f32_16x16x32_bf16 v[38:41], v[172:175], v[196:199], v[38:41]
	v_mfma_f32_16x16x32_bf16 v[34:37], v[180:183], v[196:199], v[34:37]
	v_mfma_f32_16x16x32_bf16 v[22:25], v[172:175], v[204:207], v[22:25]
	v_mfma_f32_16x16x32_bf16 v[18:21], v[180:183], v[204:207], v[18:21]
	v_mfma_f32_16x16x32_bf16 v[6:9], v[172:175], v[212:215], v[6:9]
	v_mfma_f32_16x16x32_bf16 v[2:5], v[180:183], v[212:215], v[2:5]
	s_setprio 2
	s_add_i32 s62, s62, 2
	s_add_u32 s60, s60, 0x100
	s_addc_u32 s61, s61, 0
	s_cmp_gt_u32 s62, 41
	s_mov_b64 s[18:19], s[20:21]
	s_barrier
	s_cbranch_scc0 .LBB0_2169
.LBB0_2169:
	ds_read_b128 v[106:109], v168
	ds_read_b128 v[110:113], v168 offset:1024
	ds_read_b128 v[114:117], v168 offset:2048
	ds_read_b128 v[118:121], v168 offset:3072
	ds_read_b128 v[162:165], v169
	ds_read_b128 v[172:175], v169 offset:1024
	ds_read_b128 v[176:179], v169 offset:2048
	ds_read_b128 v[180:183], v169 offset:3072
	s_add_u32 s20, s18, 0x100
	s_addc_u32 s21, s19, 0
	s_cmp_eq_u32 s62, 40
	s_cselect_b32 s25, s5, s21
	s_cselect_b32 s24, s4, s20
	s_cselect_b32 s23, s17, s61
	s_cselect_b32 s22, s16, s60
	v_lshl_add_u64 v[216:217], s[18:19], 0, v[154:155]
	s_add_i32 m0, s40, 0xc000
	ds_read_b128 v[184:187], v170
	ds_read_b128 v[188:191], v170 offset:1024
	ds_read_b128 v[192:195], v170 offset:2048
	ds_read_b128 v[196:199], v170 offset:3072
	ds_read_b128 v[200:203], v170 offset:4096
	ds_read_b128 v[204:207], v170 offset:5120
	ds_read_b128 v[208:211], v170 offset:6144
	ds_read_b128 v[212:215], v170 offset:7168
	global_load_lds_dwordx4 v[216:217], off
	v_lshl_add_u64 v[216:217], s[18:19], 0, v[156:157]
	s_add_i32 m0, s40, 0xe000
	s_nop 0
	global_load_lds_dwordx4 v[216:217], off
	s_waitcnt vmcnt(8)
	s_waitcnt lgkmcnt(0)
	s_barrier
; #define PG8_STAGE(bufoff, gbase, voff) do { _Pragma("unroll") for (int _i = 0; _i < 2; ++_i) \
;         __builtin_amdgcn_global_load_lds((const unsigned*)((const char*)(gbase) + (voff)[_i]), (LAS unsigned*)(lds + (bufoff) + ldsw + _i * 8192), 16, 0, 0); } while (0)
; #define PG8_LDA(dst, b, h) do { _Pragma("unroll") for (int m = 0; m < 4; ++m) _Pragma("unroll") for (int k = 0; k < 2; ++k) dst[m][k] = *(const LAS bf16x8*)(lds + PG8_SA(b, h) + aoff + m * 2048 + k * 1024); } while (0)
; #define PG8_MMA(ai, bj, At, Bt) do { __builtin_amdgcn_s_setprio(1); _Pragma("unroll") for (int m = 0; m < 4; ++m) _Pragma("unroll") for (int n = 0; n < 2; ++n) _Pragma("unroll") for (int k = 0; k < 2; ++k) \
;         acc[ai][bj][m][n] = __builtin_amdgcn_mfma_f32_16x16x32_bf16(Bt[n][k], At[m][k], acc[ai][bj][m][n], 0, 0, 0); __builtin_amdgcn_s_setprio(0); } while (0)
; #define PG8_WAIT_V(n) asm volatile("s_waitcnt vmcnt(" #n ")" ::: "memory")
; #define PG8_WAIT_L(n) asm volatile("s_waitcnt lgkmcnt(" #n ")" ::: "memory")
; #define PG8_BAR __builtin_amdgcn_s_barrier()
; #define PG8_SCHED __builtin_amdgcn_sched_barrier(0)
; template <class Epi>
; __device__ __forceinline__ void gemm_phase(LAS unsigned char* lds, const Gemm g, int G, int c, const Epi& E) {
;     ...
;             PG8_WAIT_V(8); PG8_WAIT_L(0); PG8_BAR; PG8_MMA(0, 0, At, B0); PG8_MMA(0, 1, At, B1); PG8_BAR; PG8_SCHED;
;             PG8_LDA(At, 0, 1); PG8_STAGE(PG8_SB(0, 0), b2, voffB); PG8_STAGE(PG8_SB(0, 1), b2 + hstepB, voffB); PG8_STAGE(PG8_SA(0, 0), a2, voffA);
;             PG8_WAIT_V(8); PG8_WAIT_L(0); PG8_BAR; PG8_MMA(1, 0, At, B0); PG8_MMA(1, 1, At, B1); PG8_BAR; PG8_SCHED;
	s_setprio 0
	v_mfma_f32_16x16x32_bf16 v[142:145], v[106:109], v[184:187], v[142:145]
	v_mfma_f32_16x16x32_bf16 v[138:141], v[114:117], v[184:187], v[138:141]
	v_mfma_f32_16x16x32_bf16 v[126:129], v[106:109], v[192:195], v[126:129]
	v_mfma_f32_16x16x32_bf16 v[122:125], v[114:117], v[192:195], v[122:125]
	v_mfma_f32_16x16x32_bf16 v[94:97], v[106:109], v[200:203], v[94:97]
	v_mfma_f32_16x16x32_bf16 v[90:93], v[114:117], v[200:203], v[90:93]
	v_mfma_f32_16x16x32_bf16 v[78:81], v[106:109], v[208:211], v[78:81]
	v_mfma_f32_16x16x32_bf16 v[74:77], v[114:117], v[208:211], v[74:77]
	v_mfma_f32_16x16x32_bf16 v[142:145], v[110:113], v[188:191], v[142:145]
	v_mfma_f32_16x16x32_bf16 v[138:141], v[118:121], v[188:191], v[138:141]
	v_mfma_f32_16x16x32_bf16 v[126:129], v[110:113], v[196:199], v[126:129]
	v_mfma_f32_16x16x32_bf16 v[122:125], v[118:121], v[196:199], v[122:125]
	v_mfma_f32_16x16x32_bf16 v[94:97], v[110:113], v[204:207], v[94:97]
	v_mfma_f32_16x16x32_bf16 v[90:93], v[118:121], v[204:207], v[90:93]
	v_mfma_f32_16x16x32_bf16 v[78:81], v[110:113], v[212:215], v[78:81]
	v_mfma_f32_16x16x32_bf16 v[74:77], v[118:121], v[212:215], v[74:77]
	s_setprio 2
	s_setprio 0
	v_mfma_f32_16x16x32_bf16 v[134:137], v[162:165], v[184:187], v[134:137]
	v_mfma_f32_16x16x32_bf16 v[130:133], v[176:179], v[184:187], v[130:133]
	v_mfma_f32_16x16x32_bf16 v[102:105], v[162:165], v[192:195], v[102:105]
	v_mfma_f32_16x16x32_bf16 v[98:101], v[176:179], v[192:195], v[98:101]
	v_mfma_f32_16x16x32_bf16 v[86:89], v[162:165], v[200:203], v[86:89]
	v_mfma_f32_16x16x32_bf16 v[82:85], v[176:179], v[200:203], v[82:85]
	v_mfma_f32_16x16x32_bf16 v[70:73], v[162:165], v[208:211], v[70:73]
	v_mfma_f32_16x16x32_bf16 v[66:69], v[176:179], v[208:211], v[66:69]
	v_mfma_f32_16x16x32_bf16 v[134:137], v[172:175], v[188:191], v[134:137]
	v_mfma_f32_16x16x32_bf16 v[130:133], v[180:183], v[188:191], v[130:133]
	v_mfma_f32_16x16x32_bf16 v[102:105], v[172:175], v[196:199], v[102:105]
	v_mfma_f32_16x16x32_bf16 v[98:101], v[180:183], v[196:199], v[98:101]
	v_mfma_f32_16x16x32_bf16 v[86:89], v[172:175], v[204:207], v[86:89]
	v_mfma_f32_16x16x32_bf16 v[82:85], v[180:183], v[204:207], v[82:85]
	v_mfma_f32_16x16x32_bf16 v[70:73], v[172:175], v[212:215], v[70:73]
	v_mfma_f32_16x16x32_bf16 v[66:69], v[180:183], v[212:215], v[66:69]
	s_setprio 2
	s_barrier
	s_add_i32 s18, s52, s38
	v_lshl_add_u64 v[216:217], s[22:23], 0, v[150:151]
	s_mov_b32 m0, s18
	ds_read_b128 v[184:187], v170 offset:16384
	ds_read_b128 v[188:191], v170 offset:17408
	ds_read_b128 v[192:195], v170 offset:18432
	ds_read_b128 v[196:199], v170 offset:19456
	ds_read_b128 v[200:203], v170 offset:20480
	ds_read_b128 v[204:207], v170 offset:21504
	ds_read_b128 v[208:211], v170 offset:22528
	ds_read_b128 v[212:215], v170 offset:23552
	global_load_lds_dwordx4 v[216:217], off
	s_add_i32 m0, s18, 0x2000
	s_add_u32 s18, s22, 0xb0000
	v_lshl_add_u64 v[218:219], s[22:23], 0, v[146:147]
	s_addc_u32 s19, s23, 0
	s_add_i32 s33, s53, s38
	global_load_lds_dwordx4 v[218:219], off
	v_lshl_add_u64 v[220:221], s[18:19], 0, v[150:151]
	s_mov_b32 m0, s33
	v_lshl_add_u64 v[222:223], s[24:25], 0, v[148:149]
	global_load_lds_dwordx4 v[220:221], off
	v_lshl_add_u64 v[220:221], s[18:19], 0, v[146:147]
	s_add_i32 m0, s33, 0x2000
	s_nop 0
	global_load_lds_dwordx4 v[220:221], off
	v_lshl_add_u64 v[220:221], s[24:25], 0, v[152:153]
	s_mov_b32 m0, s40
	s_nop 0
	global_load_lds_dwordx4 v[220:221], off
	s_mov_b32 m0, s41
	s_nop 0
	global_load_lds_dwordx4 v[222:223], off
	s_waitcnt vmcnt(8)
	s_waitcnt lgkmcnt(0)
	s_barrier
	s_setprio 0
	v_mfma_f32_16x16x32_bf16 v[62:65], v[106:109], v[184:187], v[62:65]
	v_mfma_f32_16x16x32_bf16 v[58:61], v[114:117], v[184:187], v[58:61]
	v_mfma_f32_16x16x32_bf16 v[46:49], v[106:109], v[192:195], v[46:49]
	v_mfma_f32_16x16x32_bf16 v[42:45], v[114:117], v[192:195], v[42:45]
	v_mfma_f32_16x16x32_bf16 v[30:33], v[106:109], v[200:203], v[30:33]
	v_mfma_f32_16x16x32_bf16 v[26:29], v[114:117], v[200:203], v[26:29]
	v_mfma_f32_16x16x32_bf16 v[14:17], v[106:109], v[208:211], v[14:17]
	v_mfma_f32_16x16x32_bf16 v[10:13], v[114:117], v[208:211], v[10:13]
	v_mfma_f32_16x16x32_bf16 v[62:65], v[110:113], v[188:191], v[62:65]
	v_mfma_f32_16x16x32_bf16 v[58:61], v[118:121], v[188:191], v[58:61]
	v_mfma_f32_16x16x32_bf16 v[46:49], v[110:113], v[196:199], v[46:49]
	v_mfma_f32_16x16x32_bf16 v[42:45], v[118:121], v[196:199], v[42:45]
	v_mfma_f32_16x16x32_bf16 v[30:33], v[110:113], v[204:207], v[30:33]
	v_mfma_f32_16x16x32_bf16 v[26:29], v[118:121], v[204:207], v[26:29]
	v_mfma_f32_16x16x32_bf16 v[14:17], v[110:113], v[212:215], v[14:17]
	v_mfma_f32_16x16x32_bf16 v[10:13], v[118:121], v[212:215], v[10:13]
	s_setprio 2
	s_setprio 0
	v_mfma_f32_16x16x32_bf16 v[54:57], v[162:165], v[184:187], v[54:57]
	v_mfma_f32_16x16x32_bf16 v[50:53], v[176:179], v[184:187], v[50:53]
	v_mfma_f32_16x16x32_bf16 v[38:41], v[162:165], v[192:195], v[38:41]
	v_mfma_f32_16x16x32_bf16 v[34:37], v[176:179], v[192:195], v[34:37]
	v_mfma_f32_16x16x32_bf16 v[22:25], v[162:165], v[200:203], v[22:25]
	v_mfma_f32_16x16x32_bf16 v[18:21], v[176:179], v[200:203], v[18:21]
	v_mfma_f32_16x16x32_bf16 v[6:9], v[162:165], v[208:211], v[6:9]
	v_mfma_f32_16x16x32_bf16 v[2:5], v[176:179], v[208:211], v[2:5]
	v_mfma_f32_16x16x32_bf16 v[54:57], v[172:175], v[188:191], v[54:57]
	v_mfma_f32_16x16x32_bf16 v[50:53], v[180:183], v[188:191], v[50:53]
	v_mfma_f32_16x16x32_bf16 v[38:41], v[172:175], v[196:199], v[38:41]
	v_mfma_f32_16x16x32_bf16 v[34:37], v[180:183], v[196:199], v[34:37]
	v_mfma_f32_16x16x32_bf16 v[22:25], v[172:175], v[204:207], v[22:25]
	v_mfma_f32_16x16x32_bf16 v[18:21], v[180:183], v[204:207], v[18:21]
	v_mfma_f32_16x16x32_bf16 v[6:9], v[172:175], v[212:215], v[6:9]
	v_mfma_f32_16x16x32_bf16 v[2:5], v[180:183], v[212:215], v[2:5]
	s_setprio 2
	s_barrier
; #define PG8_STAGE(bufoff, gbase, voff) do { _Pragma("unroll") for (int _i = 0; _i < 2; ++_i) \
;         __builtin_amdgcn_global_load_lds((const unsigned*)((const char*)(gbase) + (voff)[_i]), (LAS unsigned*)(lds + (bufoff) + ldsw + _i * 8192), 16, 0, 0); } while (0)
; #define PG8_LDA(dst, b, h) do { _Pragma("unroll") for (int m = 0; m < 4; ++m) _Pragma("unroll") for (int k = 0; k < 2; ++k) dst[m][k] = *(const LAS bf16x8*)(lds + PG8_SA(b, h) + aoff + m * 2048 + k * 1024); } while (0)
; #define PG8_LDB(dst, b, h) do { _Pragma("unroll") for (int n = 0; n < 2; ++n) _Pragma("unroll") for (int k = 0; k < 2; ++k) dst[n][k] = *(const LAS bf16x8*)(lds + PG8_SB(b, h) + boff + n * 2048 + k * 1024); } while (0)
; #define PG8_MMA(ai, bj, At, Bt) do { __builtin_amdgcn_s_setprio(1); _Pragma("unroll") for (int m = 0; m < 4; ++m) _Pragma("unroll") for (int n = 0; n < 2; ++n) _Pragma("unroll") for (int k = 0; k < 2; ++k) \
;         acc[ai][bj][m][n] = __builtin_amdgcn_mfma_f32_16x16x32_bf16(Bt[n][k], At[m][k], acc[ai][bj][m][n], 0, 0, 0); __builtin_amdgcn_s_setprio(0); } while (0)
; #define PG8_WAIT_V(n) asm volatile("s_waitcnt vmcnt(" #n ")" ::: "memory")
; #define PG8_WAIT_L(n) asm volatile("s_waitcnt lgkmcnt(" #n ")" ::: "memory")
; #define PG8_BAR __builtin_amdgcn_s_barrier()
; #define PG8_SCHED __builtin_amdgcn_sched_barrier(0)
; template <class Epi>
; __device__ __forceinline__ void gemm_phase(LAS unsigned char* lds, const Gemm g, int G, int c, const Epi& E) {
;     ...
;             PG8_LDB(B0, 1, 0); PG8_LDB(B1, 1, 1); PG8_SCHED; PG8_LDA(At, 1, 0); PG8_STAGE(PG8_SA(0, 1), a2 + hstepA, voffA);
;             PG8_WAIT_V(8); PG8_WAIT_L(0); PG8_BAR; PG8_MMA(0, 0, At, B0); PG8_MMA(0, 1, At, B1); PG8_BAR; PG8_SCHED;
	s_add_i32 s33, 0, 0x18000
	s_add_i32 s63, 0, 0x1c000
	v_add_u32_e32 v118, s33, v167
	v_add_u32_e32 v171, s63, v167
	ds_read_b128 v[106:109], v118
	ds_read_b128 v[110:113], v118 offset:1024
	ds_read_b128 v[114:117], v118 offset:2048
	ds_read_b128 v[118:121], v118 offset:3072
	ds_read_b128 v[162:165], v171
	ds_read_b128 v[172:175], v171 offset:1024
	ds_read_b128 v[176:179], v171 offset:2048
	ds_read_b128 v[180:183], v171 offset:3072
	s_add_u32 s18, s24, 0xb0000
	s_addc_u32 s19, s25, 0
	s_mov_b32 m0, s42
	v_lshl_add_u64 v[224:225], s[18:19], 0, v[152:153]
	ds_read_b128 v[184:187], v170 offset:32768
	ds_read_b128 v[188:191], v170 offset:33792
	ds_read_b128 v[192:195], v170 offset:34816
	ds_read_b128 v[196:199], v170 offset:35840
	ds_read_b128 v[200:203], v170 offset:36864
	ds_read_b128 v[204:207], v170 offset:37888
	ds_read_b128 v[208:211], v170 offset:38912
	ds_read_b128 v[212:215], v170 offset:39936
	global_load_lds_dwordx4 v[224:225], off
	v_lshl_add_u64 v[224:225], s[18:19], 0, v[148:149]
	s_mov_b32 m0, s43
	s_nop 0
	global_load_lds_dwordx4 v[224:225], off
	s_waitcnt vmcnt(8)
	s_waitcnt lgkmcnt(0)
	s_barrier
	s_setprio 0
	v_mfma_f32_16x16x32_bf16 v[142:145], v[106:109], v[184:187], v[142:145]
	v_mfma_f32_16x16x32_bf16 v[138:141], v[114:117], v[184:187], v[138:141]
	v_mfma_f32_16x16x32_bf16 v[126:129], v[106:109], v[192:195], v[126:129]
	v_mfma_f32_16x16x32_bf16 v[122:125], v[114:117], v[192:195], v[122:125]
	v_mfma_f32_16x16x32_bf16 v[94:97], v[106:109], v[200:203], v[94:97]
	v_mfma_f32_16x16x32_bf16 v[90:93], v[114:117], v[200:203], v[90:93]
	v_mfma_f32_16x16x32_bf16 v[78:81], v[106:109], v[208:211], v[78:81]
	v_mfma_f32_16x16x32_bf16 v[74:77], v[114:117], v[208:211], v[74:77]
	v_mfma_f32_16x16x32_bf16 v[142:145], v[110:113], v[188:191], v[142:145]
	v_mfma_f32_16x16x32_bf16 v[138:141], v[118:121], v[188:191], v[138:141]
	v_mfma_f32_16x16x32_bf16 v[126:129], v[110:113], v[196:199], v[126:129]
	v_mfma_f32_16x16x32_bf16 v[122:125], v[118:121], v[196:199], v[122:125]
	v_mfma_f32_16x16x32_bf16 v[94:97], v[110:113], v[204:207], v[94:97]
	v_mfma_f32_16x16x32_bf16 v[90:93], v[118:121], v[204:207], v[90:93]
	v_mfma_f32_16x16x32_bf16 v[78:81], v[110:113], v[212:215], v[78:81]
	v_mfma_f32_16x16x32_bf16 v[74:77], v[118:121], v[212:215], v[74:77]
	s_setprio 2
	s_setprio 0
	v_mfma_f32_16x16x32_bf16 v[134:137], v[162:165], v[184:187], v[134:137]
	v_mfma_f32_16x16x32_bf16 v[130:133], v[176:179], v[184:187], v[130:133]
	v_mfma_f32_16x16x32_bf16 v[102:105], v[162:165], v[192:195], v[102:105]
	v_mfma_f32_16x16x32_bf16 v[98:101], v[176:179], v[192:195], v[98:101]
	v_mfma_f32_16x16x32_bf16 v[86:89], v[162:165], v[200:203], v[86:89]
	v_mfma_f32_16x16x32_bf16 v[82:85], v[176:179], v[200:203], v[82:85]
	v_mfma_f32_16x16x32_bf16 v[70:73], v[162:165], v[208:211], v[70:73]
	v_mfma_f32_16x16x32_bf16 v[66:69], v[176:179], v[208:211], v[66:69]
	v_mfma_f32_16x16x32_bf16 v[134:137], v[172:175], v[188:191], v[134:137]
	v_mfma_f32_16x16x32_bf16 v[130:133], v[180:183], v[188:191], v[130:133]
	v_mfma_f32_16x16x32_bf16 v[102:105], v[172:175], v[196:199], v[102:105]
	v_mfma_f32_16x16x32_bf16 v[98:101], v[180:183], v[196:199], v[98:101]
	v_mfma_f32_16x16x32_bf16 v[86:89], v[172:175], v[204:207], v[86:89]
	v_mfma_f32_16x16x32_bf16 v[82:85], v[180:183], v[204:207], v[82:85]
	v_mfma_f32_16x16x32_bf16 v[70:73], v[172:175], v[212:215], v[70:73]
	v_mfma_f32_16x16x32_bf16 v[66:69], v[180:183], v[212:215], v[66:69]
	s_setprio 2
	s_barrier
; #define PG8_STAGE(bufoff, gbase, voff) do { _Pragma("unroll") for (int _i = 0; _i < 2; ++_i) \
;         __builtin_amdgcn_global_load_lds((const unsigned*)((const char*)(gbase) + (voff)[_i]), (LAS unsigned*)(lds + (bufoff) + ldsw + _i * 8192), 16, 0, 0); } while (0)
; #define PG8_LDA(dst, b, h) do { _Pragma("unroll") for (int m = 0; m < 4; ++m) _Pragma("unroll") for (int k = 0; k < 2; ++k) dst[m][k] = *(const LAS bf16x8*)(lds + PG8_SA(b, h) + aoff + m * 2048 + k * 1024); } while (0)
; #define PG8_MMA(ai, bj, At, Bt) do { __builtin_amdgcn_s_setprio(1); _Pragma("unroll") for (int m = 0; m < 4; ++m) _Pragma("unroll") for (int n = 0; n < 2; ++n) _Pragma("unroll") for (int k = 0; k < 2; ++k) \
;         acc[ai][bj][m][n] = __builtin_amdgcn_mfma_f32_16x16x32_bf16(Bt[n][k], At[m][k], acc[ai][bj][m][n], 0, 0, 0); __builtin_amdgcn_s_setprio(0); } while (0)
; #define PG8_WAIT_V(n) asm volatile("s_waitcnt vmcnt(" #n ")" ::: "memory")
; #define PG8_WAIT_L(n) asm volatile("s_waitcnt lgkmcnt(" #n ")" ::: "memory")
; #define PG8_BAR __builtin_amdgcn_s_barrier()
; #define PG8_SCHED __builtin_amdgcn_sched_barrier(0)
; template <class Epi>
; __device__ __forceinline__ void gemm_phase(LAS unsigned char* lds, const Gemm g, int G, int c, const Epi& E) {
;     ...
;             PG8_LDA(At, 1, 1); PG8_STAGE(PG8_SB(1, 0), b3, voffB); PG8_STAGE(PG8_SB(1, 1), b3 + hstepB, voffB); PG8_STAGE(PG8_SA(1, 0), a3, voffA);
;             PG8_WAIT_V(8); PG8_WAIT_L(0); PG8_BAR; PG8_MMA(1, 0, At, B0); PG8_MMA(1, 1, At, B1); PG8_BAR; PG8_SCHED;
;         }
;         if (wr == 0) PG8_BAR;
	s_add_i32 s18, s33, s38
	v_lshl_add_u64 v[216:217], v[216:217], 0, s[12:13]
	s_mov_b32 m0, s18
	ds_read_b128 v[184:187], v170 offset:49152
	ds_read_b128 v[188:191], v170 offset:50176
	ds_read_b128 v[192:195], v170 offset:51200
	ds_read_b128 v[196:199], v170 offset:52224
	ds_read_b128 v[200:203], v170 offset:53248
	ds_read_b128 v[204:207], v170 offset:54272
	ds_read_b128 v[208:211], v170 offset:55296
	ds_read_b128 v[212:215], v170 offset:56320
	global_load_lds_dwordx4 v[216:217], off
	s_add_i32 m0, s18, 0x2000
	s_add_u32 s18, s22, 0xb0080
	v_lshl_add_u64 v[216:217], v[218:219], 0, s[12:13]
	s_addc_u32 s19, s23, 0
	s_add_i32 s22, s63, s38
	global_load_lds_dwordx4 v[216:217], off
	v_lshl_add_u64 v[216:217], s[18:19], 0, v[150:151]
	s_mov_b32 m0, s22
	s_nop 0
	global_load_lds_dwordx4 v[216:217], off
	v_lshl_add_u64 v[216:217], s[18:19], 0, v[146:147]
	s_add_i32 m0, s22, 0x2000
	s_nop 0
	global_load_lds_dwordx4 v[216:217], off
	v_lshl_add_u64 v[216:217], v[220:221], 0, s[12:13]
	s_mov_b32 m0, s49
	s_nop 0
	global_load_lds_dwordx4 v[216:217], off
	v_lshl_add_u64 v[216:217], v[222:223], 0, s[12:13]
	s_mov_b32 m0, s50
	s_nop 0
	global_load_lds_dwordx4 v[216:217], off
	s_waitcnt vmcnt(8)
	s_waitcnt lgkmcnt(0)
	s_barrier
	s_setprio 0
	v_mfma_f32_16x16x32_bf16 v[62:65], v[106:109], v[184:187], v[62:65]
	v_mfma_f32_16x16x32_bf16 v[58:61], v[114:117], v[184:187], v[58:61]
	v_mfma_f32_16x16x32_bf16 v[46:49], v[106:109], v[192:195], v[46:49]
	v_mfma_f32_16x16x32_bf16 v[42:45], v[114:117], v[192:195], v[42:45]
	v_mfma_f32_16x16x32_bf16 v[30:33], v[106:109], v[200:203], v[30:33]
	v_mfma_f32_16x16x32_bf16 v[26:29], v[114:117], v[200:203], v[26:29]
	v_mfma_f32_16x16x32_bf16 v[14:17], v[106:109], v[208:211], v[14:17]
	v_mfma_f32_16x16x32_bf16 v[10:13], v[114:117], v[208:211], v[10:13]
	v_mfma_f32_16x16x32_bf16 v[62:65], v[110:113], v[188:191], v[62:65]
	v_mfma_f32_16x16x32_bf16 v[58:61], v[118:121], v[188:191], v[58:61]
	v_mfma_f32_16x16x32_bf16 v[46:49], v[110:113], v[196:199], v[46:49]
	v_mfma_f32_16x16x32_bf16 v[42:45], v[118:121], v[196:199], v[42:45]
	v_mfma_f32_16x16x32_bf16 v[30:33], v[110:113], v[204:207], v[30:33]
	v_mfma_f32_16x16x32_bf16 v[26:29], v[118:121], v[204:207], v[26:29]
	v_mfma_f32_16x16x32_bf16 v[14:17], v[110:113], v[212:215], v[14:17]
	v_mfma_f32_16x16x32_bf16 v[10:13], v[118:121], v[212:215], v[10:13]
	s_setprio 2
	s_setprio 0
	v_mfma_f32_16x16x32_bf16 v[54:57], v[162:165], v[184:187], v[54:57]
	v_mfma_f32_16x16x32_bf16 v[50:53], v[176:179], v[184:187], v[50:53]
	v_mfma_f32_16x16x32_bf16 v[38:41], v[162:165], v[192:195], v[38:41]
	v_mfma_f32_16x16x32_bf16 v[34:37], v[176:179], v[192:195], v[34:37]
	v_mfma_f32_16x16x32_bf16 v[22:25], v[162:165], v[200:203], v[22:25]
	v_mfma_f32_16x16x32_bf16 v[18:21], v[176:179], v[200:203], v[18:21]
	v_mfma_f32_16x16x32_bf16 v[6:9], v[162:165], v[208:211], v[6:9]
	v_mfma_f32_16x16x32_bf16 v[2:5], v[176:179], v[208:211], v[2:5]
	v_mfma_f32_16x16x32_bf16 v[54:57], v[172:175], v[188:191], v[54:57]
	v_mfma_f32_16x16x32_bf16 v[50:53], v[180:183], v[188:191], v[50:53]
	v_mfma_f32_16x16x32_bf16 v[38:41], v[172:175], v[196:199], v[38:41]
	v_mfma_f32_16x16x32_bf16 v[34:37], v[180:183], v[196:199], v[34:37]
	v_mfma_f32_16x16x32_bf16 v[22:25], v[172:175], v[204:207], v[22:25]
	v_mfma_f32_16x16x32_bf16 v[18:21], v[180:183], v[204:207], v[18:21]
	v_mfma_f32_16x16x32_bf16 v[6:9], v[172:175], v[212:215], v[6:9]
	v_mfma_f32_16x16x32_bf16 v[2:5], v[180:183], v[212:215], v[2:5]
	s_setprio 2
	s_add_i32 s62, s62, 2
	s_add_u32 s60, s60, 0x100
	s_addc_u32 s61, s61, 0
	s_cmp_gt_u32 s62, 41
	s_mov_b64 s[18:19], s[20:21]
	s_barrier
	s_cbranch_scc0 .LBB0_2169
	s_and_b64 vcc, exec, s[14:15]
	s_cbranch_vccz .LBB0_2172
	s_barrier
